# comb27 + reads-first: in every steady-state GEMM load segment all LDS fragment reads are issued before the scalar/address code and the LDS-DMA issue (dependency-checked reorder)
# baseline (speedup 1.0000x reference)
; #define PG8_STAGE(bufoff, gbase, voff) do { _Pragma("unroll") for (int _i = 0; _i < 2; ++_i) \
;         __builtin_amdgcn_global_load_lds((const unsigned*)((const char*)(gbase) + (voff)[_i]), (LAS unsigned*)(lds + (bufoff) + ldsw + _i * 8192), 16, 0, 0); } while (0)
; #define PG8_LDA(dst, b, h) do { _Pragma("unroll") for (int m = 0; m < 4; ++m) _Pragma("unroll") for (int k = 0; k < 2; ++k) dst[m][k] = *(const LAS bf16x8*)(lds + PG8_SA(b, h) + aoff + m * 2048 + k * 1024); } while (0)
; #define PG8_LDB(dst, b, h) do { _Pragma("unroll") for (int n = 0; n < 2; ++n) _Pragma("unroll") for (int k = 0; k < 2; ++k) dst[n][k] = *(const LAS bf16x8*)(lds + PG8_SB(b, h) + boff + n * 2048 + k * 1024); } while (0)
; #define PG8_MMA(ai, bj, At, Bt) do { __builtin_amdgcn_s_setprio(1); _Pragma("unroll") for (int m = 0; m < 4; ++m) _Pragma("unroll") for (int n = 0; n < 2; ++n) _Pragma("unroll") for (int k = 0; k < 2; ++k) \
;         acc[ai][bj][m][n] = __builtin_amdgcn_mfma_f32_16x16x32_bf16(Bt[n][k], At[m][k], acc[ai][bj][m][n], 0, 0, 0); __builtin_amdgcn_s_setprio(0); } while (0)
; #define PG8_WAIT_V(n) asm volatile("s_waitcnt vmcnt(" #n ")" ::: "memory")
; #define PG8_WAIT_L(n) asm volatile("s_waitcnt lgkmcnt(" #n ")" ::: "memory")
; #define PG8_BAR __builtin_amdgcn_s_barrier()
; #define PG8_SCHED __builtin_amdgcn_sched_barrier(0)
; template <class Epi>
; __device__ __forceinline__ void gemm_phase(LAS unsigned char* lds, const Gemm g, int G, int c, const Epi& E) {
;     ...
;         for (int t = 0; t < nt; t += 2) {
;             const bool last = (t == nt - 2);
;             const char* a1 = cA + (size_t)(t + 1) * kstep;
;             const char* a2 = last ? nA : cA + (size_t)(t + 2) * kstep; const char* b2 = last ? nB : cB + (size_t)(t + 2) * kstep;
;             const char* a3 = a2 + kstep; const char* b3 = b2 + kstep;
;             PG8_LDB(B0, 0, 0); PG8_LDB(B1, 0, 1); PG8_SCHED; PG8_LDA(At, 0, 0); PG8_STAGE(PG8_SA(1, 1), a1 + hstepA, voffA);
;             PG8_WAIT_V(8); PG8_WAIT_L(0); PG8_BAR; PG8_MMA(0, 0, At, B0); PG8_MMA(0, 1, At, B1); PG8_BAR; PG8_SCHED;
;             PG8_LDA(At, 0, 1); PG8_STAGE(PG8_SB(0, 0), b2, voffB); PG8_STAGE(PG8_SB(0, 1), b2 + hstepB, voffB); PG8_STAGE(PG8_SA(0, 0), a2, voffA);
;             PG8_WAIT_V(8); PG8_WAIT_L(0); PG8_BAR; PG8_MMA(1, 0, At, B0); PG8_MMA(1, 1, At, B1); PG8_BAR; PG8_SCHED;
.LBB0_236:
	ds_read_b128 v[146:149], v152
	ds_read_b128 v[158:161], v152 offset:1024
	ds_read_b128 v[162:165], v152 offset:2048
	ds_read_b128 v[166:169], v152 offset:3072
	ds_read_b128 v[170:173], v153
	ds_read_b128 v[174:177], v153 offset:1024
	ds_read_b128 v[178:181], v153 offset:2048
	ds_read_b128 v[182:185], v153 offset:3072
	ds_read_b128 v[186:189], v154
	ds_read_b128 v[190:193], v154 offset:1024
	ds_read_b128 v[194:197], v154 offset:2048
	ds_read_b128 v[198:201], v154 offset:3072
	ds_read_b128 v[202:205], v154 offset:4096
	ds_read_b128 v[206:209], v154 offset:5120
	ds_read_b128 v[210:213], v154 offset:6144
	ds_read_b128 v[214:217], v154 offset:7168
	s_add_u32 s33, s4, 0xfffc0080
	s_addc_u32 s54, s5, -1
	s_cmp_eq_u32 s85, 12
	s_cselect_b32 s57, s47, s54
	s_cselect_b32 s56, s46, s33
	s_cselect_b32 s55, s7, s84
	s_cselect_b32 s54, s43, s45
	v_lshl_add_u64 v[218:219], s[4:5], 0, v[138:139]
	s_add_i32 m0, s11, 0xc000
	s_nop 0
	global_load_lds_dwordx4 v[218:219], off
	v_lshl_add_u64 v[218:219], s[4:5], 0, v[140:141]
	s_add_i32 m0, s11, 0xe000
	s_nop 0
	global_load_lds_dwordx4 v[218:219], off
	s_waitcnt vmcnt(8)
	s_waitcnt lgkmcnt(0)
	s_barrier
	s_setprio 0
	v_mfma_f32_16x16x32_bf16 v[126:129], v[146:149], v[186:189], v[126:129]
	v_mfma_f32_16x16x32_bf16 v[122:125], v[162:165], v[186:189], v[122:125]
	v_mfma_f32_16x16x32_bf16 v[110:113], v[146:149], v[194:197], v[110:113]
	v_mfma_f32_16x16x32_bf16 v[106:109], v[162:165], v[194:197], v[106:109]
	v_mfma_f32_16x16x32_bf16 v[94:97], v[146:149], v[202:205], v[94:97]
	v_mfma_f32_16x16x32_bf16 v[90:93], v[162:165], v[202:205], v[90:93]
	v_mfma_f32_16x16x32_bf16 v[78:81], v[146:149], v[210:213], v[78:81]
	v_mfma_f32_16x16x32_bf16 v[74:77], v[162:165], v[210:213], v[74:77]
	v_mfma_f32_16x16x32_bf16 v[126:129], v[158:161], v[190:193], v[126:129]
	v_mfma_f32_16x16x32_bf16 v[122:125], v[166:169], v[190:193], v[122:125]
	v_mfma_f32_16x16x32_bf16 v[110:113], v[158:161], v[198:201], v[110:113]
	v_mfma_f32_16x16x32_bf16 v[106:109], v[166:169], v[198:201], v[106:109]
	v_mfma_f32_16x16x32_bf16 v[94:97], v[158:161], v[206:209], v[94:97]
	v_mfma_f32_16x16x32_bf16 v[90:93], v[166:169], v[206:209], v[90:93]
	v_mfma_f32_16x16x32_bf16 v[78:81], v[158:161], v[214:217], v[78:81]
	v_mfma_f32_16x16x32_bf16 v[74:77], v[166:169], v[214:217], v[74:77]
	s_setprio 2
	s_setprio 0
	v_mfma_f32_16x16x32_bf16 v[118:121], v[170:173], v[186:189], v[118:121]
	v_mfma_f32_16x16x32_bf16 v[114:117], v[178:181], v[186:189], v[114:117]
	v_mfma_f32_16x16x32_bf16 v[102:105], v[170:173], v[194:197], v[102:105]
	v_mfma_f32_16x16x32_bf16 v[98:101], v[178:181], v[194:197], v[98:101]
	v_mfma_f32_16x16x32_bf16 v[86:89], v[170:173], v[202:205], v[86:89]
	v_mfma_f32_16x16x32_bf16 v[82:85], v[178:181], v[202:205], v[82:85]
	v_mfma_f32_16x16x32_bf16 v[70:73], v[170:173], v[210:213], v[70:73]
	v_mfma_f32_16x16x32_bf16 v[66:69], v[178:181], v[210:213], v[66:69]
	v_mfma_f32_16x16x32_bf16 v[118:121], v[174:177], v[190:193], v[118:121]
	v_mfma_f32_16x16x32_bf16 v[114:117], v[182:185], v[190:193], v[114:117]
	v_mfma_f32_16x16x32_bf16 v[102:105], v[174:177], v[198:201], v[102:105]
	v_mfma_f32_16x16x32_bf16 v[98:101], v[182:185], v[198:201], v[98:101]
	v_mfma_f32_16x16x32_bf16 v[86:89], v[174:177], v[206:209], v[86:89]
	v_mfma_f32_16x16x32_bf16 v[82:85], v[182:185], v[206:209], v[82:85]
	v_mfma_f32_16x16x32_bf16 v[70:73], v[174:177], v[214:217], v[70:73]
	v_mfma_f32_16x16x32_bf16 v[66:69], v[182:185], v[214:217], v[66:69]
	s_setprio 2
	s_barrier
	ds_read_b128 v[186:189], v154 offset:16384
	ds_read_b128 v[190:193], v154 offset:17408
	ds_read_b128 v[194:197], v154 offset:18432
	ds_read_b128 v[198:201], v154 offset:19456
	ds_read_b128 v[202:205], v154 offset:20480
	ds_read_b128 v[206:209], v154 offset:21504
	ds_read_b128 v[210:213], v154 offset:22528
	ds_read_b128 v[214:217], v154 offset:23552
	s_add_i32 s33, s79, s60
	v_lshl_add_u64 v[218:219], s[54:55], 0, v[132:133]
	s_mov_b32 m0, s33
	s_nop 0
	global_load_lds_dwordx4 v[218:219], off
	s_add_i32 m0, s33, 0x2000
	s_add_u32 s62, s54, 0x40000
	v_lshl_add_u64 v[220:221], s[54:55], 0, v[136:137]
	s_addc_u32 s63, s55, 0
	s_add_i32 s33, s80, s60
	global_load_lds_dwordx4 v[220:221], off
	v_lshl_add_u64 v[222:223], s[62:63], 0, v[132:133]
	s_mov_b32 m0, s33
	v_lshl_add_u64 v[224:225], s[56:57], 0, v[134:135]
	global_load_lds_dwordx4 v[222:223], off
	v_lshl_add_u64 v[222:223], s[62:63], 0, v[136:137]
	s_add_i32 m0, s33, 0x2000
	s_nop 0
	global_load_lds_dwordx4 v[222:223], off
	v_lshl_add_u64 v[222:223], s[56:57], 0, v[130:131]
	s_mov_b32 m0, s11
	s_nop 0
	global_load_lds_dwordx4 v[222:223], off
	s_mov_b32 m0, s61
	s_nop 0
	global_load_lds_dwordx4 v[224:225], off
	s_waitcnt vmcnt(8)
	s_waitcnt lgkmcnt(0)
	s_barrier
; #define PG8_STAGE(bufoff, gbase, voff) do { _Pragma("unroll") for (int _i = 0; _i < 2; ++_i) \
;         __builtin_amdgcn_global_load_lds((const unsigned*)((const char*)(gbase) + (voff)[_i]), (LAS unsigned*)(lds + (bufoff) + ldsw + _i * 8192), 16, 0, 0); } while (0)
; #define PG8_LDA(dst, b, h) do { _Pragma("unroll") for (int m = 0; m < 4; ++m) _Pragma("unroll") for (int k = 0; k < 2; ++k) dst[m][k] = *(const LAS bf16x8*)(lds + PG8_SA(b, h) + aoff + m * 2048 + k * 1024); } while (0)
; #define PG8_LDB(dst, b, h) do { _Pragma("unroll") for (int n = 0; n < 2; ++n) _Pragma("unroll") for (int k = 0; k < 2; ++k) dst[n][k] = *(const LAS bf16x8*)(lds + PG8_SB(b, h) + boff + n * 2048 + k * 1024); } while (0)
; #define PG8_MMA(ai, bj, At, Bt) do { __builtin_amdgcn_s_setprio(1); _Pragma("unroll") for (int m = 0; m < 4; ++m) _Pragma("unroll") for (int n = 0; n < 2; ++n) _Pragma("unroll") for (int k = 0; k < 2; ++k) \
;         acc[ai][bj][m][n] = __builtin_amdgcn_mfma_f32_16x16x32_bf16(Bt[n][k], At[m][k], acc[ai][bj][m][n], 0, 0, 0); __builtin_amdgcn_s_setprio(0); } while (0)
; #define PG8_WAIT_V(n) asm volatile("s_waitcnt vmcnt(" #n ")" ::: "memory")
; #define PG8_WAIT_L(n) asm volatile("s_waitcnt lgkmcnt(" #n ")" ::: "memory")
; #define PG8_BAR __builtin_amdgcn_s_barrier()
; #define PG8_SCHED __builtin_amdgcn_sched_barrier(0)
; template <class Epi>
; __device__ __forceinline__ void gemm_phase(LAS unsigned char* lds, const Gemm g, int G, int c, const Epi& E) {
;     ...
;             PG8_WAIT_V(8); PG8_WAIT_L(0); PG8_BAR; PG8_MMA(1, 0, At, B0); PG8_MMA(1, 1, At, B1); PG8_BAR; PG8_SCHED;
;             PG8_LDB(B0, 1, 0); PG8_LDB(B1, 1, 1); PG8_SCHED; PG8_LDA(At, 1, 0); PG8_STAGE(PG8_SA(0, 1), a2 + hstepA, voffA);
;             PG8_WAIT_V(8); PG8_WAIT_L(0); PG8_BAR; PG8_MMA(0, 0, At, B0); PG8_MMA(0, 1, At, B1); PG8_BAR; PG8_SCHED;
	s_setprio 0
	v_mfma_f32_16x16x32_bf16 v[62:65], v[146:149], v[186:189], v[62:65]
	v_mfma_f32_16x16x32_bf16 v[58:61], v[162:165], v[186:189], v[58:61]
	v_mfma_f32_16x16x32_bf16 v[46:49], v[146:149], v[194:197], v[46:49]
	v_mfma_f32_16x16x32_bf16 v[42:45], v[162:165], v[194:197], v[42:45]
	v_mfma_f32_16x16x32_bf16 v[30:33], v[146:149], v[202:205], v[30:33]
	v_mfma_f32_16x16x32_bf16 v[26:29], v[162:165], v[202:205], v[26:29]
	v_mfma_f32_16x16x32_bf16 v[14:17], v[146:149], v[210:213], v[14:17]
	v_mfma_f32_16x16x32_bf16 v[10:13], v[162:165], v[210:213], v[10:13]
	v_mfma_f32_16x16x32_bf16 v[62:65], v[158:161], v[190:193], v[62:65]
	v_mfma_f32_16x16x32_bf16 v[58:61], v[166:169], v[190:193], v[58:61]
	v_mfma_f32_16x16x32_bf16 v[46:49], v[158:161], v[198:201], v[46:49]
	v_mfma_f32_16x16x32_bf16 v[42:45], v[166:169], v[198:201], v[42:45]
	v_mfma_f32_16x16x32_bf16 v[30:33], v[158:161], v[206:209], v[30:33]
	v_mfma_f32_16x16x32_bf16 v[26:29], v[166:169], v[206:209], v[26:29]
	v_mfma_f32_16x16x32_bf16 v[14:17], v[158:161], v[214:217], v[14:17]
	v_mfma_f32_16x16x32_bf16 v[10:13], v[166:169], v[214:217], v[10:13]
	s_setprio 2
	s_setprio 0
	v_mfma_f32_16x16x32_bf16 v[54:57], v[170:173], v[186:189], v[54:57]
	v_mfma_f32_16x16x32_bf16 v[50:53], v[178:181], v[186:189], v[50:53]
	v_mfma_f32_16x16x32_bf16 v[38:41], v[170:173], v[194:197], v[38:41]
	v_mfma_f32_16x16x32_bf16 v[34:37], v[178:181], v[194:197], v[34:37]
	v_mfma_f32_16x16x32_bf16 v[22:25], v[170:173], v[202:205], v[22:25]
	v_mfma_f32_16x16x32_bf16 v[18:21], v[178:181], v[202:205], v[18:21]
	v_mfma_f32_16x16x32_bf16 v[6:9], v[170:173], v[210:213], v[6:9]
	v_mfma_f32_16x16x32_bf16 v[2:5], v[178:181], v[210:213], v[2:5]
	v_mfma_f32_16x16x32_bf16 v[54:57], v[174:177], v[190:193], v[54:57]
	v_mfma_f32_16x16x32_bf16 v[50:53], v[182:185], v[190:193], v[50:53]
	v_mfma_f32_16x16x32_bf16 v[38:41], v[174:177], v[198:201], v[38:41]
	v_mfma_f32_16x16x32_bf16 v[34:37], v[182:185], v[198:201], v[34:37]
	v_mfma_f32_16x16x32_bf16 v[22:25], v[174:177], v[206:209], v[22:25]
	v_mfma_f32_16x16x32_bf16 v[18:21], v[182:185], v[206:209], v[18:21]
	v_mfma_f32_16x16x32_bf16 v[6:9], v[174:177], v[214:217], v[6:9]
	v_mfma_f32_16x16x32_bf16 v[2:5], v[182:185], v[214:217], v[2:5]
	s_setprio 2
	s_barrier
	s_add_i32 s33, 0, 0x18000
	v_add_u32_e32 v157, s33, v151
	s_add_i32 s62, 0, 0x1c000
	ds_read_b128 v[146:149], v157
	ds_read_b128 v[158:161], v157 offset:1024
	ds_read_b128 v[162:165], v157 offset:2048
	ds_read_b128 v[166:169], v157 offset:3072
	v_add_u32_e32 v157, s62, v151
	ds_read_b128 v[170:173], v157
	ds_read_b128 v[174:177], v157 offset:1024
	ds_read_b128 v[178:181], v157 offset:2048
	ds_read_b128 v[182:185], v157 offset:3072
	ds_read_b128 v[186:189], v154 offset:32768
	ds_read_b128 v[190:193], v154 offset:33792
	ds_read_b128 v[194:197], v154 offset:34816
	ds_read_b128 v[198:201], v154 offset:35840
	ds_read_b128 v[202:205], v154 offset:36864
	ds_read_b128 v[206:209], v154 offset:37888
	ds_read_b128 v[210:213], v154 offset:38912
	ds_read_b128 v[214:217], v154 offset:39936
	s_add_u32 s56, s56, 0x40000
	s_addc_u32 s57, s57, 0
	s_mov_b32 m0, s66
	v_lshl_add_u64 v[226:227], s[56:57], 0, v[130:131]
	global_load_lds_dwordx4 v[226:227], off
	v_lshl_add_u64 v[226:227], s[56:57], 0, v[134:135]
	s_mov_b32 m0, s67
	s_nop 0
	global_load_lds_dwordx4 v[226:227], off
	s_waitcnt vmcnt(8)
	s_waitcnt lgkmcnt(0)
	s_barrier
	s_setprio 0
	v_mfma_f32_16x16x32_bf16 v[126:129], v[146:149], v[186:189], v[126:129]
	v_mfma_f32_16x16x32_bf16 v[122:125], v[162:165], v[186:189], v[122:125]
	v_mfma_f32_16x16x32_bf16 v[110:113], v[146:149], v[194:197], v[110:113]
	v_mfma_f32_16x16x32_bf16 v[106:109], v[162:165], v[194:197], v[106:109]
	v_mfma_f32_16x16x32_bf16 v[94:97], v[146:149], v[202:205], v[94:97]
	v_mfma_f32_16x16x32_bf16 v[90:93], v[162:165], v[202:205], v[90:93]
	v_mfma_f32_16x16x32_bf16 v[78:81], v[146:149], v[210:213], v[78:81]
	v_mfma_f32_16x16x32_bf16 v[74:77], v[162:165], v[210:213], v[74:77]
	v_mfma_f32_16x16x32_bf16 v[126:129], v[158:161], v[190:193], v[126:129]
	v_mfma_f32_16x16x32_bf16 v[122:125], v[166:169], v[190:193], v[122:125]
	v_mfma_f32_16x16x32_bf16 v[110:113], v[158:161], v[198:201], v[110:113]
	v_mfma_f32_16x16x32_bf16 v[106:109], v[166:169], v[198:201], v[106:109]
	v_mfma_f32_16x16x32_bf16 v[94:97], v[158:161], v[206:209], v[94:97]
	v_mfma_f32_16x16x32_bf16 v[90:93], v[166:169], v[206:209], v[90:93]
	v_mfma_f32_16x16x32_bf16 v[78:81], v[158:161], v[214:217], v[78:81]
	v_mfma_f32_16x16x32_bf16 v[74:77], v[166:169], v[214:217], v[74:77]
	s_setprio 2
	s_setprio 0
	v_mfma_f32_16x16x32_bf16 v[118:121], v[170:173], v[186:189], v[118:121]
	v_mfma_f32_16x16x32_bf16 v[114:117], v[178:181], v[186:189], v[114:117]
	v_mfma_f32_16x16x32_bf16 v[102:105], v[170:173], v[194:197], v[102:105]
	v_mfma_f32_16x16x32_bf16 v[98:101], v[178:181], v[194:197], v[98:101]
	v_mfma_f32_16x16x32_bf16 v[86:89], v[170:173], v[202:205], v[86:89]
	v_mfma_f32_16x16x32_bf16 v[82:85], v[178:181], v[202:205], v[82:85]
	v_mfma_f32_16x16x32_bf16 v[70:73], v[170:173], v[210:213], v[70:73]
	v_mfma_f32_16x16x32_bf16 v[66:69], v[178:181], v[210:213], v[66:69]
	v_mfma_f32_16x16x32_bf16 v[118:121], v[174:177], v[190:193], v[118:121]
	v_mfma_f32_16x16x32_bf16 v[114:117], v[182:185], v[190:193], v[114:117]
	v_mfma_f32_16x16x32_bf16 v[102:105], v[174:177], v[198:201], v[102:105]
	v_mfma_f32_16x16x32_bf16 v[98:101], v[182:185], v[198:201], v[98:101]
	v_mfma_f32_16x16x32_bf16 v[86:89], v[174:177], v[206:209], v[86:89]
	v_mfma_f32_16x16x32_bf16 v[82:85], v[182:185], v[206:209], v[82:85]
	v_mfma_f32_16x16x32_bf16 v[70:73], v[174:177], v[214:217], v[70:73]
	v_mfma_f32_16x16x32_bf16 v[66:69], v[182:185], v[214:217], v[66:69]
	s_setprio 2
	s_barrier
; #define PG8_STAGE(bufoff, gbase, voff) do { _Pragma("unroll") for (int _i = 0; _i < 2; ++_i) \
;         __builtin_amdgcn_global_load_lds((const unsigned*)((const char*)(gbase) + (voff)[_i]), (LAS unsigned*)(lds + (bufoff) + ldsw + _i * 8192), 16, 0, 0); } while (0)
; #define PG8_LDA(dst, b, h) do { _Pragma("unroll") for (int m = 0; m < 4; ++m) _Pragma("unroll") for (int k = 0; k < 2; ++k) dst[m][k] = *(const LAS bf16x8*)(lds + PG8_SA(b, h) + aoff + m * 2048 + k * 1024); } while (0)
; #define PG8_MMA(ai, bj, At, Bt) do { __builtin_amdgcn_s_setprio(1); _Pragma("unroll") for (int m = 0; m < 4; ++m) _Pragma("unroll") for (int n = 0; n < 2; ++n) _Pragma("unroll") for (int k = 0; k < 2; ++k) \
;         acc[ai][bj][m][n] = __builtin_amdgcn_mfma_f32_16x16x32_bf16(Bt[n][k], At[m][k], acc[ai][bj][m][n], 0, 0, 0); __builtin_amdgcn_s_setprio(0); } while (0)
; #define PG8_WAIT_V(n) asm volatile("s_waitcnt vmcnt(" #n ")" ::: "memory")
; #define PG8_WAIT_L(n) asm volatile("s_waitcnt lgkmcnt(" #n ")" ::: "memory")
; #define PG8_BAR __builtin_amdgcn_s_barrier()
; #define PG8_SCHED __builtin_amdgcn_sched_barrier(0)
; template <class Epi>
; __device__ __forceinline__ void gemm_phase(LAS unsigned char* lds, const Gemm g, int G, int c, const Epi& E) {
;     ...
;             PG8_LDA(At, 1, 1); PG8_STAGE(PG8_SB(1, 0), b3, voffB); PG8_STAGE(PG8_SB(1, 1), b3 + hstepB, voffB); PG8_STAGE(PG8_SA(1, 0), a3, voffA);
;             PG8_WAIT_V(8); PG8_WAIT_L(0); PG8_BAR; PG8_MMA(1, 0, At, B0); PG8_MMA(1, 1, At, B1); PG8_BAR; PG8_SCHED;
;         }
	ds_read_b128 v[186:189], v154 offset:49152
	ds_read_b128 v[190:193], v154 offset:50176
	ds_read_b128 v[194:197], v154 offset:51200
	ds_read_b128 v[198:201], v154 offset:52224
	ds_read_b128 v[202:205], v154 offset:53248
	ds_read_b128 v[206:209], v154 offset:54272
	ds_read_b128 v[210:213], v154 offset:55296
	ds_read_b128 v[214:217], v154 offset:56320
	s_add_i32 s33, s33, s60
	v_lshl_add_u64 v[218:219], v[218:219], 0, s[20:21]
	s_mov_b32 m0, s33
	s_nop 0
	global_load_lds_dwordx4 v[218:219], off
	s_add_i32 m0, s33, 0x2000
	s_add_u32 s54, s54, 0x40080
	v_lshl_add_u64 v[218:219], v[220:221], 0, s[20:21]
	s_addc_u32 s55, s55, 0
	s_add_i32 s33, s62, s60
	global_load_lds_dwordx4 v[218:219], off
	v_lshl_add_u64 v[218:219], s[54:55], 0, v[132:133]
	s_mov_b32 m0, s33
	s_nop 0
	global_load_lds_dwordx4 v[218:219], off
	v_lshl_add_u64 v[218:219], s[54:55], 0, v[136:137]
	s_add_i32 m0, s33, 0x2000
	s_nop 0
	global_load_lds_dwordx4 v[218:219], off
	v_lshl_add_u64 v[218:219], v[222:223], 0, s[20:21]
	s_mov_b32 m0, s71
	s_nop 0
	global_load_lds_dwordx4 v[218:219], off
	v_lshl_add_u64 v[218:219], v[224:225], 0, s[20:21]
	s_mov_b32 m0, s72
	s_nop 0
	global_load_lds_dwordx4 v[218:219], off
	s_waitcnt vmcnt(8)
	s_waitcnt lgkmcnt(0)
	s_barrier
	s_setprio 0
	v_mfma_f32_16x16x32_bf16 v[62:65], v[146:149], v[186:189], v[62:65]
	v_mfma_f32_16x16x32_bf16 v[58:61], v[162:165], v[186:189], v[58:61]
	v_mfma_f32_16x16x32_bf16 v[46:49], v[146:149], v[194:197], v[46:49]
	v_mfma_f32_16x16x32_bf16 v[42:45], v[162:165], v[194:197], v[42:45]
	v_mfma_f32_16x16x32_bf16 v[30:33], v[146:149], v[202:205], v[30:33]
	v_mfma_f32_16x16x32_bf16 v[26:29], v[162:165], v[202:205], v[26:29]
	v_mfma_f32_16x16x32_bf16 v[14:17], v[146:149], v[210:213], v[14:17]
	v_mfma_f32_16x16x32_bf16 v[10:13], v[162:165], v[210:213], v[10:13]
	v_mfma_f32_16x16x32_bf16 v[62:65], v[158:161], v[190:193], v[62:65]
	v_mfma_f32_16x16x32_bf16 v[58:61], v[166:169], v[190:193], v[58:61]
	v_mfma_f32_16x16x32_bf16 v[46:49], v[158:161], v[198:201], v[46:49]
	v_mfma_f32_16x16x32_bf16 v[42:45], v[166:169], v[198:201], v[42:45]
	v_mfma_f32_16x16x32_bf16 v[30:33], v[158:161], v[206:209], v[30:33]
	v_mfma_f32_16x16x32_bf16 v[26:29], v[166:169], v[206:209], v[26:29]
	v_mfma_f32_16x16x32_bf16 v[14:17], v[158:161], v[214:217], v[14:17]
	v_mfma_f32_16x16x32_bf16 v[10:13], v[166:169], v[214:217], v[10:13]
	s_setprio 2
	s_setprio 0
	v_mfma_f32_16x16x32_bf16 v[54:57], v[170:173], v[186:189], v[54:57]
	v_mfma_f32_16x16x32_bf16 v[50:53], v[178:181], v[186:189], v[50:53]
	v_mfma_f32_16x16x32_bf16 v[38:41], v[170:173], v[194:197], v[38:41]
	v_mfma_f32_16x16x32_bf16 v[34:37], v[178:181], v[194:197], v[34:37]
	v_mfma_f32_16x16x32_bf16 v[22:25], v[170:173], v[202:205], v[22:25]
	v_mfma_f32_16x16x32_bf16 v[18:21], v[178:181], v[202:205], v[18:21]
	v_mfma_f32_16x16x32_bf16 v[6:9], v[170:173], v[210:213], v[6:9]
	v_mfma_f32_16x16x32_bf16 v[2:5], v[178:181], v[210:213], v[2:5]
	v_mfma_f32_16x16x32_bf16 v[54:57], v[174:177], v[190:193], v[54:57]
	v_mfma_f32_16x16x32_bf16 v[50:53], v[182:185], v[190:193], v[50:53]
	v_mfma_f32_16x16x32_bf16 v[38:41], v[174:177], v[198:201], v[38:41]
	v_mfma_f32_16x16x32_bf16 v[34:37], v[182:185], v[198:201], v[34:37]
	v_mfma_f32_16x16x32_bf16 v[22:25], v[174:177], v[206:209], v[22:25]
	v_mfma_f32_16x16x32_bf16 v[18:21], v[182:185], v[206:209], v[18:21]
	v_mfma_f32_16x16x32_bf16 v[6:9], v[174:177], v[214:217], v[6:9]
	v_mfma_f32_16x16x32_bf16 v[2:5], v[182:185], v[214:217], v[2:5]
	s_setprio 2
	s_barrier
	s_add_i32 s85, s85, 2
	s_add_u32 s4, s4, 0x100
	s_addc_u32 s5, s5, 0
	s_add_u32 s45, s45, 0x100
	s_addc_u32 s84, s84, 0
	s_cmp_gt_u32 s85, 13
	s_cbranch_scc0 .LBB0_236
	s_and_b64 vcc, exec, s[22:23]
	s_cbranch_vccz .LBB0_239
	s_barrier

; #define PG8_STAGE(bufoff, gbase, voff) do { _Pragma("unroll") for (int _i = 0; _i < 2; ++_i) \
;         __builtin_amdgcn_global_load_lds((const unsigned*)((const char*)(gbase) + (voff)[_i]), (LAS unsigned*)(lds + (bufoff) + ldsw + _i * 8192), 16, 0, 0); } while (0)
; #define PG8_LDA(dst, b, h) do { _Pragma("unroll") for (int m = 0; m < 4; ++m) _Pragma("unroll") for (int k = 0; k < 2; ++k) dst[m][k] = *(const LAS bf16x8*)(lds + PG8_SA(b, h) + aoff + m * 2048 + k * 1024); } while (0)
; #define PG8_LDB(dst, b, h) do { _Pragma("unroll") for (int n = 0; n < 2; ++n) _Pragma("unroll") for (int k = 0; k < 2; ++k) dst[n][k] = *(const LAS bf16x8*)(lds + PG8_SB(b, h) + boff + n * 2048 + k * 1024); } while (0)
; #define PG8_MMA(ai, bj, At, Bt) do { __builtin_amdgcn_s_setprio(1); _Pragma("unroll") for (int m = 0; m < 4; ++m) _Pragma("unroll") for (int n = 0; n < 2; ++n) _Pragma("unroll") for (int k = 0; k < 2; ++k) \
;         acc[ai][bj][m][n] = __builtin_amdgcn_mfma_f32_16x16x32_bf16(Bt[n][k], At[m][k], acc[ai][bj][m][n], 0, 0, 0); __builtin_amdgcn_s_setprio(0); } while (0)
; #define PG8_WAIT_V(n) asm volatile("s_waitcnt vmcnt(" #n ")" ::: "memory")
; #define PG8_WAIT_L(n) asm volatile("s_waitcnt lgkmcnt(" #n ")" ::: "memory")
; #define PG8_BAR __builtin_amdgcn_s_barrier()
; #define PG8_SCHED __builtin_amdgcn_sched_barrier(0)
; template <class Epi>
; __device__ __forceinline__ void gemm_phase(LAS unsigned char* lds, const Gemm g, int G, int c, const Epi& E) {
;     ...
;             const bool last = (t == nt - 2);
;             const char* a1 = cA + (size_t)(t + 1) * kstep;
;             const char* a2 = last ? nA : cA + (size_t)(t + 2) * kstep; const char* b2 = last ? nB : cB + (size_t)(t + 2) * kstep;
;             const char* a3 = a2 + kstep; const char* b3 = b2 + kstep;
;             PG8_LDB(B0, 0, 0); PG8_LDB(B1, 0, 1); PG8_SCHED; PG8_LDA(At, 0, 0); PG8_STAGE(PG8_SA(1, 1), a1 + hstepA, voffA);
;             PG8_WAIT_V(8); PG8_WAIT_L(0); PG8_BAR; PG8_MMA(0, 0, At, B0); PG8_MMA(0, 1, At, B1); PG8_BAR; PG8_SCHED;
;             PG8_LDA(At, 0, 1); PG8_STAGE(PG8_SB(0, 0), b2, voffB); PG8_STAGE(PG8_SB(0, 1), b2 + hstepB, voffB); PG8_STAGE(PG8_SA(0, 0), a2, voffA);
;             PG8_WAIT_V(8); PG8_WAIT_L(0); PG8_BAR; PG8_MMA(1, 0, At, B0); PG8_MMA(1, 1, At, B1); PG8_BAR; PG8_SCHED;
.LBB0_368:
	ds_read_b128 v[142:145], v148
	ds_read_b128 v[152:155], v148 offset:1024
	ds_read_b128 v[156:159], v148 offset:2048
	ds_read_b128 v[160:163], v148 offset:3072
	ds_read_b128 v[164:167], v149
	ds_read_b128 v[168:171], v149 offset:1024
	ds_read_b128 v[172:175], v149 offset:2048
	ds_read_b128 v[176:179], v149 offset:3072
	ds_read_b128 v[180:183], v150
	ds_read_b128 v[184:187], v150 offset:1024
	ds_read_b128 v[188:191], v150 offset:2048
	ds_read_b128 v[192:195], v150 offset:3072
	ds_read_b128 v[196:199], v150 offset:4096
	ds_read_b128 v[200:203], v150 offset:5120
	ds_read_b128 v[204:207], v150 offset:6144
	ds_read_b128 v[208:211], v150 offset:7168
	s_add_u32 s33, s20, s13
	s_addc_u32 s42, s21, 0
	s_add_u32 s43, s33, 0x100
	s_addc_u32 s44, s42, 0
	s_and_b64 s[38:39], s[24:25], exec
	s_cselect_b32 s45, s5, s44
	s_cselect_b32 s44, s4, s43
	s_add_u32 s13, s18, s13
	s_addc_u32 s38, s19, 0
	s_add_u32 s13, s13, 0x100
	s_addc_u32 s38, s38, 0
	s_and_b64 s[24:25], s[24:25], exec
	s_cselect_b32 s47, s17, s38
	s_cselect_b32 s46, s16, s13
	s_add_u32 s54, s33, 0xb0080
	s_addc_u32 s55, s42, 0
	s_add_i32 s65, s81, s56
	s_add_i32 m0, s57, 0xc000
	s_add_i32 s74, s57, 0xe000
	s_add_i32 s62, s65, 0x2000
	s_add_u32 s52, s46, 0xb0000
	s_addc_u32 s53, s47, 0
	s_add_i32 s64, s82, s56
	s_add_i32 s63, s64, 0x2000
	s_add_i32 s73, 0, 0x18000
	s_add_i32 s33, 0, 0x1c000
	s_add_u32 s42, s44, 0xb0000
	s_addc_u32 s43, s45, 0
	s_add_i32 s88, s73, s56
	s_add_i32 s38, s88, 0x2000
	s_add_u32 s24, s46, 0xb0080
	s_addc_u32 s25, s47, 0
	s_add_i32 s39, s33, s56
	s_add_i32 s13, s39, 0x2000
	v_lshl_add_u64 v[212:213], s[54:55], 0, v[136:137]
	global_load_lds_dwordx4 v[212:213], off
	v_lshl_add_u64 v[212:213], s[54:55], 0, v[132:133]
	s_mov_b32 m0, s74
	s_nop 0
	global_load_lds_dwordx4 v[212:213], off
	s_waitcnt vmcnt(8)
	s_waitcnt lgkmcnt(0)
	s_barrier
	s_setprio 0
	v_mfma_f32_16x16x32_bf16 v[126:129], v[142:145], v[180:183], v[126:129]
	v_mfma_f32_16x16x32_bf16 v[122:125], v[156:159], v[180:183], v[122:125]
	v_mfma_f32_16x16x32_bf16 v[118:121], v[142:145], v[188:191], v[118:121]
	v_mfma_f32_16x16x32_bf16 v[110:113], v[156:159], v[188:191], v[110:113]
	v_mfma_f32_16x16x32_bf16 v[102:105], v[142:145], v[196:199], v[102:105]
	v_mfma_f32_16x16x32_bf16 v[94:97], v[156:159], v[196:199], v[94:97]
	v_mfma_f32_16x16x32_bf16 v[86:89], v[142:145], v[204:207], v[86:89]
	v_mfma_f32_16x16x32_bf16 v[78:81], v[156:159], v[204:207], v[78:81]
	v_mfma_f32_16x16x32_bf16 v[126:129], v[152:155], v[184:187], v[126:129]
	v_mfma_f32_16x16x32_bf16 v[122:125], v[160:163], v[184:187], v[122:125]
	v_mfma_f32_16x16x32_bf16 v[118:121], v[152:155], v[192:195], v[118:121]
	v_mfma_f32_16x16x32_bf16 v[110:113], v[160:163], v[192:195], v[110:113]
	v_mfma_f32_16x16x32_bf16 v[102:105], v[152:155], v[200:203], v[102:105]
	v_mfma_f32_16x16x32_bf16 v[94:97], v[160:163], v[200:203], v[94:97]
	v_mfma_f32_16x16x32_bf16 v[86:89], v[152:155], v[208:211], v[86:89]
	v_mfma_f32_16x16x32_bf16 v[78:81], v[160:163], v[208:211], v[78:81]
	s_setprio 2
	s_setprio 0
	v_mfma_f32_16x16x32_bf16 v[114:117], v[164:167], v[180:183], v[114:117]
	v_mfma_f32_16x16x32_bf16 v[106:109], v[172:175], v[180:183], v[106:109]
	v_mfma_f32_16x16x32_bf16 v[98:101], v[164:167], v[188:191], v[98:101]
	v_mfma_f32_16x16x32_bf16 v[90:93], v[172:175], v[188:191], v[90:93]
	v_mfma_f32_16x16x32_bf16 v[82:85], v[164:167], v[196:199], v[82:85]
	v_mfma_f32_16x16x32_bf16 v[74:77], v[172:175], v[196:199], v[74:77]
	v_mfma_f32_16x16x32_bf16 v[70:73], v[164:167], v[204:207], v[70:73]
	v_mfma_f32_16x16x32_bf16 v[66:69], v[172:175], v[204:207], v[66:69]
	v_mfma_f32_16x16x32_bf16 v[114:117], v[168:171], v[184:187], v[114:117]
	v_mfma_f32_16x16x32_bf16 v[106:109], v[176:179], v[184:187], v[106:109]
	v_mfma_f32_16x16x32_bf16 v[98:101], v[168:171], v[192:195], v[98:101]
	v_mfma_f32_16x16x32_bf16 v[90:93], v[176:179], v[192:195], v[90:93]
	v_mfma_f32_16x16x32_bf16 v[82:85], v[168:171], v[200:203], v[82:85]
	v_mfma_f32_16x16x32_bf16 v[74:77], v[176:179], v[200:203], v[74:77]
	v_mfma_f32_16x16x32_bf16 v[70:73], v[168:171], v[208:211], v[70:73]
	v_mfma_f32_16x16x32_bf16 v[66:69], v[176:179], v[208:211], v[66:69]
	s_setprio 2
	s_barrier
	ds_read_b128 v[180:183], v150 offset:16384
	ds_read_b128 v[184:187], v150 offset:17408
	ds_read_b128 v[188:191], v150 offset:18432
	ds_read_b128 v[192:195], v150 offset:19456
	ds_read_b128 v[196:199], v150 offset:20480
	ds_read_b128 v[200:203], v150 offset:21504
	ds_read_b128 v[204:207], v150 offset:22528
	ds_read_b128 v[208:211], v150 offset:23552
	s_mov_b32 m0, s65
	v_lshl_add_u64 v[212:213], s[46:47], 0, v[134:135]
	global_load_lds_dwordx4 v[212:213], off
	v_lshl_add_u64 v[214:215], s[46:47], 0, v[130:131]
	s_mov_b32 m0, s62
	v_lshl_add_u64 v[216:217], s[52:53], 0, v[134:135]
	global_load_lds_dwordx4 v[214:215], off
	s_mov_b32 m0, s64
	v_lshl_add_u64 v[218:219], s[44:45], 0, v[132:133]
	global_load_lds_dwordx4 v[216:217], off
	v_lshl_add_u64 v[216:217], s[52:53], 0, v[130:131]
	s_mov_b32 m0, s63
	s_nop 0
	global_load_lds_dwordx4 v[216:217], off
	v_lshl_add_u64 v[216:217], s[44:45], 0, v[136:137]
	s_mov_b32 m0, s57
	s_nop 0
	global_load_lds_dwordx4 v[216:217], off
	s_mov_b32 m0, s58
	s_nop 0
	global_load_lds_dwordx4 v[218:219], off
	s_waitcnt vmcnt(8)
	s_waitcnt lgkmcnt(0)
	s_barrier
; #define PG8_STAGE(bufoff, gbase, voff) do { _Pragma("unroll") for (int _i = 0; _i < 2; ++_i) \
;         __builtin_amdgcn_global_load_lds((const unsigned*)((const char*)(gbase) + (voff)[_i]), (LAS unsigned*)(lds + (bufoff) + ldsw + _i * 8192), 16, 0, 0); } while (0)
; #define PG8_LDA(dst, b, h) do { _Pragma("unroll") for (int m = 0; m < 4; ++m) _Pragma("unroll") for (int k = 0; k < 2; ++k) dst[m][k] = *(const LAS bf16x8*)(lds + PG8_SA(b, h) + aoff + m * 2048 + k * 1024); } while (0)
; #define PG8_LDB(dst, b, h) do { _Pragma("unroll") for (int n = 0; n < 2; ++n) _Pragma("unroll") for (int k = 0; k < 2; ++k) dst[n][k] = *(const LAS bf16x8*)(lds + PG8_SB(b, h) + boff + n * 2048 + k * 1024); } while (0)
; #define PG8_MMA(ai, bj, At, Bt) do { __builtin_amdgcn_s_setprio(1); _Pragma("unroll") for (int m = 0; m < 4; ++m) _Pragma("unroll") for (int n = 0; n < 2; ++n) _Pragma("unroll") for (int k = 0; k < 2; ++k) \
;         acc[ai][bj][m][n] = __builtin_amdgcn_mfma_f32_16x16x32_bf16(Bt[n][k], At[m][k], acc[ai][bj][m][n], 0, 0, 0); __builtin_amdgcn_s_setprio(0); } while (0)
; #define PG8_WAIT_V(n) asm volatile("s_waitcnt vmcnt(" #n ")" ::: "memory")
; #define PG8_WAIT_L(n) asm volatile("s_waitcnt lgkmcnt(" #n ")" ::: "memory")
; #define PG8_BAR __builtin_amdgcn_s_barrier()
; #define PG8_SCHED __builtin_amdgcn_sched_barrier(0)
; template <class Epi>
; __device__ __forceinline__ void gemm_phase(LAS unsigned char* lds, const Gemm g, int G, int c, const Epi& E) {
;     ...
;             PG8_WAIT_V(8); PG8_WAIT_L(0); PG8_BAR; PG8_MMA(1, 0, At, B0); PG8_MMA(1, 1, At, B1); PG8_BAR; PG8_SCHED;
;             PG8_LDB(B0, 1, 0); PG8_LDB(B1, 1, 1); PG8_SCHED; PG8_LDA(At, 1, 0); PG8_STAGE(PG8_SA(0, 1), a2 + hstepA, voffA);
;             PG8_WAIT_V(8); PG8_WAIT_L(0); PG8_BAR; PG8_MMA(0, 0, At, B0); PG8_MMA(0, 1, At, B1); PG8_BAR; PG8_SCHED;
	s_setprio 0
	v_mfma_f32_16x16x32_bf16 v[62:65], v[142:145], v[180:183], v[62:65]
	v_mfma_f32_16x16x32_bf16 v[58:61], v[156:159], v[180:183], v[58:61]
	v_mfma_f32_16x16x32_bf16 v[54:57], v[142:145], v[188:191], v[54:57]
	v_mfma_f32_16x16x32_bf16 v[46:49], v[156:159], v[188:191], v[46:49]
	v_mfma_f32_16x16x32_bf16 v[38:41], v[142:145], v[196:199], v[38:41]
	v_mfma_f32_16x16x32_bf16 v[30:33], v[156:159], v[196:199], v[30:33]
	v_mfma_f32_16x16x32_bf16 v[22:25], v[142:145], v[204:207], v[22:25]
	v_mfma_f32_16x16x32_bf16 v[14:17], v[156:159], v[204:207], v[14:17]
	v_mfma_f32_16x16x32_bf16 v[62:65], v[152:155], v[184:187], v[62:65]
	v_mfma_f32_16x16x32_bf16 v[58:61], v[160:163], v[184:187], v[58:61]
	v_mfma_f32_16x16x32_bf16 v[54:57], v[152:155], v[192:195], v[54:57]
	v_mfma_f32_16x16x32_bf16 v[46:49], v[160:163], v[192:195], v[46:49]
	v_mfma_f32_16x16x32_bf16 v[38:41], v[152:155], v[200:203], v[38:41]
	v_mfma_f32_16x16x32_bf16 v[30:33], v[160:163], v[200:203], v[30:33]
	v_mfma_f32_16x16x32_bf16 v[22:25], v[152:155], v[208:211], v[22:25]
	v_mfma_f32_16x16x32_bf16 v[14:17], v[160:163], v[208:211], v[14:17]
	s_setprio 2
	s_setprio 0
	v_mfma_f32_16x16x32_bf16 v[50:53], v[164:167], v[180:183], v[50:53]
	v_mfma_f32_16x16x32_bf16 v[42:45], v[172:175], v[180:183], v[42:45]
	v_mfma_f32_16x16x32_bf16 v[34:37], v[164:167], v[188:191], v[34:37]
	v_mfma_f32_16x16x32_bf16 v[26:29], v[172:175], v[188:191], v[26:29]
	v_mfma_f32_16x16x32_bf16 v[18:21], v[164:167], v[196:199], v[18:21]
	v_mfma_f32_16x16x32_bf16 v[10:13], v[172:175], v[196:199], v[10:13]
	v_mfma_f32_16x16x32_bf16 v[6:9], v[164:167], v[204:207], v[6:9]
	v_mfma_f32_16x16x32_bf16 v[2:5], v[172:175], v[204:207], v[2:5]
	v_mfma_f32_16x16x32_bf16 v[50:53], v[168:171], v[184:187], v[50:53]
	v_mfma_f32_16x16x32_bf16 v[42:45], v[176:179], v[184:187], v[42:45]
	v_mfma_f32_16x16x32_bf16 v[34:37], v[168:171], v[192:195], v[34:37]
	v_mfma_f32_16x16x32_bf16 v[26:29], v[176:179], v[192:195], v[26:29]
	v_mfma_f32_16x16x32_bf16 v[18:21], v[168:171], v[200:203], v[18:21]
	v_mfma_f32_16x16x32_bf16 v[10:13], v[176:179], v[200:203], v[10:13]
	v_mfma_f32_16x16x32_bf16 v[6:9], v[168:171], v[208:211], v[6:9]
	v_mfma_f32_16x16x32_bf16 v[2:5], v[176:179], v[208:211], v[2:5]
	s_setprio 2
	s_barrier
	v_add_u32_e32 v151, s73, v147
	ds_read_b128 v[142:145], v151
	ds_read_b128 v[152:155], v151 offset:1024
	ds_read_b128 v[156:159], v151 offset:2048
	ds_read_b128 v[160:163], v151 offset:3072
	v_add_u32_e32 v151, s33, v147
	ds_read_b128 v[164:167], v151
	ds_read_b128 v[168:171], v151 offset:1024
	ds_read_b128 v[172:175], v151 offset:2048
	ds_read_b128 v[176:179], v151 offset:3072
	ds_read_b128 v[180:183], v150 offset:32768
	ds_read_b128 v[184:187], v150 offset:33792
	ds_read_b128 v[188:191], v150 offset:34816
	ds_read_b128 v[192:195], v150 offset:35840
	ds_read_b128 v[196:199], v150 offset:36864
	ds_read_b128 v[200:203], v150 offset:37888
	ds_read_b128 v[204:207], v150 offset:38912
	ds_read_b128 v[208:211], v150 offset:39936
	s_mov_b32 m0, s59
	v_lshl_add_u64 v[220:221], s[42:43], 0, v[136:137]
	global_load_lds_dwordx4 v[220:221], off
	v_lshl_add_u64 v[220:221], s[42:43], 0, v[132:133]
	s_mov_b32 m0, s60
	s_nop 0
	global_load_lds_dwordx4 v[220:221], off
	s_waitcnt vmcnt(8)
	s_waitcnt lgkmcnt(0)
	s_barrier
	s_setprio 0
	v_mfma_f32_16x16x32_bf16 v[126:129], v[142:145], v[180:183], v[126:129]
	v_mfma_f32_16x16x32_bf16 v[122:125], v[156:159], v[180:183], v[122:125]
	v_mfma_f32_16x16x32_bf16 v[118:121], v[142:145], v[188:191], v[118:121]
	v_mfma_f32_16x16x32_bf16 v[110:113], v[156:159], v[188:191], v[110:113]
	v_mfma_f32_16x16x32_bf16 v[102:105], v[142:145], v[196:199], v[102:105]
	v_mfma_f32_16x16x32_bf16 v[94:97], v[156:159], v[196:199], v[94:97]
	v_mfma_f32_16x16x32_bf16 v[86:89], v[142:145], v[204:207], v[86:89]
	v_mfma_f32_16x16x32_bf16 v[78:81], v[156:159], v[204:207], v[78:81]
	v_mfma_f32_16x16x32_bf16 v[126:129], v[152:155], v[184:187], v[126:129]
	v_mfma_f32_16x16x32_bf16 v[122:125], v[160:163], v[184:187], v[122:125]
	v_mfma_f32_16x16x32_bf16 v[118:121], v[152:155], v[192:195], v[118:121]
	v_mfma_f32_16x16x32_bf16 v[110:113], v[160:163], v[192:195], v[110:113]
	v_mfma_f32_16x16x32_bf16 v[102:105], v[152:155], v[200:203], v[102:105]
	v_mfma_f32_16x16x32_bf16 v[94:97], v[160:163], v[200:203], v[94:97]
	v_mfma_f32_16x16x32_bf16 v[86:89], v[152:155], v[208:211], v[86:89]
	v_mfma_f32_16x16x32_bf16 v[78:81], v[160:163], v[208:211], v[78:81]
	s_setprio 2
	s_setprio 0
	v_mfma_f32_16x16x32_bf16 v[114:117], v[164:167], v[180:183], v[114:117]
	v_mfma_f32_16x16x32_bf16 v[106:109], v[172:175], v[180:183], v[106:109]
	v_mfma_f32_16x16x32_bf16 v[98:101], v[164:167], v[188:191], v[98:101]
	v_mfma_f32_16x16x32_bf16 v[90:93], v[172:175], v[188:191], v[90:93]
	v_mfma_f32_16x16x32_bf16 v[82:85], v[164:167], v[196:199], v[82:85]
	v_mfma_f32_16x16x32_bf16 v[74:77], v[172:175], v[196:199], v[74:77]
	v_mfma_f32_16x16x32_bf16 v[70:73], v[164:167], v[204:207], v[70:73]
	v_mfma_f32_16x16x32_bf16 v[66:69], v[172:175], v[204:207], v[66:69]
	v_mfma_f32_16x16x32_bf16 v[114:117], v[168:171], v[184:187], v[114:117]
	v_mfma_f32_16x16x32_bf16 v[106:109], v[176:179], v[184:187], v[106:109]
	v_mfma_f32_16x16x32_bf16 v[98:101], v[168:171], v[192:195], v[98:101]
	v_mfma_f32_16x16x32_bf16 v[90:93], v[176:179], v[192:195], v[90:93]
	v_mfma_f32_16x16x32_bf16 v[82:85], v[168:171], v[200:203], v[82:85]
	v_mfma_f32_16x16x32_bf16 v[74:77], v[176:179], v[200:203], v[74:77]
	v_mfma_f32_16x16x32_bf16 v[70:73], v[168:171], v[208:211], v[70:73]
	v_mfma_f32_16x16x32_bf16 v[66:69], v[176:179], v[208:211], v[66:69]
	s_setprio 2
	s_barrier
; #define PG8_STAGE(bufoff, gbase, voff) do { _Pragma("unroll") for (int _i = 0; _i < 2; ++_i) \
;         __builtin_amdgcn_global_load_lds((const unsigned*)((const char*)(gbase) + (voff)[_i]), (LAS unsigned*)(lds + (bufoff) + ldsw + _i * 8192), 16, 0, 0); } while (0)
; #define PG8_LDA(dst, b, h) do { _Pragma("unroll") for (int m = 0; m < 4; ++m) _Pragma("unroll") for (int k = 0; k < 2; ++k) dst[m][k] = *(const LAS bf16x8*)(lds + PG8_SA(b, h) + aoff + m * 2048 + k * 1024); } while (0)
; #define PG8_MMA(ai, bj, At, Bt) do { __builtin_amdgcn_s_setprio(1); _Pragma("unroll") for (int m = 0; m < 4; ++m) _Pragma("unroll") for (int n = 0; n < 2; ++n) _Pragma("unroll") for (int k = 0; k < 2; ++k) \
;         acc[ai][bj][m][n] = __builtin_amdgcn_mfma_f32_16x16x32_bf16(Bt[n][k], At[m][k], acc[ai][bj][m][n], 0, 0, 0); __builtin_amdgcn_s_setprio(0); } while (0)
; #define PG8_WAIT_V(n) asm volatile("s_waitcnt vmcnt(" #n ")" ::: "memory")
; #define PG8_WAIT_L(n) asm volatile("s_waitcnt lgkmcnt(" #n ")" ::: "memory")
; #define PG8_BAR __builtin_amdgcn_s_barrier()
; #define PG8_SCHED __builtin_amdgcn_sched_barrier(0)
; template <class Epi>
; __device__ __forceinline__ void gemm_phase(LAS unsigned char* lds, const Gemm g, int G, int c, const Epi& E) {
;     ...
;             PG8_LDA(At, 1, 1); PG8_STAGE(PG8_SB(1, 0), b3, voffB); PG8_STAGE(PG8_SB(1, 1), b3 + hstepB, voffB); PG8_STAGE(PG8_SA(1, 0), a3, voffA);
;             PG8_WAIT_V(8); PG8_WAIT_L(0); PG8_BAR; PG8_MMA(1, 0, At, B0); PG8_MMA(1, 1, At, B1); PG8_BAR; PG8_SCHED;
;         }
	ds_read_b128 v[180:183], v150 offset:49152
	ds_read_b128 v[184:187], v150 offset:50176
	ds_read_b128 v[188:191], v150 offset:51200
	ds_read_b128 v[192:195], v150 offset:52224
	ds_read_b128 v[196:199], v150 offset:53248
	ds_read_b128 v[200:203], v150 offset:54272
	ds_read_b128 v[204:207], v150 offset:55296
	ds_read_b128 v[208:211], v150 offset:56320
	s_mov_b32 m0, s88
	v_lshl_add_u64 v[212:213], v[212:213], 0, s[8:9]
	global_load_lds_dwordx4 v[212:213], off
	v_lshl_add_u64 v[212:213], v[214:215], 0, s[8:9]
	s_mov_b32 m0, s38
	s_nop 0
	global_load_lds_dwordx4 v[212:213], off
	v_lshl_add_u64 v[212:213], s[24:25], 0, v[134:135]
	s_mov_b32 m0, s39
	s_nop 0
	global_load_lds_dwordx4 v[212:213], off
	v_lshl_add_u64 v[212:213], s[24:25], 0, v[130:131]
	s_mov_b32 m0, s13
	s_nop 0
	global_load_lds_dwordx4 v[212:213], off
	v_lshl_add_u64 v[212:213], v[216:217], 0, s[8:9]
	s_mov_b32 m0, s79
	s_nop 0
	global_load_lds_dwordx4 v[212:213], off
	v_lshl_add_u64 v[212:213], v[218:219], 0, s[8:9]
	s_mov_b32 m0, s80
	s_nop 0
	global_load_lds_dwordx4 v[212:213], off
	s_waitcnt vmcnt(8)
	s_waitcnt lgkmcnt(0)
	s_barrier
	s_setprio 0
	v_mfma_f32_16x16x32_bf16 v[62:65], v[142:145], v[180:183], v[62:65]
	v_mfma_f32_16x16x32_bf16 v[58:61], v[156:159], v[180:183], v[58:61]
	v_mfma_f32_16x16x32_bf16 v[54:57], v[142:145], v[188:191], v[54:57]
	v_mfma_f32_16x16x32_bf16 v[46:49], v[156:159], v[188:191], v[46:49]
	v_mfma_f32_16x16x32_bf16 v[38:41], v[142:145], v[196:199], v[38:41]
	v_mfma_f32_16x16x32_bf16 v[30:33], v[156:159], v[196:199], v[30:33]
	v_mfma_f32_16x16x32_bf16 v[22:25], v[142:145], v[204:207], v[22:25]
	v_mfma_f32_16x16x32_bf16 v[14:17], v[156:159], v[204:207], v[14:17]
	v_mfma_f32_16x16x32_bf16 v[62:65], v[152:155], v[184:187], v[62:65]
	v_mfma_f32_16x16x32_bf16 v[58:61], v[160:163], v[184:187], v[58:61]
	v_mfma_f32_16x16x32_bf16 v[54:57], v[152:155], v[192:195], v[54:57]
	v_mfma_f32_16x16x32_bf16 v[46:49], v[160:163], v[192:195], v[46:49]
	v_mfma_f32_16x16x32_bf16 v[38:41], v[152:155], v[200:203], v[38:41]
	v_mfma_f32_16x16x32_bf16 v[30:33], v[160:163], v[200:203], v[30:33]
	v_mfma_f32_16x16x32_bf16 v[22:25], v[152:155], v[208:211], v[22:25]
	v_mfma_f32_16x16x32_bf16 v[14:17], v[160:163], v[208:211], v[14:17]
	s_setprio 2
	s_setprio 0
	v_mfma_f32_16x16x32_bf16 v[50:53], v[164:167], v[180:183], v[50:53]
	v_mfma_f32_16x16x32_bf16 v[42:45], v[172:175], v[180:183], v[42:45]
	v_mfma_f32_16x16x32_bf16 v[34:37], v[164:167], v[188:191], v[34:37]
	v_mfma_f32_16x16x32_bf16 v[26:29], v[172:175], v[188:191], v[26:29]
	v_mfma_f32_16x16x32_bf16 v[18:21], v[164:167], v[196:199], v[18:21]
	v_mfma_f32_16x16x32_bf16 v[10:13], v[172:175], v[196:199], v[10:13]
	v_mfma_f32_16x16x32_bf16 v[6:9], v[164:167], v[204:207], v[6:9]
	v_mfma_f32_16x16x32_bf16 v[2:5], v[172:175], v[204:207], v[2:5]
	v_mfma_f32_16x16x32_bf16 v[50:53], v[168:171], v[184:187], v[50:53]
	v_mfma_f32_16x16x32_bf16 v[42:45], v[176:179], v[184:187], v[42:45]
	v_mfma_f32_16x16x32_bf16 v[34:37], v[168:171], v[192:195], v[34:37]
	v_mfma_f32_16x16x32_bf16 v[26:29], v[176:179], v[192:195], v[26:29]
	v_mfma_f32_16x16x32_bf16 v[18:21], v[168:171], v[200:203], v[18:21]
	v_mfma_f32_16x16x32_bf16 v[10:13], v[176:179], v[200:203], v[10:13]
	v_mfma_f32_16x16x32_bf16 v[6:9], v[168:171], v[208:211], v[6:9]
	v_mfma_f32_16x16x32_bf16 v[2:5], v[176:179], v[208:211], v[2:5]
	s_setprio 2
	s_barrier
	s_movk_i32 s13, 0x100
	s_andn2_b64 vcc, exec, s[22:23]
	s_mov_b64 s[24:25], -1
	s_mov_b64 s[22:23], 0
	s_cbranch_vccz .LBB0_368
	s_and_b64 vcc, exec, s[10:11]
	s_cbranch_vccz .LBB0_371
	s_barrier

; #define PG8_STAGE(bufoff, gbase, voff) do { _Pragma("unroll") for (int _i = 0; _i < 2; ++_i) \
;         __builtin_amdgcn_global_load_lds((const unsigned*)((const char*)(gbase) + (voff)[_i]), (LAS unsigned*)(lds + (bufoff) + ldsw + _i * 8192), 16, 0, 0); } while (0)
; #define PG8_LDA(dst, b, h) do { _Pragma("unroll") for (int m = 0; m < 4; ++m) _Pragma("unroll") for (int k = 0; k < 2; ++k) dst[m][k] = *(const LAS bf16x8*)(lds + PG8_SA(b, h) + aoff + m * 2048 + k * 1024); } while (0)
; #define PG8_LDB(dst, b, h) do { _Pragma("unroll") for (int n = 0; n < 2; ++n) _Pragma("unroll") for (int k = 0; k < 2; ++k) dst[n][k] = *(const LAS bf16x8*)(lds + PG8_SB(b, h) + boff + n * 2048 + k * 1024); } while (0)
; #define PG8_MMA(ai, bj, At, Bt) do { __builtin_amdgcn_s_setprio(1); _Pragma("unroll") for (int m = 0; m < 4; ++m) _Pragma("unroll") for (int n = 0; n < 2; ++n) _Pragma("unroll") for (int k = 0; k < 2; ++k) \
;         acc[ai][bj][m][n] = __builtin_amdgcn_mfma_f32_16x16x32_bf16(Bt[n][k], At[m][k], acc[ai][bj][m][n], 0, 0, 0); __builtin_amdgcn_s_setprio(0); } while (0)
; #define PG8_WAIT_V(n) asm volatile("s_waitcnt vmcnt(" #n ")" ::: "memory")
; #define PG8_WAIT_L(n) asm volatile("s_waitcnt lgkmcnt(" #n ")" ::: "memory")
; #define PG8_BAR __builtin_amdgcn_s_barrier()
; #define PG8_SCHED __builtin_amdgcn_sched_barrier(0)
; template <class Epi>
; __device__ __forceinline__ void gemm_phase(LAS unsigned char* lds, const Gemm g, int G, int c, const Epi& E) {
;     ...
;             const bool last = (t == nt - 2);
;             const char* a1 = cA + (size_t)(t + 1) * kstep;
;             const char* a2 = last ? nA : cA + (size_t)(t + 2) * kstep; const char* b2 = last ? nB : cB + (size_t)(t + 2) * kstep;
;             const char* a3 = a2 + kstep; const char* b3 = b2 + kstep;
;             PG8_LDB(B0, 0, 0); PG8_LDB(B1, 0, 1); PG8_SCHED; PG8_LDA(At, 0, 0); PG8_STAGE(PG8_SA(1, 1), a1 + hstepA, voffA);
;             PG8_WAIT_V(8); PG8_WAIT_L(0); PG8_BAR; PG8_MMA(0, 0, At, B0); PG8_MMA(0, 1, At, B1); PG8_BAR; PG8_SCHED;
;             PG8_LDA(At, 0, 1); PG8_STAGE(PG8_SB(0, 0), b2, voffB); PG8_STAGE(PG8_SB(0, 1), b2 + hstepB, voffB); PG8_STAGE(PG8_SA(0, 0), a2, voffA);
;             PG8_WAIT_V(8); PG8_WAIT_L(0); PG8_BAR; PG8_MMA(1, 0, At, B0); PG8_MMA(1, 1, At, B1); PG8_BAR; PG8_SCHED;
.LBB0_390:
	ds_read_b128 v[142:145], v160
	ds_read_b128 v[146:149], v160 offset:1024
	ds_read_b128 v[150:153], v160 offset:2048
	ds_read_b128 v[154:157], v160 offset:3072
	ds_read_b128 v[166:169], v161
	ds_read_b128 v[170:173], v161 offset:1024
	ds_read_b128 v[174:177], v161 offset:2048
	ds_read_b128 v[178:181], v161 offset:3072
	ds_read_b128 v[182:185], v162
	ds_read_b128 v[186:189], v162 offset:1024
	ds_read_b128 v[190:193], v162 offset:2048
	ds_read_b128 v[194:197], v162 offset:3072
	ds_read_b128 v[198:201], v162 offset:4096
	ds_read_b128 v[202:205], v162 offset:5120
	ds_read_b128 v[206:209], v162 offset:6144
	ds_read_b128 v[210:213], v162 offset:7168
	s_add_u32 s33, s8, s38
	s_addc_u32 s39, s9, 0
	s_add_u32 s56, s33, 0x100
	s_addc_u32 s57, s39, 0
	s_and_b64 s[54:55], s[10:11], exec
	s_cselect_b32 s57, s47, s57
	s_cselect_b32 s56, s46, s56
	s_add_u32 s38, s6, s38
	s_addc_u32 s54, s7, 0
	s_add_u32 s38, s38, 0x100
	s_addc_u32 s54, s54, 0
	s_and_b64 s[10:11], s[10:11], exec
	s_cselect_b32 s59, s53, s54
	s_cselect_b32 s58, s52, s38
	s_add_u32 s66, s33, 0xb0080
	s_addc_u32 s67, s39, 0
	s_add_i32 s65, s87, s14
	s_add_i32 m0, s78, 0xc000
	s_add_i32 s74, s78, 0xe000
	s_add_i32 s62, s65, 0x2000
	s_add_u32 s60, s58, 0xb0000
	s_addc_u32 s61, s59, 0
	s_add_i32 s64, s88, s14
	s_add_i32 s63, s64, 0x2000
	s_add_i32 s73, 0, 0x18000
	s_add_i32 s33, 0, 0x1c000
	s_add_u32 s54, s56, 0xb0000
	s_addc_u32 s55, s57, 0
	s_add_i32 vcc_hi, s73, s14
	s_add_i32 s39, vcc_hi, 0x2000
	s_add_u32 s10, s58, 0xb0080
	s_addc_u32 s11, s59, 0
	s_add_i32 vcc_lo, s33, s14
	s_add_i32 s38, vcc_lo, 0x2000
	v_lshl_add_u64 v[214:215], s[66:67], 0, v[130:131]
	global_load_lds_dwordx4 v[214:215], off
	v_lshl_add_u64 v[214:215], s[66:67], 0, v[134:135]
	s_mov_b32 m0, s74
	s_nop 0
	global_load_lds_dwordx4 v[214:215], off
	s_waitcnt vmcnt(8)
	s_waitcnt lgkmcnt(0)
	s_barrier
	s_setprio 0
	v_mfma_f32_16x16x32_bf16 v[126:129], v[142:145], v[182:185], v[126:129]
	v_mfma_f32_16x16x32_bf16 v[122:125], v[150:153], v[182:185], v[122:125]
	v_mfma_f32_16x16x32_bf16 v[110:113], v[142:145], v[190:193], v[110:113]
	v_mfma_f32_16x16x32_bf16 v[106:109], v[150:153], v[190:193], v[106:109]
	v_mfma_f32_16x16x32_bf16 v[94:97], v[142:145], v[198:201], v[94:97]
	v_mfma_f32_16x16x32_bf16 v[90:93], v[150:153], v[198:201], v[90:93]
	v_mfma_f32_16x16x32_bf16 v[78:81], v[142:145], v[206:209], v[78:81]
	v_mfma_f32_16x16x32_bf16 v[74:77], v[150:153], v[206:209], v[74:77]
	v_mfma_f32_16x16x32_bf16 v[126:129], v[146:149], v[186:189], v[126:129]
	v_mfma_f32_16x16x32_bf16 v[122:125], v[154:157], v[186:189], v[122:125]
	v_mfma_f32_16x16x32_bf16 v[110:113], v[146:149], v[194:197], v[110:113]
	v_mfma_f32_16x16x32_bf16 v[106:109], v[154:157], v[194:197], v[106:109]
	v_mfma_f32_16x16x32_bf16 v[94:97], v[146:149], v[202:205], v[94:97]
	v_mfma_f32_16x16x32_bf16 v[90:93], v[154:157], v[202:205], v[90:93]
	v_mfma_f32_16x16x32_bf16 v[78:81], v[146:149], v[210:213], v[78:81]
	v_mfma_f32_16x16x32_bf16 v[74:77], v[154:157], v[210:213], v[74:77]
	s_setprio 2
	s_setprio 0
	v_mfma_f32_16x16x32_bf16 v[118:121], v[166:169], v[182:185], v[118:121]
	v_mfma_f32_16x16x32_bf16 v[114:117], v[174:177], v[182:185], v[114:117]
	v_mfma_f32_16x16x32_bf16 v[102:105], v[166:169], v[190:193], v[102:105]
	v_mfma_f32_16x16x32_bf16 v[98:101], v[174:177], v[190:193], v[98:101]
	v_mfma_f32_16x16x32_bf16 v[86:89], v[166:169], v[198:201], v[86:89]
	v_mfma_f32_16x16x32_bf16 v[82:85], v[174:177], v[198:201], v[82:85]
	v_mfma_f32_16x16x32_bf16 v[70:73], v[166:169], v[206:209], v[70:73]
	v_mfma_f32_16x16x32_bf16 v[66:69], v[174:177], v[206:209], v[66:69]
	v_mfma_f32_16x16x32_bf16 v[118:121], v[170:173], v[186:189], v[118:121]
	v_mfma_f32_16x16x32_bf16 v[114:117], v[178:181], v[186:189], v[114:117]
	v_mfma_f32_16x16x32_bf16 v[102:105], v[170:173], v[194:197], v[102:105]
	v_mfma_f32_16x16x32_bf16 v[98:101], v[178:181], v[194:197], v[98:101]
	v_mfma_f32_16x16x32_bf16 v[86:89], v[170:173], v[202:205], v[86:89]
	v_mfma_f32_16x16x32_bf16 v[82:85], v[178:181], v[202:205], v[82:85]
	v_mfma_f32_16x16x32_bf16 v[70:73], v[170:173], v[210:213], v[70:73]
	v_mfma_f32_16x16x32_bf16 v[66:69], v[178:181], v[210:213], v[66:69]
	s_setprio 2
	s_barrier
	ds_read_b128 v[182:185], v162 offset:16384
	ds_read_b128 v[186:189], v162 offset:17408
	ds_read_b128 v[190:193], v162 offset:18432
	ds_read_b128 v[194:197], v162 offset:19456
	ds_read_b128 v[198:201], v162 offset:20480
	ds_read_b128 v[202:205], v162 offset:21504
	ds_read_b128 v[206:209], v162 offset:22528
	ds_read_b128 v[210:213], v162 offset:23552
	s_mov_b32 m0, s65
	v_lshl_add_u64 v[214:215], s[58:59], 0, v[132:133]
	global_load_lds_dwordx4 v[214:215], off
	v_lshl_add_u64 v[216:217], s[58:59], 0, v[136:137]
	s_mov_b32 m0, s62
	v_lshl_add_u64 v[218:219], s[60:61], 0, v[132:133]
	global_load_lds_dwordx4 v[216:217], off
	s_mov_b32 m0, s64
	v_lshl_add_u64 v[220:221], s[56:57], 0, v[134:135]
	global_load_lds_dwordx4 v[218:219], off
	v_lshl_add_u64 v[218:219], s[60:61], 0, v[136:137]
	s_mov_b32 m0, s63
	s_nop 0
	global_load_lds_dwordx4 v[218:219], off
	v_lshl_add_u64 v[218:219], s[56:57], 0, v[130:131]
	s_mov_b32 m0, s78
	s_nop 0
	global_load_lds_dwordx4 v[218:219], off
	s_mov_b32 m0, s79
	s_nop 0
	global_load_lds_dwordx4 v[220:221], off
	s_waitcnt vmcnt(8)
	s_waitcnt lgkmcnt(0)
	s_barrier
; #define PG8_STAGE(bufoff, gbase, voff) do { _Pragma("unroll") for (int _i = 0; _i < 2; ++_i) \
;         __builtin_amdgcn_global_load_lds((const unsigned*)((const char*)(gbase) + (voff)[_i]), (LAS unsigned*)(lds + (bufoff) + ldsw + _i * 8192), 16, 0, 0); } while (0)
; #define PG8_LDA(dst, b, h) do { _Pragma("unroll") for (int m = 0; m < 4; ++m) _Pragma("unroll") for (int k = 0; k < 2; ++k) dst[m][k] = *(const LAS bf16x8*)(lds + PG8_SA(b, h) + aoff + m * 2048 + k * 1024); } while (0)
; #define PG8_LDB(dst, b, h) do { _Pragma("unroll") for (int n = 0; n < 2; ++n) _Pragma("unroll") for (int k = 0; k < 2; ++k) dst[n][k] = *(const LAS bf16x8*)(lds + PG8_SB(b, h) + boff + n * 2048 + k * 1024); } while (0)
; #define PG8_MMA(ai, bj, At, Bt) do { __builtin_amdgcn_s_setprio(1); _Pragma("unroll") for (int m = 0; m < 4; ++m) _Pragma("unroll") for (int n = 0; n < 2; ++n) _Pragma("unroll") for (int k = 0; k < 2; ++k) \
;         acc[ai][bj][m][n] = __builtin_amdgcn_mfma_f32_16x16x32_bf16(Bt[n][k], At[m][k], acc[ai][bj][m][n], 0, 0, 0); __builtin_amdgcn_s_setprio(0); } while (0)
; #define PG8_WAIT_V(n) asm volatile("s_waitcnt vmcnt(" #n ")" ::: "memory")
; #define PG8_WAIT_L(n) asm volatile("s_waitcnt lgkmcnt(" #n ")" ::: "memory")
; #define PG8_BAR __builtin_amdgcn_s_barrier()
; #define PG8_SCHED __builtin_amdgcn_sched_barrier(0)
; template <class Epi>
; __device__ __forceinline__ void gemm_phase(LAS unsigned char* lds, const Gemm g, int G, int c, const Epi& E) {
;     ...
;             PG8_WAIT_V(8); PG8_WAIT_L(0); PG8_BAR; PG8_MMA(1, 0, At, B0); PG8_MMA(1, 1, At, B1); PG8_BAR; PG8_SCHED;
;             PG8_LDB(B0, 1, 0); PG8_LDB(B1, 1, 1); PG8_SCHED; PG8_LDA(At, 1, 0); PG8_STAGE(PG8_SA(0, 1), a2 + hstepA, voffA);
;             PG8_WAIT_V(8); PG8_WAIT_L(0); PG8_BAR; PG8_MMA(0, 0, At, B0); PG8_MMA(0, 1, At, B1); PG8_BAR; PG8_SCHED;
	s_setprio 0
	v_mfma_f32_16x16x32_bf16 v[62:65], v[142:145], v[182:185], v[62:65]
	v_mfma_f32_16x16x32_bf16 v[58:61], v[150:153], v[182:185], v[58:61]
	v_mfma_f32_16x16x32_bf16 v[46:49], v[142:145], v[190:193], v[46:49]
	v_mfma_f32_16x16x32_bf16 v[42:45], v[150:153], v[190:193], v[42:45]
	v_mfma_f32_16x16x32_bf16 v[30:33], v[142:145], v[198:201], v[30:33]
	v_mfma_f32_16x16x32_bf16 v[26:29], v[150:153], v[198:201], v[26:29]
	v_mfma_f32_16x16x32_bf16 v[14:17], v[142:145], v[206:209], v[14:17]
	v_mfma_f32_16x16x32_bf16 v[10:13], v[150:153], v[206:209], v[10:13]
	v_mfma_f32_16x16x32_bf16 v[62:65], v[146:149], v[186:189], v[62:65]
	v_mfma_f32_16x16x32_bf16 v[58:61], v[154:157], v[186:189], v[58:61]
	v_mfma_f32_16x16x32_bf16 v[46:49], v[146:149], v[194:197], v[46:49]
	v_mfma_f32_16x16x32_bf16 v[42:45], v[154:157], v[194:197], v[42:45]
	v_mfma_f32_16x16x32_bf16 v[30:33], v[146:149], v[202:205], v[30:33]
	v_mfma_f32_16x16x32_bf16 v[26:29], v[154:157], v[202:205], v[26:29]
	v_mfma_f32_16x16x32_bf16 v[14:17], v[146:149], v[210:213], v[14:17]
	v_mfma_f32_16x16x32_bf16 v[10:13], v[154:157], v[210:213], v[10:13]
	s_setprio 2
	s_setprio 0
	v_mfma_f32_16x16x32_bf16 v[54:57], v[166:169], v[182:185], v[54:57]
	v_mfma_f32_16x16x32_bf16 v[50:53], v[174:177], v[182:185], v[50:53]
	v_mfma_f32_16x16x32_bf16 v[38:41], v[166:169], v[190:193], v[38:41]
	v_mfma_f32_16x16x32_bf16 v[34:37], v[174:177], v[190:193], v[34:37]
	v_mfma_f32_16x16x32_bf16 v[22:25], v[166:169], v[198:201], v[22:25]
	v_mfma_f32_16x16x32_bf16 v[18:21], v[174:177], v[198:201], v[18:21]
	v_mfma_f32_16x16x32_bf16 v[6:9], v[166:169], v[206:209], v[6:9]
	v_mfma_f32_16x16x32_bf16 v[2:5], v[174:177], v[206:209], v[2:5]
	v_mfma_f32_16x16x32_bf16 v[54:57], v[170:173], v[186:189], v[54:57]
	v_mfma_f32_16x16x32_bf16 v[50:53], v[178:181], v[186:189], v[50:53]
	v_mfma_f32_16x16x32_bf16 v[38:41], v[170:173], v[194:197], v[38:41]
	v_mfma_f32_16x16x32_bf16 v[34:37], v[178:181], v[194:197], v[34:37]
	v_mfma_f32_16x16x32_bf16 v[22:25], v[170:173], v[202:205], v[22:25]
	v_mfma_f32_16x16x32_bf16 v[18:21], v[178:181], v[202:205], v[18:21]
	v_mfma_f32_16x16x32_bf16 v[6:9], v[170:173], v[210:213], v[6:9]
	v_mfma_f32_16x16x32_bf16 v[2:5], v[178:181], v[210:213], v[2:5]
	s_setprio 2
	s_barrier
	v_add_u32_e32 v154, s73, v159
	v_add_u32_e32 v178, s33, v159
	ds_read_b128 v[142:145], v154
	ds_read_b128 v[146:149], v154 offset:1024
	ds_read_b128 v[150:153], v154 offset:2048
	ds_read_b128 v[154:157], v154 offset:3072
	ds_read_b128 v[166:169], v178
	ds_read_b128 v[170:173], v178 offset:1024
	ds_read_b128 v[174:177], v178 offset:2048
	ds_read_b128 v[178:181], v178 offset:3072
	ds_read_b128 v[182:185], v162 offset:32768
	ds_read_b128 v[186:189], v162 offset:33792
	ds_read_b128 v[190:193], v162 offset:34816
	ds_read_b128 v[194:197], v162 offset:35840
	ds_read_b128 v[198:201], v162 offset:36864
	ds_read_b128 v[202:205], v162 offset:37888
	ds_read_b128 v[206:209], v162 offset:38912
	ds_read_b128 v[210:213], v162 offset:39936
	s_mov_b32 m0, s80
	v_lshl_add_u64 v[222:223], s[54:55], 0, v[130:131]
	global_load_lds_dwordx4 v[222:223], off
	v_lshl_add_u64 v[222:223], s[54:55], 0, v[134:135]
	s_mov_b32 m0, s81
	s_nop 0
	global_load_lds_dwordx4 v[222:223], off
	s_waitcnt vmcnt(8)
	s_waitcnt lgkmcnt(0)
	s_barrier
	s_setprio 0
	v_mfma_f32_16x16x32_bf16 v[126:129], v[142:145], v[182:185], v[126:129]
	v_mfma_f32_16x16x32_bf16 v[122:125], v[150:153], v[182:185], v[122:125]
	v_mfma_f32_16x16x32_bf16 v[110:113], v[142:145], v[190:193], v[110:113]
	v_mfma_f32_16x16x32_bf16 v[106:109], v[150:153], v[190:193], v[106:109]
	v_mfma_f32_16x16x32_bf16 v[94:97], v[142:145], v[198:201], v[94:97]
	v_mfma_f32_16x16x32_bf16 v[90:93], v[150:153], v[198:201], v[90:93]
	v_mfma_f32_16x16x32_bf16 v[78:81], v[142:145], v[206:209], v[78:81]
	v_mfma_f32_16x16x32_bf16 v[74:77], v[150:153], v[206:209], v[74:77]
	v_mfma_f32_16x16x32_bf16 v[126:129], v[146:149], v[186:189], v[126:129]
	v_mfma_f32_16x16x32_bf16 v[122:125], v[154:157], v[186:189], v[122:125]
	v_mfma_f32_16x16x32_bf16 v[110:113], v[146:149], v[194:197], v[110:113]
	v_mfma_f32_16x16x32_bf16 v[106:109], v[154:157], v[194:197], v[106:109]
	v_mfma_f32_16x16x32_bf16 v[94:97], v[146:149], v[202:205], v[94:97]
	v_mfma_f32_16x16x32_bf16 v[90:93], v[154:157], v[202:205], v[90:93]
	v_mfma_f32_16x16x32_bf16 v[78:81], v[146:149], v[210:213], v[78:81]
	v_mfma_f32_16x16x32_bf16 v[74:77], v[154:157], v[210:213], v[74:77]
	s_setprio 2
	s_setprio 0
	v_mfma_f32_16x16x32_bf16 v[118:121], v[166:169], v[182:185], v[118:121]
	v_mfma_f32_16x16x32_bf16 v[114:117], v[174:177], v[182:185], v[114:117]
	v_mfma_f32_16x16x32_bf16 v[102:105], v[166:169], v[190:193], v[102:105]
	v_mfma_f32_16x16x32_bf16 v[98:101], v[174:177], v[190:193], v[98:101]
	v_mfma_f32_16x16x32_bf16 v[86:89], v[166:169], v[198:201], v[86:89]
	v_mfma_f32_16x16x32_bf16 v[82:85], v[174:177], v[198:201], v[82:85]
	v_mfma_f32_16x16x32_bf16 v[70:73], v[166:169], v[206:209], v[70:73]
	v_mfma_f32_16x16x32_bf16 v[66:69], v[174:177], v[206:209], v[66:69]
	v_mfma_f32_16x16x32_bf16 v[118:121], v[170:173], v[186:189], v[118:121]
	v_mfma_f32_16x16x32_bf16 v[114:117], v[178:181], v[186:189], v[114:117]
	v_mfma_f32_16x16x32_bf16 v[102:105], v[170:173], v[194:197], v[102:105]
	v_mfma_f32_16x16x32_bf16 v[98:101], v[178:181], v[194:197], v[98:101]
	v_mfma_f32_16x16x32_bf16 v[86:89], v[170:173], v[202:205], v[86:89]
	v_mfma_f32_16x16x32_bf16 v[82:85], v[178:181], v[202:205], v[82:85]
	v_mfma_f32_16x16x32_bf16 v[70:73], v[170:173], v[210:213], v[70:73]
	v_mfma_f32_16x16x32_bf16 v[66:69], v[178:181], v[210:213], v[66:69]
	s_setprio 2
	s_barrier
; #define PG8_STAGE(bufoff, gbase, voff) do { _Pragma("unroll") for (int _i = 0; _i < 2; ++_i) \
;         __builtin_amdgcn_global_load_lds((const unsigned*)((const char*)(gbase) + (voff)[_i]), (LAS unsigned*)(lds + (bufoff) + ldsw + _i * 8192), 16, 0, 0); } while (0)
; #define PG8_LDA(dst, b, h) do { _Pragma("unroll") for (int m = 0; m < 4; ++m) _Pragma("unroll") for (int k = 0; k < 2; ++k) dst[m][k] = *(const LAS bf16x8*)(lds + PG8_SA(b, h) + aoff + m * 2048 + k * 1024); } while (0)
; #define PG8_MMA(ai, bj, At, Bt) do { __builtin_amdgcn_s_setprio(1); _Pragma("unroll") for (int m = 0; m < 4; ++m) _Pragma("unroll") for (int n = 0; n < 2; ++n) _Pragma("unroll") for (int k = 0; k < 2; ++k) \
;         acc[ai][bj][m][n] = __builtin_amdgcn_mfma_f32_16x16x32_bf16(Bt[n][k], At[m][k], acc[ai][bj][m][n], 0, 0, 0); __builtin_amdgcn_s_setprio(0); } while (0)
; #define PG8_WAIT_V(n) asm volatile("s_waitcnt vmcnt(" #n ")" ::: "memory")
; #define PG8_WAIT_L(n) asm volatile("s_waitcnt lgkmcnt(" #n ")" ::: "memory")
; #define PG8_BAR __builtin_amdgcn_s_barrier()
; #define PG8_SCHED __builtin_amdgcn_sched_barrier(0)
; template <class Epi>
; __device__ __forceinline__ void gemm_phase(LAS unsigned char* lds, const Gemm g, int G, int c, const Epi& E) {
;     ...
;             PG8_LDA(At, 1, 1); PG8_STAGE(PG8_SB(1, 0), b3, voffB); PG8_STAGE(PG8_SB(1, 1), b3 + hstepB, voffB); PG8_STAGE(PG8_SA(1, 0), a3, voffA);
;             PG8_WAIT_V(8); PG8_WAIT_L(0); PG8_BAR; PG8_MMA(1, 0, At, B0); PG8_MMA(1, 1, At, B1); PG8_BAR; PG8_SCHED;
;         }
	ds_read_b128 v[182:185], v162 offset:49152
	ds_read_b128 v[186:189], v162 offset:50176
	ds_read_b128 v[190:193], v162 offset:51200
	ds_read_b128 v[194:197], v162 offset:52224
	ds_read_b128 v[198:201], v162 offset:53248
	ds_read_b128 v[202:205], v162 offset:54272
	ds_read_b128 v[206:209], v162 offset:55296
	ds_read_b128 v[210:213], v162 offset:56320
	s_mov_b32 m0, vcc_hi
	v_lshl_add_u64 v[214:215], v[214:215], 0, s[24:25]
	global_load_lds_dwordx4 v[214:215], off
	v_lshl_add_u64 v[214:215], v[216:217], 0, s[24:25]
	s_mov_b32 m0, s39
	s_nop 0
	global_load_lds_dwordx4 v[214:215], off
	v_lshl_add_u64 v[214:215], s[10:11], 0, v[132:133]
	s_mov_b32 m0, vcc_lo
	s_nop 0
	global_load_lds_dwordx4 v[214:215], off
	v_lshl_add_u64 v[214:215], s[10:11], 0, v[136:137]
	s_mov_b32 m0, s38
	s_nop 0
	global_load_lds_dwordx4 v[214:215], off
	v_lshl_add_u64 v[214:215], v[218:219], 0, s[24:25]
	s_mov_b32 m0, s85
	s_nop 0
	global_load_lds_dwordx4 v[214:215], off
	v_lshl_add_u64 v[214:215], v[220:221], 0, s[24:25]
	s_mov_b32 m0, s86
	s_nop 0
	global_load_lds_dwordx4 v[214:215], off
	s_waitcnt vmcnt(8)
	s_waitcnt lgkmcnt(0)
	s_barrier
	s_setprio 0
	v_mfma_f32_16x16x32_bf16 v[62:65], v[142:145], v[182:185], v[62:65]
	v_mfma_f32_16x16x32_bf16 v[58:61], v[150:153], v[182:185], v[58:61]
	v_mfma_f32_16x16x32_bf16 v[46:49], v[142:145], v[190:193], v[46:49]
	v_mfma_f32_16x16x32_bf16 v[42:45], v[150:153], v[190:193], v[42:45]
	v_mfma_f32_16x16x32_bf16 v[30:33], v[142:145], v[198:201], v[30:33]
	v_mfma_f32_16x16x32_bf16 v[26:29], v[150:153], v[198:201], v[26:29]
	v_mfma_f32_16x16x32_bf16 v[14:17], v[142:145], v[206:209], v[14:17]
	v_mfma_f32_16x16x32_bf16 v[10:13], v[150:153], v[206:209], v[10:13]
	v_mfma_f32_16x16x32_bf16 v[62:65], v[146:149], v[186:189], v[62:65]
	v_mfma_f32_16x16x32_bf16 v[58:61], v[154:157], v[186:189], v[58:61]
	v_mfma_f32_16x16x32_bf16 v[46:49], v[146:149], v[194:197], v[46:49]
	v_mfma_f32_16x16x32_bf16 v[42:45], v[154:157], v[194:197], v[42:45]
	v_mfma_f32_16x16x32_bf16 v[30:33], v[146:149], v[202:205], v[30:33]
	v_mfma_f32_16x16x32_bf16 v[26:29], v[154:157], v[202:205], v[26:29]
	v_mfma_f32_16x16x32_bf16 v[14:17], v[146:149], v[210:213], v[14:17]
	v_mfma_f32_16x16x32_bf16 v[10:13], v[154:157], v[210:213], v[10:13]
	s_setprio 2
	s_setprio 0
	v_mfma_f32_16x16x32_bf16 v[54:57], v[166:169], v[182:185], v[54:57]
	v_mfma_f32_16x16x32_bf16 v[50:53], v[174:177], v[182:185], v[50:53]
	v_mfma_f32_16x16x32_bf16 v[38:41], v[166:169], v[190:193], v[38:41]
	v_mfma_f32_16x16x32_bf16 v[34:37], v[174:177], v[190:193], v[34:37]
	v_mfma_f32_16x16x32_bf16 v[22:25], v[166:169], v[198:201], v[22:25]
	v_mfma_f32_16x16x32_bf16 v[18:21], v[174:177], v[198:201], v[18:21]
	v_mfma_f32_16x16x32_bf16 v[6:9], v[166:169], v[206:209], v[6:9]
	v_mfma_f32_16x16x32_bf16 v[2:5], v[174:177], v[206:209], v[2:5]
	v_mfma_f32_16x16x32_bf16 v[54:57], v[170:173], v[186:189], v[54:57]
	v_mfma_f32_16x16x32_bf16 v[50:53], v[178:181], v[186:189], v[50:53]
	v_mfma_f32_16x16x32_bf16 v[38:41], v[170:173], v[194:197], v[38:41]
	v_mfma_f32_16x16x32_bf16 v[34:37], v[178:181], v[194:197], v[34:37]
	v_mfma_f32_16x16x32_bf16 v[22:25], v[170:173], v[202:205], v[22:25]
	v_mfma_f32_16x16x32_bf16 v[18:21], v[178:181], v[202:205], v[18:21]
	v_mfma_f32_16x16x32_bf16 v[6:9], v[170:173], v[210:213], v[6:9]
	v_mfma_f32_16x16x32_bf16 v[2:5], v[178:181], v[210:213], v[2:5]
	s_setprio 2
	s_barrier
	s_movk_i32 s38, 0x100
	s_andn2_b64 vcc, exec, s[4:5]
	s_mov_b64 s[10:11], -1
	s_mov_b64 s[4:5], 0
	s_cbranch_vccz .LBB0_390
	s_and_b64 vcc, exec, s[44:45]
	s_cbranch_vccz .LBB0_393
	s_barrier

; #define PG8_STAGE(bufoff, gbase, voff) do { _Pragma("unroll") for (int _i = 0; _i < 2; ++_i) \
;         __builtin_amdgcn_global_load_lds((const unsigned*)((const char*)(gbase) + (voff)[_i]), (LAS unsigned*)(lds + (bufoff) + ldsw + _i * 8192), 16, 0, 0); } while (0)
; #define PG8_LDA(dst, b, h) do { _Pragma("unroll") for (int m = 0; m < 4; ++m) _Pragma("unroll") for (int k = 0; k < 2; ++k) dst[m][k] = *(const LAS bf16x8*)(lds + PG8_SA(b, h) + aoff + m * 2048 + k * 1024); } while (0)
; #define PG8_LDB(dst, b, h) do { _Pragma("unroll") for (int n = 0; n < 2; ++n) _Pragma("unroll") for (int k = 0; k < 2; ++k) dst[n][k] = *(const LAS bf16x8*)(lds + PG8_SB(b, h) + boff + n * 2048 + k * 1024); } while (0)
; #define PG8_MMA(ai, bj, At, Bt) do { __builtin_amdgcn_s_setprio(1); _Pragma("unroll") for (int m = 0; m < 4; ++m) _Pragma("unroll") for (int n = 0; n < 2; ++n) _Pragma("unroll") for (int k = 0; k < 2; ++k) \
;         acc[ai][bj][m][n] = __builtin_amdgcn_mfma_f32_16x16x32_bf16(Bt[n][k], At[m][k], acc[ai][bj][m][n], 0, 0, 0); __builtin_amdgcn_s_setprio(0); } while (0)
; #define PG8_WAIT_V(n) asm volatile("s_waitcnt vmcnt(" #n ")" ::: "memory")
; #define PG8_WAIT_L(n) asm volatile("s_waitcnt lgkmcnt(" #n ")" ::: "memory")
; #define PG8_BAR __builtin_amdgcn_s_barrier()
; #define PG8_SCHED __builtin_amdgcn_sched_barrier(0)
; template <class Epi>
; __device__ __forceinline__ void gemm_phase(LAS unsigned char* lds, const Gemm g, int G, int c, const Epi& E) {
;     ...
;             const bool last = (t == nt - 2);
;             const char* a1 = cA + (size_t)(t + 1) * kstep;
;             const char* a2 = last ? nA : cA + (size_t)(t + 2) * kstep; const char* b2 = last ? nB : cB + (size_t)(t + 2) * kstep;
;             const char* a3 = a2 + kstep; const char* b3 = b2 + kstep;
;             PG8_LDB(B0, 0, 0); PG8_LDB(B1, 0, 1); PG8_SCHED; PG8_LDA(At, 0, 0); PG8_STAGE(PG8_SA(1, 1), a1 + hstepA, voffA);
;             PG8_WAIT_V(8); PG8_WAIT_L(0); PG8_BAR; PG8_MMA(0, 0, At, B0); PG8_MMA(0, 1, At, B1); PG8_BAR; PG8_SCHED;
;             PG8_LDA(At, 0, 1); PG8_STAGE(PG8_SB(0, 0), b2, voffB); PG8_STAGE(PG8_SB(0, 1), b2 + hstepB, voffB); PG8_STAGE(PG8_SA(0, 0), a2, voffA);
;             PG8_WAIT_V(8); PG8_WAIT_L(0); PG8_BAR; PG8_MMA(1, 0, At, B0); PG8_MMA(1, 1, At, B1); PG8_BAR; PG8_SCHED;
.LBB0_476:
	ds_read_b128 v[130:133], v166
	ds_read_b128 v[134:137], v166 offset:1024
	ds_read_b128 v[150:153], v166 offset:2048
	ds_read_b128 v[154:157], v166 offset:3072
	ds_read_b128 v[158:161], v167
	ds_read_b128 v[172:175], v167 offset:1024
	ds_read_b128 v[176:179], v167 offset:2048
	ds_read_b128 v[180:183], v167 offset:3072
	ds_read_b128 v[184:187], v168
	ds_read_b128 v[188:191], v168 offset:1024
	ds_read_b128 v[192:195], v168 offset:2048
	ds_read_b128 v[196:199], v168 offset:3072
	ds_read_b128 v[200:203], v168 offset:4096
	ds_read_b128 v[204:207], v168 offset:5120
	ds_read_b128 v[208:211], v168 offset:6144
	ds_read_b128 v[212:215], v168 offset:7168
	s_add_u32 s33, s8, s38
	s_addc_u32 s39, s9, 0
	s_add_u32 s56, s33, 0x100
	s_addc_u32 s57, s39, 0
	s_and_b64 s[54:55], s[10:11], exec
	s_cselect_b32 s57, s47, s57
	s_cselect_b32 s56, s46, s56
	s_add_u32 s38, s6, s38
	s_addc_u32 s54, s7, 0
	s_add_u32 s38, s38, 0x100
	s_addc_u32 s54, s54, 0
	s_and_b64 s[10:11], s[10:11], exec
	s_cselect_b32 s59, s53, s54
	s_cselect_b32 s58, s52, s38
	s_add_u32 s66, s33, 0xb0080
	s_addc_u32 s67, s39, 0
	s_add_i32 s63, s95, s83
	s_add_i32 m0, s86, 0xc000
	s_add_i32 s64, s86, 0xe000
	s_add_i32 s74, s63, 0x2000
	s_add_u32 s60, s58, 0xb0000
	s_addc_u32 s61, s59, 0
	s_add_i32 s75, s96, s83
	s_add_i32 s62, s75, 0x2000
	s_add_i32 vcc_hi, 0, 0x18000
	s_add_i32 vcc_lo, 0, 0x1c000
	s_add_u32 s54, s56, 0xb0000
	s_addc_u32 s55, s57, 0
	s_add_i32 s39, vcc_hi, s83
	s_add_i32 s73, s39, 0x2000
	s_add_u32 s10, s58, 0xb0080
	s_addc_u32 s11, s59, 0
	s_add_i32 s38, vcc_lo, s83
	s_add_i32 s33, s38, 0x2000
	v_lshl_add_u64 v[162:163], s[66:67], 0, v[138:139]
	global_load_lds_dwordx4 v[162:163], off
	v_lshl_add_u64 v[162:163], s[66:67], 0, v[142:143]
	s_mov_b32 m0, s64
	s_nop 0
	global_load_lds_dwordx4 v[162:163], off
	s_waitcnt vmcnt(8)
	s_waitcnt lgkmcnt(0)
	s_barrier
	s_setprio 0
	v_mfma_f32_16x16x32_bf16 v[126:129], v[130:133], v[184:187], v[126:129]
	v_mfma_f32_16x16x32_bf16 v[122:125], v[150:153], v[184:187], v[122:125]
	v_mfma_f32_16x16x32_bf16 v[110:113], v[130:133], v[192:195], v[110:113]
	v_mfma_f32_16x16x32_bf16 v[106:109], v[150:153], v[192:195], v[106:109]
	v_mfma_f32_16x16x32_bf16 v[94:97], v[130:133], v[200:203], v[94:97]
	v_mfma_f32_16x16x32_bf16 v[90:93], v[150:153], v[200:203], v[90:93]
	v_mfma_f32_16x16x32_bf16 v[78:81], v[130:133], v[208:211], v[78:81]
	v_mfma_f32_16x16x32_bf16 v[74:77], v[150:153], v[208:211], v[74:77]
	v_mfma_f32_16x16x32_bf16 v[126:129], v[134:137], v[188:191], v[126:129]
	v_mfma_f32_16x16x32_bf16 v[122:125], v[154:157], v[188:191], v[122:125]
	v_mfma_f32_16x16x32_bf16 v[110:113], v[134:137], v[196:199], v[110:113]
	v_mfma_f32_16x16x32_bf16 v[106:109], v[154:157], v[196:199], v[106:109]
	v_mfma_f32_16x16x32_bf16 v[94:97], v[134:137], v[204:207], v[94:97]
	v_mfma_f32_16x16x32_bf16 v[90:93], v[154:157], v[204:207], v[90:93]
	v_mfma_f32_16x16x32_bf16 v[78:81], v[134:137], v[212:215], v[78:81]
	v_mfma_f32_16x16x32_bf16 v[74:77], v[154:157], v[212:215], v[74:77]
	s_setprio 2
	s_setprio 0
	v_mfma_f32_16x16x32_bf16 v[118:121], v[158:161], v[184:187], v[118:121]
	v_mfma_f32_16x16x32_bf16 v[114:117], v[176:179], v[184:187], v[114:117]
	v_mfma_f32_16x16x32_bf16 v[102:105], v[158:161], v[192:195], v[102:105]
	v_mfma_f32_16x16x32_bf16 v[98:101], v[176:179], v[192:195], v[98:101]
	v_mfma_f32_16x16x32_bf16 v[86:89], v[158:161], v[200:203], v[86:89]
	v_mfma_f32_16x16x32_bf16 v[82:85], v[176:179], v[200:203], v[82:85]
	v_mfma_f32_16x16x32_bf16 v[70:73], v[158:161], v[208:211], v[70:73]
	v_mfma_f32_16x16x32_bf16 v[66:69], v[176:179], v[208:211], v[66:69]
	v_mfma_f32_16x16x32_bf16 v[118:121], v[172:175], v[188:191], v[118:121]
	v_mfma_f32_16x16x32_bf16 v[114:117], v[180:183], v[188:191], v[114:117]
	v_mfma_f32_16x16x32_bf16 v[102:105], v[172:175], v[196:199], v[102:105]
	v_mfma_f32_16x16x32_bf16 v[98:101], v[180:183], v[196:199], v[98:101]
	v_mfma_f32_16x16x32_bf16 v[86:89], v[172:175], v[204:207], v[86:89]
	v_mfma_f32_16x16x32_bf16 v[82:85], v[180:183], v[204:207], v[82:85]
	v_mfma_f32_16x16x32_bf16 v[70:73], v[172:175], v[212:215], v[70:73]
	v_mfma_f32_16x16x32_bf16 v[66:69], v[180:183], v[212:215], v[66:69]
	s_setprio 2
	s_barrier
	ds_read_b128 v[184:187], v168 offset:16384
	ds_read_b128 v[188:191], v168 offset:17408
	ds_read_b128 v[192:195], v168 offset:18432
	ds_read_b128 v[196:199], v168 offset:19456
	ds_read_b128 v[200:203], v168 offset:20480
	ds_read_b128 v[204:207], v168 offset:21504
	ds_read_b128 v[208:211], v168 offset:22528
	ds_read_b128 v[212:215], v168 offset:23552
	s_mov_b32 m0, s63
	v_lshl_add_u64 v[162:163], s[58:59], 0, v[140:141]
	global_load_lds_dwordx4 v[162:163], off
	v_lshl_add_u64 v[216:217], s[58:59], 0, v[144:145]
	s_mov_b32 m0, s74
	v_lshl_add_u64 v[218:219], s[60:61], 0, v[140:141]
	global_load_lds_dwordx4 v[216:217], off
	s_mov_b32 m0, s75
	v_lshl_add_u64 v[220:221], s[56:57], 0, v[142:143]
	global_load_lds_dwordx4 v[218:219], off
	v_lshl_add_u64 v[218:219], s[60:61], 0, v[144:145]
	s_mov_b32 m0, s62
	s_nop 0
	global_load_lds_dwordx4 v[218:219], off
	v_lshl_add_u64 v[218:219], s[56:57], 0, v[138:139]
	s_mov_b32 m0, s86
	s_nop 0
	global_load_lds_dwordx4 v[218:219], off
	s_mov_b32 m0, s87
	s_nop 0
	global_load_lds_dwordx4 v[220:221], off
	s_waitcnt vmcnt(8)
	s_waitcnt lgkmcnt(0)
	s_barrier
; #define PG8_STAGE(bufoff, gbase, voff) do { _Pragma("unroll") for (int _i = 0; _i < 2; ++_i) \
;         __builtin_amdgcn_global_load_lds((const unsigned*)((const char*)(gbase) + (voff)[_i]), (LAS unsigned*)(lds + (bufoff) + ldsw + _i * 8192), 16, 0, 0); } while (0)
; #define PG8_LDA(dst, b, h) do { _Pragma("unroll") for (int m = 0; m < 4; ++m) _Pragma("unroll") for (int k = 0; k < 2; ++k) dst[m][k] = *(const LAS bf16x8*)(lds + PG8_SA(b, h) + aoff + m * 2048 + k * 1024); } while (0)
; #define PG8_LDB(dst, b, h) do { _Pragma("unroll") for (int n = 0; n < 2; ++n) _Pragma("unroll") for (int k = 0; k < 2; ++k) dst[n][k] = *(const LAS bf16x8*)(lds + PG8_SB(b, h) + boff + n * 2048 + k * 1024); } while (0)
; #define PG8_MMA(ai, bj, At, Bt) do { __builtin_amdgcn_s_setprio(1); _Pragma("unroll") for (int m = 0; m < 4; ++m) _Pragma("unroll") for (int n = 0; n < 2; ++n) _Pragma("unroll") for (int k = 0; k < 2; ++k) \
;         acc[ai][bj][m][n] = __builtin_amdgcn_mfma_f32_16x16x32_bf16(Bt[n][k], At[m][k], acc[ai][bj][m][n], 0, 0, 0); __builtin_amdgcn_s_setprio(0); } while (0)
; #define PG8_WAIT_V(n) asm volatile("s_waitcnt vmcnt(" #n ")" ::: "memory")
; #define PG8_WAIT_L(n) asm volatile("s_waitcnt lgkmcnt(" #n ")" ::: "memory")
; #define PG8_BAR __builtin_amdgcn_s_barrier()
; #define PG8_SCHED __builtin_amdgcn_sched_barrier(0)
; template <class Epi>
; __device__ __forceinline__ void gemm_phase(LAS unsigned char* lds, const Gemm g, int G, int c, const Epi& E) {
;     ...
;             PG8_WAIT_V(8); PG8_WAIT_L(0); PG8_BAR; PG8_MMA(1, 0, At, B0); PG8_MMA(1, 1, At, B1); PG8_BAR; PG8_SCHED;
;             PG8_LDB(B0, 1, 0); PG8_LDB(B1, 1, 1); PG8_SCHED; PG8_LDA(At, 1, 0); PG8_STAGE(PG8_SA(0, 1), a2 + hstepA, voffA);
;             PG8_WAIT_V(8); PG8_WAIT_L(0); PG8_BAR; PG8_MMA(0, 0, At, B0); PG8_MMA(0, 1, At, B1); PG8_BAR; PG8_SCHED;
	s_setprio 0
	v_mfma_f32_16x16x32_bf16 v[62:65], v[130:133], v[184:187], v[62:65]
	v_mfma_f32_16x16x32_bf16 v[58:61], v[150:153], v[184:187], v[58:61]
	v_mfma_f32_16x16x32_bf16 v[46:49], v[130:133], v[192:195], v[46:49]
	v_mfma_f32_16x16x32_bf16 v[42:45], v[150:153], v[192:195], v[42:45]
	v_mfma_f32_16x16x32_bf16 v[30:33], v[130:133], v[200:203], v[30:33]
	v_mfma_f32_16x16x32_bf16 v[26:29], v[150:153], v[200:203], v[26:29]
	v_mfma_f32_16x16x32_bf16 v[14:17], v[130:133], v[208:211], v[14:17]
	v_mfma_f32_16x16x32_bf16 v[10:13], v[150:153], v[208:211], v[10:13]
	v_mfma_f32_16x16x32_bf16 v[62:65], v[134:137], v[188:191], v[62:65]
	v_mfma_f32_16x16x32_bf16 v[58:61], v[154:157], v[188:191], v[58:61]
	v_mfma_f32_16x16x32_bf16 v[46:49], v[134:137], v[196:199], v[46:49]
	v_mfma_f32_16x16x32_bf16 v[42:45], v[154:157], v[196:199], v[42:45]
	v_mfma_f32_16x16x32_bf16 v[30:33], v[134:137], v[204:207], v[30:33]
	v_mfma_f32_16x16x32_bf16 v[26:29], v[154:157], v[204:207], v[26:29]
	v_mfma_f32_16x16x32_bf16 v[14:17], v[134:137], v[212:215], v[14:17]
	v_mfma_f32_16x16x32_bf16 v[10:13], v[154:157], v[212:215], v[10:13]
	s_setprio 2
	s_setprio 0
	v_mfma_f32_16x16x32_bf16 v[54:57], v[158:161], v[184:187], v[54:57]
	v_mfma_f32_16x16x32_bf16 v[50:53], v[176:179], v[184:187], v[50:53]
	v_mfma_f32_16x16x32_bf16 v[38:41], v[158:161], v[192:195], v[38:41]
	v_mfma_f32_16x16x32_bf16 v[34:37], v[176:179], v[192:195], v[34:37]
	v_mfma_f32_16x16x32_bf16 v[22:25], v[158:161], v[200:203], v[22:25]
	v_mfma_f32_16x16x32_bf16 v[18:21], v[176:179], v[200:203], v[18:21]
	v_mfma_f32_16x16x32_bf16 v[6:9], v[158:161], v[208:211], v[6:9]
	v_mfma_f32_16x16x32_bf16 v[2:5], v[176:179], v[208:211], v[2:5]
	v_mfma_f32_16x16x32_bf16 v[54:57], v[172:175], v[188:191], v[54:57]
	v_mfma_f32_16x16x32_bf16 v[50:53], v[180:183], v[188:191], v[50:53]
	v_mfma_f32_16x16x32_bf16 v[38:41], v[172:175], v[196:199], v[38:41]
	v_mfma_f32_16x16x32_bf16 v[34:37], v[180:183], v[196:199], v[34:37]
	v_mfma_f32_16x16x32_bf16 v[22:25], v[172:175], v[204:207], v[22:25]
	v_mfma_f32_16x16x32_bf16 v[18:21], v[180:183], v[204:207], v[18:21]
	v_mfma_f32_16x16x32_bf16 v[6:9], v[172:175], v[212:215], v[6:9]
	v_mfma_f32_16x16x32_bf16 v[2:5], v[180:183], v[212:215], v[2:5]
	s_setprio 2
	s_barrier
	v_add_u32_e32 v154, vcc_hi, v165
	v_add_u32_e32 v180, vcc_lo, v165
	ds_read_b128 v[130:133], v154
	ds_read_b128 v[134:137], v154 offset:1024
	ds_read_b128 v[150:153], v154 offset:2048
	ds_read_b128 v[154:157], v154 offset:3072
	ds_read_b128 v[158:161], v180
	ds_read_b128 v[172:175], v180 offset:1024
	ds_read_b128 v[176:179], v180 offset:2048
	ds_read_b128 v[180:183], v180 offset:3072
	ds_read_b128 v[184:187], v168 offset:32768
	ds_read_b128 v[188:191], v168 offset:33792
	ds_read_b128 v[192:195], v168 offset:34816
	ds_read_b128 v[196:199], v168 offset:35840
	ds_read_b128 v[200:203], v168 offset:36864
	ds_read_b128 v[204:207], v168 offset:37888
	ds_read_b128 v[208:211], v168 offset:38912
	ds_read_b128 v[212:215], v168 offset:39936
	s_mov_b32 m0, s88
	v_lshl_add_u64 v[222:223], s[54:55], 0, v[138:139]
	global_load_lds_dwordx4 v[222:223], off
	v_lshl_add_u64 v[222:223], s[54:55], 0, v[142:143]
	s_mov_b32 m0, s89
	s_nop 0
	global_load_lds_dwordx4 v[222:223], off
	s_waitcnt vmcnt(8)
	s_waitcnt lgkmcnt(0)
	s_barrier
	s_setprio 0
	v_mfma_f32_16x16x32_bf16 v[126:129], v[130:133], v[184:187], v[126:129]
	v_mfma_f32_16x16x32_bf16 v[122:125], v[150:153], v[184:187], v[122:125]
	v_mfma_f32_16x16x32_bf16 v[110:113], v[130:133], v[192:195], v[110:113]
	v_mfma_f32_16x16x32_bf16 v[106:109], v[150:153], v[192:195], v[106:109]
	v_mfma_f32_16x16x32_bf16 v[94:97], v[130:133], v[200:203], v[94:97]
	v_mfma_f32_16x16x32_bf16 v[90:93], v[150:153], v[200:203], v[90:93]
	v_mfma_f32_16x16x32_bf16 v[78:81], v[130:133], v[208:211], v[78:81]
	v_mfma_f32_16x16x32_bf16 v[74:77], v[150:153], v[208:211], v[74:77]
	v_mfma_f32_16x16x32_bf16 v[126:129], v[134:137], v[188:191], v[126:129]
	v_mfma_f32_16x16x32_bf16 v[122:125], v[154:157], v[188:191], v[122:125]
	v_mfma_f32_16x16x32_bf16 v[110:113], v[134:137], v[196:199], v[110:113]
	v_mfma_f32_16x16x32_bf16 v[106:109], v[154:157], v[196:199], v[106:109]
	v_mfma_f32_16x16x32_bf16 v[94:97], v[134:137], v[204:207], v[94:97]
	v_mfma_f32_16x16x32_bf16 v[90:93], v[154:157], v[204:207], v[90:93]
	v_mfma_f32_16x16x32_bf16 v[78:81], v[134:137], v[212:215], v[78:81]
	v_mfma_f32_16x16x32_bf16 v[74:77], v[154:157], v[212:215], v[74:77]
	s_setprio 2
	s_setprio 0
	v_mfma_f32_16x16x32_bf16 v[118:121], v[158:161], v[184:187], v[118:121]
	v_mfma_f32_16x16x32_bf16 v[114:117], v[176:179], v[184:187], v[114:117]
	v_mfma_f32_16x16x32_bf16 v[102:105], v[158:161], v[192:195], v[102:105]
	v_mfma_f32_16x16x32_bf16 v[98:101], v[176:179], v[192:195], v[98:101]
	v_mfma_f32_16x16x32_bf16 v[86:89], v[158:161], v[200:203], v[86:89]
	v_mfma_f32_16x16x32_bf16 v[82:85], v[176:179], v[200:203], v[82:85]
	v_mfma_f32_16x16x32_bf16 v[70:73], v[158:161], v[208:211], v[70:73]
	v_mfma_f32_16x16x32_bf16 v[66:69], v[176:179], v[208:211], v[66:69]
	v_mfma_f32_16x16x32_bf16 v[118:121], v[172:175], v[188:191], v[118:121]
	v_mfma_f32_16x16x32_bf16 v[114:117], v[180:183], v[188:191], v[114:117]
	v_mfma_f32_16x16x32_bf16 v[102:105], v[172:175], v[196:199], v[102:105]
	v_mfma_f32_16x16x32_bf16 v[98:101], v[180:183], v[196:199], v[98:101]
	v_mfma_f32_16x16x32_bf16 v[86:89], v[172:175], v[204:207], v[86:89]
	v_mfma_f32_16x16x32_bf16 v[82:85], v[180:183], v[204:207], v[82:85]
	v_mfma_f32_16x16x32_bf16 v[70:73], v[172:175], v[212:215], v[70:73]
	v_mfma_f32_16x16x32_bf16 v[66:69], v[180:183], v[212:215], v[66:69]
	s_setprio 2
	s_barrier
; #define PG8_STAGE(bufoff, gbase, voff) do { _Pragma("unroll") for (int _i = 0; _i < 2; ++_i) \
;         __builtin_amdgcn_global_load_lds((const unsigned*)((const char*)(gbase) + (voff)[_i]), (LAS unsigned*)(lds + (bufoff) + ldsw + _i * 8192), 16, 0, 0); } while (0)
; #define PG8_LDA(dst, b, h) do { _Pragma("unroll") for (int m = 0; m < 4; ++m) _Pragma("unroll") for (int k = 0; k < 2; ++k) dst[m][k] = *(const LAS bf16x8*)(lds + PG8_SA(b, h) + aoff + m * 2048 + k * 1024); } while (0)
; #define PG8_MMA(ai, bj, At, Bt) do { __builtin_amdgcn_s_setprio(1); _Pragma("unroll") for (int m = 0; m < 4; ++m) _Pragma("unroll") for (int n = 0; n < 2; ++n) _Pragma("unroll") for (int k = 0; k < 2; ++k) \
;         acc[ai][bj][m][n] = __builtin_amdgcn_mfma_f32_16x16x32_bf16(Bt[n][k], At[m][k], acc[ai][bj][m][n], 0, 0, 0); __builtin_amdgcn_s_setprio(0); } while (0)
; #define PG8_WAIT_V(n) asm volatile("s_waitcnt vmcnt(" #n ")" ::: "memory")
; #define PG8_WAIT_L(n) asm volatile("s_waitcnt lgkmcnt(" #n ")" ::: "memory")
; #define PG8_BAR __builtin_amdgcn_s_barrier()
; #define PG8_SCHED __builtin_amdgcn_sched_barrier(0)
; template <class Epi>
; __device__ __forceinline__ void gemm_phase(LAS unsigned char* lds, const Gemm g, int G, int c, const Epi& E) {
;     ...
;             PG8_LDA(At, 1, 1); PG8_STAGE(PG8_SB(1, 0), b3, voffB); PG8_STAGE(PG8_SB(1, 1), b3 + hstepB, voffB); PG8_STAGE(PG8_SA(1, 0), a3, voffA);
;             PG8_WAIT_V(8); PG8_WAIT_L(0); PG8_BAR; PG8_MMA(1, 0, At, B0); PG8_MMA(1, 1, At, B1); PG8_BAR; PG8_SCHED;
;         }
	ds_read_b128 v[184:187], v168 offset:49152
	ds_read_b128 v[188:191], v168 offset:50176
	ds_read_b128 v[192:195], v168 offset:51200
	ds_read_b128 v[196:199], v168 offset:52224
	ds_read_b128 v[200:203], v168 offset:53248
	ds_read_b128 v[204:207], v168 offset:54272
	ds_read_b128 v[208:211], v168 offset:55296
	ds_read_b128 v[212:215], v168 offset:56320
	s_mov_b32 m0, s39
	v_lshl_add_u64 v[162:163], v[162:163], 0, s[24:25]
	global_load_lds_dwordx4 v[162:163], off
	v_lshl_add_u64 v[162:163], v[216:217], 0, s[24:25]
	s_mov_b32 m0, s73
	s_nop 0
	global_load_lds_dwordx4 v[162:163], off
	v_lshl_add_u64 v[162:163], s[10:11], 0, v[140:141]
	s_mov_b32 m0, s38
	s_nop 0
	global_load_lds_dwordx4 v[162:163], off
	v_lshl_add_u64 v[162:163], s[10:11], 0, v[144:145]
	s_mov_b32 m0, s33
	s_nop 0
	global_load_lds_dwordx4 v[162:163], off
	v_lshl_add_u64 v[162:163], v[218:219], 0, s[24:25]
	s_mov_b32 m0, s93
	s_nop 0
	global_load_lds_dwordx4 v[162:163], off
	v_lshl_add_u64 v[162:163], v[220:221], 0, s[24:25]
	s_mov_b32 m0, s94
	s_nop 0
	global_load_lds_dwordx4 v[162:163], off
	s_waitcnt vmcnt(8)
	s_waitcnt lgkmcnt(0)
	s_barrier
	s_setprio 0
	v_mfma_f32_16x16x32_bf16 v[62:65], v[130:133], v[184:187], v[62:65]
	v_mfma_f32_16x16x32_bf16 v[58:61], v[150:153], v[184:187], v[58:61]
	v_mfma_f32_16x16x32_bf16 v[46:49], v[130:133], v[192:195], v[46:49]
	v_mfma_f32_16x16x32_bf16 v[42:45], v[150:153], v[192:195], v[42:45]
	v_mfma_f32_16x16x32_bf16 v[30:33], v[130:133], v[200:203], v[30:33]
	v_mfma_f32_16x16x32_bf16 v[26:29], v[150:153], v[200:203], v[26:29]
	v_mfma_f32_16x16x32_bf16 v[14:17], v[130:133], v[208:211], v[14:17]
	v_mfma_f32_16x16x32_bf16 v[10:13], v[150:153], v[208:211], v[10:13]
	v_mfma_f32_16x16x32_bf16 v[62:65], v[134:137], v[188:191], v[62:65]
	v_mfma_f32_16x16x32_bf16 v[58:61], v[154:157], v[188:191], v[58:61]
	v_mfma_f32_16x16x32_bf16 v[46:49], v[134:137], v[196:199], v[46:49]
	v_mfma_f32_16x16x32_bf16 v[42:45], v[154:157], v[196:199], v[42:45]
	v_mfma_f32_16x16x32_bf16 v[30:33], v[134:137], v[204:207], v[30:33]
	v_mfma_f32_16x16x32_bf16 v[26:29], v[154:157], v[204:207], v[26:29]
	v_mfma_f32_16x16x32_bf16 v[14:17], v[134:137], v[212:215], v[14:17]
	v_mfma_f32_16x16x32_bf16 v[10:13], v[154:157], v[212:215], v[10:13]
	s_setprio 2
	s_setprio 0
	v_mfma_f32_16x16x32_bf16 v[54:57], v[158:161], v[184:187], v[54:57]
	v_mfma_f32_16x16x32_bf16 v[50:53], v[176:179], v[184:187], v[50:53]
	v_mfma_f32_16x16x32_bf16 v[38:41], v[158:161], v[192:195], v[38:41]
	v_mfma_f32_16x16x32_bf16 v[34:37], v[176:179], v[192:195], v[34:37]
	v_mfma_f32_16x16x32_bf16 v[22:25], v[158:161], v[200:203], v[22:25]
	v_mfma_f32_16x16x32_bf16 v[18:21], v[176:179], v[200:203], v[18:21]
	v_mfma_f32_16x16x32_bf16 v[6:9], v[158:161], v[208:211], v[6:9]
	v_mfma_f32_16x16x32_bf16 v[2:5], v[176:179], v[208:211], v[2:5]
	v_mfma_f32_16x16x32_bf16 v[54:57], v[172:175], v[188:191], v[54:57]
	v_mfma_f32_16x16x32_bf16 v[50:53], v[180:183], v[188:191], v[50:53]
	v_mfma_f32_16x16x32_bf16 v[38:41], v[172:175], v[196:199], v[38:41]
	v_mfma_f32_16x16x32_bf16 v[34:37], v[180:183], v[196:199], v[34:37]
	v_mfma_f32_16x16x32_bf16 v[22:25], v[172:175], v[204:207], v[22:25]
	v_mfma_f32_16x16x32_bf16 v[18:21], v[180:183], v[204:207], v[18:21]
	v_mfma_f32_16x16x32_bf16 v[6:9], v[172:175], v[212:215], v[6:9]
	v_mfma_f32_16x16x32_bf16 v[2:5], v[180:183], v[212:215], v[2:5]
	s_setprio 2
	s_barrier
	s_movk_i32 s38, 0x100
	s_andn2_b64 vcc, exec, s[4:5]
	s_mov_b64 s[10:11], -1
	s_mov_b64 s[4:5], 0
	s_cbranch_vccz .LBB0_476
	s_and_b64 vcc, exec, s[44:45]
	s_cbranch_vccz .LBB0_479
	s_barrier

; #define PG8_STAGE(bufoff, gbase, voff) do { _Pragma("unroll") for (int _i = 0; _i < 2; ++_i) \
;         __builtin_amdgcn_global_load_lds((const unsigned*)((const char*)(gbase) + (voff)[_i]), (LAS unsigned*)(lds + (bufoff) + ldsw + _i * 8192), 16, 0, 0); } while (0)
; #define PG8_LDA(dst, b, h) do { _Pragma("unroll") for (int m = 0; m < 4; ++m) _Pragma("unroll") for (int k = 0; k < 2; ++k) dst[m][k] = *(const LAS bf16x8*)(lds + PG8_SA(b, h) + aoff + m * 2048 + k * 1024); } while (0)
; #define PG8_LDB(dst, b, h) do { _Pragma("unroll") for (int n = 0; n < 2; ++n) _Pragma("unroll") for (int k = 0; k < 2; ++k) dst[n][k] = *(const LAS bf16x8*)(lds + PG8_SB(b, h) + boff + n * 2048 + k * 1024); } while (0)
; #define PG8_MMA(ai, bj, At, Bt) do { __builtin_amdgcn_s_setprio(1); _Pragma("unroll") for (int m = 0; m < 4; ++m) _Pragma("unroll") for (int n = 0; n < 2; ++n) _Pragma("unroll") for (int k = 0; k < 2; ++k) \
;         acc[ai][bj][m][n] = __builtin_amdgcn_mfma_f32_16x16x32_bf16(Bt[n][k], At[m][k], acc[ai][bj][m][n], 0, 0, 0); __builtin_amdgcn_s_setprio(0); } while (0)
; #define PG8_WAIT_V(n) asm volatile("s_waitcnt vmcnt(" #n ")" ::: "memory")
; #define PG8_WAIT_L(n) asm volatile("s_waitcnt lgkmcnt(" #n ")" ::: "memory")
; #define PG8_BAR __builtin_amdgcn_s_barrier()
; #define PG8_SCHED __builtin_amdgcn_sched_barrier(0)
; template <class Epi>
; __device__ __forceinline__ void gemm_phase(LAS unsigned char* lds, const Gemm g, int G, int c, const Epi& E) {
;     ...
;             const bool last = (t == nt - 2);
;             const char* a1 = cA + (size_t)(t + 1) * kstep;
;             const char* a2 = last ? nA : cA + (size_t)(t + 2) * kstep; const char* b2 = last ? nB : cB + (size_t)(t + 2) * kstep;
;             const char* a3 = a2 + kstep; const char* b3 = b2 + kstep;
;             PG8_LDB(B0, 0, 0); PG8_LDB(B1, 0, 1); PG8_SCHED; PG8_LDA(At, 0, 0); PG8_STAGE(PG8_SA(1, 1), a1 + hstepA, voffA);
;             PG8_WAIT_V(8); PG8_WAIT_L(0); PG8_BAR; PG8_MMA(0, 0, At, B0); PG8_MMA(0, 1, At, B1); PG8_BAR; PG8_SCHED;
;             PG8_LDA(At, 0, 1); PG8_STAGE(PG8_SB(0, 0), b2, voffB); PG8_STAGE(PG8_SB(0, 1), b2 + hstepB, voffB); PG8_STAGE(PG8_SA(0, 0), a2, voffA);
;             PG8_WAIT_V(8); PG8_WAIT_L(0); PG8_BAR; PG8_MMA(1, 0, At, B0); PG8_MMA(1, 1, At, B1); PG8_BAR; PG8_SCHED;
.LBB0_594:
	ds_read_b128 v[142:145], v166
	ds_read_b128 v[146:149], v166 offset:1024
	ds_read_b128 v[150:153], v166 offset:2048
	ds_read_b128 v[154:157], v166 offset:3072
	ds_read_b128 v[158:161], v167
	ds_read_b128 v[170:173], v167 offset:1024
	ds_read_b128 v[174:177], v167 offset:2048
	ds_read_b128 v[178:181], v167 offset:3072
	ds_read_b128 v[182:185], v168
	ds_read_b128 v[186:189], v168 offset:1024
	ds_read_b128 v[190:193], v168 offset:2048
	ds_read_b128 v[194:197], v168 offset:3072
	ds_read_b128 v[198:201], v168 offset:4096
	ds_read_b128 v[202:205], v168 offset:5120
	ds_read_b128 v[206:209], v168 offset:6144
	ds_read_b128 v[210:213], v168 offset:7168
	s_add_u32 s33, s8, s38
	s_addc_u32 s62, s9, 0
	s_add_u32 s39, s33, 0x100
	s_addc_u32 s58, s62, 0
	s_and_b64 s[56:57], s[54:55], exec
	s_cselect_b32 s59, s45, s58
	s_cselect_b32 s58, s44, s39
	s_add_u32 s38, s6, s38
	s_addc_u32 s39, s7, 0
	s_add_u32 s56, s38, 0x100
	s_addc_u32 s57, s39, 0
	s_and_b64 s[38:39], s[54:55], exec
	s_cselect_b32 s61, s47, s57
	s_cselect_b32 s60, s46, s56
	s_add_u32 s68, s33, 0xb0080
	s_addc_u32 s69, s62, 0
	s_add_i32 s63, s86, s23
	s_add_i32 m0, s72, 0xc000
	s_add_i32 s64, s72, 0xe000
	s_add_i32 s74, s63, 0x2000
	s_add_u32 s66, s60, 0xb0000
	s_addc_u32 s67, s61, 0
	s_add_i32 s62, s87, s23
	s_add_i32 s75, s62, 0x2000
	s_add_i32 s97, 0, 0x18000
	s_add_i32 s33, 0, 0x1c000
	s_add_u32 s56, s58, 0xb0000
	s_addc_u32 s57, s59, 0
	s_add_i32 s96, s97, s23
	s_add_i32 s39, s96, 0x2000
	s_add_u32 s54, s60, 0xb0080
	s_addc_u32 s55, s61, 0
	s_add_i32 s95, s33, s23
	s_add_i32 s38, s95, 0x2000
	v_lshl_add_u64 v[162:163], s[68:69], 0, v[136:137]
	global_load_lds_dwordx4 v[162:163], off
	v_lshl_add_u64 v[162:163], s[68:69], 0, v[132:133]
	s_mov_b32 m0, s64
	s_nop 0
	global_load_lds_dwordx4 v[162:163], off
	s_waitcnt vmcnt(8)
	s_waitcnt lgkmcnt(0)
	s_barrier
	s_setprio 0
	v_mfma_f32_16x16x32_bf16 v[126:129], v[142:145], v[182:185], v[126:129]
	v_mfma_f32_16x16x32_bf16 v[122:125], v[150:153], v[182:185], v[122:125]
	v_mfma_f32_16x16x32_bf16 v[110:113], v[142:145], v[190:193], v[110:113]
	v_mfma_f32_16x16x32_bf16 v[106:109], v[150:153], v[190:193], v[106:109]
	v_mfma_f32_16x16x32_bf16 v[94:97], v[142:145], v[198:201], v[94:97]
	v_mfma_f32_16x16x32_bf16 v[90:93], v[150:153], v[198:201], v[90:93]
	v_mfma_f32_16x16x32_bf16 v[78:81], v[142:145], v[206:209], v[78:81]
	v_mfma_f32_16x16x32_bf16 v[74:77], v[150:153], v[206:209], v[74:77]
	v_mfma_f32_16x16x32_bf16 v[126:129], v[146:149], v[186:189], v[126:129]
	v_mfma_f32_16x16x32_bf16 v[122:125], v[154:157], v[186:189], v[122:125]
	v_mfma_f32_16x16x32_bf16 v[110:113], v[146:149], v[194:197], v[110:113]
	v_mfma_f32_16x16x32_bf16 v[106:109], v[154:157], v[194:197], v[106:109]
	v_mfma_f32_16x16x32_bf16 v[94:97], v[146:149], v[202:205], v[94:97]
	v_mfma_f32_16x16x32_bf16 v[90:93], v[154:157], v[202:205], v[90:93]
	v_mfma_f32_16x16x32_bf16 v[78:81], v[146:149], v[210:213], v[78:81]
	v_mfma_f32_16x16x32_bf16 v[74:77], v[154:157], v[210:213], v[74:77]
	s_setprio 2
	s_setprio 0
	v_mfma_f32_16x16x32_bf16 v[118:121], v[158:161], v[182:185], v[118:121]
	v_mfma_f32_16x16x32_bf16 v[114:117], v[174:177], v[182:185], v[114:117]
	v_mfma_f32_16x16x32_bf16 v[102:105], v[158:161], v[190:193], v[102:105]
	v_mfma_f32_16x16x32_bf16 v[98:101], v[174:177], v[190:193], v[98:101]
	v_mfma_f32_16x16x32_bf16 v[86:89], v[158:161], v[198:201], v[86:89]
	v_mfma_f32_16x16x32_bf16 v[82:85], v[174:177], v[198:201], v[82:85]
	v_mfma_f32_16x16x32_bf16 v[70:73], v[158:161], v[206:209], v[70:73]
	v_mfma_f32_16x16x32_bf16 v[66:69], v[174:177], v[206:209], v[66:69]
	v_mfma_f32_16x16x32_bf16 v[118:121], v[170:173], v[186:189], v[118:121]
	v_mfma_f32_16x16x32_bf16 v[114:117], v[178:181], v[186:189], v[114:117]
	v_mfma_f32_16x16x32_bf16 v[102:105], v[170:173], v[194:197], v[102:105]
	v_mfma_f32_16x16x32_bf16 v[98:101], v[178:181], v[194:197], v[98:101]
	v_mfma_f32_16x16x32_bf16 v[86:89], v[170:173], v[202:205], v[86:89]
	v_mfma_f32_16x16x32_bf16 v[82:85], v[178:181], v[202:205], v[82:85]
	v_mfma_f32_16x16x32_bf16 v[70:73], v[170:173], v[210:213], v[70:73]
	v_mfma_f32_16x16x32_bf16 v[66:69], v[178:181], v[210:213], v[66:69]
	s_setprio 2
	s_barrier
	ds_read_b128 v[182:185], v168 offset:16384
	ds_read_b128 v[186:189], v168 offset:17408
	ds_read_b128 v[190:193], v168 offset:18432
	ds_read_b128 v[194:197], v168 offset:19456
	ds_read_b128 v[198:201], v168 offset:20480
	ds_read_b128 v[202:205], v168 offset:21504
	ds_read_b128 v[206:209], v168 offset:22528
	ds_read_b128 v[210:213], v168 offset:23552
	s_mov_b32 m0, s63
	v_lshl_add_u64 v[162:163], s[60:61], 0, v[134:135]
	global_load_lds_dwordx4 v[162:163], off
	v_lshl_add_u64 v[214:215], s[60:61], 0, v[130:131]
	s_mov_b32 m0, s74
	v_lshl_add_u64 v[216:217], s[66:67], 0, v[134:135]
	global_load_lds_dwordx4 v[214:215], off
	s_mov_b32 m0, s62
	v_lshl_add_u64 v[218:219], s[58:59], 0, v[132:133]
	global_load_lds_dwordx4 v[216:217], off
	v_lshl_add_u64 v[216:217], s[66:67], 0, v[130:131]
	s_mov_b32 m0, s75
	s_nop 0
	global_load_lds_dwordx4 v[216:217], off
	v_lshl_add_u64 v[216:217], s[58:59], 0, v[136:137]
	s_mov_b32 m0, s72
	s_nop 0
	global_load_lds_dwordx4 v[216:217], off
	s_mov_b32 m0, s73
	s_nop 0
	global_load_lds_dwordx4 v[218:219], off
	s_waitcnt vmcnt(8)
	s_waitcnt lgkmcnt(0)
	s_barrier
; #define PG8_STAGE(bufoff, gbase, voff) do { _Pragma("unroll") for (int _i = 0; _i < 2; ++_i) \
;         __builtin_amdgcn_global_load_lds((const unsigned*)((const char*)(gbase) + (voff)[_i]), (LAS unsigned*)(lds + (bufoff) + ldsw + _i * 8192), 16, 0, 0); } while (0)
; #define PG8_LDA(dst, b, h) do { _Pragma("unroll") for (int m = 0; m < 4; ++m) _Pragma("unroll") for (int k = 0; k < 2; ++k) dst[m][k] = *(const LAS bf16x8*)(lds + PG8_SA(b, h) + aoff + m * 2048 + k * 1024); } while (0)
; #define PG8_LDB(dst, b, h) do { _Pragma("unroll") for (int n = 0; n < 2; ++n) _Pragma("unroll") for (int k = 0; k < 2; ++k) dst[n][k] = *(const LAS bf16x8*)(lds + PG8_SB(b, h) + boff + n * 2048 + k * 1024); } while (0)
; #define PG8_MMA(ai, bj, At, Bt) do { __builtin_amdgcn_s_setprio(1); _Pragma("unroll") for (int m = 0; m < 4; ++m) _Pragma("unroll") for (int n = 0; n < 2; ++n) _Pragma("unroll") for (int k = 0; k < 2; ++k) \
;         acc[ai][bj][m][n] = __builtin_amdgcn_mfma_f32_16x16x32_bf16(Bt[n][k], At[m][k], acc[ai][bj][m][n], 0, 0, 0); __builtin_amdgcn_s_setprio(0); } while (0)
; #define PG8_WAIT_V(n) asm volatile("s_waitcnt vmcnt(" #n ")" ::: "memory")
; #define PG8_WAIT_L(n) asm volatile("s_waitcnt lgkmcnt(" #n ")" ::: "memory")
; #define PG8_BAR __builtin_amdgcn_s_barrier()
; #define PG8_SCHED __builtin_amdgcn_sched_barrier(0)
; template <class Epi>
; __device__ __forceinline__ void gemm_phase(LAS unsigned char* lds, const Gemm g, int G, int c, const Epi& E) {
;     ...
;             PG8_WAIT_V(8); PG8_WAIT_L(0); PG8_BAR; PG8_MMA(1, 0, At, B0); PG8_MMA(1, 1, At, B1); PG8_BAR; PG8_SCHED;
;             PG8_LDB(B0, 1, 0); PG8_LDB(B1, 1, 1); PG8_SCHED; PG8_LDA(At, 1, 0); PG8_STAGE(PG8_SA(0, 1), a2 + hstepA, voffA);
;             PG8_WAIT_V(8); PG8_WAIT_L(0); PG8_BAR; PG8_MMA(0, 0, At, B0); PG8_MMA(0, 1, At, B1); PG8_BAR; PG8_SCHED;
	s_setprio 0
	v_mfma_f32_16x16x32_bf16 v[62:65], v[142:145], v[182:185], v[62:65]
	v_mfma_f32_16x16x32_bf16 v[58:61], v[150:153], v[182:185], v[58:61]
	v_mfma_f32_16x16x32_bf16 v[46:49], v[142:145], v[190:193], v[46:49]
	v_mfma_f32_16x16x32_bf16 v[42:45], v[150:153], v[190:193], v[42:45]
	v_mfma_f32_16x16x32_bf16 v[30:33], v[142:145], v[198:201], v[30:33]
	v_mfma_f32_16x16x32_bf16 v[26:29], v[150:153], v[198:201], v[26:29]
	v_mfma_f32_16x16x32_bf16 v[14:17], v[142:145], v[206:209], v[14:17]
	v_mfma_f32_16x16x32_bf16 v[10:13], v[150:153], v[206:209], v[10:13]
	v_mfma_f32_16x16x32_bf16 v[62:65], v[146:149], v[186:189], v[62:65]
	v_mfma_f32_16x16x32_bf16 v[58:61], v[154:157], v[186:189], v[58:61]
	v_mfma_f32_16x16x32_bf16 v[46:49], v[146:149], v[194:197], v[46:49]
	v_mfma_f32_16x16x32_bf16 v[42:45], v[154:157], v[194:197], v[42:45]
	v_mfma_f32_16x16x32_bf16 v[30:33], v[146:149], v[202:205], v[30:33]
	v_mfma_f32_16x16x32_bf16 v[26:29], v[154:157], v[202:205], v[26:29]
	v_mfma_f32_16x16x32_bf16 v[14:17], v[146:149], v[210:213], v[14:17]
	v_mfma_f32_16x16x32_bf16 v[10:13], v[154:157], v[210:213], v[10:13]
	s_setprio 2
	s_setprio 0
	v_mfma_f32_16x16x32_bf16 v[54:57], v[158:161], v[182:185], v[54:57]
	v_mfma_f32_16x16x32_bf16 v[50:53], v[174:177], v[182:185], v[50:53]
	v_mfma_f32_16x16x32_bf16 v[38:41], v[158:161], v[190:193], v[38:41]
	v_mfma_f32_16x16x32_bf16 v[34:37], v[174:177], v[190:193], v[34:37]
	v_mfma_f32_16x16x32_bf16 v[22:25], v[158:161], v[198:201], v[22:25]
	v_mfma_f32_16x16x32_bf16 v[18:21], v[174:177], v[198:201], v[18:21]
	v_mfma_f32_16x16x32_bf16 v[6:9], v[158:161], v[206:209], v[6:9]
	v_mfma_f32_16x16x32_bf16 v[2:5], v[174:177], v[206:209], v[2:5]
	v_mfma_f32_16x16x32_bf16 v[54:57], v[170:173], v[186:189], v[54:57]
	v_mfma_f32_16x16x32_bf16 v[50:53], v[178:181], v[186:189], v[50:53]
	v_mfma_f32_16x16x32_bf16 v[38:41], v[170:173], v[194:197], v[38:41]
	v_mfma_f32_16x16x32_bf16 v[34:37], v[178:181], v[194:197], v[34:37]
	v_mfma_f32_16x16x32_bf16 v[22:25], v[170:173], v[202:205], v[22:25]
	v_mfma_f32_16x16x32_bf16 v[18:21], v[178:181], v[202:205], v[18:21]
	v_mfma_f32_16x16x32_bf16 v[6:9], v[170:173], v[210:213], v[6:9]
	v_mfma_f32_16x16x32_bf16 v[2:5], v[178:181], v[210:213], v[2:5]
	s_setprio 2
	s_barrier
	v_add_u32_e32 v154, s97, v165
	v_add_u32_e32 v178, s33, v165
	ds_read_b128 v[142:145], v154
	ds_read_b128 v[146:149], v154 offset:1024
	ds_read_b128 v[150:153], v154 offset:2048
	ds_read_b128 v[154:157], v154 offset:3072
	ds_read_b128 v[158:161], v178
	ds_read_b128 v[170:173], v178 offset:1024
	ds_read_b128 v[174:177], v178 offset:2048
	ds_read_b128 v[178:181], v178 offset:3072
	ds_read_b128 v[182:185], v168 offset:32768
	ds_read_b128 v[186:189], v168 offset:33792
	ds_read_b128 v[190:193], v168 offset:34816
	ds_read_b128 v[194:197], v168 offset:35840
	ds_read_b128 v[198:201], v168 offset:36864
	ds_read_b128 v[202:205], v168 offset:37888
	ds_read_b128 v[206:209], v168 offset:38912
	ds_read_b128 v[210:213], v168 offset:39936
	s_mov_b32 m0, s78
	v_lshl_add_u64 v[220:221], s[56:57], 0, v[136:137]
	global_load_lds_dwordx4 v[220:221], off
	v_lshl_add_u64 v[220:221], s[56:57], 0, v[132:133]
	s_mov_b32 m0, s81
	s_nop 0
	global_load_lds_dwordx4 v[220:221], off
	s_waitcnt vmcnt(8)
	s_waitcnt lgkmcnt(0)
	s_barrier
	s_setprio 0
	v_mfma_f32_16x16x32_bf16 v[126:129], v[142:145], v[182:185], v[126:129]
	v_mfma_f32_16x16x32_bf16 v[122:125], v[150:153], v[182:185], v[122:125]
	v_mfma_f32_16x16x32_bf16 v[110:113], v[142:145], v[190:193], v[110:113]
	v_mfma_f32_16x16x32_bf16 v[106:109], v[150:153], v[190:193], v[106:109]
	v_mfma_f32_16x16x32_bf16 v[94:97], v[142:145], v[198:201], v[94:97]
	v_mfma_f32_16x16x32_bf16 v[90:93], v[150:153], v[198:201], v[90:93]
	v_mfma_f32_16x16x32_bf16 v[78:81], v[142:145], v[206:209], v[78:81]
	v_mfma_f32_16x16x32_bf16 v[74:77], v[150:153], v[206:209], v[74:77]
	v_mfma_f32_16x16x32_bf16 v[126:129], v[146:149], v[186:189], v[126:129]
	v_mfma_f32_16x16x32_bf16 v[122:125], v[154:157], v[186:189], v[122:125]
	v_mfma_f32_16x16x32_bf16 v[110:113], v[146:149], v[194:197], v[110:113]
	v_mfma_f32_16x16x32_bf16 v[106:109], v[154:157], v[194:197], v[106:109]
	v_mfma_f32_16x16x32_bf16 v[94:97], v[146:149], v[202:205], v[94:97]
	v_mfma_f32_16x16x32_bf16 v[90:93], v[154:157], v[202:205], v[90:93]
	v_mfma_f32_16x16x32_bf16 v[78:81], v[146:149], v[210:213], v[78:81]
	v_mfma_f32_16x16x32_bf16 v[74:77], v[154:157], v[210:213], v[74:77]
	s_setprio 2
	s_setprio 0
	v_mfma_f32_16x16x32_bf16 v[118:121], v[158:161], v[182:185], v[118:121]
	v_mfma_f32_16x16x32_bf16 v[114:117], v[174:177], v[182:185], v[114:117]
	v_mfma_f32_16x16x32_bf16 v[102:105], v[158:161], v[190:193], v[102:105]
	v_mfma_f32_16x16x32_bf16 v[98:101], v[174:177], v[190:193], v[98:101]
	v_mfma_f32_16x16x32_bf16 v[86:89], v[158:161], v[198:201], v[86:89]
	v_mfma_f32_16x16x32_bf16 v[82:85], v[174:177], v[198:201], v[82:85]
	v_mfma_f32_16x16x32_bf16 v[70:73], v[158:161], v[206:209], v[70:73]
	v_mfma_f32_16x16x32_bf16 v[66:69], v[174:177], v[206:209], v[66:69]
	v_mfma_f32_16x16x32_bf16 v[118:121], v[170:173], v[186:189], v[118:121]
	v_mfma_f32_16x16x32_bf16 v[114:117], v[178:181], v[186:189], v[114:117]
	v_mfma_f32_16x16x32_bf16 v[102:105], v[170:173], v[194:197], v[102:105]
	v_mfma_f32_16x16x32_bf16 v[98:101], v[178:181], v[194:197], v[98:101]
	v_mfma_f32_16x16x32_bf16 v[86:89], v[170:173], v[202:205], v[86:89]
	v_mfma_f32_16x16x32_bf16 v[82:85], v[178:181], v[202:205], v[82:85]
	v_mfma_f32_16x16x32_bf16 v[70:73], v[170:173], v[210:213], v[70:73]
	v_mfma_f32_16x16x32_bf16 v[66:69], v[178:181], v[210:213], v[66:69]
	s_setprio 2
	s_barrier
; #define PG8_STAGE(bufoff, gbase, voff) do { _Pragma("unroll") for (int _i = 0; _i < 2; ++_i) \
;         __builtin_amdgcn_global_load_lds((const unsigned*)((const char*)(gbase) + (voff)[_i]), (LAS unsigned*)(lds + (bufoff) + ldsw + _i * 8192), 16, 0, 0); } while (0)
; #define PG8_LDA(dst, b, h) do { _Pragma("unroll") for (int m = 0; m < 4; ++m) _Pragma("unroll") for (int k = 0; k < 2; ++k) dst[m][k] = *(const LAS bf16x8*)(lds + PG8_SA(b, h) + aoff + m * 2048 + k * 1024); } while (0)
; #define PG8_MMA(ai, bj, At, Bt) do { __builtin_amdgcn_s_setprio(1); _Pragma("unroll") for (int m = 0; m < 4; ++m) _Pragma("unroll") for (int n = 0; n < 2; ++n) _Pragma("unroll") for (int k = 0; k < 2; ++k) \
;         acc[ai][bj][m][n] = __builtin_amdgcn_mfma_f32_16x16x32_bf16(Bt[n][k], At[m][k], acc[ai][bj][m][n], 0, 0, 0); __builtin_amdgcn_s_setprio(0); } while (0)
; #define PG8_WAIT_V(n) asm volatile("s_waitcnt vmcnt(" #n ")" ::: "memory")
; #define PG8_WAIT_L(n) asm volatile("s_waitcnt lgkmcnt(" #n ")" ::: "memory")
; #define PG8_BAR __builtin_amdgcn_s_barrier()
; #define PG8_SCHED __builtin_amdgcn_sched_barrier(0)
; template <class Epi>
; __device__ __forceinline__ void gemm_phase(LAS unsigned char* lds, const Gemm g, int G, int c, const Epi& E) {
;     ...
;             PG8_LDA(At, 1, 1); PG8_STAGE(PG8_SB(1, 0), b3, voffB); PG8_STAGE(PG8_SB(1, 1), b3 + hstepB, voffB); PG8_STAGE(PG8_SA(1, 0), a3, voffA);
;             PG8_WAIT_V(8); PG8_WAIT_L(0); PG8_BAR; PG8_MMA(1, 0, At, B0); PG8_MMA(1, 1, At, B1); PG8_BAR; PG8_SCHED;
;         }
	ds_read_b128 v[182:185], v168 offset:49152
	ds_read_b128 v[186:189], v168 offset:50176
	ds_read_b128 v[190:193], v168 offset:51200
	ds_read_b128 v[194:197], v168 offset:52224
	ds_read_b128 v[198:201], v168 offset:53248
	ds_read_b128 v[202:205], v168 offset:54272
	ds_read_b128 v[206:209], v168 offset:55296
	ds_read_b128 v[210:213], v168 offset:56320
	s_mov_b32 m0, s96
	v_lshl_add_u64 v[162:163], v[162:163], 0, s[18:19]
	global_load_lds_dwordx4 v[162:163], off
	v_lshl_add_u64 v[162:163], v[214:215], 0, s[18:19]
	s_mov_b32 m0, s39
	s_nop 0
	global_load_lds_dwordx4 v[162:163], off
	v_lshl_add_u64 v[162:163], s[54:55], 0, v[134:135]
	s_mov_b32 m0, s95
	s_nop 0
	global_load_lds_dwordx4 v[162:163], off
	v_lshl_add_u64 v[162:163], s[54:55], 0, v[130:131]
	s_mov_b32 m0, s38
	s_nop 0
	global_load_lds_dwordx4 v[162:163], off
	v_lshl_add_u64 v[162:163], v[216:217], 0, s[18:19]
	s_mov_b32 m0, s84
	s_nop 0
	global_load_lds_dwordx4 v[162:163], off
	v_lshl_add_u64 v[162:163], v[218:219], 0, s[18:19]
	s_mov_b32 m0, s85
	s_nop 0
	global_load_lds_dwordx4 v[162:163], off
	s_waitcnt vmcnt(8)
	s_waitcnt lgkmcnt(0)
	s_barrier
	s_setprio 0
	v_mfma_f32_16x16x32_bf16 v[62:65], v[142:145], v[182:185], v[62:65]
	v_mfma_f32_16x16x32_bf16 v[58:61], v[150:153], v[182:185], v[58:61]
	v_mfma_f32_16x16x32_bf16 v[46:49], v[142:145], v[190:193], v[46:49]
	v_mfma_f32_16x16x32_bf16 v[42:45], v[150:153], v[190:193], v[42:45]
	v_mfma_f32_16x16x32_bf16 v[30:33], v[142:145], v[198:201], v[30:33]
	v_mfma_f32_16x16x32_bf16 v[26:29], v[150:153], v[198:201], v[26:29]
	v_mfma_f32_16x16x32_bf16 v[14:17], v[142:145], v[206:209], v[14:17]
	v_mfma_f32_16x16x32_bf16 v[10:13], v[150:153], v[206:209], v[10:13]
	v_mfma_f32_16x16x32_bf16 v[62:65], v[146:149], v[186:189], v[62:65]
	v_mfma_f32_16x16x32_bf16 v[58:61], v[154:157], v[186:189], v[58:61]
	v_mfma_f32_16x16x32_bf16 v[46:49], v[146:149], v[194:197], v[46:49]
	v_mfma_f32_16x16x32_bf16 v[42:45], v[154:157], v[194:197], v[42:45]
	v_mfma_f32_16x16x32_bf16 v[30:33], v[146:149], v[202:205], v[30:33]
	v_mfma_f32_16x16x32_bf16 v[26:29], v[154:157], v[202:205], v[26:29]
	v_mfma_f32_16x16x32_bf16 v[14:17], v[146:149], v[210:213], v[14:17]
	v_mfma_f32_16x16x32_bf16 v[10:13], v[154:157], v[210:213], v[10:13]
	s_setprio 2
	s_setprio 0
	v_mfma_f32_16x16x32_bf16 v[54:57], v[158:161], v[182:185], v[54:57]
	v_mfma_f32_16x16x32_bf16 v[50:53], v[174:177], v[182:185], v[50:53]
	v_mfma_f32_16x16x32_bf16 v[38:41], v[158:161], v[190:193], v[38:41]
	v_mfma_f32_16x16x32_bf16 v[34:37], v[174:177], v[190:193], v[34:37]
	v_mfma_f32_16x16x32_bf16 v[22:25], v[158:161], v[198:201], v[22:25]
	v_mfma_f32_16x16x32_bf16 v[18:21], v[174:177], v[198:201], v[18:21]
	v_mfma_f32_16x16x32_bf16 v[6:9], v[158:161], v[206:209], v[6:9]
	v_mfma_f32_16x16x32_bf16 v[2:5], v[174:177], v[206:209], v[2:5]
	v_mfma_f32_16x16x32_bf16 v[54:57], v[170:173], v[186:189], v[54:57]
	v_mfma_f32_16x16x32_bf16 v[50:53], v[178:181], v[186:189], v[50:53]
	v_mfma_f32_16x16x32_bf16 v[38:41], v[170:173], v[194:197], v[38:41]
	v_mfma_f32_16x16x32_bf16 v[34:37], v[178:181], v[194:197], v[34:37]
	v_mfma_f32_16x16x32_bf16 v[22:25], v[170:173], v[202:205], v[22:25]
	v_mfma_f32_16x16x32_bf16 v[18:21], v[178:181], v[202:205], v[18:21]
	v_mfma_f32_16x16x32_bf16 v[6:9], v[170:173], v[210:213], v[6:9]
	v_mfma_f32_16x16x32_bf16 v[2:5], v[178:181], v[210:213], v[2:5]
	s_setprio 2
	s_barrier
	s_movk_i32 s38, 0x100
	s_andn2_b64 vcc, exec, s[4:5]
	s_mov_b64 s[54:55], -1
	s_mov_b64 s[4:5], 0
	s_cbranch_vccz .LBB0_594
	s_and_b64 vcc, exec, s[20:21]
	s_cbranch_vccz .LBB0_597
	s_barrier

; #define PG8_STAGE(bufoff, gbase, voff) do { _Pragma("unroll") for (int _i = 0; _i < 2; ++_i) \
;         __builtin_amdgcn_global_load_lds((const unsigned*)((const char*)(gbase) + (voff)[_i]), (LAS unsigned*)(lds + (bufoff) + ldsw + _i * 8192), 16, 0, 0); } while (0)
; #define PG8_LDA(dst, b, h) do { _Pragma("unroll") for (int m = 0; m < 4; ++m) _Pragma("unroll") for (int k = 0; k < 2; ++k) dst[m][k] = *(const LAS bf16x8*)(lds + PG8_SA(b, h) + aoff + m * 2048 + k * 1024); } while (0)
; #define PG8_LDB(dst, b, h) do { _Pragma("unroll") for (int n = 0; n < 2; ++n) _Pragma("unroll") for (int k = 0; k < 2; ++k) dst[n][k] = *(const LAS bf16x8*)(lds + PG8_SB(b, h) + boff + n * 2048 + k * 1024); } while (0)
; #define PG8_MMA(ai, bj, At, Bt) do { __builtin_amdgcn_s_setprio(1); _Pragma("unroll") for (int m = 0; m < 4; ++m) _Pragma("unroll") for (int n = 0; n < 2; ++n) _Pragma("unroll") for (int k = 0; k < 2; ++k) \
;         acc[ai][bj][m][n] = __builtin_amdgcn_mfma_f32_16x16x32_bf16(Bt[n][k], At[m][k], acc[ai][bj][m][n], 0, 0, 0); __builtin_amdgcn_s_setprio(0); } while (0)
; #define PG8_WAIT_V(n) asm volatile("s_waitcnt vmcnt(" #n ")" ::: "memory")
; #define PG8_WAIT_L(n) asm volatile("s_waitcnt lgkmcnt(" #n ")" ::: "memory")
; #define PG8_BAR __builtin_amdgcn_s_barrier()
; #define PG8_SCHED __builtin_amdgcn_sched_barrier(0)
; template <class Epi>
; __device__ __forceinline__ void gemm_phase(LAS unsigned char* lds, const Gemm g, int G, int c, const Epi& E) {
;     ...
;             PG8_LDB(B0, 0, 0); PG8_LDB(B1, 0, 1); PG8_SCHED; PG8_LDA(At, 0, 0); PG8_STAGE(PG8_SA(1, 1), a1 + hstepA, voffA);
;             PG8_WAIT_V(8); PG8_WAIT_L(0); PG8_BAR; PG8_MMA(0, 0, At, B0); PG8_MMA(0, 1, At, B1); PG8_BAR; PG8_SCHED;
;             PG8_LDA(At, 0, 1); PG8_STAGE(PG8_SB(0, 0), b2, voffB); PG8_STAGE(PG8_SB(0, 1), b2 + hstepB, voffB); PG8_STAGE(PG8_SA(0, 0), a2, voffA);
.LBB0_765:
	ds_read_b128 v[146:149], v152
	ds_read_b128 v[156:159], v152 offset:1024
	ds_read_b128 v[160:163], v152 offset:2048
	ds_read_b128 v[164:167], v152 offset:3072
	ds_read_b128 v[168:171], v153
	ds_read_b128 v[172:175], v153 offset:1024
	ds_read_b128 v[176:179], v153 offset:2048
	ds_read_b128 v[180:183], v153 offset:3072
	ds_read_b128 v[184:187], v154
	ds_read_b128 v[188:191], v154 offset:1024
	ds_read_b128 v[192:195], v154 offset:2048
	ds_read_b128 v[196:199], v154 offset:3072
	ds_read_b128 v[200:203], v154 offset:4096
	ds_read_b128 v[204:207], v154 offset:5120
	ds_read_b128 v[208:211], v154 offset:6144
	ds_read_b128 v[212:215], v154 offset:7168
	s_add_u32 s33, s44, 0xfff00080
	s_addc_u32 s46, s45, -1
	s_cmp_eq_u32 s83, 60
	s_cselect_b32 s53, s15, s46
	s_cselect_b32 s52, s78, s33
	s_cselect_b32 s47, s11, s82
	s_cselect_b32 s46, s13, s81
	v_lshl_add_u64 v[216:217], s[44:45], 0, v[138:139]
	s_add_i32 m0, s17, 0xc000
	s_nop 0
	global_load_lds_dwordx4 v[216:217], off
	v_lshl_add_u64 v[216:217], s[44:45], 0, v[140:141]
	s_add_i32 m0, s17, 0xe000
	s_nop 0
	global_load_lds_dwordx4 v[216:217], off
	s_waitcnt vmcnt(8)
	s_waitcnt lgkmcnt(0)
	s_barrier
	s_setprio 0
	v_mfma_f32_16x16x32_bf16 v[126:129], v[146:149], v[184:187], v[126:129]
	v_mfma_f32_16x16x32_bf16 v[122:125], v[160:163], v[184:187], v[122:125]
	v_mfma_f32_16x16x32_bf16 v[118:121], v[146:149], v[192:195], v[118:121]
	v_mfma_f32_16x16x32_bf16 v[110:113], v[160:163], v[192:195], v[110:113]
	v_mfma_f32_16x16x32_bf16 v[102:105], v[146:149], v[200:203], v[102:105]
	v_mfma_f32_16x16x32_bf16 v[94:97], v[160:163], v[200:203], v[94:97]
	v_mfma_f32_16x16x32_bf16 v[86:89], v[146:149], v[208:211], v[86:89]
	v_mfma_f32_16x16x32_bf16 v[78:81], v[160:163], v[208:211], v[78:81]
	v_mfma_f32_16x16x32_bf16 v[126:129], v[156:159], v[188:191], v[126:129]
	v_mfma_f32_16x16x32_bf16 v[122:125], v[164:167], v[188:191], v[122:125]
	v_mfma_f32_16x16x32_bf16 v[118:121], v[156:159], v[196:199], v[118:121]
	v_mfma_f32_16x16x32_bf16 v[110:113], v[164:167], v[196:199], v[110:113]
	v_mfma_f32_16x16x32_bf16 v[102:105], v[156:159], v[204:207], v[102:105]
	v_mfma_f32_16x16x32_bf16 v[94:97], v[164:167], v[204:207], v[94:97]
	v_mfma_f32_16x16x32_bf16 v[86:89], v[156:159], v[212:215], v[86:89]
	v_mfma_f32_16x16x32_bf16 v[78:81], v[164:167], v[212:215], v[78:81]
	s_setprio 2
	s_setprio 0
	v_mfma_f32_16x16x32_bf16 v[114:117], v[168:171], v[184:187], v[114:117]
	v_mfma_f32_16x16x32_bf16 v[106:109], v[176:179], v[184:187], v[106:109]
	v_mfma_f32_16x16x32_bf16 v[98:101], v[168:171], v[192:195], v[98:101]
	v_mfma_f32_16x16x32_bf16 v[90:93], v[176:179], v[192:195], v[90:93]
	v_mfma_f32_16x16x32_bf16 v[82:85], v[168:171], v[200:203], v[82:85]
	v_mfma_f32_16x16x32_bf16 v[74:77], v[176:179], v[200:203], v[74:77]
	v_mfma_f32_16x16x32_bf16 v[70:73], v[168:171], v[208:211], v[70:73]
	v_mfma_f32_16x16x32_bf16 v[66:69], v[176:179], v[208:211], v[66:69]
	v_mfma_f32_16x16x32_bf16 v[114:117], v[172:175], v[188:191], v[114:117]
	v_mfma_f32_16x16x32_bf16 v[106:109], v[180:183], v[188:191], v[106:109]
	v_mfma_f32_16x16x32_bf16 v[98:101], v[172:175], v[196:199], v[98:101]
	v_mfma_f32_16x16x32_bf16 v[90:93], v[180:183], v[196:199], v[90:93]
	v_mfma_f32_16x16x32_bf16 v[82:85], v[172:175], v[204:207], v[82:85]
	v_mfma_f32_16x16x32_bf16 v[74:77], v[180:183], v[204:207], v[74:77]
	v_mfma_f32_16x16x32_bf16 v[70:73], v[172:175], v[212:215], v[70:73]
	v_mfma_f32_16x16x32_bf16 v[66:69], v[180:183], v[212:215], v[66:69]
	s_setprio 2
	s_barrier
	ds_read_b128 v[184:187], v154 offset:16384
	ds_read_b128 v[188:191], v154 offset:17408
	ds_read_b128 v[192:195], v154 offset:18432
	ds_read_b128 v[196:199], v154 offset:19456
	ds_read_b128 v[200:203], v154 offset:20480
	ds_read_b128 v[204:207], v154 offset:21504
	ds_read_b128 v[208:211], v154 offset:22528
	ds_read_b128 v[212:215], v154 offset:23552
	s_add_i32 s33, s72, s61
	v_lshl_add_u64 v[216:217], s[46:47], 0, v[134:135]
	s_mov_b32 m0, s33
	s_nop 0
	global_load_lds_dwordx4 v[216:217], off
	s_add_i32 m0, s33, 0x2000
	s_add_u32 s62, s46, 0x100000
	v_lshl_add_u64 v[218:219], s[46:47], 0, v[130:131]
	s_addc_u32 s63, s47, 0
	s_add_i32 s33, s73, s61
	global_load_lds_dwordx4 v[218:219], off
	v_lshl_add_u64 v[220:221], s[62:63], 0, v[134:135]
	s_mov_b32 m0, s33
	v_lshl_add_u64 v[224:225], s[52:53], 0, v[132:133]
	global_load_lds_dwordx4 v[220:221], off
	v_lshl_add_u64 v[220:221], s[62:63], 0, v[130:131]
	s_add_i32 m0, s33, 0x2000
	s_nop 0
	global_load_lds_dwordx4 v[220:221], off
	v_lshl_add_u64 v[220:221], s[52:53], 0, v[136:137]
	s_mov_b32 m0, s17
	s_nop 0
	global_load_lds_dwordx4 v[220:221], off
	s_mov_b32 m0, s39
	s_nop 0
	global_load_lds_dwordx4 v[224:225], off
	s_waitcnt vmcnt(8)
	s_waitcnt lgkmcnt(0)
	s_barrier
; #define PG8_STAGE(bufoff, gbase, voff) do { _Pragma("unroll") for (int _i = 0; _i < 2; ++_i) \
;         __builtin_amdgcn_global_load_lds((const unsigned*)((const char*)(gbase) + (voff)[_i]), (LAS unsigned*)(lds + (bufoff) + ldsw + _i * 8192), 16, 0, 0); } while (0)
; #define PG8_LDA(dst, b, h) do { _Pragma("unroll") for (int m = 0; m < 4; ++m) _Pragma("unroll") for (int k = 0; k < 2; ++k) dst[m][k] = *(const LAS bf16x8*)(lds + PG8_SA(b, h) + aoff + m * 2048 + k * 1024); } while (0)
; #define PG8_LDB(dst, b, h) do { _Pragma("unroll") for (int n = 0; n < 2; ++n) _Pragma("unroll") for (int k = 0; k < 2; ++k) dst[n][k] = *(const LAS bf16x8*)(lds + PG8_SB(b, h) + boff + n * 2048 + k * 1024); } while (0)
; #define PG8_MMA(ai, bj, At, Bt) do { __builtin_amdgcn_s_setprio(1); _Pragma("unroll") for (int m = 0; m < 4; ++m) _Pragma("unroll") for (int n = 0; n < 2; ++n) _Pragma("unroll") for (int k = 0; k < 2; ++k) \
;         acc[ai][bj][m][n] = __builtin_amdgcn_mfma_f32_16x16x32_bf16(Bt[n][k], At[m][k], acc[ai][bj][m][n], 0, 0, 0); __builtin_amdgcn_s_setprio(0); } while (0)
; #define PG8_WAIT_V(n) asm volatile("s_waitcnt vmcnt(" #n ")" ::: "memory")
; #define PG8_WAIT_L(n) asm volatile("s_waitcnt lgkmcnt(" #n ")" ::: "memory")
; #define PG8_BAR __builtin_amdgcn_s_barrier()
; #define PG8_SCHED __builtin_amdgcn_sched_barrier(0)
; template <class Epi>
; __device__ __forceinline__ void gemm_phase(LAS unsigned char* lds, const Gemm g, int G, int c, const Epi& E) {
;     ...
;             PG8_WAIT_V(8); PG8_WAIT_L(0); PG8_BAR; PG8_MMA(1, 0, At, B0); PG8_MMA(1, 1, At, B1); PG8_BAR; PG8_SCHED;
;             PG8_LDB(B0, 1, 0); PG8_LDB(B1, 1, 1); PG8_SCHED; PG8_LDA(At, 1, 0); PG8_STAGE(PG8_SA(0, 1), a2 + hstepA, voffA);
;             PG8_WAIT_V(8); PG8_WAIT_L(0); PG8_BAR; PG8_MMA(0, 0, At, B0); PG8_MMA(0, 1, At, B1); PG8_BAR; PG8_SCHED;
	s_setprio 0
	v_mfma_f32_16x16x32_bf16 v[62:65], v[146:149], v[184:187], v[62:65]
	v_mfma_f32_16x16x32_bf16 v[58:61], v[160:163], v[184:187], v[58:61]
	v_mfma_f32_16x16x32_bf16 v[54:57], v[146:149], v[192:195], v[54:57]
	v_mfma_f32_16x16x32_bf16 v[46:49], v[160:163], v[192:195], v[46:49]
	v_mfma_f32_16x16x32_bf16 v[38:41], v[146:149], v[200:203], v[38:41]
	v_mfma_f32_16x16x32_bf16 v[30:33], v[160:163], v[200:203], v[30:33]
	v_mfma_f32_16x16x32_bf16 v[22:25], v[146:149], v[208:211], v[22:25]
	v_mfma_f32_16x16x32_bf16 v[14:17], v[160:163], v[208:211], v[14:17]
	v_mfma_f32_16x16x32_bf16 v[62:65], v[156:159], v[188:191], v[62:65]
	v_mfma_f32_16x16x32_bf16 v[58:61], v[164:167], v[188:191], v[58:61]
	v_mfma_f32_16x16x32_bf16 v[54:57], v[156:159], v[196:199], v[54:57]
	v_mfma_f32_16x16x32_bf16 v[46:49], v[164:167], v[196:199], v[46:49]
	v_mfma_f32_16x16x32_bf16 v[38:41], v[156:159], v[204:207], v[38:41]
	v_mfma_f32_16x16x32_bf16 v[30:33], v[164:167], v[204:207], v[30:33]
	v_mfma_f32_16x16x32_bf16 v[22:25], v[156:159], v[212:215], v[22:25]
	v_mfma_f32_16x16x32_bf16 v[14:17], v[164:167], v[212:215], v[14:17]
	s_setprio 2
	s_setprio 0
	v_mfma_f32_16x16x32_bf16 v[50:53], v[168:171], v[184:187], v[50:53]
	v_mfma_f32_16x16x32_bf16 v[42:45], v[176:179], v[184:187], v[42:45]
	v_mfma_f32_16x16x32_bf16 v[34:37], v[168:171], v[192:195], v[34:37]
	v_mfma_f32_16x16x32_bf16 v[26:29], v[176:179], v[192:195], v[26:29]
	v_mfma_f32_16x16x32_bf16 v[18:21], v[168:171], v[200:203], v[18:21]
	v_mfma_f32_16x16x32_bf16 v[10:13], v[176:179], v[200:203], v[10:13]
	v_mfma_f32_16x16x32_bf16 v[6:9], v[168:171], v[208:211], v[6:9]
	v_mfma_f32_16x16x32_bf16 v[2:5], v[176:179], v[208:211], v[2:5]
	v_mfma_f32_16x16x32_bf16 v[50:53], v[172:175], v[188:191], v[50:53]
	v_mfma_f32_16x16x32_bf16 v[42:45], v[180:183], v[188:191], v[42:45]
	v_mfma_f32_16x16x32_bf16 v[34:37], v[172:175], v[196:199], v[34:37]
	v_mfma_f32_16x16x32_bf16 v[26:29], v[180:183], v[196:199], v[26:29]
	v_mfma_f32_16x16x32_bf16 v[18:21], v[172:175], v[204:207], v[18:21]
	v_mfma_f32_16x16x32_bf16 v[10:13], v[180:183], v[204:207], v[10:13]
	v_mfma_f32_16x16x32_bf16 v[6:9], v[172:175], v[212:215], v[6:9]
	v_mfma_f32_16x16x32_bf16 v[2:5], v[180:183], v[212:215], v[2:5]
	s_setprio 2
	s_barrier
	s_add_i32 s33, 0, 0x18000
	v_add_u32_e32 v155, s33, v151
	s_add_i32 s62, 0, 0x1c000
	ds_read_b128 v[146:149], v155
	ds_read_b128 v[156:159], v155 offset:1024
	ds_read_b128 v[160:163], v155 offset:2048
	ds_read_b128 v[164:167], v155 offset:3072
	v_add_u32_e32 v155, s62, v151
	ds_read_b128 v[168:171], v155
	ds_read_b128 v[172:175], v155 offset:1024
	ds_read_b128 v[176:179], v155 offset:2048
	ds_read_b128 v[180:183], v155 offset:3072
	ds_read_b128 v[184:187], v154 offset:32768
	ds_read_b128 v[188:191], v154 offset:33792
	ds_read_b128 v[192:195], v154 offset:34816
	ds_read_b128 v[196:199], v154 offset:35840
	ds_read_b128 v[200:203], v154 offset:36864
	ds_read_b128 v[204:207], v154 offset:37888
	ds_read_b128 v[208:211], v154 offset:38912
	ds_read_b128 v[212:215], v154 offset:39936
	s_add_u32 s52, s52, 0x100000
	s_addc_u32 s53, s53, 0
	s_mov_b32 m0, s43
	v_lshl_add_u64 v[226:227], s[52:53], 0, v[136:137]
	global_load_lds_dwordx4 v[226:227], off
	v_lshl_add_u64 v[226:227], s[52:53], 0, v[132:133]
	s_mov_b32 m0, s66
	s_nop 0
	global_load_lds_dwordx4 v[226:227], off
	s_waitcnt vmcnt(8)
	s_waitcnt lgkmcnt(0)
	s_barrier
	s_setprio 0
	v_mfma_f32_16x16x32_bf16 v[126:129], v[146:149], v[184:187], v[126:129]
	v_mfma_f32_16x16x32_bf16 v[122:125], v[160:163], v[184:187], v[122:125]
	v_mfma_f32_16x16x32_bf16 v[118:121], v[146:149], v[192:195], v[118:121]
	v_mfma_f32_16x16x32_bf16 v[110:113], v[160:163], v[192:195], v[110:113]
	v_mfma_f32_16x16x32_bf16 v[102:105], v[146:149], v[200:203], v[102:105]
	v_mfma_f32_16x16x32_bf16 v[94:97], v[160:163], v[200:203], v[94:97]
	v_mfma_f32_16x16x32_bf16 v[86:89], v[146:149], v[208:211], v[86:89]
	v_mfma_f32_16x16x32_bf16 v[78:81], v[160:163], v[208:211], v[78:81]
	v_mfma_f32_16x16x32_bf16 v[126:129], v[156:159], v[188:191], v[126:129]
	v_mfma_f32_16x16x32_bf16 v[122:125], v[164:167], v[188:191], v[122:125]
	v_mfma_f32_16x16x32_bf16 v[118:121], v[156:159], v[196:199], v[118:121]
	v_mfma_f32_16x16x32_bf16 v[110:113], v[164:167], v[196:199], v[110:113]
	v_mfma_f32_16x16x32_bf16 v[102:105], v[156:159], v[204:207], v[102:105]
	v_mfma_f32_16x16x32_bf16 v[94:97], v[164:167], v[204:207], v[94:97]
	v_mfma_f32_16x16x32_bf16 v[86:89], v[156:159], v[212:215], v[86:89]
	v_mfma_f32_16x16x32_bf16 v[78:81], v[164:167], v[212:215], v[78:81]
	s_setprio 2
	s_setprio 0
	v_mfma_f32_16x16x32_bf16 v[114:117], v[168:171], v[184:187], v[114:117]
	v_mfma_f32_16x16x32_bf16 v[106:109], v[176:179], v[184:187], v[106:109]
	v_mfma_f32_16x16x32_bf16 v[98:101], v[168:171], v[192:195], v[98:101]
	v_mfma_f32_16x16x32_bf16 v[90:93], v[176:179], v[192:195], v[90:93]
	v_mfma_f32_16x16x32_bf16 v[82:85], v[168:171], v[200:203], v[82:85]
	v_mfma_f32_16x16x32_bf16 v[74:77], v[176:179], v[200:203], v[74:77]
	v_mfma_f32_16x16x32_bf16 v[70:73], v[168:171], v[208:211], v[70:73]
	v_mfma_f32_16x16x32_bf16 v[66:69], v[176:179], v[208:211], v[66:69]
	v_mfma_f32_16x16x32_bf16 v[114:117], v[172:175], v[188:191], v[114:117]
	v_mfma_f32_16x16x32_bf16 v[106:109], v[180:183], v[188:191], v[106:109]
	v_mfma_f32_16x16x32_bf16 v[98:101], v[172:175], v[196:199], v[98:101]
	v_mfma_f32_16x16x32_bf16 v[90:93], v[180:183], v[196:199], v[90:93]
	v_mfma_f32_16x16x32_bf16 v[82:85], v[172:175], v[204:207], v[82:85]
	v_mfma_f32_16x16x32_bf16 v[74:77], v[180:183], v[204:207], v[74:77]
	v_mfma_f32_16x16x32_bf16 v[70:73], v[172:175], v[212:215], v[70:73]
	v_mfma_f32_16x16x32_bf16 v[66:69], v[180:183], v[212:215], v[66:69]
	s_setprio 2
	s_barrier
; #define PG8_STAGE(bufoff, gbase, voff) do { _Pragma("unroll") for (int _i = 0; _i < 2; ++_i) \
;         __builtin_amdgcn_global_load_lds((const unsigned*)((const char*)(gbase) + (voff)[_i]), (LAS unsigned*)(lds + (bufoff) + ldsw + _i * 8192), 16, 0, 0); } while (0)
; #define PG8_LDA(dst, b, h) do { _Pragma("unroll") for (int m = 0; m < 4; ++m) _Pragma("unroll") for (int k = 0; k < 2; ++k) dst[m][k] = *(const LAS bf16x8*)(lds + PG8_SA(b, h) + aoff + m * 2048 + k * 1024); } while (0)
; #define PG8_MMA(ai, bj, At, Bt) do { __builtin_amdgcn_s_setprio(1); _Pragma("unroll") for (int m = 0; m < 4; ++m) _Pragma("unroll") for (int n = 0; n < 2; ++n) _Pragma("unroll") for (int k = 0; k < 2; ++k) \
;         acc[ai][bj][m][n] = __builtin_amdgcn_mfma_f32_16x16x32_bf16(Bt[n][k], At[m][k], acc[ai][bj][m][n], 0, 0, 0); __builtin_amdgcn_s_setprio(0); } while (0)
; #define PG8_WAIT_V(n) asm volatile("s_waitcnt vmcnt(" #n ")" ::: "memory")
; #define PG8_WAIT_L(n) asm volatile("s_waitcnt lgkmcnt(" #n ")" ::: "memory")
; #define PG8_BAR __builtin_amdgcn_s_barrier()
; #define PG8_SCHED __builtin_amdgcn_sched_barrier(0)
; template <class Epi>
; __device__ __forceinline__ void gemm_phase(LAS unsigned char* lds, const Gemm g, int G, int c, const Epi& E) {
;     ...
;             PG8_LDA(At, 1, 1); PG8_STAGE(PG8_SB(1, 0), b3, voffB); PG8_STAGE(PG8_SB(1, 1), b3 + hstepB, voffB); PG8_STAGE(PG8_SA(1, 0), a3, voffA);
;             PG8_WAIT_V(8); PG8_WAIT_L(0); PG8_BAR; PG8_MMA(1, 0, At, B0); PG8_MMA(1, 1, At, B1); PG8_BAR; PG8_SCHED;
;         }
	ds_read_b128 v[184:187], v154 offset:49152
	ds_read_b128 v[188:191], v154 offset:50176
	ds_read_b128 v[192:195], v154 offset:51200
	ds_read_b128 v[196:199], v154 offset:52224
	ds_read_b128 v[200:203], v154 offset:53248
	ds_read_b128 v[204:207], v154 offset:54272
	ds_read_b128 v[208:211], v154 offset:55296
	ds_read_b128 v[212:215], v154 offset:56320
	s_add_i32 s33, s33, s61
	v_lshl_add_u64 v[216:217], v[216:217], 0, s[6:7]
	s_mov_b32 m0, s33
	s_nop 0
	global_load_lds_dwordx4 v[216:217], off
	s_add_i32 m0, s33, 0x2000
	s_add_u32 s46, s46, 0x100080
	v_lshl_add_u64 v[216:217], v[218:219], 0, s[6:7]
	s_addc_u32 s47, s47, 0
	s_add_i32 s33, s62, s61
	global_load_lds_dwordx4 v[216:217], off
	v_lshl_add_u64 v[216:217], s[46:47], 0, v[134:135]
	s_mov_b32 m0, s33
	s_nop 0
	global_load_lds_dwordx4 v[216:217], off
	v_lshl_add_u64 v[216:217], s[46:47], 0, v[130:131]
	s_add_i32 m0, s33, 0x2000
	s_nop 0
	global_load_lds_dwordx4 v[216:217], off
	v_lshl_add_u64 v[216:217], v[220:221], 0, s[6:7]
	s_mov_b32 m0, s70
	s_nop 0
	global_load_lds_dwordx4 v[216:217], off
	v_lshl_add_u64 v[216:217], v[224:225], 0, s[6:7]
	s_mov_b32 m0, s71
	s_nop 0
	global_load_lds_dwordx4 v[216:217], off
	s_waitcnt vmcnt(8)
	s_waitcnt lgkmcnt(0)
	s_barrier
	s_setprio 0
	v_mfma_f32_16x16x32_bf16 v[62:65], v[146:149], v[184:187], v[62:65]
	v_mfma_f32_16x16x32_bf16 v[58:61], v[160:163], v[184:187], v[58:61]
	v_mfma_f32_16x16x32_bf16 v[54:57], v[146:149], v[192:195], v[54:57]
	v_mfma_f32_16x16x32_bf16 v[46:49], v[160:163], v[192:195], v[46:49]
	v_mfma_f32_16x16x32_bf16 v[38:41], v[146:149], v[200:203], v[38:41]
	v_mfma_f32_16x16x32_bf16 v[30:33], v[160:163], v[200:203], v[30:33]
	v_mfma_f32_16x16x32_bf16 v[22:25], v[146:149], v[208:211], v[22:25]
	v_mfma_f32_16x16x32_bf16 v[14:17], v[160:163], v[208:211], v[14:17]
	v_mfma_f32_16x16x32_bf16 v[62:65], v[156:159], v[188:191], v[62:65]
	v_mfma_f32_16x16x32_bf16 v[58:61], v[164:167], v[188:191], v[58:61]
	v_mfma_f32_16x16x32_bf16 v[54:57], v[156:159], v[196:199], v[54:57]
	v_mfma_f32_16x16x32_bf16 v[46:49], v[164:167], v[196:199], v[46:49]
	v_mfma_f32_16x16x32_bf16 v[38:41], v[156:159], v[204:207], v[38:41]
	v_mfma_f32_16x16x32_bf16 v[30:33], v[164:167], v[204:207], v[30:33]
	v_mfma_f32_16x16x32_bf16 v[22:25], v[156:159], v[212:215], v[22:25]
	v_mfma_f32_16x16x32_bf16 v[14:17], v[164:167], v[212:215], v[14:17]
	s_setprio 2
	s_setprio 0
	v_mfma_f32_16x16x32_bf16 v[50:53], v[168:171], v[184:187], v[50:53]
	v_mfma_f32_16x16x32_bf16 v[42:45], v[176:179], v[184:187], v[42:45]
	v_mfma_f32_16x16x32_bf16 v[34:37], v[168:171], v[192:195], v[34:37]
	v_mfma_f32_16x16x32_bf16 v[26:29], v[176:179], v[192:195], v[26:29]
	v_mfma_f32_16x16x32_bf16 v[18:21], v[168:171], v[200:203], v[18:21]
	v_mfma_f32_16x16x32_bf16 v[10:13], v[176:179], v[200:203], v[10:13]
	v_mfma_f32_16x16x32_bf16 v[6:9], v[168:171], v[208:211], v[6:9]
	v_mfma_f32_16x16x32_bf16 v[2:5], v[176:179], v[208:211], v[2:5]
	v_mfma_f32_16x16x32_bf16 v[50:53], v[172:175], v[188:191], v[50:53]
	v_mfma_f32_16x16x32_bf16 v[42:45], v[180:183], v[188:191], v[42:45]
	v_mfma_f32_16x16x32_bf16 v[34:37], v[172:175], v[196:199], v[34:37]
	v_mfma_f32_16x16x32_bf16 v[26:29], v[180:183], v[196:199], v[26:29]
	v_mfma_f32_16x16x32_bf16 v[18:21], v[172:175], v[204:207], v[18:21]
	v_mfma_f32_16x16x32_bf16 v[10:13], v[180:183], v[204:207], v[10:13]
	v_mfma_f32_16x16x32_bf16 v[6:9], v[172:175], v[212:215], v[6:9]
	v_mfma_f32_16x16x32_bf16 v[2:5], v[180:183], v[212:215], v[2:5]
	s_setprio 2
	s_barrier
	s_add_i32 s83, s83, 2
	s_add_u32 s44, s44, 0x100
	s_addc_u32 s45, s45, 0
	s_add_u32 s81, s81, 0x100
	s_addc_u32 s82, s82, 0
	s_cmp_gt_u32 s83, 61
	s_cbranch_scc0 .LBB0_765
	s_and_b64 vcc, exec, s[8:9]
	s_cbranch_vccz .LBB0_768
	s_barrier

; #define PG8_STAGE(bufoff, gbase, voff) do { _Pragma("unroll") for (int _i = 0; _i < 2; ++_i) \
;         __builtin_amdgcn_global_load_lds((const unsigned*)((const char*)(gbase) + (voff)[_i]), (LAS unsigned*)(lds + (bufoff) + ldsw + _i * 8192), 16, 0, 0); } while (0)
; #define PG8_LDA(dst, b, h) do { _Pragma("unroll") for (int m = 0; m < 4; ++m) _Pragma("unroll") for (int k = 0; k < 2; ++k) dst[m][k] = *(const LAS bf16x8*)(lds + PG8_SA(b, h) + aoff + m * 2048 + k * 1024); } while (0)
; #define PG8_LDB(dst, b, h) do { _Pragma("unroll") for (int n = 0; n < 2; ++n) _Pragma("unroll") for (int k = 0; k < 2; ++k) dst[n][k] = *(const LAS bf16x8*)(lds + PG8_SB(b, h) + boff + n * 2048 + k * 1024); } while (0)
; #define PG8_MMA(ai, bj, At, Bt) do { __builtin_amdgcn_s_setprio(1); _Pragma("unroll") for (int m = 0; m < 4; ++m) _Pragma("unroll") for (int n = 0; n < 2; ++n) _Pragma("unroll") for (int k = 0; k < 2; ++k) \
;         acc[ai][bj][m][n] = __builtin_amdgcn_mfma_f32_16x16x32_bf16(Bt[n][k], At[m][k], acc[ai][bj][m][n], 0, 0, 0); __builtin_amdgcn_s_setprio(0); } while (0)
; #define PG8_WAIT_V(n) asm volatile("s_waitcnt vmcnt(" #n ")" ::: "memory")
; #define PG8_WAIT_L(n) asm volatile("s_waitcnt lgkmcnt(" #n ")" ::: "memory")
; #define PG8_BAR __builtin_amdgcn_s_barrier()
; #define PG8_SCHED __builtin_amdgcn_sched_barrier(0)
; template <class Epi>
; __device__ __forceinline__ void gemm_phase(LAS unsigned char* lds, const Gemm g, int G, int c, const Epi& E) {
;     ...
;             const bool last = (t == nt - 2);
;             const char* a1 = cA + (size_t)(t + 1) * kstep;
;             const char* a2 = last ? nA : cA + (size_t)(t + 2) * kstep; const char* b2 = last ? nB : cB + (size_t)(t + 2) * kstep;
;             const char* a3 = a2 + kstep; const char* b3 = b2 + kstep;
;             PG8_LDB(B0, 0, 0); PG8_LDB(B1, 0, 1); PG8_SCHED; PG8_LDA(At, 0, 0); PG8_STAGE(PG8_SA(1, 1), a1 + hstepA, voffA);
;             PG8_WAIT_V(8); PG8_WAIT_L(0); PG8_BAR; PG8_MMA(0, 0, At, B0); PG8_MMA(0, 1, At, B1); PG8_BAR; PG8_SCHED;
;             PG8_LDA(At, 0, 1); PG8_STAGE(PG8_SB(0, 0), b2, voffB); PG8_STAGE(PG8_SB(0, 1), b2 + hstepB, voffB); PG8_STAGE(PG8_SA(0, 0), a2, voffA);
.LBB0_781:
	ds_read_b128 v[150:153], v146
	ds_read_b128 v[154:157], v146 offset:1024
	ds_read_b128 v[158:161], v146 offset:2048
	ds_read_b128 v[162:165], v146 offset:3072
	ds_read_b128 v[166:169], v147
	ds_read_b128 v[170:173], v147 offset:1024
	ds_read_b128 v[174:177], v147 offset:2048
	ds_read_b128 v[178:181], v147 offset:3072
	ds_read_b128 v[182:185], v148
	ds_read_b128 v[186:189], v148 offset:1024
	ds_read_b128 v[190:193], v148 offset:2048
	ds_read_b128 v[194:197], v148 offset:3072
	ds_read_b128 v[198:201], v148 offset:4096
	ds_read_b128 v[202:205], v148 offset:5120
	ds_read_b128 v[206:209], v148 offset:6144
	ds_read_b128 v[210:213], v148 offset:7168
	s_add_u32 s52, s46, 0x100
	s_addc_u32 s53, s47, 0
	s_add_u32 s33, s90, s46
	s_addc_u32 s55, s91, s47
	s_cmp_eq_u32 s92, 4
	s_cselect_b32 s56, 0, s52
	s_cselect_b32 s57, 0, s53
	s_cselect_b32 s54, s89, s33
	s_cselect_b32 s55, s25, s55
	s_add_u32 s56, s2, s56
	s_addc_u32 s57, s3, s57
	s_mov_b32 m0, s83
	v_lshl_add_u64 v[142:143], v[138:139], 0, s[46:47]
	global_load_lds_dwordx4 v[142:143], off
	v_lshl_add_u64 v[142:143], v[140:141], 0, s[46:47]
	s_mov_b32 m0, s84
	s_nop 0
	global_load_lds_dwordx4 v[142:143], off
	s_waitcnt vmcnt(8)
	s_waitcnt lgkmcnt(0)
	s_barrier
	s_setprio 0
	v_mfma_f32_16x16x32_bf16 v[126:129], v[150:153], v[182:185], v[126:129]
	v_mfma_f32_16x16x32_bf16 v[122:125], v[158:161], v[182:185], v[122:125]
	v_mfma_f32_16x16x32_bf16 v[118:121], v[150:153], v[190:193], v[118:121]
	v_mfma_f32_16x16x32_bf16 v[110:113], v[158:161], v[190:193], v[110:113]
	v_mfma_f32_16x16x32_bf16 v[102:105], v[150:153], v[198:201], v[102:105]
	v_mfma_f32_16x16x32_bf16 v[94:97], v[158:161], v[198:201], v[94:97]
	v_mfma_f32_16x16x32_bf16 v[86:89], v[150:153], v[206:209], v[86:89]
	v_mfma_f32_16x16x32_bf16 v[78:81], v[158:161], v[206:209], v[78:81]
	v_mfma_f32_16x16x32_bf16 v[126:129], v[154:157], v[186:189], v[126:129]
	v_mfma_f32_16x16x32_bf16 v[122:125], v[162:165], v[186:189], v[122:125]
	v_mfma_f32_16x16x32_bf16 v[118:121], v[154:157], v[194:197], v[118:121]
	v_mfma_f32_16x16x32_bf16 v[110:113], v[162:165], v[194:197], v[110:113]
	v_mfma_f32_16x16x32_bf16 v[102:105], v[154:157], v[202:205], v[102:105]
	v_mfma_f32_16x16x32_bf16 v[94:97], v[162:165], v[202:205], v[94:97]
	v_mfma_f32_16x16x32_bf16 v[86:89], v[154:157], v[210:213], v[86:89]
	v_mfma_f32_16x16x32_bf16 v[78:81], v[162:165], v[210:213], v[78:81]
	s_setprio 2
	s_setprio 0
	v_mfma_f32_16x16x32_bf16 v[114:117], v[166:169], v[182:185], v[114:117]
	v_mfma_f32_16x16x32_bf16 v[106:109], v[174:177], v[182:185], v[106:109]
	v_mfma_f32_16x16x32_bf16 v[98:101], v[166:169], v[190:193], v[98:101]
	v_mfma_f32_16x16x32_bf16 v[90:93], v[174:177], v[190:193], v[90:93]
	v_mfma_f32_16x16x32_bf16 v[82:85], v[166:169], v[198:201], v[82:85]
	v_mfma_f32_16x16x32_bf16 v[74:77], v[174:177], v[198:201], v[74:77]
	v_mfma_f32_16x16x32_bf16 v[70:73], v[166:169], v[206:209], v[70:73]
	v_mfma_f32_16x16x32_bf16 v[66:69], v[174:177], v[206:209], v[66:69]
	v_mfma_f32_16x16x32_bf16 v[114:117], v[170:173], v[186:189], v[114:117]
	v_mfma_f32_16x16x32_bf16 v[106:109], v[178:181], v[186:189], v[106:109]
	v_mfma_f32_16x16x32_bf16 v[98:101], v[170:173], v[194:197], v[98:101]
	v_mfma_f32_16x16x32_bf16 v[90:93], v[178:181], v[194:197], v[90:93]
	v_mfma_f32_16x16x32_bf16 v[82:85], v[170:173], v[202:205], v[82:85]
	v_mfma_f32_16x16x32_bf16 v[74:77], v[178:181], v[202:205], v[74:77]
	v_mfma_f32_16x16x32_bf16 v[70:73], v[170:173], v[210:213], v[70:73]
	v_mfma_f32_16x16x32_bf16 v[66:69], v[178:181], v[210:213], v[66:69]
	s_setprio 2
	s_barrier
	ds_read_b128 v[182:185], v148 offset:16384
	ds_read_b128 v[186:189], v148 offset:17408
	ds_read_b128 v[190:193], v148 offset:18432
	ds_read_b128 v[194:197], v148 offset:19456
	ds_read_b128 v[198:201], v148 offset:20480
	ds_read_b128 v[202:205], v148 offset:21504
	ds_read_b128 v[206:209], v148 offset:22528
	ds_read_b128 v[210:213], v148 offset:23552
	s_mov_b32 m0, s85
	v_lshl_add_u64 v[142:143], s[54:55], 0, v[134:135]
	s_add_u32 s46, s54, 0x20000
	global_load_lds_dwordx4 v[142:143], off
	v_lshl_add_u64 v[214:215], s[54:55], 0, v[130:131]
	s_mov_b32 m0, s86
	s_addc_u32 s47, s55, 0
	global_load_lds_dwordx4 v[214:215], off
	v_lshl_add_u64 v[216:217], s[46:47], 0, v[134:135]
	s_mov_b32 m0, s87
	v_lshl_add_u64 v[218:219], s[56:57], 0, v[132:133]
	global_load_lds_dwordx4 v[216:217], off
	v_lshl_add_u64 v[216:217], s[46:47], 0, v[130:131]
	s_mov_b32 m0, s88
	s_nop 0
	global_load_lds_dwordx4 v[216:217], off
	v_lshl_add_u64 v[216:217], s[56:57], 0, v[136:137]
	s_mov_b32 m0, s45
	s_nop 0
	global_load_lds_dwordx4 v[216:217], off
	s_mov_b32 m0, s61
	s_nop 0
	global_load_lds_dwordx4 v[218:219], off
	s_waitcnt vmcnt(8)
	s_waitcnt lgkmcnt(0)
	s_barrier
; #define PG8_STAGE(bufoff, gbase, voff) do { _Pragma("unroll") for (int _i = 0; _i < 2; ++_i) \
;         __builtin_amdgcn_global_load_lds((const unsigned*)((const char*)(gbase) + (voff)[_i]), (LAS unsigned*)(lds + (bufoff) + ldsw + _i * 8192), 16, 0, 0); } while (0)
; #define PG8_LDA(dst, b, h) do { _Pragma("unroll") for (int m = 0; m < 4; ++m) _Pragma("unroll") for (int k = 0; k < 2; ++k) dst[m][k] = *(const LAS bf16x8*)(lds + PG8_SA(b, h) + aoff + m * 2048 + k * 1024); } while (0)
; #define PG8_LDB(dst, b, h) do { _Pragma("unroll") for (int n = 0; n < 2; ++n) _Pragma("unroll") for (int k = 0; k < 2; ++k) dst[n][k] = *(const LAS bf16x8*)(lds + PG8_SB(b, h) + boff + n * 2048 + k * 1024); } while (0)
; #define PG8_MMA(ai, bj, At, Bt) do { __builtin_amdgcn_s_setprio(1); _Pragma("unroll") for (int m = 0; m < 4; ++m) _Pragma("unroll") for (int n = 0; n < 2; ++n) _Pragma("unroll") for (int k = 0; k < 2; ++k) \
;         acc[ai][bj][m][n] = __builtin_amdgcn_mfma_f32_16x16x32_bf16(Bt[n][k], At[m][k], acc[ai][bj][m][n], 0, 0, 0); __builtin_amdgcn_s_setprio(0); } while (0)
; #define PG8_WAIT_V(n) asm volatile("s_waitcnt vmcnt(" #n ")" ::: "memory")
; #define PG8_WAIT_L(n) asm volatile("s_waitcnt lgkmcnt(" #n ")" ::: "memory")
; #define PG8_BAR __builtin_amdgcn_s_barrier()
; #define PG8_SCHED __builtin_amdgcn_sched_barrier(0)
; template <class Epi>
; __device__ __forceinline__ void gemm_phase(LAS unsigned char* lds, const Gemm g, int G, int c, const Epi& E) {
;     ...
;             PG8_WAIT_V(8); PG8_WAIT_L(0); PG8_BAR; PG8_MMA(1, 0, At, B0); PG8_MMA(1, 1, At, B1); PG8_BAR; PG8_SCHED;
;             PG8_LDB(B0, 1, 0); PG8_LDB(B1, 1, 1); PG8_SCHED; PG8_LDA(At, 1, 0); PG8_STAGE(PG8_SA(0, 1), a2 + hstepA, voffA);
;             PG8_WAIT_V(8); PG8_WAIT_L(0); PG8_BAR; PG8_MMA(0, 0, At, B0); PG8_MMA(0, 1, At, B1); PG8_BAR; PG8_SCHED;
	s_setprio 0
	v_mfma_f32_16x16x32_bf16 v[62:65], v[150:153], v[182:185], v[62:65]
	v_mfma_f32_16x16x32_bf16 v[58:61], v[158:161], v[182:185], v[58:61]
	v_mfma_f32_16x16x32_bf16 v[54:57], v[150:153], v[190:193], v[54:57]
	v_mfma_f32_16x16x32_bf16 v[46:49], v[158:161], v[190:193], v[46:49]
	v_mfma_f32_16x16x32_bf16 v[38:41], v[150:153], v[198:201], v[38:41]
	v_mfma_f32_16x16x32_bf16 v[30:33], v[158:161], v[198:201], v[30:33]
	v_mfma_f32_16x16x32_bf16 v[22:25], v[150:153], v[206:209], v[22:25]
	v_mfma_f32_16x16x32_bf16 v[14:17], v[158:161], v[206:209], v[14:17]
	v_mfma_f32_16x16x32_bf16 v[62:65], v[154:157], v[186:189], v[62:65]
	v_mfma_f32_16x16x32_bf16 v[58:61], v[162:165], v[186:189], v[58:61]
	v_mfma_f32_16x16x32_bf16 v[54:57], v[154:157], v[194:197], v[54:57]
	v_mfma_f32_16x16x32_bf16 v[46:49], v[162:165], v[194:197], v[46:49]
	v_mfma_f32_16x16x32_bf16 v[38:41], v[154:157], v[202:205], v[38:41]
	v_mfma_f32_16x16x32_bf16 v[30:33], v[162:165], v[202:205], v[30:33]
	v_mfma_f32_16x16x32_bf16 v[22:25], v[154:157], v[210:213], v[22:25]
	v_mfma_f32_16x16x32_bf16 v[14:17], v[162:165], v[210:213], v[14:17]
	s_setprio 2
	s_setprio 0
	v_mfma_f32_16x16x32_bf16 v[50:53], v[166:169], v[182:185], v[50:53]
	v_mfma_f32_16x16x32_bf16 v[42:45], v[174:177], v[182:185], v[42:45]
	v_mfma_f32_16x16x32_bf16 v[34:37], v[166:169], v[190:193], v[34:37]
	v_mfma_f32_16x16x32_bf16 v[26:29], v[174:177], v[190:193], v[26:29]
	v_mfma_f32_16x16x32_bf16 v[18:21], v[166:169], v[198:201], v[18:21]
	v_mfma_f32_16x16x32_bf16 v[10:13], v[174:177], v[198:201], v[10:13]
	v_mfma_f32_16x16x32_bf16 v[6:9], v[166:169], v[206:209], v[6:9]
	v_mfma_f32_16x16x32_bf16 v[2:5], v[174:177], v[206:209], v[2:5]
	v_mfma_f32_16x16x32_bf16 v[50:53], v[170:173], v[186:189], v[50:53]
	v_mfma_f32_16x16x32_bf16 v[42:45], v[178:181], v[186:189], v[42:45]
	v_mfma_f32_16x16x32_bf16 v[34:37], v[170:173], v[194:197], v[34:37]
	v_mfma_f32_16x16x32_bf16 v[26:29], v[178:181], v[194:197], v[26:29]
	v_mfma_f32_16x16x32_bf16 v[18:21], v[170:173], v[202:205], v[18:21]
	v_mfma_f32_16x16x32_bf16 v[10:13], v[178:181], v[202:205], v[10:13]
	v_mfma_f32_16x16x32_bf16 v[6:9], v[170:173], v[210:213], v[6:9]
	v_mfma_f32_16x16x32_bf16 v[2:5], v[178:181], v[210:213], v[2:5]
	s_setprio 2
	s_barrier
	s_add_i32 s33, 0, 0x18000
	v_add_u32_e32 v149, s33, v145
	s_add_i32 s62, 0, 0x1c000
	ds_read_b128 v[150:153], v149
	ds_read_b128 v[154:157], v149 offset:1024
	ds_read_b128 v[158:161], v149 offset:2048
	ds_read_b128 v[162:165], v149 offset:3072
	v_add_u32_e32 v149, s62, v145
	ds_read_b128 v[166:169], v149
	ds_read_b128 v[170:173], v149 offset:1024
	ds_read_b128 v[174:177], v149 offset:2048
	ds_read_b128 v[178:181], v149 offset:3072
	ds_read_b128 v[182:185], v148 offset:32768
	ds_read_b128 v[186:189], v148 offset:33792
	ds_read_b128 v[190:193], v148 offset:34816
	ds_read_b128 v[194:197], v148 offset:35840
	ds_read_b128 v[198:201], v148 offset:36864
	ds_read_b128 v[202:205], v148 offset:37888
	ds_read_b128 v[206:209], v148 offset:38912
	ds_read_b128 v[210:213], v148 offset:39936
	s_add_u32 s46, s56, 0x20000
	s_addc_u32 s47, s57, 0
	s_mov_b32 m0, s66
	v_lshl_add_u64 v[220:221], s[46:47], 0, v[136:137]
	global_load_lds_dwordx4 v[220:221], off
	v_lshl_add_u64 v[220:221], s[46:47], 0, v[132:133]
	s_mov_b32 m0, s67
	s_nop 0
	global_load_lds_dwordx4 v[220:221], off
	s_waitcnt vmcnt(8)
	s_waitcnt lgkmcnt(0)
	s_barrier
	s_setprio 0
	v_mfma_f32_16x16x32_bf16 v[126:129], v[150:153], v[182:185], v[126:129]
	v_mfma_f32_16x16x32_bf16 v[122:125], v[158:161], v[182:185], v[122:125]
	v_mfma_f32_16x16x32_bf16 v[118:121], v[150:153], v[190:193], v[118:121]
	v_mfma_f32_16x16x32_bf16 v[110:113], v[158:161], v[190:193], v[110:113]
	v_mfma_f32_16x16x32_bf16 v[102:105], v[150:153], v[198:201], v[102:105]
	v_mfma_f32_16x16x32_bf16 v[94:97], v[158:161], v[198:201], v[94:97]
	v_mfma_f32_16x16x32_bf16 v[86:89], v[150:153], v[206:209], v[86:89]
	v_mfma_f32_16x16x32_bf16 v[78:81], v[158:161], v[206:209], v[78:81]
	v_mfma_f32_16x16x32_bf16 v[126:129], v[154:157], v[186:189], v[126:129]
	v_mfma_f32_16x16x32_bf16 v[122:125], v[162:165], v[186:189], v[122:125]
	v_mfma_f32_16x16x32_bf16 v[118:121], v[154:157], v[194:197], v[118:121]
	v_mfma_f32_16x16x32_bf16 v[110:113], v[162:165], v[194:197], v[110:113]
	v_mfma_f32_16x16x32_bf16 v[102:105], v[154:157], v[202:205], v[102:105]
	v_mfma_f32_16x16x32_bf16 v[94:97], v[162:165], v[202:205], v[94:97]
	v_mfma_f32_16x16x32_bf16 v[86:89], v[154:157], v[210:213], v[86:89]
	v_mfma_f32_16x16x32_bf16 v[78:81], v[162:165], v[210:213], v[78:81]
	s_setprio 2
	s_setprio 0
	v_mfma_f32_16x16x32_bf16 v[114:117], v[166:169], v[182:185], v[114:117]
	v_mfma_f32_16x16x32_bf16 v[106:109], v[174:177], v[182:185], v[106:109]
	v_mfma_f32_16x16x32_bf16 v[98:101], v[166:169], v[190:193], v[98:101]
	v_mfma_f32_16x16x32_bf16 v[90:93], v[174:177], v[190:193], v[90:93]
	v_mfma_f32_16x16x32_bf16 v[82:85], v[166:169], v[198:201], v[82:85]
	v_mfma_f32_16x16x32_bf16 v[74:77], v[174:177], v[198:201], v[74:77]
	v_mfma_f32_16x16x32_bf16 v[70:73], v[166:169], v[206:209], v[70:73]
	v_mfma_f32_16x16x32_bf16 v[66:69], v[174:177], v[206:209], v[66:69]
	v_mfma_f32_16x16x32_bf16 v[114:117], v[170:173], v[186:189], v[114:117]
	v_mfma_f32_16x16x32_bf16 v[106:109], v[178:181], v[186:189], v[106:109]
	v_mfma_f32_16x16x32_bf16 v[98:101], v[170:173], v[194:197], v[98:101]
	v_mfma_f32_16x16x32_bf16 v[90:93], v[178:181], v[194:197], v[90:93]
	v_mfma_f32_16x16x32_bf16 v[82:85], v[170:173], v[202:205], v[82:85]
	v_mfma_f32_16x16x32_bf16 v[74:77], v[178:181], v[202:205], v[74:77]
	v_mfma_f32_16x16x32_bf16 v[70:73], v[170:173], v[210:213], v[70:73]
	v_mfma_f32_16x16x32_bf16 v[66:69], v[178:181], v[210:213], v[66:69]
	s_setprio 2
	s_barrier
; #define PG8_STAGE(bufoff, gbase, voff) do { _Pragma("unroll") for (int _i = 0; _i < 2; ++_i) \
;         __builtin_amdgcn_global_load_lds((const unsigned*)((const char*)(gbase) + (voff)[_i]), (LAS unsigned*)(lds + (bufoff) + ldsw + _i * 8192), 16, 0, 0); } while (0)
; #define PG8_LDA(dst, b, h) do { _Pragma("unroll") for (int m = 0; m < 4; ++m) _Pragma("unroll") for (int k = 0; k < 2; ++k) dst[m][k] = *(const LAS bf16x8*)(lds + PG8_SA(b, h) + aoff + m * 2048 + k * 1024); } while (0)
; #define PG8_MMA(ai, bj, At, Bt) do { __builtin_amdgcn_s_setprio(1); _Pragma("unroll") for (int m = 0; m < 4; ++m) _Pragma("unroll") for (int n = 0; n < 2; ++n) _Pragma("unroll") for (int k = 0; k < 2; ++k) \
;         acc[ai][bj][m][n] = __builtin_amdgcn_mfma_f32_16x16x32_bf16(Bt[n][k], At[m][k], acc[ai][bj][m][n], 0, 0, 0); __builtin_amdgcn_s_setprio(0); } while (0)
; #define PG8_WAIT_V(n) asm volatile("s_waitcnt vmcnt(" #n ")" ::: "memory")
; #define PG8_WAIT_L(n) asm volatile("s_waitcnt lgkmcnt(" #n ")" ::: "memory")
; #define PG8_BAR __builtin_amdgcn_s_barrier()
; #define PG8_SCHED __builtin_amdgcn_sched_barrier(0)
; template <class Epi>
; __device__ __forceinline__ void gemm_phase(LAS unsigned char* lds, const Gemm g, int G, int c, const Epi& E) {
;     ...
;             PG8_LDA(At, 1, 1); PG8_STAGE(PG8_SB(1, 0), b3, voffB); PG8_STAGE(PG8_SB(1, 1), b3 + hstepB, voffB); PG8_STAGE(PG8_SA(1, 0), a3, voffA);
;             PG8_WAIT_V(8); PG8_WAIT_L(0); PG8_BAR; PG8_MMA(1, 0, At, B0); PG8_MMA(1, 1, At, B1); PG8_BAR; PG8_SCHED;
;         }
	ds_read_b128 v[182:185], v148 offset:49152
	ds_read_b128 v[186:189], v148 offset:50176
	ds_read_b128 v[190:193], v148 offset:51200
	ds_read_b128 v[194:197], v148 offset:52224
	ds_read_b128 v[198:201], v148 offset:53248
	ds_read_b128 v[202:205], v148 offset:54272
	ds_read_b128 v[206:209], v148 offset:55296
	ds_read_b128 v[210:213], v148 offset:56320
	s_add_i32 s33, s33, s58
	v_lshl_add_u64 v[142:143], v[142:143], 0, s[6:7]
	s_mov_b32 m0, s33
	s_nop 0
	global_load_lds_dwordx4 v[142:143], off
	s_add_i32 m0, s33, 0x2000
	s_add_u32 s46, s54, 0x20080
	v_lshl_add_u64 v[142:143], v[214:215], 0, s[6:7]
	s_addc_u32 s47, s55, 0
	s_add_i32 s33, s62, s58
	global_load_lds_dwordx4 v[142:143], off
	v_lshl_add_u64 v[142:143], s[46:47], 0, v[134:135]
	s_mov_b32 m0, s33
	s_nop 0
	global_load_lds_dwordx4 v[142:143], off
	v_lshl_add_u64 v[142:143], s[46:47], 0, v[130:131]
	s_add_i32 m0, s33, 0x2000
	s_nop 0
	global_load_lds_dwordx4 v[142:143], off
	v_lshl_add_u64 v[142:143], v[216:217], 0, s[6:7]
	s_mov_b32 m0, s71
	s_nop 0
	global_load_lds_dwordx4 v[142:143], off
	v_lshl_add_u64 v[142:143], v[218:219], 0, s[6:7]
	s_mov_b32 m0, s72
	s_nop 0
	global_load_lds_dwordx4 v[142:143], off
	s_waitcnt vmcnt(8)
	s_waitcnt lgkmcnt(0)
	s_barrier
	s_setprio 0
	v_mfma_f32_16x16x32_bf16 v[62:65], v[150:153], v[182:185], v[62:65]
	v_mfma_f32_16x16x32_bf16 v[58:61], v[158:161], v[182:185], v[58:61]
	v_mfma_f32_16x16x32_bf16 v[54:57], v[150:153], v[190:193], v[54:57]
	v_mfma_f32_16x16x32_bf16 v[46:49], v[158:161], v[190:193], v[46:49]
	v_mfma_f32_16x16x32_bf16 v[38:41], v[150:153], v[198:201], v[38:41]
	v_mfma_f32_16x16x32_bf16 v[30:33], v[158:161], v[198:201], v[30:33]
	v_mfma_f32_16x16x32_bf16 v[22:25], v[150:153], v[206:209], v[22:25]
	v_mfma_f32_16x16x32_bf16 v[14:17], v[158:161], v[206:209], v[14:17]
	v_mfma_f32_16x16x32_bf16 v[62:65], v[154:157], v[186:189], v[62:65]
	v_mfma_f32_16x16x32_bf16 v[58:61], v[162:165], v[186:189], v[58:61]
	v_mfma_f32_16x16x32_bf16 v[54:57], v[154:157], v[194:197], v[54:57]
	v_mfma_f32_16x16x32_bf16 v[46:49], v[162:165], v[194:197], v[46:49]
	v_mfma_f32_16x16x32_bf16 v[38:41], v[154:157], v[202:205], v[38:41]
	v_mfma_f32_16x16x32_bf16 v[30:33], v[162:165], v[202:205], v[30:33]
	v_mfma_f32_16x16x32_bf16 v[22:25], v[154:157], v[210:213], v[22:25]
	v_mfma_f32_16x16x32_bf16 v[14:17], v[162:165], v[210:213], v[14:17]
	s_setprio 2
	s_setprio 0
	v_mfma_f32_16x16x32_bf16 v[50:53], v[166:169], v[182:185], v[50:53]
	v_mfma_f32_16x16x32_bf16 v[42:45], v[174:177], v[182:185], v[42:45]
	v_mfma_f32_16x16x32_bf16 v[34:37], v[166:169], v[190:193], v[34:37]
	v_mfma_f32_16x16x32_bf16 v[26:29], v[174:177], v[190:193], v[26:29]
	v_mfma_f32_16x16x32_bf16 v[18:21], v[166:169], v[198:201], v[18:21]
	v_mfma_f32_16x16x32_bf16 v[10:13], v[174:177], v[198:201], v[10:13]
	v_mfma_f32_16x16x32_bf16 v[6:9], v[166:169], v[206:209], v[6:9]
	v_mfma_f32_16x16x32_bf16 v[2:5], v[174:177], v[206:209], v[2:5]
	v_mfma_f32_16x16x32_bf16 v[50:53], v[170:173], v[186:189], v[50:53]
	v_mfma_f32_16x16x32_bf16 v[42:45], v[178:181], v[186:189], v[42:45]
	v_mfma_f32_16x16x32_bf16 v[34:37], v[170:173], v[194:197], v[34:37]
	v_mfma_f32_16x16x32_bf16 v[26:29], v[178:181], v[194:197], v[26:29]
	v_mfma_f32_16x16x32_bf16 v[18:21], v[170:173], v[202:205], v[18:21]
	v_mfma_f32_16x16x32_bf16 v[10:13], v[178:181], v[202:205], v[10:13]
	v_mfma_f32_16x16x32_bf16 v[6:9], v[170:173], v[210:213], v[6:9]
	v_mfma_f32_16x16x32_bf16 v[2:5], v[178:181], v[210:213], v[2:5]
	s_setprio 2
	s_barrier
	s_add_i32 s92, s92, 2
	s_cmp_gt_u32 s92, 5
	s_mov_b64 s[46:47], s[52:53]
	s_cbranch_scc0 .LBB0_781
	s_and_b64 vcc, exec, s[8:9]
	s_cbranch_vccz .LBB0_784
	s_barrier

; #define PG8_STAGE(bufoff, gbase, voff) do { _Pragma("unroll") for (int _i = 0; _i < 2; ++_i) \
;         __builtin_amdgcn_global_load_lds((const unsigned*)((const char*)(gbase) + (voff)[_i]), (LAS unsigned*)(lds + (bufoff) + ldsw + _i * 8192), 16, 0, 0); } while (0)
; #define PG8_LDA(dst, b, h) do { _Pragma("unroll") for (int m = 0; m < 4; ++m) _Pragma("unroll") for (int k = 0; k < 2; ++k) dst[m][k] = *(const LAS bf16x8*)(lds + PG8_SA(b, h) + aoff + m * 2048 + k * 1024); } while (0)
; #define PG8_LDB(dst, b, h) do { _Pragma("unroll") for (int n = 0; n < 2; ++n) _Pragma("unroll") for (int k = 0; k < 2; ++k) dst[n][k] = *(const LAS bf16x8*)(lds + PG8_SB(b, h) + boff + n * 2048 + k * 1024); } while (0)
; #define PG8_MMA(ai, bj, At, Bt) do { __builtin_amdgcn_s_setprio(1); _Pragma("unroll") for (int m = 0; m < 4; ++m) _Pragma("unroll") for (int n = 0; n < 2; ++n) _Pragma("unroll") for (int k = 0; k < 2; ++k) \
;         acc[ai][bj][m][n] = __builtin_amdgcn_mfma_f32_16x16x32_bf16(Bt[n][k], At[m][k], acc[ai][bj][m][n], 0, 0, 0); __builtin_amdgcn_s_setprio(0); } while (0)
; #define PG8_WAIT_V(n) asm volatile("s_waitcnt vmcnt(" #n ")" ::: "memory")
; #define PG8_WAIT_L(n) asm volatile("s_waitcnt lgkmcnt(" #n ")" ::: "memory")
; #define PG8_BAR __builtin_amdgcn_s_barrier()
; #define PG8_SCHED __builtin_amdgcn_sched_barrier(0)
; template <class Epi>
; __device__ __forceinline__ void gemm_phase(LAS unsigned char* lds, const Gemm g, int G, int c, const Epi& E) {
;     ...
;             const bool last = (t == nt - 2);
;             const char* a1 = cA + (size_t)(t + 1) * kstep;
;             const char* a2 = last ? nA : cA + (size_t)(t + 2) * kstep; const char* b2 = last ? nB : cB + (size_t)(t + 2) * kstep;
;             const char* a3 = a2 + kstep; const char* b3 = b2 + kstep;
;             PG8_LDB(B0, 0, 0); PG8_LDB(B1, 0, 1); PG8_SCHED; PG8_LDA(At, 0, 0); PG8_STAGE(PG8_SA(1, 1), a1 + hstepA, voffA);
;             PG8_WAIT_V(8); PG8_WAIT_L(0); PG8_BAR; PG8_MMA(0, 0, At, B0); PG8_MMA(0, 1, At, B1); PG8_BAR; PG8_SCHED;
;             PG8_LDA(At, 0, 1); PG8_STAGE(PG8_SB(0, 0), b2, voffB); PG8_STAGE(PG8_SB(0, 1), b2 + hstepB, voffB); PG8_STAGE(PG8_SA(0, 0), a2, voffA);
.LBB0_903:
	ds_read_b128 v[130:133], v170
	ds_read_b128 v[134:137], v170 offset:1024
	ds_read_b128 v[138:141], v170 offset:2048
	ds_read_b128 v[142:145], v170 offset:3072
	ds_read_b128 v[162:165], v171
	ds_read_b128 v[174:177], v171 offset:1024
	ds_read_b128 v[178:181], v171 offset:2048
	ds_read_b128 v[182:185], v171 offset:3072
	ds_read_b128 v[186:189], v172
	ds_read_b128 v[190:193], v172 offset:1024
	ds_read_b128 v[194:197], v172 offset:2048
	ds_read_b128 v[198:201], v172 offset:3072
	ds_read_b128 v[202:205], v172 offset:4096
	ds_read_b128 v[206:209], v172 offset:5120
	ds_read_b128 v[210:213], v172 offset:6144
	ds_read_b128 v[214:217], v172 offset:7168
	s_add_u32 s33, s4, 0xfffc0080
	s_addc_u32 s42, s5, -1
	s_cmp_eq_u32 s46, 12
	s_cselect_b32 s45, s19, s42
	s_cselect_b32 s44, s18, s33
	s_cselect_b32 s43, s15, s39
	s_cselect_b32 s42, s17, s23
	v_lshl_add_u64 v[166:167], s[4:5], 0, v[154:155]
	s_add_i32 m0, s25, 0xc000
	s_nop 0
	global_load_lds_dwordx4 v[166:167], off
	v_lshl_add_u64 v[166:167], s[4:5], 0, v[156:157]
	s_add_i32 m0, s25, 0xe000
	s_nop 0
	global_load_lds_dwordx4 v[166:167], off
	s_waitcnt vmcnt(8)
	s_waitcnt lgkmcnt(0)
	s_barrier
	s_setprio 0
	v_mfma_f32_16x16x32_bf16 v[126:129], v[130:133], v[186:189], v[126:129]
	v_mfma_f32_16x16x32_bf16 v[122:125], v[138:141], v[186:189], v[122:125]
	v_mfma_f32_16x16x32_bf16 v[110:113], v[130:133], v[194:197], v[110:113]
	v_mfma_f32_16x16x32_bf16 v[106:109], v[138:141], v[194:197], v[106:109]
	v_mfma_f32_16x16x32_bf16 v[94:97], v[130:133], v[202:205], v[94:97]
	v_mfma_f32_16x16x32_bf16 v[90:93], v[138:141], v[202:205], v[90:93]
	v_mfma_f32_16x16x32_bf16 v[78:81], v[130:133], v[210:213], v[78:81]
	v_mfma_f32_16x16x32_bf16 v[74:77], v[138:141], v[210:213], v[74:77]
	v_mfma_f32_16x16x32_bf16 v[126:129], v[134:137], v[190:193], v[126:129]
	v_mfma_f32_16x16x32_bf16 v[122:125], v[142:145], v[190:193], v[122:125]
	v_mfma_f32_16x16x32_bf16 v[110:113], v[134:137], v[198:201], v[110:113]
	v_mfma_f32_16x16x32_bf16 v[106:109], v[142:145], v[198:201], v[106:109]
	v_mfma_f32_16x16x32_bf16 v[94:97], v[134:137], v[206:209], v[94:97]
	v_mfma_f32_16x16x32_bf16 v[90:93], v[142:145], v[206:209], v[90:93]
	v_mfma_f32_16x16x32_bf16 v[78:81], v[134:137], v[214:217], v[78:81]
	v_mfma_f32_16x16x32_bf16 v[74:77], v[142:145], v[214:217], v[74:77]
	s_setprio 2
	s_setprio 0
	v_mfma_f32_16x16x32_bf16 v[118:121], v[162:165], v[186:189], v[118:121]
	v_mfma_f32_16x16x32_bf16 v[114:117], v[178:181], v[186:189], v[114:117]
	v_mfma_f32_16x16x32_bf16 v[102:105], v[162:165], v[194:197], v[102:105]
	v_mfma_f32_16x16x32_bf16 v[98:101], v[178:181], v[194:197], v[98:101]
	v_mfma_f32_16x16x32_bf16 v[86:89], v[162:165], v[202:205], v[86:89]
	v_mfma_f32_16x16x32_bf16 v[82:85], v[178:181], v[202:205], v[82:85]
	v_mfma_f32_16x16x32_bf16 v[70:73], v[162:165], v[210:213], v[70:73]
	v_mfma_f32_16x16x32_bf16 v[66:69], v[178:181], v[210:213], v[66:69]
	v_mfma_f32_16x16x32_bf16 v[118:121], v[174:177], v[190:193], v[118:121]
	v_mfma_f32_16x16x32_bf16 v[114:117], v[182:185], v[190:193], v[114:117]
	v_mfma_f32_16x16x32_bf16 v[102:105], v[174:177], v[198:201], v[102:105]
	v_mfma_f32_16x16x32_bf16 v[98:101], v[182:185], v[198:201], v[98:101]
	v_mfma_f32_16x16x32_bf16 v[86:89], v[174:177], v[206:209], v[86:89]
	v_mfma_f32_16x16x32_bf16 v[82:85], v[182:185], v[206:209], v[82:85]
	v_mfma_f32_16x16x32_bf16 v[70:73], v[174:177], v[214:217], v[70:73]
	v_mfma_f32_16x16x32_bf16 v[66:69], v[182:185], v[214:217], v[66:69]
	s_setprio 2
	s_barrier
	ds_read_b128 v[186:189], v172 offset:16384
	ds_read_b128 v[190:193], v172 offset:17408
	ds_read_b128 v[194:197], v172 offset:18432
	ds_read_b128 v[198:201], v172 offset:19456
	ds_read_b128 v[202:205], v172 offset:20480
	ds_read_b128 v[206:209], v172 offset:21504
	ds_read_b128 v[210:213], v172 offset:22528
	ds_read_b128 v[214:217], v172 offset:23552
	s_add_i32 s33, s72, s54
	v_lshl_add_u64 v[166:167], s[42:43], 0, v[150:151]
	s_mov_b32 m0, s33
	s_nop 0
	global_load_lds_dwordx4 v[166:167], off
	s_add_i32 m0, s33, 0x2000
	s_add_u32 s62, s42, 0x40000
	v_lshl_add_u64 v[218:219], s[42:43], 0, v[146:147]
	s_addc_u32 s63, s43, 0
	s_add_i32 s33, s73, s54
	global_load_lds_dwordx4 v[218:219], off
	v_lshl_add_u64 v[220:221], s[62:63], 0, v[150:151]
	s_mov_b32 m0, s33
	v_lshl_add_u64 v[222:223], s[44:45], 0, v[148:149]
	global_load_lds_dwordx4 v[220:221], off
	v_lshl_add_u64 v[220:221], s[62:63], 0, v[146:147]
	s_add_i32 m0, s33, 0x2000
	s_nop 0
	global_load_lds_dwordx4 v[220:221], off
	v_lshl_add_u64 v[220:221], s[44:45], 0, v[152:153]
	s_mov_b32 m0, s25
	s_nop 0
	global_load_lds_dwordx4 v[220:221], off
	s_mov_b32 m0, s57
	s_nop 0
	global_load_lds_dwordx4 v[222:223], off
	s_waitcnt vmcnt(8)
	s_waitcnt lgkmcnt(0)
	s_barrier
; #define PG8_STAGE(bufoff, gbase, voff) do { _Pragma("unroll") for (int _i = 0; _i < 2; ++_i) \
;         __builtin_amdgcn_global_load_lds((const unsigned*)((const char*)(gbase) + (voff)[_i]), (LAS unsigned*)(lds + (bufoff) + ldsw + _i * 8192), 16, 0, 0); } while (0)
; #define PG8_LDA(dst, b, h) do { _Pragma("unroll") for (int m = 0; m < 4; ++m) _Pragma("unroll") for (int k = 0; k < 2; ++k) dst[m][k] = *(const LAS bf16x8*)(lds + PG8_SA(b, h) + aoff + m * 2048 + k * 1024); } while (0)
; #define PG8_LDB(dst, b, h) do { _Pragma("unroll") for (int n = 0; n < 2; ++n) _Pragma("unroll") for (int k = 0; k < 2; ++k) dst[n][k] = *(const LAS bf16x8*)(lds + PG8_SB(b, h) + boff + n * 2048 + k * 1024); } while (0)
; #define PG8_MMA(ai, bj, At, Bt) do { __builtin_amdgcn_s_setprio(1); _Pragma("unroll") for (int m = 0; m < 4; ++m) _Pragma("unroll") for (int n = 0; n < 2; ++n) _Pragma("unroll") for (int k = 0; k < 2; ++k) \
;         acc[ai][bj][m][n] = __builtin_amdgcn_mfma_f32_16x16x32_bf16(Bt[n][k], At[m][k], acc[ai][bj][m][n], 0, 0, 0); __builtin_amdgcn_s_setprio(0); } while (0)
; #define PG8_WAIT_V(n) asm volatile("s_waitcnt vmcnt(" #n ")" ::: "memory")
; #define PG8_WAIT_L(n) asm volatile("s_waitcnt lgkmcnt(" #n ")" ::: "memory")
; #define PG8_BAR __builtin_amdgcn_s_barrier()
; #define PG8_SCHED __builtin_amdgcn_sched_barrier(0)
; template <class Epi>
; __device__ __forceinline__ void gemm_phase(LAS unsigned char* lds, const Gemm g, int G, int c, const Epi& E) {
;     ...
;             PG8_WAIT_V(8); PG8_WAIT_L(0); PG8_BAR; PG8_MMA(1, 0, At, B0); PG8_MMA(1, 1, At, B1); PG8_BAR; PG8_SCHED;
;             PG8_LDB(B0, 1, 0); PG8_LDB(B1, 1, 1); PG8_SCHED; PG8_LDA(At, 1, 0); PG8_STAGE(PG8_SA(0, 1), a2 + hstepA, voffA);
;             PG8_WAIT_V(8); PG8_WAIT_L(0); PG8_BAR; PG8_MMA(0, 0, At, B0); PG8_MMA(0, 1, At, B1); PG8_BAR; PG8_SCHED;
	s_setprio 0
	v_mfma_f32_16x16x32_bf16 v[62:65], v[130:133], v[186:189], v[62:65]
	v_mfma_f32_16x16x32_bf16 v[58:61], v[138:141], v[186:189], v[58:61]
	v_mfma_f32_16x16x32_bf16 v[46:49], v[130:133], v[194:197], v[46:49]
	v_mfma_f32_16x16x32_bf16 v[42:45], v[138:141], v[194:197], v[42:45]
	v_mfma_f32_16x16x32_bf16 v[30:33], v[130:133], v[202:205], v[30:33]
	v_mfma_f32_16x16x32_bf16 v[26:29], v[138:141], v[202:205], v[26:29]
	v_mfma_f32_16x16x32_bf16 v[14:17], v[130:133], v[210:213], v[14:17]
	v_mfma_f32_16x16x32_bf16 v[10:13], v[138:141], v[210:213], v[10:13]
	v_mfma_f32_16x16x32_bf16 v[62:65], v[134:137], v[190:193], v[62:65]
	v_mfma_f32_16x16x32_bf16 v[58:61], v[142:145], v[190:193], v[58:61]
	v_mfma_f32_16x16x32_bf16 v[46:49], v[134:137], v[198:201], v[46:49]
	v_mfma_f32_16x16x32_bf16 v[42:45], v[142:145], v[198:201], v[42:45]
	v_mfma_f32_16x16x32_bf16 v[30:33], v[134:137], v[206:209], v[30:33]
	v_mfma_f32_16x16x32_bf16 v[26:29], v[142:145], v[206:209], v[26:29]
	v_mfma_f32_16x16x32_bf16 v[14:17], v[134:137], v[214:217], v[14:17]
	v_mfma_f32_16x16x32_bf16 v[10:13], v[142:145], v[214:217], v[10:13]
	s_setprio 2
	s_setprio 0
	v_mfma_f32_16x16x32_bf16 v[54:57], v[162:165], v[186:189], v[54:57]
	v_mfma_f32_16x16x32_bf16 v[50:53], v[178:181], v[186:189], v[50:53]
	v_mfma_f32_16x16x32_bf16 v[38:41], v[162:165], v[194:197], v[38:41]
	v_mfma_f32_16x16x32_bf16 v[34:37], v[178:181], v[194:197], v[34:37]
	v_mfma_f32_16x16x32_bf16 v[22:25], v[162:165], v[202:205], v[22:25]
	v_mfma_f32_16x16x32_bf16 v[18:21], v[178:181], v[202:205], v[18:21]
	v_mfma_f32_16x16x32_bf16 v[6:9], v[162:165], v[210:213], v[6:9]
	v_mfma_f32_16x16x32_bf16 v[2:5], v[178:181], v[210:213], v[2:5]
	v_mfma_f32_16x16x32_bf16 v[54:57], v[174:177], v[190:193], v[54:57]
	v_mfma_f32_16x16x32_bf16 v[50:53], v[182:185], v[190:193], v[50:53]
	v_mfma_f32_16x16x32_bf16 v[38:41], v[174:177], v[198:201], v[38:41]
	v_mfma_f32_16x16x32_bf16 v[34:37], v[182:185], v[198:201], v[34:37]
	v_mfma_f32_16x16x32_bf16 v[22:25], v[174:177], v[206:209], v[22:25]
	v_mfma_f32_16x16x32_bf16 v[18:21], v[182:185], v[206:209], v[18:21]
	v_mfma_f32_16x16x32_bf16 v[6:9], v[174:177], v[214:217], v[6:9]
	v_mfma_f32_16x16x32_bf16 v[2:5], v[182:185], v[214:217], v[2:5]
	s_setprio 2
	s_barrier
	s_add_i32 s33, 0, 0x18000
	s_add_i32 s47, 0, 0x1c000
	v_add_u32_e32 v142, s33, v169
	v_add_u32_e32 v173, s47, v169
	ds_read_b128 v[130:133], v142
	ds_read_b128 v[134:137], v142 offset:1024
	ds_read_b128 v[138:141], v142 offset:2048
	ds_read_b128 v[142:145], v142 offset:3072
	ds_read_b128 v[162:165], v173
	ds_read_b128 v[174:177], v173 offset:1024
	ds_read_b128 v[178:181], v173 offset:2048
	ds_read_b128 v[182:185], v173 offset:3072
	ds_read_b128 v[186:189], v172 offset:32768
	ds_read_b128 v[190:193], v172 offset:33792
	ds_read_b128 v[194:197], v172 offset:34816
	ds_read_b128 v[198:201], v172 offset:35840
	ds_read_b128 v[202:205], v172 offset:36864
	ds_read_b128 v[206:209], v172 offset:37888
	ds_read_b128 v[210:213], v172 offset:38912
	ds_read_b128 v[214:217], v172 offset:39936
	s_add_u32 s44, s44, 0x40000
	s_addc_u32 s45, s45, 0
	s_mov_b32 m0, s58
	v_lshl_add_u64 v[224:225], s[44:45], 0, v[152:153]
	global_load_lds_dwordx4 v[224:225], off
	v_lshl_add_u64 v[224:225], s[44:45], 0, v[148:149]
	s_mov_b32 m0, s59
	s_nop 0
	global_load_lds_dwordx4 v[224:225], off
	s_waitcnt vmcnt(8)
	s_waitcnt lgkmcnt(0)
	s_barrier
	s_setprio 0
	v_mfma_f32_16x16x32_bf16 v[126:129], v[130:133], v[186:189], v[126:129]
	v_mfma_f32_16x16x32_bf16 v[122:125], v[138:141], v[186:189], v[122:125]
	v_mfma_f32_16x16x32_bf16 v[110:113], v[130:133], v[194:197], v[110:113]
	v_mfma_f32_16x16x32_bf16 v[106:109], v[138:141], v[194:197], v[106:109]
	v_mfma_f32_16x16x32_bf16 v[94:97], v[130:133], v[202:205], v[94:97]
	v_mfma_f32_16x16x32_bf16 v[90:93], v[138:141], v[202:205], v[90:93]
	v_mfma_f32_16x16x32_bf16 v[78:81], v[130:133], v[210:213], v[78:81]
	v_mfma_f32_16x16x32_bf16 v[74:77], v[138:141], v[210:213], v[74:77]
	v_mfma_f32_16x16x32_bf16 v[126:129], v[134:137], v[190:193], v[126:129]
	v_mfma_f32_16x16x32_bf16 v[122:125], v[142:145], v[190:193], v[122:125]
	v_mfma_f32_16x16x32_bf16 v[110:113], v[134:137], v[198:201], v[110:113]
	v_mfma_f32_16x16x32_bf16 v[106:109], v[142:145], v[198:201], v[106:109]
	v_mfma_f32_16x16x32_bf16 v[94:97], v[134:137], v[206:209], v[94:97]
	v_mfma_f32_16x16x32_bf16 v[90:93], v[142:145], v[206:209], v[90:93]
	v_mfma_f32_16x16x32_bf16 v[78:81], v[134:137], v[214:217], v[78:81]
	v_mfma_f32_16x16x32_bf16 v[74:77], v[142:145], v[214:217], v[74:77]
	s_setprio 2
	s_setprio 0
	v_mfma_f32_16x16x32_bf16 v[118:121], v[162:165], v[186:189], v[118:121]
	v_mfma_f32_16x16x32_bf16 v[114:117], v[178:181], v[186:189], v[114:117]
	v_mfma_f32_16x16x32_bf16 v[102:105], v[162:165], v[194:197], v[102:105]
	v_mfma_f32_16x16x32_bf16 v[98:101], v[178:181], v[194:197], v[98:101]
	v_mfma_f32_16x16x32_bf16 v[86:89], v[162:165], v[202:205], v[86:89]
	v_mfma_f32_16x16x32_bf16 v[82:85], v[178:181], v[202:205], v[82:85]
	v_mfma_f32_16x16x32_bf16 v[70:73], v[162:165], v[210:213], v[70:73]
	v_mfma_f32_16x16x32_bf16 v[66:69], v[178:181], v[210:213], v[66:69]
	v_mfma_f32_16x16x32_bf16 v[118:121], v[174:177], v[190:193], v[118:121]
	v_mfma_f32_16x16x32_bf16 v[114:117], v[182:185], v[190:193], v[114:117]
	v_mfma_f32_16x16x32_bf16 v[102:105], v[174:177], v[198:201], v[102:105]
	v_mfma_f32_16x16x32_bf16 v[98:101], v[182:185], v[198:201], v[98:101]
	v_mfma_f32_16x16x32_bf16 v[86:89], v[174:177], v[206:209], v[86:89]
	v_mfma_f32_16x16x32_bf16 v[82:85], v[182:185], v[206:209], v[82:85]
	v_mfma_f32_16x16x32_bf16 v[70:73], v[174:177], v[214:217], v[70:73]
	v_mfma_f32_16x16x32_bf16 v[66:69], v[182:185], v[214:217], v[66:69]
	s_setprio 2
	s_barrier
; #define PG8_STAGE(bufoff, gbase, voff) do { _Pragma("unroll") for (int _i = 0; _i < 2; ++_i) \
;         __builtin_amdgcn_global_load_lds((const unsigned*)((const char*)(gbase) + (voff)[_i]), (LAS unsigned*)(lds + (bufoff) + ldsw + _i * 8192), 16, 0, 0); } while (0)
; #define PG8_LDA(dst, b, h) do { _Pragma("unroll") for (int m = 0; m < 4; ++m) _Pragma("unroll") for (int k = 0; k < 2; ++k) dst[m][k] = *(const LAS bf16x8*)(lds + PG8_SA(b, h) + aoff + m * 2048 + k * 1024); } while (0)
; #define PG8_MMA(ai, bj, At, Bt) do { __builtin_amdgcn_s_setprio(1); _Pragma("unroll") for (int m = 0; m < 4; ++m) _Pragma("unroll") for (int n = 0; n < 2; ++n) _Pragma("unroll") for (int k = 0; k < 2; ++k) \
;         acc[ai][bj][m][n] = __builtin_amdgcn_mfma_f32_16x16x32_bf16(Bt[n][k], At[m][k], acc[ai][bj][m][n], 0, 0, 0); __builtin_amdgcn_s_setprio(0); } while (0)
; #define PG8_WAIT_V(n) asm volatile("s_waitcnt vmcnt(" #n ")" ::: "memory")
; #define PG8_WAIT_L(n) asm volatile("s_waitcnt lgkmcnt(" #n ")" ::: "memory")
; #define PG8_BAR __builtin_amdgcn_s_barrier()
; #define PG8_SCHED __builtin_amdgcn_sched_barrier(0)
; template <class Epi>
; __device__ __forceinline__ void gemm_phase(LAS unsigned char* lds, const Gemm g, int G, int c, const Epi& E) {
;     ...
;             PG8_LDA(At, 1, 1); PG8_STAGE(PG8_SB(1, 0), b3, voffB); PG8_STAGE(PG8_SB(1, 1), b3 + hstepB, voffB); PG8_STAGE(PG8_SA(1, 0), a3, voffA);
;             PG8_WAIT_V(8); PG8_WAIT_L(0); PG8_BAR; PG8_MMA(1, 0, At, B0); PG8_MMA(1, 1, At, B1); PG8_BAR; PG8_SCHED;
;         }
	ds_read_b128 v[186:189], v172 offset:49152
	ds_read_b128 v[190:193], v172 offset:50176
	ds_read_b128 v[194:197], v172 offset:51200
	ds_read_b128 v[198:201], v172 offset:52224
	ds_read_b128 v[202:205], v172 offset:53248
	ds_read_b128 v[206:209], v172 offset:54272
	ds_read_b128 v[210:213], v172 offset:55296
	ds_read_b128 v[214:217], v172 offset:56320
	s_add_i32 s33, s33, s54
	v_lshl_add_u64 v[166:167], v[166:167], 0, s[10:11]
	s_mov_b32 m0, s33
	s_nop 0
	global_load_lds_dwordx4 v[166:167], off
	s_add_i32 m0, s33, 0x2000
	s_add_u32 s42, s42, 0x40080
	v_lshl_add_u64 v[166:167], v[218:219], 0, s[10:11]
	s_addc_u32 s43, s43, 0
	s_add_i32 s33, s47, s54
	global_load_lds_dwordx4 v[166:167], off
	v_lshl_add_u64 v[166:167], s[42:43], 0, v[150:151]
	s_mov_b32 m0, s33
	s_nop 0
	global_load_lds_dwordx4 v[166:167], off
	v_lshl_add_u64 v[166:167], s[42:43], 0, v[146:147]
	s_add_i32 m0, s33, 0x2000
	s_nop 0
	global_load_lds_dwordx4 v[166:167], off
	v_lshl_add_u64 v[166:167], v[220:221], 0, s[10:11]
	s_mov_b32 m0, s69
	s_nop 0
	global_load_lds_dwordx4 v[166:167], off
	v_lshl_add_u64 v[166:167], v[222:223], 0, s[10:11]
	s_mov_b32 m0, s70
	s_nop 0
	global_load_lds_dwordx4 v[166:167], off
	s_waitcnt vmcnt(8)
	s_waitcnt lgkmcnt(0)
	s_barrier
	s_setprio 0
	v_mfma_f32_16x16x32_bf16 v[62:65], v[130:133], v[186:189], v[62:65]
	v_mfma_f32_16x16x32_bf16 v[58:61], v[138:141], v[186:189], v[58:61]
	v_mfma_f32_16x16x32_bf16 v[46:49], v[130:133], v[194:197], v[46:49]
	v_mfma_f32_16x16x32_bf16 v[42:45], v[138:141], v[194:197], v[42:45]
	v_mfma_f32_16x16x32_bf16 v[30:33], v[130:133], v[202:205], v[30:33]
	v_mfma_f32_16x16x32_bf16 v[26:29], v[138:141], v[202:205], v[26:29]
	v_mfma_f32_16x16x32_bf16 v[14:17], v[130:133], v[210:213], v[14:17]
	v_mfma_f32_16x16x32_bf16 v[10:13], v[138:141], v[210:213], v[10:13]
	v_mfma_f32_16x16x32_bf16 v[62:65], v[134:137], v[190:193], v[62:65]
	v_mfma_f32_16x16x32_bf16 v[58:61], v[142:145], v[190:193], v[58:61]
	v_mfma_f32_16x16x32_bf16 v[46:49], v[134:137], v[198:201], v[46:49]
	v_mfma_f32_16x16x32_bf16 v[42:45], v[142:145], v[198:201], v[42:45]
	v_mfma_f32_16x16x32_bf16 v[30:33], v[134:137], v[206:209], v[30:33]
	v_mfma_f32_16x16x32_bf16 v[26:29], v[142:145], v[206:209], v[26:29]
	v_mfma_f32_16x16x32_bf16 v[14:17], v[134:137], v[214:217], v[14:17]
	v_mfma_f32_16x16x32_bf16 v[10:13], v[142:145], v[214:217], v[10:13]
	s_setprio 2
	s_setprio 0
	v_mfma_f32_16x16x32_bf16 v[54:57], v[162:165], v[186:189], v[54:57]
	v_mfma_f32_16x16x32_bf16 v[50:53], v[178:181], v[186:189], v[50:53]
	v_mfma_f32_16x16x32_bf16 v[38:41], v[162:165], v[194:197], v[38:41]
	v_mfma_f32_16x16x32_bf16 v[34:37], v[178:181], v[194:197], v[34:37]
	v_mfma_f32_16x16x32_bf16 v[22:25], v[162:165], v[202:205], v[22:25]
	v_mfma_f32_16x16x32_bf16 v[18:21], v[178:181], v[202:205], v[18:21]
	v_mfma_f32_16x16x32_bf16 v[6:9], v[162:165], v[210:213], v[6:9]
	v_mfma_f32_16x16x32_bf16 v[2:5], v[178:181], v[210:213], v[2:5]
	v_mfma_f32_16x16x32_bf16 v[54:57], v[174:177], v[190:193], v[54:57]
	v_mfma_f32_16x16x32_bf16 v[50:53], v[182:185], v[190:193], v[50:53]
	v_mfma_f32_16x16x32_bf16 v[38:41], v[174:177], v[198:201], v[38:41]
	v_mfma_f32_16x16x32_bf16 v[34:37], v[182:185], v[198:201], v[34:37]
	v_mfma_f32_16x16x32_bf16 v[22:25], v[174:177], v[206:209], v[22:25]
	v_mfma_f32_16x16x32_bf16 v[18:21], v[182:185], v[206:209], v[18:21]
	v_mfma_f32_16x16x32_bf16 v[6:9], v[174:177], v[214:217], v[6:9]
	v_mfma_f32_16x16x32_bf16 v[2:5], v[182:185], v[214:217], v[2:5]
	s_setprio 2
	s_barrier
	s_add_i32 s46, s46, 2
	s_add_u32 s4, s4, 0x100
	s_addc_u32 s5, s5, 0
	s_add_u32 s23, s23, 0x100
	s_addc_u32 s39, s39, 0
	s_cmp_gt_u32 s46, 13
	s_cbranch_scc0 .LBB0_903
	s_and_b64 vcc, exec, s[12:13]
	s_cbranch_vccz .LBB0_906
	s_barrier

; #define PG8_STAGE(bufoff, gbase, voff) do { _Pragma("unroll") for (int _i = 0; _i < 2; ++_i) \
;         __builtin_amdgcn_global_load_lds((const unsigned*)((const char*)(gbase) + (voff)[_i]), (LAS unsigned*)(lds + (bufoff) + ldsw + _i * 8192), 16, 0, 0); } while (0)
; #define PG8_LDA(dst, b, h) do { _Pragma("unroll") for (int m = 0; m < 4; ++m) _Pragma("unroll") for (int k = 0; k < 2; ++k) dst[m][k] = *(const LAS bf16x8*)(lds + PG8_SA(b, h) + aoff + m * 2048 + k * 1024); } while (0)
; #define PG8_LDB(dst, b, h) do { _Pragma("unroll") for (int n = 0; n < 2; ++n) _Pragma("unroll") for (int k = 0; k < 2; ++k) dst[n][k] = *(const LAS bf16x8*)(lds + PG8_SB(b, h) + boff + n * 2048 + k * 1024); } while (0)
; #define PG8_MMA(ai, bj, At, Bt) do { __builtin_amdgcn_s_setprio(1); _Pragma("unroll") for (int m = 0; m < 4; ++m) _Pragma("unroll") for (int n = 0; n < 2; ++n) _Pragma("unroll") for (int k = 0; k < 2; ++k) \
;         acc[ai][bj][m][n] = __builtin_amdgcn_mfma_f32_16x16x32_bf16(Bt[n][k], At[m][k], acc[ai][bj][m][n], 0, 0, 0); __builtin_amdgcn_s_setprio(0); } while (0)
; #define PG8_WAIT_V(n) asm volatile("s_waitcnt vmcnt(" #n ")" ::: "memory")
; #define PG8_WAIT_L(n) asm volatile("s_waitcnt lgkmcnt(" #n ")" ::: "memory")
; #define PG8_BAR __builtin_amdgcn_s_barrier()
; #define PG8_SCHED __builtin_amdgcn_sched_barrier(0)
; template <class Epi>
; __device__ __forceinline__ void gemm_phase(LAS unsigned char* lds, const Gemm g, int G, int c, const Epi& E) {
;     ...
;             const bool last = (t == nt - 2);
;             const char* a1 = cA + (size_t)(t + 1) * kstep;
;             const char* a2 = last ? nA : cA + (size_t)(t + 2) * kstep; const char* b2 = last ? nB : cB + (size_t)(t + 2) * kstep;
;             const char* a3 = a2 + kstep; const char* b3 = b2 + kstep;
;             PG8_LDB(B0, 0, 0); PG8_LDB(B1, 0, 1); PG8_SCHED; PG8_LDA(At, 0, 0); PG8_STAGE(PG8_SA(1, 1), a1 + hstepA, voffA);
;             PG8_WAIT_V(8); PG8_WAIT_L(0); PG8_BAR; PG8_MMA(0, 0, At, B0); PG8_MMA(0, 1, At, B1); PG8_BAR; PG8_SCHED;
;             PG8_LDA(At, 0, 1); PG8_STAGE(PG8_SB(0, 0), b2, voffB); PG8_STAGE(PG8_SB(0, 1), b2 + hstepB, voffB); PG8_STAGE(PG8_SA(0, 0), a2, voffA);
.LBB0_1058:
	ds_read_b128 v[152:155], v148
	ds_read_b128 v[156:159], v148 offset:1024
	ds_read_b128 v[160:163], v148 offset:2048
	ds_read_b128 v[164:167], v148 offset:3072
	ds_read_b128 v[168:171], v149
	ds_read_b128 v[172:175], v149 offset:1024
	ds_read_b128 v[176:179], v149 offset:2048
	ds_read_b128 v[180:183], v149 offset:3072
	ds_read_b128 v[184:187], v150
	ds_read_b128 v[188:191], v150 offset:1024
	ds_read_b128 v[192:195], v150 offset:2048
	ds_read_b128 v[196:199], v150 offset:3072
	ds_read_b128 v[200:203], v150 offset:4096
	ds_read_b128 v[204:207], v150 offset:5120
	ds_read_b128 v[208:211], v150 offset:6144
	ds_read_b128 v[212:215], v150 offset:7168
	s_add_u32 s33, s4, 0xfffc0080
	s_addc_u32 s38, s5, -1
	s_cmp_eq_u32 s80, 12
	s_cselect_b32 s41, s21, s38
	s_cselect_b32 s40, s20, s33
	s_cselect_b32 s39, s17, s79
	s_cselect_b32 s38, s19, s78
	v_lshl_add_u64 v[216:217], s[4:5], 0, v[138:139]
	s_add_i32 m0, s25, 0xc000
	s_nop 0
	global_load_lds_dwordx4 v[216:217], off
	v_lshl_add_u64 v[216:217], s[4:5], 0, v[140:141]
	s_add_i32 m0, s25, 0xe000
	s_nop 0
	global_load_lds_dwordx4 v[216:217], off
	s_waitcnt vmcnt(8)
	s_waitcnt lgkmcnt(0)
	s_barrier
	s_setprio 0
	v_mfma_f32_16x16x32_bf16 v[126:129], v[152:155], v[184:187], v[126:129]
	v_mfma_f32_16x16x32_bf16 v[122:125], v[160:163], v[184:187], v[122:125]
	v_mfma_f32_16x16x32_bf16 v[110:113], v[152:155], v[192:195], v[110:113]
	v_mfma_f32_16x16x32_bf16 v[106:109], v[160:163], v[192:195], v[106:109]
	v_mfma_f32_16x16x32_bf16 v[94:97], v[152:155], v[200:203], v[94:97]
	v_mfma_f32_16x16x32_bf16 v[90:93], v[160:163], v[200:203], v[90:93]
	v_mfma_f32_16x16x32_bf16 v[78:81], v[152:155], v[208:211], v[78:81]
	v_mfma_f32_16x16x32_bf16 v[74:77], v[160:163], v[208:211], v[74:77]
	v_mfma_f32_16x16x32_bf16 v[126:129], v[156:159], v[188:191], v[126:129]
	v_mfma_f32_16x16x32_bf16 v[122:125], v[164:167], v[188:191], v[122:125]
	v_mfma_f32_16x16x32_bf16 v[110:113], v[156:159], v[196:199], v[110:113]
	v_mfma_f32_16x16x32_bf16 v[106:109], v[164:167], v[196:199], v[106:109]
	v_mfma_f32_16x16x32_bf16 v[94:97], v[156:159], v[204:207], v[94:97]
	v_mfma_f32_16x16x32_bf16 v[90:93], v[164:167], v[204:207], v[90:93]
	v_mfma_f32_16x16x32_bf16 v[78:81], v[156:159], v[212:215], v[78:81]
	v_mfma_f32_16x16x32_bf16 v[74:77], v[164:167], v[212:215], v[74:77]
	s_setprio 2
	s_setprio 0
	v_mfma_f32_16x16x32_bf16 v[118:121], v[168:171], v[184:187], v[118:121]
	v_mfma_f32_16x16x32_bf16 v[114:117], v[176:179], v[184:187], v[114:117]
	v_mfma_f32_16x16x32_bf16 v[102:105], v[168:171], v[192:195], v[102:105]
	v_mfma_f32_16x16x32_bf16 v[98:101], v[176:179], v[192:195], v[98:101]
	v_mfma_f32_16x16x32_bf16 v[86:89], v[168:171], v[200:203], v[86:89]
	v_mfma_f32_16x16x32_bf16 v[82:85], v[176:179], v[200:203], v[82:85]
	v_mfma_f32_16x16x32_bf16 v[70:73], v[168:171], v[208:211], v[70:73]
	v_mfma_f32_16x16x32_bf16 v[66:69], v[176:179], v[208:211], v[66:69]
	v_mfma_f32_16x16x32_bf16 v[118:121], v[172:175], v[188:191], v[118:121]
	v_mfma_f32_16x16x32_bf16 v[114:117], v[180:183], v[188:191], v[114:117]
	v_mfma_f32_16x16x32_bf16 v[102:105], v[172:175], v[196:199], v[102:105]
	v_mfma_f32_16x16x32_bf16 v[98:101], v[180:183], v[196:199], v[98:101]
	v_mfma_f32_16x16x32_bf16 v[86:89], v[172:175], v[204:207], v[86:89]
	v_mfma_f32_16x16x32_bf16 v[82:85], v[180:183], v[204:207], v[82:85]
	v_mfma_f32_16x16x32_bf16 v[70:73], v[172:175], v[212:215], v[70:73]
	v_mfma_f32_16x16x32_bf16 v[66:69], v[180:183], v[212:215], v[66:69]
	s_setprio 2
	s_barrier
	ds_read_b128 v[184:187], v150 offset:16384
	ds_read_b128 v[188:191], v150 offset:17408
	ds_read_b128 v[192:195], v150 offset:18432
	ds_read_b128 v[196:199], v150 offset:19456
	ds_read_b128 v[200:203], v150 offset:20480
	ds_read_b128 v[204:207], v150 offset:21504
	ds_read_b128 v[208:211], v150 offset:22528
	ds_read_b128 v[212:215], v150 offset:23552
	s_add_i32 s33, s60, s46
	v_lshl_add_u64 v[216:217], s[38:39], 0, v[134:135]
	s_mov_b32 m0, s33
	s_nop 0
	global_load_lds_dwordx4 v[216:217], off
	s_add_i32 m0, s33, 0x2000
	s_add_u32 s62, s38, 0x40000
	v_lshl_add_u64 v[218:219], s[38:39], 0, v[130:131]
	s_addc_u32 s63, s39, 0
	s_add_i32 s33, s61, s46
	global_load_lds_dwordx4 v[218:219], off
	v_lshl_add_u64 v[220:221], s[62:63], 0, v[134:135]
	s_mov_b32 m0, s33
	v_lshl_add_u64 v[222:223], s[40:41], 0, v[132:133]
	global_load_lds_dwordx4 v[220:221], off
	v_lshl_add_u64 v[220:221], s[62:63], 0, v[130:131]
	s_add_i32 m0, s33, 0x2000
	s_nop 0
	global_load_lds_dwordx4 v[220:221], off
	v_lshl_add_u64 v[220:221], s[40:41], 0, v[136:137]
	s_mov_b32 m0, s25
	s_nop 0
	global_load_lds_dwordx4 v[220:221], off
	s_mov_b32 m0, s37
	s_nop 0
	global_load_lds_dwordx4 v[222:223], off
	s_waitcnt vmcnt(8)
	s_waitcnt lgkmcnt(0)
	s_barrier
; #define PG8_STAGE(bufoff, gbase, voff) do { _Pragma("unroll") for (int _i = 0; _i < 2; ++_i) \
;         __builtin_amdgcn_global_load_lds((const unsigned*)((const char*)(gbase) + (voff)[_i]), (LAS unsigned*)(lds + (bufoff) + ldsw + _i * 8192), 16, 0, 0); } while (0)
; #define PG8_LDA(dst, b, h) do { _Pragma("unroll") for (int m = 0; m < 4; ++m) _Pragma("unroll") for (int k = 0; k < 2; ++k) dst[m][k] = *(const LAS bf16x8*)(lds + PG8_SA(b, h) + aoff + m * 2048 + k * 1024); } while (0)
; #define PG8_LDB(dst, b, h) do { _Pragma("unroll") for (int n = 0; n < 2; ++n) _Pragma("unroll") for (int k = 0; k < 2; ++k) dst[n][k] = *(const LAS bf16x8*)(lds + PG8_SB(b, h) + boff + n * 2048 + k * 1024); } while (0)
; #define PG8_MMA(ai, bj, At, Bt) do { __builtin_amdgcn_s_setprio(1); _Pragma("unroll") for (int m = 0; m < 4; ++m) _Pragma("unroll") for (int n = 0; n < 2; ++n) _Pragma("unroll") for (int k = 0; k < 2; ++k) \
;         acc[ai][bj][m][n] = __builtin_amdgcn_mfma_f32_16x16x32_bf16(Bt[n][k], At[m][k], acc[ai][bj][m][n], 0, 0, 0); __builtin_amdgcn_s_setprio(0); } while (0)
; #define PG8_WAIT_V(n) asm volatile("s_waitcnt vmcnt(" #n ")" ::: "memory")
; #define PG8_WAIT_L(n) asm volatile("s_waitcnt lgkmcnt(" #n ")" ::: "memory")
; #define PG8_BAR __builtin_amdgcn_s_barrier()
; #define PG8_SCHED __builtin_amdgcn_sched_barrier(0)
; template <class Epi>
; __device__ __forceinline__ void gemm_phase(LAS unsigned char* lds, const Gemm g, int G, int c, const Epi& E) {
;     ...
;             PG8_WAIT_V(8); PG8_WAIT_L(0); PG8_BAR; PG8_MMA(1, 0, At, B0); PG8_MMA(1, 1, At, B1); PG8_BAR; PG8_SCHED;
;             PG8_LDB(B0, 1, 0); PG8_LDB(B1, 1, 1); PG8_SCHED; PG8_LDA(At, 1, 0); PG8_STAGE(PG8_SA(0, 1), a2 + hstepA, voffA);
;             PG8_WAIT_V(8); PG8_WAIT_L(0); PG8_BAR; PG8_MMA(0, 0, At, B0); PG8_MMA(0, 1, At, B1); PG8_BAR; PG8_SCHED;
	s_setprio 0
	v_mfma_f32_16x16x32_bf16 v[62:65], v[152:155], v[184:187], v[62:65]
	v_mfma_f32_16x16x32_bf16 v[58:61], v[160:163], v[184:187], v[58:61]
	v_mfma_f32_16x16x32_bf16 v[46:49], v[152:155], v[192:195], v[46:49]
	v_mfma_f32_16x16x32_bf16 v[42:45], v[160:163], v[192:195], v[42:45]
	v_mfma_f32_16x16x32_bf16 v[30:33], v[152:155], v[200:203], v[30:33]
	v_mfma_f32_16x16x32_bf16 v[26:29], v[160:163], v[200:203], v[26:29]
	v_mfma_f32_16x16x32_bf16 v[14:17], v[152:155], v[208:211], v[14:17]
	v_mfma_f32_16x16x32_bf16 v[10:13], v[160:163], v[208:211], v[10:13]
	v_mfma_f32_16x16x32_bf16 v[62:65], v[156:159], v[188:191], v[62:65]
	v_mfma_f32_16x16x32_bf16 v[58:61], v[164:167], v[188:191], v[58:61]
	v_mfma_f32_16x16x32_bf16 v[46:49], v[156:159], v[196:199], v[46:49]
	v_mfma_f32_16x16x32_bf16 v[42:45], v[164:167], v[196:199], v[42:45]
	v_mfma_f32_16x16x32_bf16 v[30:33], v[156:159], v[204:207], v[30:33]
	v_mfma_f32_16x16x32_bf16 v[26:29], v[164:167], v[204:207], v[26:29]
	v_mfma_f32_16x16x32_bf16 v[14:17], v[156:159], v[212:215], v[14:17]
	v_mfma_f32_16x16x32_bf16 v[10:13], v[164:167], v[212:215], v[10:13]
	s_setprio 2
	s_setprio 0
	v_mfma_f32_16x16x32_bf16 v[54:57], v[168:171], v[184:187], v[54:57]
	v_mfma_f32_16x16x32_bf16 v[50:53], v[176:179], v[184:187], v[50:53]
	v_mfma_f32_16x16x32_bf16 v[38:41], v[168:171], v[192:195], v[38:41]
	v_mfma_f32_16x16x32_bf16 v[34:37], v[176:179], v[192:195], v[34:37]
	v_mfma_f32_16x16x32_bf16 v[22:25], v[168:171], v[200:203], v[22:25]
	v_mfma_f32_16x16x32_bf16 v[18:21], v[176:179], v[200:203], v[18:21]
	v_mfma_f32_16x16x32_bf16 v[6:9], v[168:171], v[208:211], v[6:9]
	v_mfma_f32_16x16x32_bf16 v[2:5], v[176:179], v[208:211], v[2:5]
	v_mfma_f32_16x16x32_bf16 v[54:57], v[172:175], v[188:191], v[54:57]
	v_mfma_f32_16x16x32_bf16 v[50:53], v[180:183], v[188:191], v[50:53]
	v_mfma_f32_16x16x32_bf16 v[38:41], v[172:175], v[196:199], v[38:41]
	v_mfma_f32_16x16x32_bf16 v[34:37], v[180:183], v[196:199], v[34:37]
	v_mfma_f32_16x16x32_bf16 v[22:25], v[172:175], v[204:207], v[22:25]
	v_mfma_f32_16x16x32_bf16 v[18:21], v[180:183], v[204:207], v[18:21]
	v_mfma_f32_16x16x32_bf16 v[6:9], v[172:175], v[212:215], v[6:9]
	v_mfma_f32_16x16x32_bf16 v[2:5], v[180:183], v[212:215], v[2:5]
	s_setprio 2
	s_barrier
	s_add_i32 s33, 0, 0x18000
	s_add_i32 s62, 0, 0x1c000
	v_add_u32_e32 v164, s33, v147
	v_add_u32_e32 v180, s62, v147
	ds_read_b128 v[152:155], v164
	ds_read_b128 v[156:159], v164 offset:1024
	ds_read_b128 v[160:163], v164 offset:2048
	ds_read_b128 v[164:167], v164 offset:3072
	ds_read_b128 v[168:171], v180
	ds_read_b128 v[172:175], v180 offset:1024
	ds_read_b128 v[176:179], v180 offset:2048
	ds_read_b128 v[180:183], v180 offset:3072
	ds_read_b128 v[184:187], v150 offset:32768
	ds_read_b128 v[188:191], v150 offset:33792
	ds_read_b128 v[192:195], v150 offset:34816
	ds_read_b128 v[196:199], v150 offset:35840
	ds_read_b128 v[200:203], v150 offset:36864
	ds_read_b128 v[204:207], v150 offset:37888
	ds_read_b128 v[208:211], v150 offset:38912
	ds_read_b128 v[212:215], v150 offset:39936
	s_add_u32 s40, s40, 0x40000
	s_addc_u32 s41, s41, 0
	s_mov_b32 m0, s47
	v_lshl_add_u64 v[224:225], s[40:41], 0, v[136:137]
	global_load_lds_dwordx4 v[224:225], off
	v_lshl_add_u64 v[224:225], s[40:41], 0, v[132:133]
	s_mov_b32 m0, s52
	s_nop 0
	global_load_lds_dwordx4 v[224:225], off
	s_waitcnt vmcnt(8)
	s_waitcnt lgkmcnt(0)
	s_barrier
	s_setprio 0
	v_mfma_f32_16x16x32_bf16 v[126:129], v[152:155], v[184:187], v[126:129]
	v_mfma_f32_16x16x32_bf16 v[122:125], v[160:163], v[184:187], v[122:125]
	v_mfma_f32_16x16x32_bf16 v[110:113], v[152:155], v[192:195], v[110:113]
	v_mfma_f32_16x16x32_bf16 v[106:109], v[160:163], v[192:195], v[106:109]
	v_mfma_f32_16x16x32_bf16 v[94:97], v[152:155], v[200:203], v[94:97]
	v_mfma_f32_16x16x32_bf16 v[90:93], v[160:163], v[200:203], v[90:93]
	v_mfma_f32_16x16x32_bf16 v[78:81], v[152:155], v[208:211], v[78:81]
	v_mfma_f32_16x16x32_bf16 v[74:77], v[160:163], v[208:211], v[74:77]
	v_mfma_f32_16x16x32_bf16 v[126:129], v[156:159], v[188:191], v[126:129]
	v_mfma_f32_16x16x32_bf16 v[122:125], v[164:167], v[188:191], v[122:125]
	v_mfma_f32_16x16x32_bf16 v[110:113], v[156:159], v[196:199], v[110:113]
	v_mfma_f32_16x16x32_bf16 v[106:109], v[164:167], v[196:199], v[106:109]
	v_mfma_f32_16x16x32_bf16 v[94:97], v[156:159], v[204:207], v[94:97]
	v_mfma_f32_16x16x32_bf16 v[90:93], v[164:167], v[204:207], v[90:93]
	v_mfma_f32_16x16x32_bf16 v[78:81], v[156:159], v[212:215], v[78:81]
	v_mfma_f32_16x16x32_bf16 v[74:77], v[164:167], v[212:215], v[74:77]
	s_setprio 2
	s_setprio 0
	v_mfma_f32_16x16x32_bf16 v[118:121], v[168:171], v[184:187], v[118:121]
	v_mfma_f32_16x16x32_bf16 v[114:117], v[176:179], v[184:187], v[114:117]
	v_mfma_f32_16x16x32_bf16 v[102:105], v[168:171], v[192:195], v[102:105]
	v_mfma_f32_16x16x32_bf16 v[98:101], v[176:179], v[192:195], v[98:101]
	v_mfma_f32_16x16x32_bf16 v[86:89], v[168:171], v[200:203], v[86:89]
	v_mfma_f32_16x16x32_bf16 v[82:85], v[176:179], v[200:203], v[82:85]
	v_mfma_f32_16x16x32_bf16 v[70:73], v[168:171], v[208:211], v[70:73]
	v_mfma_f32_16x16x32_bf16 v[66:69], v[176:179], v[208:211], v[66:69]
	v_mfma_f32_16x16x32_bf16 v[118:121], v[172:175], v[188:191], v[118:121]
	v_mfma_f32_16x16x32_bf16 v[114:117], v[180:183], v[188:191], v[114:117]
	v_mfma_f32_16x16x32_bf16 v[102:105], v[172:175], v[196:199], v[102:105]
	v_mfma_f32_16x16x32_bf16 v[98:101], v[180:183], v[196:199], v[98:101]
	v_mfma_f32_16x16x32_bf16 v[86:89], v[172:175], v[204:207], v[86:89]
	v_mfma_f32_16x16x32_bf16 v[82:85], v[180:183], v[204:207], v[82:85]
	v_mfma_f32_16x16x32_bf16 v[70:73], v[172:175], v[212:215], v[70:73]
	v_mfma_f32_16x16x32_bf16 v[66:69], v[180:183], v[212:215], v[66:69]
	s_setprio 2
	s_barrier
; #define PG8_STAGE(bufoff, gbase, voff) do { _Pragma("unroll") for (int _i = 0; _i < 2; ++_i) \
;         __builtin_amdgcn_global_load_lds((const unsigned*)((const char*)(gbase) + (voff)[_i]), (LAS unsigned*)(lds + (bufoff) + ldsw + _i * 8192), 16, 0, 0); } while (0)
; #define PG8_LDA(dst, b, h) do { _Pragma("unroll") for (int m = 0; m < 4; ++m) _Pragma("unroll") for (int k = 0; k < 2; ++k) dst[m][k] = *(const LAS bf16x8*)(lds + PG8_SA(b, h) + aoff + m * 2048 + k * 1024); } while (0)
; #define PG8_MMA(ai, bj, At, Bt) do { __builtin_amdgcn_s_setprio(1); _Pragma("unroll") for (int m = 0; m < 4; ++m) _Pragma("unroll") for (int n = 0; n < 2; ++n) _Pragma("unroll") for (int k = 0; k < 2; ++k) \
;         acc[ai][bj][m][n] = __builtin_amdgcn_mfma_f32_16x16x32_bf16(Bt[n][k], At[m][k], acc[ai][bj][m][n], 0, 0, 0); __builtin_amdgcn_s_setprio(0); } while (0)
; #define PG8_WAIT_V(n) asm volatile("s_waitcnt vmcnt(" #n ")" ::: "memory")
; #define PG8_WAIT_L(n) asm volatile("s_waitcnt lgkmcnt(" #n ")" ::: "memory")
; #define PG8_BAR __builtin_amdgcn_s_barrier()
; #define PG8_SCHED __builtin_amdgcn_sched_barrier(0)
; template <class Epi>
; __device__ __forceinline__ void gemm_phase(LAS unsigned char* lds, const Gemm g, int G, int c, const Epi& E) {
;     ...
;             PG8_LDA(At, 1, 1); PG8_STAGE(PG8_SB(1, 0), b3, voffB); PG8_STAGE(PG8_SB(1, 1), b3 + hstepB, voffB); PG8_STAGE(PG8_SA(1, 0), a3, voffA);
;             PG8_WAIT_V(8); PG8_WAIT_L(0); PG8_BAR; PG8_MMA(1, 0, At, B0); PG8_MMA(1, 1, At, B1); PG8_BAR; PG8_SCHED;
;         }
	ds_read_b128 v[184:187], v150 offset:49152
	ds_read_b128 v[188:191], v150 offset:50176
	ds_read_b128 v[192:195], v150 offset:51200
	ds_read_b128 v[196:199], v150 offset:52224
	ds_read_b128 v[200:203], v150 offset:53248
	ds_read_b128 v[204:207], v150 offset:54272
	ds_read_b128 v[208:211], v150 offset:55296
	ds_read_b128 v[212:215], v150 offset:56320
	s_add_i32 s33, s33, s46
	v_lshl_add_u64 v[216:217], v[216:217], 0, s[12:13]
	s_mov_b32 m0, s33
	s_nop 0
	global_load_lds_dwordx4 v[216:217], off
	s_add_i32 m0, s33, 0x2000
	s_add_u32 s38, s38, 0x40080
	v_lshl_add_u64 v[216:217], v[218:219], 0, s[12:13]
	s_addc_u32 s39, s39, 0
	s_add_i32 s33, s62, s46
	global_load_lds_dwordx4 v[216:217], off
	v_lshl_add_u64 v[216:217], s[38:39], 0, v[134:135]
	s_mov_b32 m0, s33
	s_nop 0
	global_load_lds_dwordx4 v[216:217], off
	v_lshl_add_u64 v[216:217], s[38:39], 0, v[130:131]
	s_add_i32 m0, s33, 0x2000
	s_nop 0
	global_load_lds_dwordx4 v[216:217], off
	v_lshl_add_u64 v[216:217], v[220:221], 0, s[12:13]
	s_mov_b32 m0, s57
	s_nop 0
	global_load_lds_dwordx4 v[216:217], off
	v_lshl_add_u64 v[216:217], v[222:223], 0, s[12:13]
	s_mov_b32 m0, s58
	s_nop 0
	global_load_lds_dwordx4 v[216:217], off
	s_waitcnt vmcnt(8)
	s_waitcnt lgkmcnt(0)
	s_barrier
	s_setprio 0
	v_mfma_f32_16x16x32_bf16 v[62:65], v[152:155], v[184:187], v[62:65]
	v_mfma_f32_16x16x32_bf16 v[58:61], v[160:163], v[184:187], v[58:61]
	v_mfma_f32_16x16x32_bf16 v[46:49], v[152:155], v[192:195], v[46:49]
	v_mfma_f32_16x16x32_bf16 v[42:45], v[160:163], v[192:195], v[42:45]
	v_mfma_f32_16x16x32_bf16 v[30:33], v[152:155], v[200:203], v[30:33]
	v_mfma_f32_16x16x32_bf16 v[26:29], v[160:163], v[200:203], v[26:29]
	v_mfma_f32_16x16x32_bf16 v[14:17], v[152:155], v[208:211], v[14:17]
	v_mfma_f32_16x16x32_bf16 v[10:13], v[160:163], v[208:211], v[10:13]
	v_mfma_f32_16x16x32_bf16 v[62:65], v[156:159], v[188:191], v[62:65]
	v_mfma_f32_16x16x32_bf16 v[58:61], v[164:167], v[188:191], v[58:61]
	v_mfma_f32_16x16x32_bf16 v[46:49], v[156:159], v[196:199], v[46:49]
	v_mfma_f32_16x16x32_bf16 v[42:45], v[164:167], v[196:199], v[42:45]
	v_mfma_f32_16x16x32_bf16 v[30:33], v[156:159], v[204:207], v[30:33]
	v_mfma_f32_16x16x32_bf16 v[26:29], v[164:167], v[204:207], v[26:29]
	v_mfma_f32_16x16x32_bf16 v[14:17], v[156:159], v[212:215], v[14:17]
	v_mfma_f32_16x16x32_bf16 v[10:13], v[164:167], v[212:215], v[10:13]
	s_setprio 2
	s_setprio 0
	v_mfma_f32_16x16x32_bf16 v[54:57], v[168:171], v[184:187], v[54:57]
	v_mfma_f32_16x16x32_bf16 v[50:53], v[176:179], v[184:187], v[50:53]
	v_mfma_f32_16x16x32_bf16 v[38:41], v[168:171], v[192:195], v[38:41]
	v_mfma_f32_16x16x32_bf16 v[34:37], v[176:179], v[192:195], v[34:37]
	v_mfma_f32_16x16x32_bf16 v[22:25], v[168:171], v[200:203], v[22:25]
	v_mfma_f32_16x16x32_bf16 v[18:21], v[176:179], v[200:203], v[18:21]
	v_mfma_f32_16x16x32_bf16 v[6:9], v[168:171], v[208:211], v[6:9]
	v_mfma_f32_16x16x32_bf16 v[2:5], v[176:179], v[208:211], v[2:5]
	v_mfma_f32_16x16x32_bf16 v[54:57], v[172:175], v[188:191], v[54:57]
	v_mfma_f32_16x16x32_bf16 v[50:53], v[180:183], v[188:191], v[50:53]
	v_mfma_f32_16x16x32_bf16 v[38:41], v[172:175], v[196:199], v[38:41]
	v_mfma_f32_16x16x32_bf16 v[34:37], v[180:183], v[196:199], v[34:37]
	v_mfma_f32_16x16x32_bf16 v[22:25], v[172:175], v[204:207], v[22:25]
	v_mfma_f32_16x16x32_bf16 v[18:21], v[180:183], v[204:207], v[18:21]
	v_mfma_f32_16x16x32_bf16 v[6:9], v[172:175], v[212:215], v[6:9]
	v_mfma_f32_16x16x32_bf16 v[2:5], v[180:183], v[212:215], v[2:5]
	s_setprio 2
	s_barrier
	s_add_i32 s80, s80, 2
	s_add_u32 s4, s4, 0x100
	s_addc_u32 s5, s5, 0
	s_add_u32 s78, s78, 0x100
	s_addc_u32 s79, s79, 0
	s_cmp_gt_u32 s80, 13
	s_cbranch_scc0 .LBB0_1058
	s_and_b64 vcc, exec, s[14:15]
	s_cbranch_vccz .LBB0_1061
	s_barrier

; #define PG8_STAGE(bufoff, gbase, voff) do { _Pragma("unroll") for (int _i = 0; _i < 2; ++_i) \
;         __builtin_amdgcn_global_load_lds((const unsigned*)((const char*)(gbase) + (voff)[_i]), (LAS unsigned*)(lds + (bufoff) + ldsw + _i * 8192), 16, 0, 0); } while (0)
; #define PG8_LDA(dst, b, h) do { _Pragma("unroll") for (int m = 0; m < 4; ++m) _Pragma("unroll") for (int k = 0; k < 2; ++k) dst[m][k] = *(const LAS bf16x8*)(lds + PG8_SA(b, h) + aoff + m * 2048 + k * 1024); } while (0)
; #define PG8_LDB(dst, b, h) do { _Pragma("unroll") for (int n = 0; n < 2; ++n) _Pragma("unroll") for (int k = 0; k < 2; ++k) dst[n][k] = *(const LAS bf16x8*)(lds + PG8_SB(b, h) + boff + n * 2048 + k * 1024); } while (0)
; #define PG8_MMA(ai, bj, At, Bt) do { __builtin_amdgcn_s_setprio(1); _Pragma("unroll") for (int m = 0; m < 4; ++m) _Pragma("unroll") for (int n = 0; n < 2; ++n) _Pragma("unroll") for (int k = 0; k < 2; ++k) \
;         acc[ai][bj][m][n] = __builtin_amdgcn_mfma_f32_16x16x32_bf16(Bt[n][k], At[m][k], acc[ai][bj][m][n], 0, 0, 0); __builtin_amdgcn_s_setprio(0); } while (0)
; #define PG8_WAIT_V(n) asm volatile("s_waitcnt vmcnt(" #n ")" ::: "memory")
; #define PG8_WAIT_L(n) asm volatile("s_waitcnt lgkmcnt(" #n ")" ::: "memory")
; #define PG8_BAR __builtin_amdgcn_s_barrier()
; #define PG8_SCHED __builtin_amdgcn_sched_barrier(0)
; template <class Epi>
; __device__ __forceinline__ void gemm_phase(LAS unsigned char* lds, const Gemm g, int G, int c, const Epi& E) {
;     ...
;             const bool last = (t == nt - 2);
;             const char* a1 = cA + (size_t)(t + 1) * kstep;
;             const char* a2 = last ? nA : cA + (size_t)(t + 2) * kstep; const char* b2 = last ? nB : cB + (size_t)(t + 2) * kstep;
;             const char* a3 = a2 + kstep; const char* b3 = b2 + kstep;
;             PG8_LDB(B0, 0, 0); PG8_LDB(B1, 0, 1); PG8_SCHED; PG8_LDA(At, 0, 0); PG8_STAGE(PG8_SA(1, 1), a1 + hstepA, voffA);
;             PG8_WAIT_V(8); PG8_WAIT_L(0); PG8_BAR; PG8_MMA(0, 0, At, B0); PG8_MMA(0, 1, At, B1); PG8_BAR; PG8_SCHED;
;             PG8_LDA(At, 0, 1); PG8_STAGE(PG8_SB(0, 0), b2, voffB); PG8_STAGE(PG8_SB(0, 1), b2 + hstepB, voffB); PG8_STAGE(PG8_SA(0, 0), a2, voffA);
.LBB0_1143:
	ds_read_b128 v[122:125], v168
	ds_read_b128 v[126:129], v168 offset:1024
	ds_read_b128 v[130:133], v168 offset:2048
	ds_read_b128 v[134:137], v168 offset:3072
	ds_read_b128 v[162:165], v169
	ds_read_b128 v[172:175], v169 offset:1024
	ds_read_b128 v[176:179], v169 offset:2048
	ds_read_b128 v[180:183], v169 offset:3072
	ds_read_b128 v[184:187], v170
	ds_read_b128 v[188:191], v170 offset:1024
	ds_read_b128 v[192:195], v170 offset:2048
	ds_read_b128 v[196:199], v170 offset:3072
	ds_read_b128 v[200:203], v170 offset:4096
	ds_read_b128 v[204:207], v170 offset:5120
	ds_read_b128 v[208:211], v170 offset:6144
	ds_read_b128 v[212:215], v170 offset:7168
	s_add_u32 s18, s16, 0x100
	s_addc_u32 s19, s17, 0
	s_cmp_eq_u32 s68, 40
	s_cselect_b32 s23, s5, s19
	s_cselect_b32 s22, s4, s18
	s_cselect_b32 s21, s15, s67
	s_cselect_b32 s20, s14, s66
	v_lshl_add_u64 v[216:217], s[16:17], 0, v[154:155]
	s_add_i32 m0, s38, 0xc000
	s_nop 0
	global_load_lds_dwordx4 v[216:217], off
	v_lshl_add_u64 v[216:217], s[16:17], 0, v[156:157]
	s_add_i32 m0, s38, 0xe000
	s_nop 0
	global_load_lds_dwordx4 v[216:217], off
	s_waitcnt vmcnt(8)
	s_waitcnt lgkmcnt(0)
	s_barrier
	s_setprio 0
	v_mfma_f32_16x16x32_bf16 v[142:145], v[122:125], v[184:187], v[142:145]
	v_mfma_f32_16x16x32_bf16 v[138:141], v[130:133], v[184:187], v[138:141]
	v_mfma_f32_16x16x32_bf16 v[118:121], v[122:125], v[192:195], v[118:121]
	v_mfma_f32_16x16x32_bf16 v[106:109], v[130:133], v[192:195], v[106:109]
	v_mfma_f32_16x16x32_bf16 v[102:105], v[122:125], v[200:203], v[102:105]
	v_mfma_f32_16x16x32_bf16 v[90:93], v[130:133], v[200:203], v[90:93]
	v_mfma_f32_16x16x32_bf16 v[86:89], v[122:125], v[208:211], v[86:89]
	v_mfma_f32_16x16x32_bf16 v[74:77], v[130:133], v[208:211], v[74:77]
	v_mfma_f32_16x16x32_bf16 v[142:145], v[126:129], v[188:191], v[142:145]
	v_mfma_f32_16x16x32_bf16 v[138:141], v[134:137], v[188:191], v[138:141]
	v_mfma_f32_16x16x32_bf16 v[118:121], v[126:129], v[196:199], v[118:121]
	v_mfma_f32_16x16x32_bf16 v[106:109], v[134:137], v[196:199], v[106:109]
	v_mfma_f32_16x16x32_bf16 v[102:105], v[126:129], v[204:207], v[102:105]
	v_mfma_f32_16x16x32_bf16 v[90:93], v[134:137], v[204:207], v[90:93]
	v_mfma_f32_16x16x32_bf16 v[86:89], v[126:129], v[212:215], v[86:89]
	v_mfma_f32_16x16x32_bf16 v[74:77], v[134:137], v[212:215], v[74:77]
	s_setprio 2
	s_setprio 0
	v_mfma_f32_16x16x32_bf16 v[114:117], v[162:165], v[184:187], v[114:117]
	v_mfma_f32_16x16x32_bf16 v[110:113], v[176:179], v[184:187], v[110:113]
	v_mfma_f32_16x16x32_bf16 v[98:101], v[162:165], v[192:195], v[98:101]
	v_mfma_f32_16x16x32_bf16 v[94:97], v[176:179], v[192:195], v[94:97]
	v_mfma_f32_16x16x32_bf16 v[82:85], v[162:165], v[200:203], v[82:85]
	v_mfma_f32_16x16x32_bf16 v[78:81], v[176:179], v[200:203], v[78:81]
	v_mfma_f32_16x16x32_bf16 v[70:73], v[162:165], v[208:211], v[70:73]
	v_mfma_f32_16x16x32_bf16 v[66:69], v[176:179], v[208:211], v[66:69]
	v_mfma_f32_16x16x32_bf16 v[114:117], v[172:175], v[188:191], v[114:117]
	v_mfma_f32_16x16x32_bf16 v[110:113], v[180:183], v[188:191], v[110:113]
	v_mfma_f32_16x16x32_bf16 v[98:101], v[172:175], v[196:199], v[98:101]
	v_mfma_f32_16x16x32_bf16 v[94:97], v[180:183], v[196:199], v[94:97]
	v_mfma_f32_16x16x32_bf16 v[82:85], v[172:175], v[204:207], v[82:85]
	v_mfma_f32_16x16x32_bf16 v[78:81], v[180:183], v[204:207], v[78:81]
	v_mfma_f32_16x16x32_bf16 v[70:73], v[172:175], v[212:215], v[70:73]
	v_mfma_f32_16x16x32_bf16 v[66:69], v[180:183], v[212:215], v[66:69]
	s_setprio 2
	s_barrier
	ds_read_b128 v[184:187], v170 offset:16384
	ds_read_b128 v[188:191], v170 offset:17408
	ds_read_b128 v[192:195], v170 offset:18432
	ds_read_b128 v[196:199], v170 offset:19456
	ds_read_b128 v[200:203], v170 offset:20480
	ds_read_b128 v[204:207], v170 offset:21504
	ds_read_b128 v[208:211], v170 offset:22528
	ds_read_b128 v[212:215], v170 offset:23552
	s_add_i32 s16, s54, s36
	v_lshl_add_u64 v[216:217], s[20:21], 0, v[150:151]
	s_mov_b32 m0, s16
	s_nop 0
	global_load_lds_dwordx4 v[216:217], off
	s_add_i32 m0, s16, 0x2000
	s_add_u32 s16, s20, 0xb0000
	v_lshl_add_u64 v[218:219], s[20:21], 0, v[146:147]
	s_addc_u32 s17, s21, 0
	s_add_i32 s33, s55, s36
	global_load_lds_dwordx4 v[218:219], off
	v_lshl_add_u64 v[220:221], s[16:17], 0, v[150:151]
	s_mov_b32 m0, s33
	v_lshl_add_u64 v[222:223], s[22:23], 0, v[148:149]
	global_load_lds_dwordx4 v[220:221], off
	v_lshl_add_u64 v[220:221], s[16:17], 0, v[146:147]
	s_add_i32 m0, s33, 0x2000
	s_nop 0
	global_load_lds_dwordx4 v[220:221], off
	v_lshl_add_u64 v[220:221], s[22:23], 0, v[152:153]
	s_mov_b32 m0, s38
	s_nop 0
	global_load_lds_dwordx4 v[220:221], off
	s_mov_b32 m0, s39
	s_nop 0
	global_load_lds_dwordx4 v[222:223], off
	s_waitcnt vmcnt(8)
	s_waitcnt lgkmcnt(0)
	s_barrier
; #define PG8_STAGE(bufoff, gbase, voff) do { _Pragma("unroll") for (int _i = 0; _i < 2; ++_i) \
;         __builtin_amdgcn_global_load_lds((const unsigned*)((const char*)(gbase) + (voff)[_i]), (LAS unsigned*)(lds + (bufoff) + ldsw + _i * 8192), 16, 0, 0); } while (0)
; #define PG8_LDA(dst, b, h) do { _Pragma("unroll") for (int m = 0; m < 4; ++m) _Pragma("unroll") for (int k = 0; k < 2; ++k) dst[m][k] = *(const LAS bf16x8*)(lds + PG8_SA(b, h) + aoff + m * 2048 + k * 1024); } while (0)
; #define PG8_LDB(dst, b, h) do { _Pragma("unroll") for (int n = 0; n < 2; ++n) _Pragma("unroll") for (int k = 0; k < 2; ++k) dst[n][k] = *(const LAS bf16x8*)(lds + PG8_SB(b, h) + boff + n * 2048 + k * 1024); } while (0)
; #define PG8_MMA(ai, bj, At, Bt) do { __builtin_amdgcn_s_setprio(1); _Pragma("unroll") for (int m = 0; m < 4; ++m) _Pragma("unroll") for (int n = 0; n < 2; ++n) _Pragma("unroll") for (int k = 0; k < 2; ++k) \
;         acc[ai][bj][m][n] = __builtin_amdgcn_mfma_f32_16x16x32_bf16(Bt[n][k], At[m][k], acc[ai][bj][m][n], 0, 0, 0); __builtin_amdgcn_s_setprio(0); } while (0)
; #define PG8_WAIT_V(n) asm volatile("s_waitcnt vmcnt(" #n ")" ::: "memory")
; #define PG8_WAIT_L(n) asm volatile("s_waitcnt lgkmcnt(" #n ")" ::: "memory")
; #define PG8_BAR __builtin_amdgcn_s_barrier()
; #define PG8_SCHED __builtin_amdgcn_sched_barrier(0)
; template <class Epi>
; __device__ __forceinline__ void gemm_phase(LAS unsigned char* lds, const Gemm g, int G, int c, const Epi& E) {
;     ...
;             PG8_WAIT_V(8); PG8_WAIT_L(0); PG8_BAR; PG8_MMA(1, 0, At, B0); PG8_MMA(1, 1, At, B1); PG8_BAR; PG8_SCHED;
;             PG8_LDB(B0, 1, 0); PG8_LDB(B1, 1, 1); PG8_SCHED; PG8_LDA(At, 1, 0); PG8_STAGE(PG8_SA(0, 1), a2 + hstepA, voffA);
;             PG8_WAIT_V(8); PG8_WAIT_L(0); PG8_BAR; PG8_MMA(0, 0, At, B0); PG8_MMA(0, 1, At, B1); PG8_BAR; PG8_SCHED;
	s_setprio 0
	v_mfma_f32_16x16x32_bf16 v[62:65], v[122:125], v[184:187], v[62:65]
	v_mfma_f32_16x16x32_bf16 v[58:61], v[130:133], v[184:187], v[58:61]
	v_mfma_f32_16x16x32_bf16 v[54:57], v[122:125], v[192:195], v[54:57]
	v_mfma_f32_16x16x32_bf16 v[42:45], v[130:133], v[192:195], v[42:45]
	v_mfma_f32_16x16x32_bf16 v[38:41], v[122:125], v[200:203], v[38:41]
	v_mfma_f32_16x16x32_bf16 v[26:29], v[130:133], v[200:203], v[26:29]
	v_mfma_f32_16x16x32_bf16 v[22:25], v[122:125], v[208:211], v[22:25]
	v_mfma_f32_16x16x32_bf16 v[10:13], v[130:133], v[208:211], v[10:13]
	v_mfma_f32_16x16x32_bf16 v[62:65], v[126:129], v[188:191], v[62:65]
	v_mfma_f32_16x16x32_bf16 v[58:61], v[134:137], v[188:191], v[58:61]
	v_mfma_f32_16x16x32_bf16 v[54:57], v[126:129], v[196:199], v[54:57]
	v_mfma_f32_16x16x32_bf16 v[42:45], v[134:137], v[196:199], v[42:45]
	v_mfma_f32_16x16x32_bf16 v[38:41], v[126:129], v[204:207], v[38:41]
	v_mfma_f32_16x16x32_bf16 v[26:29], v[134:137], v[204:207], v[26:29]
	v_mfma_f32_16x16x32_bf16 v[22:25], v[126:129], v[212:215], v[22:25]
	v_mfma_f32_16x16x32_bf16 v[10:13], v[134:137], v[212:215], v[10:13]
	s_setprio 2
	s_setprio 0
	v_mfma_f32_16x16x32_bf16 v[50:53], v[162:165], v[184:187], v[50:53]
	v_mfma_f32_16x16x32_bf16 v[46:49], v[176:179], v[184:187], v[46:49]
	v_mfma_f32_16x16x32_bf16 v[34:37], v[162:165], v[192:195], v[34:37]
	v_mfma_f32_16x16x32_bf16 v[30:33], v[176:179], v[192:195], v[30:33]
	v_mfma_f32_16x16x32_bf16 v[18:21], v[162:165], v[200:203], v[18:21]
	v_mfma_f32_16x16x32_bf16 v[14:17], v[176:179], v[200:203], v[14:17]
	v_mfma_f32_16x16x32_bf16 v[6:9], v[162:165], v[208:211], v[6:9]
	v_mfma_f32_16x16x32_bf16 v[2:5], v[176:179], v[208:211], v[2:5]
	v_mfma_f32_16x16x32_bf16 v[50:53], v[172:175], v[188:191], v[50:53]
	v_mfma_f32_16x16x32_bf16 v[46:49], v[180:183], v[188:191], v[46:49]
	v_mfma_f32_16x16x32_bf16 v[34:37], v[172:175], v[196:199], v[34:37]
	v_mfma_f32_16x16x32_bf16 v[30:33], v[180:183], v[196:199], v[30:33]
	v_mfma_f32_16x16x32_bf16 v[18:21], v[172:175], v[204:207], v[18:21]
	v_mfma_f32_16x16x32_bf16 v[14:17], v[180:183], v[204:207], v[14:17]
	v_mfma_f32_16x16x32_bf16 v[6:9], v[172:175], v[212:215], v[6:9]
	v_mfma_f32_16x16x32_bf16 v[2:5], v[180:183], v[212:215], v[2:5]
	s_setprio 2
	s_barrier
	s_add_i32 s33, 0, 0x18000
	s_add_i32 s62, 0, 0x1c000
	v_add_u32_e32 v134, s33, v167
	v_add_u32_e32 v171, s62, v167
	ds_read_b128 v[122:125], v134
	ds_read_b128 v[126:129], v134 offset:1024
	ds_read_b128 v[130:133], v134 offset:2048
	ds_read_b128 v[134:137], v134 offset:3072
	ds_read_b128 v[162:165], v171
	ds_read_b128 v[172:175], v171 offset:1024
	ds_read_b128 v[176:179], v171 offset:2048
	ds_read_b128 v[180:183], v171 offset:3072
	ds_read_b128 v[184:187], v170 offset:32768
	ds_read_b128 v[188:191], v170 offset:33792
	ds_read_b128 v[192:195], v170 offset:34816
	ds_read_b128 v[196:199], v170 offset:35840
	ds_read_b128 v[200:203], v170 offset:36864
	ds_read_b128 v[204:207], v170 offset:37888
	ds_read_b128 v[208:211], v170 offset:38912
	ds_read_b128 v[212:215], v170 offset:39936
	s_add_u32 s16, s22, 0xb0000
	s_addc_u32 s17, s23, 0
	s_mov_b32 m0, s40
	v_lshl_add_u64 v[224:225], s[16:17], 0, v[152:153]
	global_load_lds_dwordx4 v[224:225], off
	v_lshl_add_u64 v[224:225], s[16:17], 0, v[148:149]
	s_mov_b32 m0, s41
	s_nop 0
	global_load_lds_dwordx4 v[224:225], off
	s_waitcnt vmcnt(8)
	s_waitcnt lgkmcnt(0)
	s_barrier
	s_setprio 0
	v_mfma_f32_16x16x32_bf16 v[142:145], v[122:125], v[184:187], v[142:145]
	v_mfma_f32_16x16x32_bf16 v[138:141], v[130:133], v[184:187], v[138:141]
	v_mfma_f32_16x16x32_bf16 v[118:121], v[122:125], v[192:195], v[118:121]
	v_mfma_f32_16x16x32_bf16 v[106:109], v[130:133], v[192:195], v[106:109]
	v_mfma_f32_16x16x32_bf16 v[102:105], v[122:125], v[200:203], v[102:105]
	v_mfma_f32_16x16x32_bf16 v[90:93], v[130:133], v[200:203], v[90:93]
	v_mfma_f32_16x16x32_bf16 v[86:89], v[122:125], v[208:211], v[86:89]
	v_mfma_f32_16x16x32_bf16 v[74:77], v[130:133], v[208:211], v[74:77]
	v_mfma_f32_16x16x32_bf16 v[142:145], v[126:129], v[188:191], v[142:145]
	v_mfma_f32_16x16x32_bf16 v[138:141], v[134:137], v[188:191], v[138:141]
	v_mfma_f32_16x16x32_bf16 v[118:121], v[126:129], v[196:199], v[118:121]
	v_mfma_f32_16x16x32_bf16 v[106:109], v[134:137], v[196:199], v[106:109]
	v_mfma_f32_16x16x32_bf16 v[102:105], v[126:129], v[204:207], v[102:105]
	v_mfma_f32_16x16x32_bf16 v[90:93], v[134:137], v[204:207], v[90:93]
	v_mfma_f32_16x16x32_bf16 v[86:89], v[126:129], v[212:215], v[86:89]
	v_mfma_f32_16x16x32_bf16 v[74:77], v[134:137], v[212:215], v[74:77]
	s_setprio 2
	s_setprio 0
	v_mfma_f32_16x16x32_bf16 v[114:117], v[162:165], v[184:187], v[114:117]
	v_mfma_f32_16x16x32_bf16 v[110:113], v[176:179], v[184:187], v[110:113]
	v_mfma_f32_16x16x32_bf16 v[98:101], v[162:165], v[192:195], v[98:101]
	v_mfma_f32_16x16x32_bf16 v[94:97], v[176:179], v[192:195], v[94:97]
	v_mfma_f32_16x16x32_bf16 v[82:85], v[162:165], v[200:203], v[82:85]
	v_mfma_f32_16x16x32_bf16 v[78:81], v[176:179], v[200:203], v[78:81]
	v_mfma_f32_16x16x32_bf16 v[70:73], v[162:165], v[208:211], v[70:73]
	v_mfma_f32_16x16x32_bf16 v[66:69], v[176:179], v[208:211], v[66:69]
	v_mfma_f32_16x16x32_bf16 v[114:117], v[172:175], v[188:191], v[114:117]
	v_mfma_f32_16x16x32_bf16 v[110:113], v[180:183], v[188:191], v[110:113]
	v_mfma_f32_16x16x32_bf16 v[98:101], v[172:175], v[196:199], v[98:101]
	v_mfma_f32_16x16x32_bf16 v[94:97], v[180:183], v[196:199], v[94:97]
	v_mfma_f32_16x16x32_bf16 v[82:85], v[172:175], v[204:207], v[82:85]
	v_mfma_f32_16x16x32_bf16 v[78:81], v[180:183], v[204:207], v[78:81]
	v_mfma_f32_16x16x32_bf16 v[70:73], v[172:175], v[212:215], v[70:73]
	v_mfma_f32_16x16x32_bf16 v[66:69], v[180:183], v[212:215], v[66:69]
	s_setprio 2
	s_barrier
; #define PG8_STAGE(bufoff, gbase, voff) do { _Pragma("unroll") for (int _i = 0; _i < 2; ++_i) \
;         __builtin_amdgcn_global_load_lds((const unsigned*)((const char*)(gbase) + (voff)[_i]), (LAS unsigned*)(lds + (bufoff) + ldsw + _i * 8192), 16, 0, 0); } while (0)
; #define PG8_LDA(dst, b, h) do { _Pragma("unroll") for (int m = 0; m < 4; ++m) _Pragma("unroll") for (int k = 0; k < 2; ++k) dst[m][k] = *(const LAS bf16x8*)(lds + PG8_SA(b, h) + aoff + m * 2048 + k * 1024); } while (0)
; #define PG8_MMA(ai, bj, At, Bt) do { __builtin_amdgcn_s_setprio(1); _Pragma("unroll") for (int m = 0; m < 4; ++m) _Pragma("unroll") for (int n = 0; n < 2; ++n) _Pragma("unroll") for (int k = 0; k < 2; ++k) \
;         acc[ai][bj][m][n] = __builtin_amdgcn_mfma_f32_16x16x32_bf16(Bt[n][k], At[m][k], acc[ai][bj][m][n], 0, 0, 0); __builtin_amdgcn_s_setprio(0); } while (0)
; #define PG8_WAIT_V(n) asm volatile("s_waitcnt vmcnt(" #n ")" ::: "memory")
; #define PG8_WAIT_L(n) asm volatile("s_waitcnt lgkmcnt(" #n ")" ::: "memory")
; #define PG8_BAR __builtin_amdgcn_s_barrier()
; #define PG8_SCHED __builtin_amdgcn_sched_barrier(0)
; template <class Epi>
; __device__ __forceinline__ void gemm_phase(LAS unsigned char* lds, const Gemm g, int G, int c, const Epi& E) {
;     ...
;             PG8_LDA(At, 1, 1); PG8_STAGE(PG8_SB(1, 0), b3, voffB); PG8_STAGE(PG8_SB(1, 1), b3 + hstepB, voffB); PG8_STAGE(PG8_SA(1, 0), a3, voffA);
;             PG8_WAIT_V(8); PG8_WAIT_L(0); PG8_BAR; PG8_MMA(1, 0, At, B0); PG8_MMA(1, 1, At, B1); PG8_BAR; PG8_SCHED;
;         }
	ds_read_b128 v[184:187], v170 offset:49152
	ds_read_b128 v[188:191], v170 offset:50176
	ds_read_b128 v[192:195], v170 offset:51200
	ds_read_b128 v[196:199], v170 offset:52224
	ds_read_b128 v[200:203], v170 offset:53248
	ds_read_b128 v[204:207], v170 offset:54272
	ds_read_b128 v[208:211], v170 offset:55296
	ds_read_b128 v[212:215], v170 offset:56320
	s_add_i32 s16, s33, s36
	v_lshl_add_u64 v[216:217], v[216:217], 0, s[10:11]
	s_mov_b32 m0, s16
	s_nop 0
	global_load_lds_dwordx4 v[216:217], off
	s_add_i32 m0, s16, 0x2000
	s_add_u32 s16, s20, 0xb0080
	v_lshl_add_u64 v[216:217], v[218:219], 0, s[10:11]
	s_addc_u32 s17, s21, 0
	s_add_i32 s20, s62, s36
	global_load_lds_dwordx4 v[216:217], off
	v_lshl_add_u64 v[216:217], s[16:17], 0, v[150:151]
	s_mov_b32 m0, s20
	s_nop 0
	global_load_lds_dwordx4 v[216:217], off
	v_lshl_add_u64 v[216:217], s[16:17], 0, v[146:147]
	s_add_i32 m0, s20, 0x2000
	s_nop 0
	global_load_lds_dwordx4 v[216:217], off
	v_lshl_add_u64 v[216:217], v[220:221], 0, s[10:11]
	s_mov_b32 m0, s47
	s_nop 0
	global_load_lds_dwordx4 v[216:217], off
	v_lshl_add_u64 v[216:217], v[222:223], 0, s[10:11]
	s_mov_b32 m0, s52
	s_nop 0
	global_load_lds_dwordx4 v[216:217], off
	s_waitcnt vmcnt(8)
	s_waitcnt lgkmcnt(0)
	s_barrier
	s_setprio 0
	v_mfma_f32_16x16x32_bf16 v[62:65], v[122:125], v[184:187], v[62:65]
	v_mfma_f32_16x16x32_bf16 v[58:61], v[130:133], v[184:187], v[58:61]
	v_mfma_f32_16x16x32_bf16 v[54:57], v[122:125], v[192:195], v[54:57]
	v_mfma_f32_16x16x32_bf16 v[42:45], v[130:133], v[192:195], v[42:45]
	v_mfma_f32_16x16x32_bf16 v[38:41], v[122:125], v[200:203], v[38:41]
	v_mfma_f32_16x16x32_bf16 v[26:29], v[130:133], v[200:203], v[26:29]
	v_mfma_f32_16x16x32_bf16 v[22:25], v[122:125], v[208:211], v[22:25]
	v_mfma_f32_16x16x32_bf16 v[10:13], v[130:133], v[208:211], v[10:13]
	v_mfma_f32_16x16x32_bf16 v[62:65], v[126:129], v[188:191], v[62:65]
	v_mfma_f32_16x16x32_bf16 v[58:61], v[134:137], v[188:191], v[58:61]
	v_mfma_f32_16x16x32_bf16 v[54:57], v[126:129], v[196:199], v[54:57]
	v_mfma_f32_16x16x32_bf16 v[42:45], v[134:137], v[196:199], v[42:45]
	v_mfma_f32_16x16x32_bf16 v[38:41], v[126:129], v[204:207], v[38:41]
	v_mfma_f32_16x16x32_bf16 v[26:29], v[134:137], v[204:207], v[26:29]
	v_mfma_f32_16x16x32_bf16 v[22:25], v[126:129], v[212:215], v[22:25]
	v_mfma_f32_16x16x32_bf16 v[10:13], v[134:137], v[212:215], v[10:13]
	s_setprio 2
	s_setprio 0
	v_mfma_f32_16x16x32_bf16 v[50:53], v[162:165], v[184:187], v[50:53]
	v_mfma_f32_16x16x32_bf16 v[46:49], v[176:179], v[184:187], v[46:49]
	v_mfma_f32_16x16x32_bf16 v[34:37], v[162:165], v[192:195], v[34:37]
	v_mfma_f32_16x16x32_bf16 v[30:33], v[176:179], v[192:195], v[30:33]
	v_mfma_f32_16x16x32_bf16 v[18:21], v[162:165], v[200:203], v[18:21]
	v_mfma_f32_16x16x32_bf16 v[14:17], v[176:179], v[200:203], v[14:17]
	v_mfma_f32_16x16x32_bf16 v[6:9], v[162:165], v[208:211], v[6:9]
	v_mfma_f32_16x16x32_bf16 v[2:5], v[176:179], v[208:211], v[2:5]
	v_mfma_f32_16x16x32_bf16 v[50:53], v[172:175], v[188:191], v[50:53]
	v_mfma_f32_16x16x32_bf16 v[46:49], v[180:183], v[188:191], v[46:49]
	v_mfma_f32_16x16x32_bf16 v[34:37], v[172:175], v[196:199], v[34:37]
	v_mfma_f32_16x16x32_bf16 v[30:33], v[180:183], v[196:199], v[30:33]
	v_mfma_f32_16x16x32_bf16 v[18:21], v[172:175], v[204:207], v[18:21]
	v_mfma_f32_16x16x32_bf16 v[14:17], v[180:183], v[204:207], v[14:17]
	v_mfma_f32_16x16x32_bf16 v[6:9], v[172:175], v[212:215], v[6:9]
	v_mfma_f32_16x16x32_bf16 v[2:5], v[180:183], v[212:215], v[2:5]
	s_setprio 2
	s_barrier
	s_add_i32 s68, s68, 2
	s_add_u32 s66, s66, 0x100
	s_addc_u32 s67, s67, 0
	s_cmp_gt_u32 s68, 41
	s_mov_b64 s[16:17], s[18:19]
	s_cbranch_scc0 .LBB0_1143
	s_and_b64 vcc, exec, s[12:13]
	s_cbranch_vccz .LBB0_1146
	s_barrier

; #define PG8_STAGE(bufoff, gbase, voff) do { _Pragma("unroll") for (int _i = 0; _i < 2; ++_i) \
;         __builtin_amdgcn_global_load_lds((const unsigned*)((const char*)(gbase) + (voff)[_i]), (LAS unsigned*)(lds + (bufoff) + ldsw + _i * 8192), 16, 0, 0); } while (0)
; #define PG8_LDA(dst, b, h) do { _Pragma("unroll") for (int m = 0; m < 4; ++m) _Pragma("unroll") for (int k = 0; k < 2; ++k) dst[m][k] = *(const LAS bf16x8*)(lds + PG8_SA(b, h) + aoff + m * 2048 + k * 1024); } while (0)
; #define PG8_LDB(dst, b, h) do { _Pragma("unroll") for (int n = 0; n < 2; ++n) _Pragma("unroll") for (int k = 0; k < 2; ++k) dst[n][k] = *(const LAS bf16x8*)(lds + PG8_SB(b, h) + boff + n * 2048 + k * 1024); } while (0)
; #define PG8_MMA(ai, bj, At, Bt) do { __builtin_amdgcn_s_setprio(1); _Pragma("unroll") for (int m = 0; m < 4; ++m) _Pragma("unroll") for (int n = 0; n < 2; ++n) _Pragma("unroll") for (int k = 0; k < 2; ++k) \
;         acc[ai][bj][m][n] = __builtin_amdgcn_mfma_f32_16x16x32_bf16(Bt[n][k], At[m][k], acc[ai][bj][m][n], 0, 0, 0); __builtin_amdgcn_s_setprio(0); } while (0)
; #define PG8_WAIT_V(n) asm volatile("s_waitcnt vmcnt(" #n ")" ::: "memory")
; #define PG8_WAIT_L(n) asm volatile("s_waitcnt lgkmcnt(" #n ")" ::: "memory")
; #define PG8_BAR __builtin_amdgcn_s_barrier()
; #define PG8_SCHED __builtin_amdgcn_sched_barrier(0)
; template <class Epi>
; __device__ __forceinline__ void gemm_phase(LAS unsigned char* lds, const Gemm g, int G, int c, const Epi& E) {
;     ...
;             const bool last = (t == nt - 2);
;             const char* a1 = cA + (size_t)(t + 1) * kstep;
;             const char* a2 = last ? nA : cA + (size_t)(t + 2) * kstep; const char* b2 = last ? nB : cB + (size_t)(t + 2) * kstep;
;             const char* a3 = a2 + kstep; const char* b3 = b2 + kstep;
;             PG8_LDB(B0, 0, 0); PG8_LDB(B1, 0, 1); PG8_SCHED; PG8_LDA(At, 0, 0); PG8_STAGE(PG8_SA(1, 1), a1 + hstepA, voffA);
;             PG8_WAIT_V(8); PG8_WAIT_L(0); PG8_BAR; PG8_MMA(0, 0, At, B0); PG8_MMA(0, 1, At, B1); PG8_BAR; PG8_SCHED;
;             PG8_LDA(At, 0, 1); PG8_STAGE(PG8_SB(0, 0), b2, voffB); PG8_STAGE(PG8_SB(0, 1), b2 + hstepB, voffB); PG8_STAGE(PG8_SA(0, 0), a2, voffA);
.LBB0_1297:
	ds_read_b128 v[146:149], v152
	ds_read_b128 v[158:161], v152 offset:1024
	ds_read_b128 v[162:165], v152 offset:2048
	ds_read_b128 v[166:169], v152 offset:3072
	ds_read_b128 v[170:173], v153
	ds_read_b128 v[174:177], v153 offset:1024
	ds_read_b128 v[178:181], v153 offset:2048
	ds_read_b128 v[182:185], v153 offset:3072
	ds_read_b128 v[186:189], v154
	ds_read_b128 v[190:193], v154 offset:1024
	ds_read_b128 v[194:197], v154 offset:2048
	ds_read_b128 v[198:201], v154 offset:3072
	ds_read_b128 v[202:205], v154 offset:4096
	ds_read_b128 v[206:209], v154 offset:5120
	ds_read_b128 v[210:213], v154 offset:6144
	ds_read_b128 v[214:217], v154 offset:7168
	s_add_u32 s33, s4, 0xfffc0080
	s_addc_u32 s46, s5, -1
	s_cmp_eq_u32 s81, 12
	s_cselect_b32 s49, s43, s46
	s_cselect_b32 s48, s42, s33
	s_cselect_b32 s47, s7, s80
	s_cselect_b32 s46, s39, s41
	v_lshl_add_u64 v[218:219], s[4:5], 0, v[138:139]
	s_add_i32 m0, s11, 0xc000
	s_nop 0
	global_load_lds_dwordx4 v[218:219], off
	v_lshl_add_u64 v[218:219], s[4:5], 0, v[140:141]
	s_add_i32 m0, s11, 0xe000
	s_nop 0
	global_load_lds_dwordx4 v[218:219], off
	s_waitcnt vmcnt(8)
	s_waitcnt lgkmcnt(0)
	s_barrier
	s_setprio 0
	v_mfma_f32_16x16x32_bf16 v[126:129], v[146:149], v[186:189], v[126:129]
	v_mfma_f32_16x16x32_bf16 v[122:125], v[162:165], v[186:189], v[122:125]
	v_mfma_f32_16x16x32_bf16 v[110:113], v[146:149], v[194:197], v[110:113]
	v_mfma_f32_16x16x32_bf16 v[106:109], v[162:165], v[194:197], v[106:109]
	v_mfma_f32_16x16x32_bf16 v[94:97], v[146:149], v[202:205], v[94:97]
	v_mfma_f32_16x16x32_bf16 v[90:93], v[162:165], v[202:205], v[90:93]
	v_mfma_f32_16x16x32_bf16 v[78:81], v[146:149], v[210:213], v[78:81]
	v_mfma_f32_16x16x32_bf16 v[74:77], v[162:165], v[210:213], v[74:77]
	v_mfma_f32_16x16x32_bf16 v[126:129], v[158:161], v[190:193], v[126:129]
	v_mfma_f32_16x16x32_bf16 v[122:125], v[166:169], v[190:193], v[122:125]
	v_mfma_f32_16x16x32_bf16 v[110:113], v[158:161], v[198:201], v[110:113]
	v_mfma_f32_16x16x32_bf16 v[106:109], v[166:169], v[198:201], v[106:109]
	v_mfma_f32_16x16x32_bf16 v[94:97], v[158:161], v[206:209], v[94:97]
	v_mfma_f32_16x16x32_bf16 v[90:93], v[166:169], v[206:209], v[90:93]
	v_mfma_f32_16x16x32_bf16 v[78:81], v[158:161], v[214:217], v[78:81]
	v_mfma_f32_16x16x32_bf16 v[74:77], v[166:169], v[214:217], v[74:77]
	s_setprio 2
	s_setprio 0
	v_mfma_f32_16x16x32_bf16 v[118:121], v[170:173], v[186:189], v[118:121]
	v_mfma_f32_16x16x32_bf16 v[114:117], v[178:181], v[186:189], v[114:117]
	v_mfma_f32_16x16x32_bf16 v[102:105], v[170:173], v[194:197], v[102:105]
	v_mfma_f32_16x16x32_bf16 v[98:101], v[178:181], v[194:197], v[98:101]
	v_mfma_f32_16x16x32_bf16 v[86:89], v[170:173], v[202:205], v[86:89]
	v_mfma_f32_16x16x32_bf16 v[82:85], v[178:181], v[202:205], v[82:85]
	v_mfma_f32_16x16x32_bf16 v[70:73], v[170:173], v[210:213], v[70:73]
	v_mfma_f32_16x16x32_bf16 v[66:69], v[178:181], v[210:213], v[66:69]
	v_mfma_f32_16x16x32_bf16 v[118:121], v[174:177], v[190:193], v[118:121]
	v_mfma_f32_16x16x32_bf16 v[114:117], v[182:185], v[190:193], v[114:117]
	v_mfma_f32_16x16x32_bf16 v[102:105], v[174:177], v[198:201], v[102:105]
	v_mfma_f32_16x16x32_bf16 v[98:101], v[182:185], v[198:201], v[98:101]
	v_mfma_f32_16x16x32_bf16 v[86:89], v[174:177], v[206:209], v[86:89]
	v_mfma_f32_16x16x32_bf16 v[82:85], v[182:185], v[206:209], v[82:85]
	v_mfma_f32_16x16x32_bf16 v[70:73], v[174:177], v[214:217], v[70:73]
	v_mfma_f32_16x16x32_bf16 v[66:69], v[182:185], v[214:217], v[66:69]
	s_setprio 2
	s_barrier
	ds_read_b128 v[186:189], v154 offset:16384
	ds_read_b128 v[190:193], v154 offset:17408
	ds_read_b128 v[194:197], v154 offset:18432
	ds_read_b128 v[198:201], v154 offset:19456
	ds_read_b128 v[202:205], v154 offset:20480
	ds_read_b128 v[206:209], v154 offset:21504
	ds_read_b128 v[210:213], v154 offset:22528
	ds_read_b128 v[214:217], v154 offset:23552
	s_add_i32 s33, s71, s56
	v_lshl_add_u64 v[218:219], s[46:47], 0, v[132:133]
	s_mov_b32 m0, s33
	s_nop 0
	global_load_lds_dwordx4 v[218:219], off
	s_add_i32 m0, s33, 0x2000
	s_add_u32 s62, s46, 0x40000
	v_lshl_add_u64 v[220:221], s[46:47], 0, v[136:137]
	s_addc_u32 s63, s47, 0
	s_add_i32 s33, s72, s56
	global_load_lds_dwordx4 v[220:221], off
	v_lshl_add_u64 v[222:223], s[62:63], 0, v[132:133]
	s_mov_b32 m0, s33
	v_lshl_add_u64 v[224:225], s[48:49], 0, v[134:135]
	global_load_lds_dwordx4 v[222:223], off
	v_lshl_add_u64 v[222:223], s[62:63], 0, v[136:137]
	s_add_i32 m0, s33, 0x2000
	s_nop 0
	global_load_lds_dwordx4 v[222:223], off
	v_lshl_add_u64 v[222:223], s[48:49], 0, v[130:131]
	s_mov_b32 m0, s11
	s_nop 0
	global_load_lds_dwordx4 v[222:223], off
	s_mov_b32 m0, s57
	s_nop 0
	global_load_lds_dwordx4 v[224:225], off
	s_waitcnt vmcnt(8)
	s_waitcnt lgkmcnt(0)
	s_barrier
; #define PG8_STAGE(bufoff, gbase, voff) do { _Pragma("unroll") for (int _i = 0; _i < 2; ++_i) \
;         __builtin_amdgcn_global_load_lds((const unsigned*)((const char*)(gbase) + (voff)[_i]), (LAS unsigned*)(lds + (bufoff) + ldsw + _i * 8192), 16, 0, 0); } while (0)
; #define PG8_LDA(dst, b, h) do { _Pragma("unroll") for (int m = 0; m < 4; ++m) _Pragma("unroll") for (int k = 0; k < 2; ++k) dst[m][k] = *(const LAS bf16x8*)(lds + PG8_SA(b, h) + aoff + m * 2048 + k * 1024); } while (0)
; #define PG8_LDB(dst, b, h) do { _Pragma("unroll") for (int n = 0; n < 2; ++n) _Pragma("unroll") for (int k = 0; k < 2; ++k) dst[n][k] = *(const LAS bf16x8*)(lds + PG8_SB(b, h) + boff + n * 2048 + k * 1024); } while (0)
; #define PG8_MMA(ai, bj, At, Bt) do { __builtin_amdgcn_s_setprio(1); _Pragma("unroll") for (int m = 0; m < 4; ++m) _Pragma("unroll") for (int n = 0; n < 2; ++n) _Pragma("unroll") for (int k = 0; k < 2; ++k) \
;         acc[ai][bj][m][n] = __builtin_amdgcn_mfma_f32_16x16x32_bf16(Bt[n][k], At[m][k], acc[ai][bj][m][n], 0, 0, 0); __builtin_amdgcn_s_setprio(0); } while (0)
; #define PG8_WAIT_V(n) asm volatile("s_waitcnt vmcnt(" #n ")" ::: "memory")
; #define PG8_WAIT_L(n) asm volatile("s_waitcnt lgkmcnt(" #n ")" ::: "memory")
; #define PG8_BAR __builtin_amdgcn_s_barrier()
; #define PG8_SCHED __builtin_amdgcn_sched_barrier(0)
; template <class Epi>
; __device__ __forceinline__ void gemm_phase(LAS unsigned char* lds, const Gemm g, int G, int c, const Epi& E) {
;     ...
;             PG8_WAIT_V(8); PG8_WAIT_L(0); PG8_BAR; PG8_MMA(1, 0, At, B0); PG8_MMA(1, 1, At, B1); PG8_BAR; PG8_SCHED;
;             PG8_LDB(B0, 1, 0); PG8_LDB(B1, 1, 1); PG8_SCHED; PG8_LDA(At, 1, 0); PG8_STAGE(PG8_SA(0, 1), a2 + hstepA, voffA);
;             PG8_WAIT_V(8); PG8_WAIT_L(0); PG8_BAR; PG8_MMA(0, 0, At, B0); PG8_MMA(0, 1, At, B1); PG8_BAR; PG8_SCHED;
	s_setprio 0
	v_mfma_f32_16x16x32_bf16 v[62:65], v[146:149], v[186:189], v[62:65]
	v_mfma_f32_16x16x32_bf16 v[58:61], v[162:165], v[186:189], v[58:61]
	v_mfma_f32_16x16x32_bf16 v[46:49], v[146:149], v[194:197], v[46:49]
	v_mfma_f32_16x16x32_bf16 v[42:45], v[162:165], v[194:197], v[42:45]
	v_mfma_f32_16x16x32_bf16 v[30:33], v[146:149], v[202:205], v[30:33]
	v_mfma_f32_16x16x32_bf16 v[26:29], v[162:165], v[202:205], v[26:29]
	v_mfma_f32_16x16x32_bf16 v[14:17], v[146:149], v[210:213], v[14:17]
	v_mfma_f32_16x16x32_bf16 v[10:13], v[162:165], v[210:213], v[10:13]
	v_mfma_f32_16x16x32_bf16 v[62:65], v[158:161], v[190:193], v[62:65]
	v_mfma_f32_16x16x32_bf16 v[58:61], v[166:169], v[190:193], v[58:61]
	v_mfma_f32_16x16x32_bf16 v[46:49], v[158:161], v[198:201], v[46:49]
	v_mfma_f32_16x16x32_bf16 v[42:45], v[166:169], v[198:201], v[42:45]
	v_mfma_f32_16x16x32_bf16 v[30:33], v[158:161], v[206:209], v[30:33]
	v_mfma_f32_16x16x32_bf16 v[26:29], v[166:169], v[206:209], v[26:29]
	v_mfma_f32_16x16x32_bf16 v[14:17], v[158:161], v[214:217], v[14:17]
	v_mfma_f32_16x16x32_bf16 v[10:13], v[166:169], v[214:217], v[10:13]
	s_setprio 2
	s_setprio 0
	v_mfma_f32_16x16x32_bf16 v[54:57], v[170:173], v[186:189], v[54:57]
	v_mfma_f32_16x16x32_bf16 v[50:53], v[178:181], v[186:189], v[50:53]
	v_mfma_f32_16x16x32_bf16 v[38:41], v[170:173], v[194:197], v[38:41]
	v_mfma_f32_16x16x32_bf16 v[34:37], v[178:181], v[194:197], v[34:37]
	v_mfma_f32_16x16x32_bf16 v[22:25], v[170:173], v[202:205], v[22:25]
	v_mfma_f32_16x16x32_bf16 v[18:21], v[178:181], v[202:205], v[18:21]
	v_mfma_f32_16x16x32_bf16 v[6:9], v[170:173], v[210:213], v[6:9]
	v_mfma_f32_16x16x32_bf16 v[2:5], v[178:181], v[210:213], v[2:5]
	v_mfma_f32_16x16x32_bf16 v[54:57], v[174:177], v[190:193], v[54:57]
	v_mfma_f32_16x16x32_bf16 v[50:53], v[182:185], v[190:193], v[50:53]
	v_mfma_f32_16x16x32_bf16 v[38:41], v[174:177], v[198:201], v[38:41]
	v_mfma_f32_16x16x32_bf16 v[34:37], v[182:185], v[198:201], v[34:37]
	v_mfma_f32_16x16x32_bf16 v[22:25], v[174:177], v[206:209], v[22:25]
	v_mfma_f32_16x16x32_bf16 v[18:21], v[182:185], v[206:209], v[18:21]
	v_mfma_f32_16x16x32_bf16 v[6:9], v[174:177], v[214:217], v[6:9]
	v_mfma_f32_16x16x32_bf16 v[2:5], v[182:185], v[214:217], v[2:5]
	s_setprio 2
	s_barrier
	s_add_i32 s33, 0, 0x18000
	v_add_u32_e32 v157, s33, v151
	s_add_i32 s62, 0, 0x1c000
	ds_read_b128 v[146:149], v157
	ds_read_b128 v[158:161], v157 offset:1024
	ds_read_b128 v[162:165], v157 offset:2048
	ds_read_b128 v[166:169], v157 offset:3072
	v_add_u32_e32 v157, s62, v151
	ds_read_b128 v[170:173], v157
	ds_read_b128 v[174:177], v157 offset:1024
	ds_read_b128 v[178:181], v157 offset:2048
	ds_read_b128 v[182:185], v157 offset:3072
	ds_read_b128 v[186:189], v154 offset:32768
	ds_read_b128 v[190:193], v154 offset:33792
	ds_read_b128 v[194:197], v154 offset:34816
	ds_read_b128 v[198:201], v154 offset:35840
	ds_read_b128 v[202:205], v154 offset:36864
	ds_read_b128 v[206:209], v154 offset:37888
	ds_read_b128 v[210:213], v154 offset:38912
	ds_read_b128 v[214:217], v154 offset:39936
	s_add_u32 s48, s48, 0x40000
	s_addc_u32 s49, s49, 0
	s_mov_b32 m0, s58
	v_lshl_add_u64 v[226:227], s[48:49], 0, v[130:131]
	global_load_lds_dwordx4 v[226:227], off
	v_lshl_add_u64 v[226:227], s[48:49], 0, v[134:135]
	s_mov_b32 m0, s59
	s_nop 0
	global_load_lds_dwordx4 v[226:227], off
	s_waitcnt vmcnt(8)
	s_waitcnt lgkmcnt(0)
	s_barrier
	s_setprio 0
	v_mfma_f32_16x16x32_bf16 v[126:129], v[146:149], v[186:189], v[126:129]
	v_mfma_f32_16x16x32_bf16 v[122:125], v[162:165], v[186:189], v[122:125]
	v_mfma_f32_16x16x32_bf16 v[110:113], v[146:149], v[194:197], v[110:113]
	v_mfma_f32_16x16x32_bf16 v[106:109], v[162:165], v[194:197], v[106:109]
	v_mfma_f32_16x16x32_bf16 v[94:97], v[146:149], v[202:205], v[94:97]
	v_mfma_f32_16x16x32_bf16 v[90:93], v[162:165], v[202:205], v[90:93]
	v_mfma_f32_16x16x32_bf16 v[78:81], v[146:149], v[210:213], v[78:81]
	v_mfma_f32_16x16x32_bf16 v[74:77], v[162:165], v[210:213], v[74:77]
	v_mfma_f32_16x16x32_bf16 v[126:129], v[158:161], v[190:193], v[126:129]
	v_mfma_f32_16x16x32_bf16 v[122:125], v[166:169], v[190:193], v[122:125]
	v_mfma_f32_16x16x32_bf16 v[110:113], v[158:161], v[198:201], v[110:113]
	v_mfma_f32_16x16x32_bf16 v[106:109], v[166:169], v[198:201], v[106:109]
	v_mfma_f32_16x16x32_bf16 v[94:97], v[158:161], v[206:209], v[94:97]
	v_mfma_f32_16x16x32_bf16 v[90:93], v[166:169], v[206:209], v[90:93]
	v_mfma_f32_16x16x32_bf16 v[78:81], v[158:161], v[214:217], v[78:81]
	v_mfma_f32_16x16x32_bf16 v[74:77], v[166:169], v[214:217], v[74:77]
	s_setprio 2
	s_setprio 0
	v_mfma_f32_16x16x32_bf16 v[118:121], v[170:173], v[186:189], v[118:121]
	v_mfma_f32_16x16x32_bf16 v[114:117], v[178:181], v[186:189], v[114:117]
	v_mfma_f32_16x16x32_bf16 v[102:105], v[170:173], v[194:197], v[102:105]
	v_mfma_f32_16x16x32_bf16 v[98:101], v[178:181], v[194:197], v[98:101]
	v_mfma_f32_16x16x32_bf16 v[86:89], v[170:173], v[202:205], v[86:89]
	v_mfma_f32_16x16x32_bf16 v[82:85], v[178:181], v[202:205], v[82:85]
	v_mfma_f32_16x16x32_bf16 v[70:73], v[170:173], v[210:213], v[70:73]
	v_mfma_f32_16x16x32_bf16 v[66:69], v[178:181], v[210:213], v[66:69]
	v_mfma_f32_16x16x32_bf16 v[118:121], v[174:177], v[190:193], v[118:121]
	v_mfma_f32_16x16x32_bf16 v[114:117], v[182:185], v[190:193], v[114:117]
	v_mfma_f32_16x16x32_bf16 v[102:105], v[174:177], v[198:201], v[102:105]
	v_mfma_f32_16x16x32_bf16 v[98:101], v[182:185], v[198:201], v[98:101]
	v_mfma_f32_16x16x32_bf16 v[86:89], v[174:177], v[206:209], v[86:89]
	v_mfma_f32_16x16x32_bf16 v[82:85], v[182:185], v[206:209], v[82:85]
	v_mfma_f32_16x16x32_bf16 v[70:73], v[174:177], v[214:217], v[70:73]
	v_mfma_f32_16x16x32_bf16 v[66:69], v[182:185], v[214:217], v[66:69]
	s_setprio 2
	s_barrier
; #define PG8_STAGE(bufoff, gbase, voff) do { _Pragma("unroll") for (int _i = 0; _i < 2; ++_i) \
;         __builtin_amdgcn_global_load_lds((const unsigned*)((const char*)(gbase) + (voff)[_i]), (LAS unsigned*)(lds + (bufoff) + ldsw + _i * 8192), 16, 0, 0); } while (0)
; #define PG8_LDA(dst, b, h) do { _Pragma("unroll") for (int m = 0; m < 4; ++m) _Pragma("unroll") for (int k = 0; k < 2; ++k) dst[m][k] = *(const LAS bf16x8*)(lds + PG8_SA(b, h) + aoff + m * 2048 + k * 1024); } while (0)
; #define PG8_MMA(ai, bj, At, Bt) do { __builtin_amdgcn_s_setprio(1); _Pragma("unroll") for (int m = 0; m < 4; ++m) _Pragma("unroll") for (int n = 0; n < 2; ++n) _Pragma("unroll") for (int k = 0; k < 2; ++k) \
;         acc[ai][bj][m][n] = __builtin_amdgcn_mfma_f32_16x16x32_bf16(Bt[n][k], At[m][k], acc[ai][bj][m][n], 0, 0, 0); __builtin_amdgcn_s_setprio(0); } while (0)
; #define PG8_WAIT_V(n) asm volatile("s_waitcnt vmcnt(" #n ")" ::: "memory")
; #define PG8_WAIT_L(n) asm volatile("s_waitcnt lgkmcnt(" #n ")" ::: "memory")
; #define PG8_BAR __builtin_amdgcn_s_barrier()
; #define PG8_SCHED __builtin_amdgcn_sched_barrier(0)
; template <class Epi>
; __device__ __forceinline__ void gemm_phase(LAS unsigned char* lds, const Gemm g, int G, int c, const Epi& E) {
;     ...
;             PG8_LDA(At, 1, 1); PG8_STAGE(PG8_SB(1, 0), b3, voffB); PG8_STAGE(PG8_SB(1, 1), b3 + hstepB, voffB); PG8_STAGE(PG8_SA(1, 0), a3, voffA);
;             PG8_WAIT_V(8); PG8_WAIT_L(0); PG8_BAR; PG8_MMA(1, 0, At, B0); PG8_MMA(1, 1, At, B1); PG8_BAR; PG8_SCHED;
;         }
	ds_read_b128 v[186:189], v154 offset:49152
	ds_read_b128 v[190:193], v154 offset:50176
	ds_read_b128 v[194:197], v154 offset:51200
	ds_read_b128 v[198:201], v154 offset:52224
	ds_read_b128 v[202:205], v154 offset:53248
	ds_read_b128 v[206:209], v154 offset:54272
	ds_read_b128 v[210:213], v154 offset:55296
	ds_read_b128 v[214:217], v154 offset:56320
	s_add_i32 s33, s33, s56
	v_lshl_add_u64 v[218:219], v[218:219], 0, s[20:21]
	s_mov_b32 m0, s33
	s_nop 0
	global_load_lds_dwordx4 v[218:219], off
	s_add_i32 m0, s33, 0x2000
	s_add_u32 s46, s46, 0x40080
	v_lshl_add_u64 v[218:219], v[220:221], 0, s[20:21]
	s_addc_u32 s47, s47, 0
	s_add_i32 s33, s62, s56
	global_load_lds_dwordx4 v[218:219], off
	v_lshl_add_u64 v[218:219], s[46:47], 0, v[132:133]
	s_mov_b32 m0, s33
	s_nop 0
	global_load_lds_dwordx4 v[218:219], off
	v_lshl_add_u64 v[218:219], s[46:47], 0, v[136:137]
	s_add_i32 m0, s33, 0x2000
	s_nop 0
	global_load_lds_dwordx4 v[218:219], off
	v_lshl_add_u64 v[218:219], v[222:223], 0, s[20:21]
	s_mov_b32 m0, s67
	s_nop 0
	global_load_lds_dwordx4 v[218:219], off
	v_lshl_add_u64 v[218:219], v[224:225], 0, s[20:21]
	s_mov_b32 m0, s68
	s_nop 0
	global_load_lds_dwordx4 v[218:219], off
	s_waitcnt vmcnt(8)
	s_waitcnt lgkmcnt(0)
	s_barrier
	s_setprio 0
	v_mfma_f32_16x16x32_bf16 v[62:65], v[146:149], v[186:189], v[62:65]
	v_mfma_f32_16x16x32_bf16 v[58:61], v[162:165], v[186:189], v[58:61]
	v_mfma_f32_16x16x32_bf16 v[46:49], v[146:149], v[194:197], v[46:49]
	v_mfma_f32_16x16x32_bf16 v[42:45], v[162:165], v[194:197], v[42:45]
	v_mfma_f32_16x16x32_bf16 v[30:33], v[146:149], v[202:205], v[30:33]
	v_mfma_f32_16x16x32_bf16 v[26:29], v[162:165], v[202:205], v[26:29]
	v_mfma_f32_16x16x32_bf16 v[14:17], v[146:149], v[210:213], v[14:17]
	v_mfma_f32_16x16x32_bf16 v[10:13], v[162:165], v[210:213], v[10:13]
	v_mfma_f32_16x16x32_bf16 v[62:65], v[158:161], v[190:193], v[62:65]
	v_mfma_f32_16x16x32_bf16 v[58:61], v[166:169], v[190:193], v[58:61]
	v_mfma_f32_16x16x32_bf16 v[46:49], v[158:161], v[198:201], v[46:49]
	v_mfma_f32_16x16x32_bf16 v[42:45], v[166:169], v[198:201], v[42:45]
	v_mfma_f32_16x16x32_bf16 v[30:33], v[158:161], v[206:209], v[30:33]
	v_mfma_f32_16x16x32_bf16 v[26:29], v[166:169], v[206:209], v[26:29]
	v_mfma_f32_16x16x32_bf16 v[14:17], v[158:161], v[214:217], v[14:17]
	v_mfma_f32_16x16x32_bf16 v[10:13], v[166:169], v[214:217], v[10:13]
	s_setprio 2
	s_setprio 0
	v_mfma_f32_16x16x32_bf16 v[54:57], v[170:173], v[186:189], v[54:57]
	v_mfma_f32_16x16x32_bf16 v[50:53], v[178:181], v[186:189], v[50:53]
	v_mfma_f32_16x16x32_bf16 v[38:41], v[170:173], v[194:197], v[38:41]
	v_mfma_f32_16x16x32_bf16 v[34:37], v[178:181], v[194:197], v[34:37]
	v_mfma_f32_16x16x32_bf16 v[22:25], v[170:173], v[202:205], v[22:25]
	v_mfma_f32_16x16x32_bf16 v[18:21], v[178:181], v[202:205], v[18:21]
	v_mfma_f32_16x16x32_bf16 v[6:9], v[170:173], v[210:213], v[6:9]
	v_mfma_f32_16x16x32_bf16 v[2:5], v[178:181], v[210:213], v[2:5]
	v_mfma_f32_16x16x32_bf16 v[54:57], v[174:177], v[190:193], v[54:57]
	v_mfma_f32_16x16x32_bf16 v[50:53], v[182:185], v[190:193], v[50:53]
	v_mfma_f32_16x16x32_bf16 v[38:41], v[174:177], v[198:201], v[38:41]
	v_mfma_f32_16x16x32_bf16 v[34:37], v[182:185], v[198:201], v[34:37]
	v_mfma_f32_16x16x32_bf16 v[22:25], v[174:177], v[206:209], v[22:25]
	v_mfma_f32_16x16x32_bf16 v[18:21], v[182:185], v[206:209], v[18:21]
	v_mfma_f32_16x16x32_bf16 v[6:9], v[174:177], v[214:217], v[6:9]
	v_mfma_f32_16x16x32_bf16 v[2:5], v[182:185], v[214:217], v[2:5]
	s_setprio 2
	s_barrier
	s_add_i32 s81, s81, 2
	s_add_u32 s4, s4, 0x100
	s_addc_u32 s5, s5, 0
	s_add_u32 s41, s41, 0x100
	s_addc_u32 s80, s80, 0
	s_cmp_gt_u32 s81, 13
	s_cbranch_scc0 .LBB0_1297
	s_and_b64 vcc, exec, s[22:23]
	s_cbranch_vccz .LBB0_1300
	s_barrier

; #define PG8_STAGE(bufoff, gbase, voff) do { _Pragma("unroll") for (int _i = 0; _i < 2; ++_i) \
;         __builtin_amdgcn_global_load_lds((const unsigned*)((const char*)(gbase) + (voff)[_i]), (LAS unsigned*)(lds + (bufoff) + ldsw + _i * 8192), 16, 0, 0); } while (0)
; #define PG8_LDA(dst, b, h) do { _Pragma("unroll") for (int m = 0; m < 4; ++m) _Pragma("unroll") for (int k = 0; k < 2; ++k) dst[m][k] = *(const LAS bf16x8*)(lds + PG8_SA(b, h) + aoff + m * 2048 + k * 1024); } while (0)
; #define PG8_LDB(dst, b, h) do { _Pragma("unroll") for (int n = 0; n < 2; ++n) _Pragma("unroll") for (int k = 0; k < 2; ++k) dst[n][k] = *(const LAS bf16x8*)(lds + PG8_SB(b, h) + boff + n * 2048 + k * 1024); } while (0)
; #define PG8_MMA(ai, bj, At, Bt) do { __builtin_amdgcn_s_setprio(1); _Pragma("unroll") for (int m = 0; m < 4; ++m) _Pragma("unroll") for (int n = 0; n < 2; ++n) _Pragma("unroll") for (int k = 0; k < 2; ++k) \
;         acc[ai][bj][m][n] = __builtin_amdgcn_mfma_f32_16x16x32_bf16(Bt[n][k], At[m][k], acc[ai][bj][m][n], 0, 0, 0); __builtin_amdgcn_s_setprio(0); } while (0)
; #define PG8_WAIT_V(n) asm volatile("s_waitcnt vmcnt(" #n ")" ::: "memory")
; #define PG8_WAIT_L(n) asm volatile("s_waitcnt lgkmcnt(" #n ")" ::: "memory")
; #define PG8_BAR __builtin_amdgcn_s_barrier()
; #define PG8_SCHED __builtin_amdgcn_sched_barrier(0)
; template <class Epi>
; __device__ __forceinline__ void gemm_phase(LAS unsigned char* lds, const Gemm g, int G, int c, const Epi& E) {
;     ...
;             const bool last = (t == nt - 2);
;             const char* a1 = cA + (size_t)(t + 1) * kstep;
;             const char* a2 = last ? nA : cA + (size_t)(t + 2) * kstep; const char* b2 = last ? nB : cB + (size_t)(t + 2) * kstep;
;             const char* a3 = a2 + kstep; const char* b3 = b2 + kstep;
;             PG8_LDB(B0, 0, 0); PG8_LDB(B1, 0, 1); PG8_SCHED; PG8_LDA(At, 0, 0); PG8_STAGE(PG8_SA(1, 1), a1 + hstepA, voffA);
;             PG8_WAIT_V(8); PG8_WAIT_L(0); PG8_BAR; PG8_MMA(0, 0, At, B0); PG8_MMA(0, 1, At, B1); PG8_BAR; PG8_SCHED;
;             PG8_LDA(At, 0, 1); PG8_STAGE(PG8_SB(0, 0), b2, voffB); PG8_STAGE(PG8_SB(0, 1), b2 + hstepB, voffB); PG8_STAGE(PG8_SA(0, 0), a2, voffA);
.LBB0_1429:
	ds_read_b128 v[142:145], v148
	ds_read_b128 v[152:155], v148 offset:1024
	ds_read_b128 v[156:159], v148 offset:2048
	ds_read_b128 v[160:163], v148 offset:3072
	ds_read_b128 v[164:167], v149
	ds_read_b128 v[168:171], v149 offset:1024
	ds_read_b128 v[172:175], v149 offset:2048
	ds_read_b128 v[176:179], v149 offset:3072
	ds_read_b128 v[180:183], v150
	ds_read_b128 v[184:187], v150 offset:1024
	ds_read_b128 v[188:191], v150 offset:2048
	ds_read_b128 v[192:195], v150 offset:3072
	ds_read_b128 v[196:199], v150 offset:4096
	ds_read_b128 v[200:203], v150 offset:5120
	ds_read_b128 v[204:207], v150 offset:6144
	ds_read_b128 v[208:211], v150 offset:7168
	s_add_u32 s33, s18, s13
	s_addc_u32 s42, s19, 0
	s_add_u32 s38, s33, 0x100
	s_addc_u32 s39, s42, 0
	s_and_b64 s[24:25], s[22:23], exec
	s_cselect_b32 s39, s5, s39
	s_cselect_b32 s38, s4, s38
	s_add_u32 s13, s16, s13
	s_addc_u32 s24, s17, 0
	s_add_u32 s13, s13, 0x100
	s_addc_u32 s24, s24, 0
	s_and_b64 s[22:23], s[22:23], exec
	s_cselect_b32 s41, s15, s24
	s_cselect_b32 s40, s14, s13
	s_add_u32 s44, s33, 0xb0080
	s_addc_u32 s45, s42, 0
	s_add_i32 s65, s72, s48
	s_add_i32 m0, s49, 0xc000
	s_add_i32 s85, s49, 0xe000
	s_add_i32 s62, s65, 0x2000
	s_add_u32 s42, s40, 0xb0000
	s_addc_u32 s43, s41, 0
	s_add_i32 s64, s73, s48
	s_add_i32 s63, s64, 0x2000
	s_add_i32 s84, 0, 0x18000
	s_add_i32 s33, 0, 0x1c000
	s_add_u32 s24, s38, 0xb0000
	s_addc_u32 s25, s39, 0
	s_add_i32 s83, s84, s48
	s_add_i32 s13, s83, 0x2000
	s_add_u32 s22, s40, 0xb0080
	s_addc_u32 s23, s41, 0
	s_add_i32 s75, s33, s48
	s_add_i32 s74, s75, 0x2000
	v_lshl_add_u64 v[212:213], s[44:45], 0, v[136:137]
	global_load_lds_dwordx4 v[212:213], off
	v_lshl_add_u64 v[212:213], s[44:45], 0, v[132:133]
	s_mov_b32 m0, s85
	s_nop 0
	global_load_lds_dwordx4 v[212:213], off
	s_waitcnt vmcnt(8)
	s_waitcnt lgkmcnt(0)
	s_barrier
	s_setprio 0
	v_mfma_f32_16x16x32_bf16 v[126:129], v[142:145], v[180:183], v[126:129]
	v_mfma_f32_16x16x32_bf16 v[122:125], v[156:159], v[180:183], v[122:125]
	v_mfma_f32_16x16x32_bf16 v[118:121], v[142:145], v[188:191], v[118:121]
	v_mfma_f32_16x16x32_bf16 v[110:113], v[156:159], v[188:191], v[110:113]
	v_mfma_f32_16x16x32_bf16 v[102:105], v[142:145], v[196:199], v[102:105]
	v_mfma_f32_16x16x32_bf16 v[94:97], v[156:159], v[196:199], v[94:97]
	v_mfma_f32_16x16x32_bf16 v[86:89], v[142:145], v[204:207], v[86:89]
	v_mfma_f32_16x16x32_bf16 v[78:81], v[156:159], v[204:207], v[78:81]
	v_mfma_f32_16x16x32_bf16 v[126:129], v[152:155], v[184:187], v[126:129]
	v_mfma_f32_16x16x32_bf16 v[122:125], v[160:163], v[184:187], v[122:125]
	v_mfma_f32_16x16x32_bf16 v[118:121], v[152:155], v[192:195], v[118:121]
	v_mfma_f32_16x16x32_bf16 v[110:113], v[160:163], v[192:195], v[110:113]
	v_mfma_f32_16x16x32_bf16 v[102:105], v[152:155], v[200:203], v[102:105]
	v_mfma_f32_16x16x32_bf16 v[94:97], v[160:163], v[200:203], v[94:97]
	v_mfma_f32_16x16x32_bf16 v[86:89], v[152:155], v[208:211], v[86:89]
	v_mfma_f32_16x16x32_bf16 v[78:81], v[160:163], v[208:211], v[78:81]
	s_setprio 2
	s_setprio 0
	v_mfma_f32_16x16x32_bf16 v[114:117], v[164:167], v[180:183], v[114:117]
	v_mfma_f32_16x16x32_bf16 v[106:109], v[172:175], v[180:183], v[106:109]
	v_mfma_f32_16x16x32_bf16 v[98:101], v[164:167], v[188:191], v[98:101]
	v_mfma_f32_16x16x32_bf16 v[90:93], v[172:175], v[188:191], v[90:93]
	v_mfma_f32_16x16x32_bf16 v[82:85], v[164:167], v[196:199], v[82:85]
	v_mfma_f32_16x16x32_bf16 v[74:77], v[172:175], v[196:199], v[74:77]
	v_mfma_f32_16x16x32_bf16 v[70:73], v[164:167], v[204:207], v[70:73]
	v_mfma_f32_16x16x32_bf16 v[66:69], v[172:175], v[204:207], v[66:69]
	v_mfma_f32_16x16x32_bf16 v[114:117], v[168:171], v[184:187], v[114:117]
	v_mfma_f32_16x16x32_bf16 v[106:109], v[176:179], v[184:187], v[106:109]
	v_mfma_f32_16x16x32_bf16 v[98:101], v[168:171], v[192:195], v[98:101]
	v_mfma_f32_16x16x32_bf16 v[90:93], v[176:179], v[192:195], v[90:93]
	v_mfma_f32_16x16x32_bf16 v[82:85], v[168:171], v[200:203], v[82:85]
	v_mfma_f32_16x16x32_bf16 v[74:77], v[176:179], v[200:203], v[74:77]
	v_mfma_f32_16x16x32_bf16 v[70:73], v[168:171], v[208:211], v[70:73]
	v_mfma_f32_16x16x32_bf16 v[66:69], v[176:179], v[208:211], v[66:69]
	s_setprio 2
	s_barrier
	ds_read_b128 v[180:183], v150 offset:16384
	ds_read_b128 v[184:187], v150 offset:17408
	ds_read_b128 v[188:191], v150 offset:18432
	ds_read_b128 v[192:195], v150 offset:19456
	ds_read_b128 v[196:199], v150 offset:20480
	ds_read_b128 v[200:203], v150 offset:21504
	ds_read_b128 v[204:207], v150 offset:22528
	ds_read_b128 v[208:211], v150 offset:23552
	s_mov_b32 m0, s65
	v_lshl_add_u64 v[212:213], s[40:41], 0, v[134:135]
	global_load_lds_dwordx4 v[212:213], off
	v_lshl_add_u64 v[214:215], s[40:41], 0, v[130:131]
	s_mov_b32 m0, s62
	v_lshl_add_u64 v[216:217], s[42:43], 0, v[134:135]
	global_load_lds_dwordx4 v[214:215], off
	s_mov_b32 m0, s64
	v_lshl_add_u64 v[218:219], s[38:39], 0, v[132:133]
	global_load_lds_dwordx4 v[216:217], off
	v_lshl_add_u64 v[216:217], s[42:43], 0, v[130:131]
	s_mov_b32 m0, s63
	s_nop 0
	global_load_lds_dwordx4 v[216:217], off
	v_lshl_add_u64 v[216:217], s[38:39], 0, v[136:137]
	s_mov_b32 m0, s49
	s_nop 0
	global_load_lds_dwordx4 v[216:217], off
	s_mov_b32 m0, s52
	s_nop 0
	global_load_lds_dwordx4 v[218:219], off
	s_waitcnt vmcnt(8)
	s_waitcnt lgkmcnt(0)
	s_barrier
; #define PG8_STAGE(bufoff, gbase, voff) do { _Pragma("unroll") for (int _i = 0; _i < 2; ++_i) \
;         __builtin_amdgcn_global_load_lds((const unsigned*)((const char*)(gbase) + (voff)[_i]), (LAS unsigned*)(lds + (bufoff) + ldsw + _i * 8192), 16, 0, 0); } while (0)
; #define PG8_LDA(dst, b, h) do { _Pragma("unroll") for (int m = 0; m < 4; ++m) _Pragma("unroll") for (int k = 0; k < 2; ++k) dst[m][k] = *(const LAS bf16x8*)(lds + PG8_SA(b, h) + aoff + m * 2048 + k * 1024); } while (0)
; #define PG8_LDB(dst, b, h) do { _Pragma("unroll") for (int n = 0; n < 2; ++n) _Pragma("unroll") for (int k = 0; k < 2; ++k) dst[n][k] = *(const LAS bf16x8*)(lds + PG8_SB(b, h) + boff + n * 2048 + k * 1024); } while (0)
; #define PG8_MMA(ai, bj, At, Bt) do { __builtin_amdgcn_s_setprio(1); _Pragma("unroll") for (int m = 0; m < 4; ++m) _Pragma("unroll") for (int n = 0; n < 2; ++n) _Pragma("unroll") for (int k = 0; k < 2; ++k) \
;         acc[ai][bj][m][n] = __builtin_amdgcn_mfma_f32_16x16x32_bf16(Bt[n][k], At[m][k], acc[ai][bj][m][n], 0, 0, 0); __builtin_amdgcn_s_setprio(0); } while (0)
; #define PG8_WAIT_V(n) asm volatile("s_waitcnt vmcnt(" #n ")" ::: "memory")
; #define PG8_WAIT_L(n) asm volatile("s_waitcnt lgkmcnt(" #n ")" ::: "memory")
; #define PG8_BAR __builtin_amdgcn_s_barrier()
; #define PG8_SCHED __builtin_amdgcn_sched_barrier(0)
; template <class Epi>
; __device__ __forceinline__ void gemm_phase(LAS unsigned char* lds, const Gemm g, int G, int c, const Epi& E) {
;     ...
;             PG8_WAIT_V(8); PG8_WAIT_L(0); PG8_BAR; PG8_MMA(1, 0, At, B0); PG8_MMA(1, 1, At, B1); PG8_BAR; PG8_SCHED;
;             PG8_LDB(B0, 1, 0); PG8_LDB(B1, 1, 1); PG8_SCHED; PG8_LDA(At, 1, 0); PG8_STAGE(PG8_SA(0, 1), a2 + hstepA, voffA);
;             PG8_WAIT_V(8); PG8_WAIT_L(0); PG8_BAR; PG8_MMA(0, 0, At, B0); PG8_MMA(0, 1, At, B1); PG8_BAR; PG8_SCHED;
	s_setprio 0
	v_mfma_f32_16x16x32_bf16 v[62:65], v[142:145], v[180:183], v[62:65]
	v_mfma_f32_16x16x32_bf16 v[58:61], v[156:159], v[180:183], v[58:61]
	v_mfma_f32_16x16x32_bf16 v[54:57], v[142:145], v[188:191], v[54:57]
	v_mfma_f32_16x16x32_bf16 v[46:49], v[156:159], v[188:191], v[46:49]
	v_mfma_f32_16x16x32_bf16 v[38:41], v[142:145], v[196:199], v[38:41]
	v_mfma_f32_16x16x32_bf16 v[30:33], v[156:159], v[196:199], v[30:33]
	v_mfma_f32_16x16x32_bf16 v[22:25], v[142:145], v[204:207], v[22:25]
	v_mfma_f32_16x16x32_bf16 v[14:17], v[156:159], v[204:207], v[14:17]
	v_mfma_f32_16x16x32_bf16 v[62:65], v[152:155], v[184:187], v[62:65]
	v_mfma_f32_16x16x32_bf16 v[58:61], v[160:163], v[184:187], v[58:61]
	v_mfma_f32_16x16x32_bf16 v[54:57], v[152:155], v[192:195], v[54:57]
	v_mfma_f32_16x16x32_bf16 v[46:49], v[160:163], v[192:195], v[46:49]
	v_mfma_f32_16x16x32_bf16 v[38:41], v[152:155], v[200:203], v[38:41]
	v_mfma_f32_16x16x32_bf16 v[30:33], v[160:163], v[200:203], v[30:33]
	v_mfma_f32_16x16x32_bf16 v[22:25], v[152:155], v[208:211], v[22:25]
	v_mfma_f32_16x16x32_bf16 v[14:17], v[160:163], v[208:211], v[14:17]
	s_setprio 2
	s_setprio 0
	v_mfma_f32_16x16x32_bf16 v[50:53], v[164:167], v[180:183], v[50:53]
	v_mfma_f32_16x16x32_bf16 v[42:45], v[172:175], v[180:183], v[42:45]
	v_mfma_f32_16x16x32_bf16 v[34:37], v[164:167], v[188:191], v[34:37]
	v_mfma_f32_16x16x32_bf16 v[26:29], v[172:175], v[188:191], v[26:29]
	v_mfma_f32_16x16x32_bf16 v[18:21], v[164:167], v[196:199], v[18:21]
	v_mfma_f32_16x16x32_bf16 v[10:13], v[172:175], v[196:199], v[10:13]
	v_mfma_f32_16x16x32_bf16 v[6:9], v[164:167], v[204:207], v[6:9]
	v_mfma_f32_16x16x32_bf16 v[2:5], v[172:175], v[204:207], v[2:5]
	v_mfma_f32_16x16x32_bf16 v[50:53], v[168:171], v[184:187], v[50:53]
	v_mfma_f32_16x16x32_bf16 v[42:45], v[176:179], v[184:187], v[42:45]
	v_mfma_f32_16x16x32_bf16 v[34:37], v[168:171], v[192:195], v[34:37]
	v_mfma_f32_16x16x32_bf16 v[26:29], v[176:179], v[192:195], v[26:29]
	v_mfma_f32_16x16x32_bf16 v[18:21], v[168:171], v[200:203], v[18:21]
	v_mfma_f32_16x16x32_bf16 v[10:13], v[176:179], v[200:203], v[10:13]
	v_mfma_f32_16x16x32_bf16 v[6:9], v[168:171], v[208:211], v[6:9]
	v_mfma_f32_16x16x32_bf16 v[2:5], v[176:179], v[208:211], v[2:5]
	s_setprio 2
	s_barrier
	v_add_u32_e32 v151, s84, v147
	ds_read_b128 v[142:145], v151
	ds_read_b128 v[152:155], v151 offset:1024
	ds_read_b128 v[156:159], v151 offset:2048
	ds_read_b128 v[160:163], v151 offset:3072
	v_add_u32_e32 v151, s33, v147
	ds_read_b128 v[164:167], v151
	ds_read_b128 v[168:171], v151 offset:1024
	ds_read_b128 v[172:175], v151 offset:2048
	ds_read_b128 v[176:179], v151 offset:3072
	ds_read_b128 v[180:183], v150 offset:32768
	ds_read_b128 v[184:187], v150 offset:33792
	ds_read_b128 v[188:191], v150 offset:34816
	ds_read_b128 v[192:195], v150 offset:35840
	ds_read_b128 v[196:199], v150 offset:36864
	ds_read_b128 v[200:203], v150 offset:37888
	ds_read_b128 v[204:207], v150 offset:38912
	ds_read_b128 v[208:211], v150 offset:39936
	s_mov_b32 m0, s53
	v_lshl_add_u64 v[220:221], s[24:25], 0, v[136:137]
	global_load_lds_dwordx4 v[220:221], off
	v_lshl_add_u64 v[220:221], s[24:25], 0, v[132:133]
	s_mov_b32 m0, s54
	s_nop 0
	global_load_lds_dwordx4 v[220:221], off
	s_waitcnt vmcnt(8)
	s_waitcnt lgkmcnt(0)
	s_barrier
	s_setprio 0
	v_mfma_f32_16x16x32_bf16 v[126:129], v[142:145], v[180:183], v[126:129]
	v_mfma_f32_16x16x32_bf16 v[122:125], v[156:159], v[180:183], v[122:125]
	v_mfma_f32_16x16x32_bf16 v[118:121], v[142:145], v[188:191], v[118:121]
	v_mfma_f32_16x16x32_bf16 v[110:113], v[156:159], v[188:191], v[110:113]
	v_mfma_f32_16x16x32_bf16 v[102:105], v[142:145], v[196:199], v[102:105]
	v_mfma_f32_16x16x32_bf16 v[94:97], v[156:159], v[196:199], v[94:97]
	v_mfma_f32_16x16x32_bf16 v[86:89], v[142:145], v[204:207], v[86:89]
	v_mfma_f32_16x16x32_bf16 v[78:81], v[156:159], v[204:207], v[78:81]
	v_mfma_f32_16x16x32_bf16 v[126:129], v[152:155], v[184:187], v[126:129]
	v_mfma_f32_16x16x32_bf16 v[122:125], v[160:163], v[184:187], v[122:125]
	v_mfma_f32_16x16x32_bf16 v[118:121], v[152:155], v[192:195], v[118:121]
	v_mfma_f32_16x16x32_bf16 v[110:113], v[160:163], v[192:195], v[110:113]
	v_mfma_f32_16x16x32_bf16 v[102:105], v[152:155], v[200:203], v[102:105]
	v_mfma_f32_16x16x32_bf16 v[94:97], v[160:163], v[200:203], v[94:97]
	v_mfma_f32_16x16x32_bf16 v[86:89], v[152:155], v[208:211], v[86:89]
	v_mfma_f32_16x16x32_bf16 v[78:81], v[160:163], v[208:211], v[78:81]
	s_setprio 2
	s_setprio 0
	v_mfma_f32_16x16x32_bf16 v[114:117], v[164:167], v[180:183], v[114:117]
	v_mfma_f32_16x16x32_bf16 v[106:109], v[172:175], v[180:183], v[106:109]
	v_mfma_f32_16x16x32_bf16 v[98:101], v[164:167], v[188:191], v[98:101]
	v_mfma_f32_16x16x32_bf16 v[90:93], v[172:175], v[188:191], v[90:93]
	v_mfma_f32_16x16x32_bf16 v[82:85], v[164:167], v[196:199], v[82:85]
	v_mfma_f32_16x16x32_bf16 v[74:77], v[172:175], v[196:199], v[74:77]
	v_mfma_f32_16x16x32_bf16 v[70:73], v[164:167], v[204:207], v[70:73]
	v_mfma_f32_16x16x32_bf16 v[66:69], v[172:175], v[204:207], v[66:69]
	v_mfma_f32_16x16x32_bf16 v[114:117], v[168:171], v[184:187], v[114:117]
	v_mfma_f32_16x16x32_bf16 v[106:109], v[176:179], v[184:187], v[106:109]
	v_mfma_f32_16x16x32_bf16 v[98:101], v[168:171], v[192:195], v[98:101]
	v_mfma_f32_16x16x32_bf16 v[90:93], v[176:179], v[192:195], v[90:93]
	v_mfma_f32_16x16x32_bf16 v[82:85], v[168:171], v[200:203], v[82:85]
	v_mfma_f32_16x16x32_bf16 v[74:77], v[176:179], v[200:203], v[74:77]
	v_mfma_f32_16x16x32_bf16 v[70:73], v[168:171], v[208:211], v[70:73]
	v_mfma_f32_16x16x32_bf16 v[66:69], v[176:179], v[208:211], v[66:69]
	s_setprio 2
	s_barrier
; #define PG8_STAGE(bufoff, gbase, voff) do { _Pragma("unroll") for (int _i = 0; _i < 2; ++_i) \
;         __builtin_amdgcn_global_load_lds((const unsigned*)((const char*)(gbase) + (voff)[_i]), (LAS unsigned*)(lds + (bufoff) + ldsw + _i * 8192), 16, 0, 0); } while (0)
; #define PG8_LDA(dst, b, h) do { _Pragma("unroll") for (int m = 0; m < 4; ++m) _Pragma("unroll") for (int k = 0; k < 2; ++k) dst[m][k] = *(const LAS bf16x8*)(lds + PG8_SA(b, h) + aoff + m * 2048 + k * 1024); } while (0)
; #define PG8_MMA(ai, bj, At, Bt) do { __builtin_amdgcn_s_setprio(1); _Pragma("unroll") for (int m = 0; m < 4; ++m) _Pragma("unroll") for (int n = 0; n < 2; ++n) _Pragma("unroll") for (int k = 0; k < 2; ++k) \
;         acc[ai][bj][m][n] = __builtin_amdgcn_mfma_f32_16x16x32_bf16(Bt[n][k], At[m][k], acc[ai][bj][m][n], 0, 0, 0); __builtin_amdgcn_s_setprio(0); } while (0)
; #define PG8_WAIT_V(n) asm volatile("s_waitcnt vmcnt(" #n ")" ::: "memory")
; #define PG8_WAIT_L(n) asm volatile("s_waitcnt lgkmcnt(" #n ")" ::: "memory")
; #define PG8_BAR __builtin_amdgcn_s_barrier()
; #define PG8_SCHED __builtin_amdgcn_sched_barrier(0)
; template <class Epi>
; __device__ __forceinline__ void gemm_phase(LAS unsigned char* lds, const Gemm g, int G, int c, const Epi& E) {
;     ...
;             PG8_LDA(At, 1, 1); PG8_STAGE(PG8_SB(1, 0), b3, voffB); PG8_STAGE(PG8_SB(1, 1), b3 + hstepB, voffB); PG8_STAGE(PG8_SA(1, 0), a3, voffA);
;             PG8_WAIT_V(8); PG8_WAIT_L(0); PG8_BAR; PG8_MMA(1, 0, At, B0); PG8_MMA(1, 1, At, B1); PG8_BAR; PG8_SCHED;
;         }
	ds_read_b128 v[180:183], v150 offset:49152
	ds_read_b128 v[184:187], v150 offset:50176
	ds_read_b128 v[188:191], v150 offset:51200
	ds_read_b128 v[192:195], v150 offset:52224
	ds_read_b128 v[196:199], v150 offset:53248
	ds_read_b128 v[200:203], v150 offset:54272
	ds_read_b128 v[204:207], v150 offset:55296
	ds_read_b128 v[208:211], v150 offset:56320
	s_mov_b32 m0, s83
	v_lshl_add_u64 v[212:213], v[212:213], 0, s[8:9]
	global_load_lds_dwordx4 v[212:213], off
	v_lshl_add_u64 v[212:213], v[214:215], 0, s[8:9]
	s_mov_b32 m0, s13
	s_nop 0
	global_load_lds_dwordx4 v[212:213], off
	v_lshl_add_u64 v[212:213], s[22:23], 0, v[134:135]
	s_mov_b32 m0, s75
	s_nop 0
	global_load_lds_dwordx4 v[212:213], off
	v_lshl_add_u64 v[212:213], s[22:23], 0, v[130:131]
	s_mov_b32 m0, s74
	s_nop 0
	global_load_lds_dwordx4 v[212:213], off
	v_lshl_add_u64 v[212:213], v[216:217], 0, s[8:9]
	s_mov_b32 m0, s70
	s_nop 0
	global_load_lds_dwordx4 v[212:213], off
	v_lshl_add_u64 v[212:213], v[218:219], 0, s[8:9]
	s_mov_b32 m0, s71
	s_nop 0
	global_load_lds_dwordx4 v[212:213], off
	s_waitcnt vmcnt(8)
	s_waitcnt lgkmcnt(0)
	s_barrier
	s_setprio 0
	v_mfma_f32_16x16x32_bf16 v[62:65], v[142:145], v[180:183], v[62:65]
	v_mfma_f32_16x16x32_bf16 v[58:61], v[156:159], v[180:183], v[58:61]
	v_mfma_f32_16x16x32_bf16 v[54:57], v[142:145], v[188:191], v[54:57]
	v_mfma_f32_16x16x32_bf16 v[46:49], v[156:159], v[188:191], v[46:49]
	v_mfma_f32_16x16x32_bf16 v[38:41], v[142:145], v[196:199], v[38:41]
	v_mfma_f32_16x16x32_bf16 v[30:33], v[156:159], v[196:199], v[30:33]
	v_mfma_f32_16x16x32_bf16 v[22:25], v[142:145], v[204:207], v[22:25]
	v_mfma_f32_16x16x32_bf16 v[14:17], v[156:159], v[204:207], v[14:17]
	v_mfma_f32_16x16x32_bf16 v[62:65], v[152:155], v[184:187], v[62:65]
	v_mfma_f32_16x16x32_bf16 v[58:61], v[160:163], v[184:187], v[58:61]
	v_mfma_f32_16x16x32_bf16 v[54:57], v[152:155], v[192:195], v[54:57]
	v_mfma_f32_16x16x32_bf16 v[46:49], v[160:163], v[192:195], v[46:49]
	v_mfma_f32_16x16x32_bf16 v[38:41], v[152:155], v[200:203], v[38:41]
	v_mfma_f32_16x16x32_bf16 v[30:33], v[160:163], v[200:203], v[30:33]
	v_mfma_f32_16x16x32_bf16 v[22:25], v[152:155], v[208:211], v[22:25]
	v_mfma_f32_16x16x32_bf16 v[14:17], v[160:163], v[208:211], v[14:17]
	s_setprio 2
	s_setprio 0
	v_mfma_f32_16x16x32_bf16 v[50:53], v[164:167], v[180:183], v[50:53]
	v_mfma_f32_16x16x32_bf16 v[42:45], v[172:175], v[180:183], v[42:45]
	v_mfma_f32_16x16x32_bf16 v[34:37], v[164:167], v[188:191], v[34:37]
	v_mfma_f32_16x16x32_bf16 v[26:29], v[172:175], v[188:191], v[26:29]
	v_mfma_f32_16x16x32_bf16 v[18:21], v[164:167], v[196:199], v[18:21]
	v_mfma_f32_16x16x32_bf16 v[10:13], v[172:175], v[196:199], v[10:13]
	v_mfma_f32_16x16x32_bf16 v[6:9], v[164:167], v[204:207], v[6:9]
	v_mfma_f32_16x16x32_bf16 v[2:5], v[172:175], v[204:207], v[2:5]
	v_mfma_f32_16x16x32_bf16 v[50:53], v[168:171], v[184:187], v[50:53]
	v_mfma_f32_16x16x32_bf16 v[42:45], v[176:179], v[184:187], v[42:45]
	v_mfma_f32_16x16x32_bf16 v[34:37], v[168:171], v[192:195], v[34:37]
	v_mfma_f32_16x16x32_bf16 v[26:29], v[176:179], v[192:195], v[26:29]
	v_mfma_f32_16x16x32_bf16 v[18:21], v[168:171], v[200:203], v[18:21]
	v_mfma_f32_16x16x32_bf16 v[10:13], v[176:179], v[200:203], v[10:13]
	v_mfma_f32_16x16x32_bf16 v[6:9], v[168:171], v[208:211], v[6:9]
	v_mfma_f32_16x16x32_bf16 v[2:5], v[176:179], v[208:211], v[2:5]
	s_setprio 2
	s_barrier
	s_movk_i32 s13, 0x100
	s_andn2_b64 vcc, exec, s[20:21]
	s_mov_b64 s[22:23], -1
	s_mov_b64 s[20:21], 0
	s_cbranch_vccz .LBB0_1429
	s_and_b64 vcc, exec, s[10:11]
	s_cbranch_vccz .LBB0_1432
	s_barrier

; #define PG8_STAGE(bufoff, gbase, voff) do { _Pragma("unroll") for (int _i = 0; _i < 2; ++_i) \
;         __builtin_amdgcn_global_load_lds((const unsigned*)((const char*)(gbase) + (voff)[_i]), (LAS unsigned*)(lds + (bufoff) + ldsw + _i * 8192), 16, 0, 0); } while (0)
; #define PG8_LDA(dst, b, h) do { _Pragma("unroll") for (int m = 0; m < 4; ++m) _Pragma("unroll") for (int k = 0; k < 2; ++k) dst[m][k] = *(const LAS bf16x8*)(lds + PG8_SA(b, h) + aoff + m * 2048 + k * 1024); } while (0)
; #define PG8_LDB(dst, b, h) do { _Pragma("unroll") for (int n = 0; n < 2; ++n) _Pragma("unroll") for (int k = 0; k < 2; ++k) dst[n][k] = *(const LAS bf16x8*)(lds + PG8_SB(b, h) + boff + n * 2048 + k * 1024); } while (0)
; #define PG8_MMA(ai, bj, At, Bt) do { __builtin_amdgcn_s_setprio(1); _Pragma("unroll") for (int m = 0; m < 4; ++m) _Pragma("unroll") for (int n = 0; n < 2; ++n) _Pragma("unroll") for (int k = 0; k < 2; ++k) \
;         acc[ai][bj][m][n] = __builtin_amdgcn_mfma_f32_16x16x32_bf16(Bt[n][k], At[m][k], acc[ai][bj][m][n], 0, 0, 0); __builtin_amdgcn_s_setprio(0); } while (0)
; #define PG8_WAIT_V(n) asm volatile("s_waitcnt vmcnt(" #n ")" ::: "memory")
; #define PG8_WAIT_L(n) asm volatile("s_waitcnt lgkmcnt(" #n ")" ::: "memory")
; #define PG8_BAR __builtin_amdgcn_s_barrier()
; #define PG8_SCHED __builtin_amdgcn_sched_barrier(0)
; template <class Epi>
; __device__ __forceinline__ void gemm_phase(LAS unsigned char* lds, const Gemm g, int G, int c, const Epi& E) {
;     ...
;             const bool last = (t == nt - 2);
;             const char* a1 = cA + (size_t)(t + 1) * kstep;
;             const char* a2 = last ? nA : cA + (size_t)(t + 2) * kstep; const char* b2 = last ? nB : cB + (size_t)(t + 2) * kstep;
;             const char* a3 = a2 + kstep; const char* b3 = b2 + kstep;
;             PG8_LDB(B0, 0, 0); PG8_LDB(B1, 0, 1); PG8_SCHED; PG8_LDA(At, 0, 0); PG8_STAGE(PG8_SA(1, 1), a1 + hstepA, voffA);
;             PG8_WAIT_V(8); PG8_WAIT_L(0); PG8_BAR; PG8_MMA(0, 0, At, B0); PG8_MMA(0, 1, At, B1); PG8_BAR; PG8_SCHED;
;             PG8_LDA(At, 0, 1); PG8_STAGE(PG8_SB(0, 0), b2, voffB); PG8_STAGE(PG8_SB(0, 1), b2 + hstepB, voffB); PG8_STAGE(PG8_SA(0, 0), a2, voffA);
.LBB0_1451:
	ds_read_b128 v[142:145], v160
	ds_read_b128 v[146:149], v160 offset:1024
	ds_read_b128 v[150:153], v160 offset:2048
	ds_read_b128 v[154:157], v160 offset:3072
	ds_read_b128 v[166:169], v161
	ds_read_b128 v[170:173], v161 offset:1024
	ds_read_b128 v[174:177], v161 offset:2048
	ds_read_b128 v[178:181], v161 offset:3072
	ds_read_b128 v[182:185], v162
	ds_read_b128 v[186:189], v162 offset:1024
	ds_read_b128 v[190:193], v162 offset:2048
	ds_read_b128 v[194:197], v162 offset:3072
	ds_read_b128 v[198:201], v162 offset:4096
	ds_read_b128 v[202:205], v162 offset:5120
	ds_read_b128 v[206:209], v162 offset:6144
	ds_read_b128 v[210:213], v162 offset:7168
	s_add_u32 s33, s8, s44
	s_addc_u32 s45, s9, 0
	s_add_u32 s48, s33, 0x100
	s_addc_u32 s49, s45, 0
	s_and_b64 s[46:47], s[10:11], exec
	s_cselect_b32 s47, s41, s49
	s_cselect_b32 s46, s40, s48
	s_add_u32 s44, s6, s44
	s_addc_u32 s48, s7, 0
	s_add_u32 s44, s44, 0x100
	s_addc_u32 s48, s48, 0
	s_and_b64 s[10:11], s[10:11], exec
	s_cselect_b32 s49, s43, s48
	s_cselect_b32 s48, s42, s44
	s_add_u32 s54, s33, 0xb0080
	s_addc_u32 s55, s45, 0
	s_add_i32 s65, s82, s66
	s_add_i32 m0, s69, 0xc000
	s_add_i32 s74, s69, 0xe000
	s_add_i32 s62, s65, 0x2000
	s_add_u32 s52, s48, 0xb0000
	s_addc_u32 s53, s49, 0
	s_add_i32 s64, s83, s66
	s_add_i32 s63, s64, 0x2000
	s_add_i32 s97, 0, 0x18000
	s_add_i32 s33, 0, 0x1c000
	s_add_u32 s44, s46, 0xb0000
	s_addc_u32 s45, s47, 0
	s_add_i32 s96, s97, s66
	s_add_i32 s94, s96, 0x2000
	s_add_u32 s10, s48, 0xb0080
	s_addc_u32 s11, s49, 0
	s_add_i32 s95, s33, s66
	s_add_i32 s93, s95, 0x2000
	v_lshl_add_u64 v[214:215], s[54:55], 0, v[130:131]
	global_load_lds_dwordx4 v[214:215], off
	v_lshl_add_u64 v[214:215], s[54:55], 0, v[134:135]
	s_mov_b32 m0, s74
	s_nop 0
	global_load_lds_dwordx4 v[214:215], off
	s_waitcnt vmcnt(8)
	s_waitcnt lgkmcnt(0)
	s_barrier
	s_setprio 0
	v_mfma_f32_16x16x32_bf16 v[126:129], v[142:145], v[182:185], v[126:129]
	v_mfma_f32_16x16x32_bf16 v[122:125], v[150:153], v[182:185], v[122:125]
	v_mfma_f32_16x16x32_bf16 v[110:113], v[142:145], v[190:193], v[110:113]
	v_mfma_f32_16x16x32_bf16 v[106:109], v[150:153], v[190:193], v[106:109]
	v_mfma_f32_16x16x32_bf16 v[94:97], v[142:145], v[198:201], v[94:97]
	v_mfma_f32_16x16x32_bf16 v[90:93], v[150:153], v[198:201], v[90:93]
	v_mfma_f32_16x16x32_bf16 v[78:81], v[142:145], v[206:209], v[78:81]
	v_mfma_f32_16x16x32_bf16 v[74:77], v[150:153], v[206:209], v[74:77]
	v_mfma_f32_16x16x32_bf16 v[126:129], v[146:149], v[186:189], v[126:129]
	v_mfma_f32_16x16x32_bf16 v[122:125], v[154:157], v[186:189], v[122:125]
	v_mfma_f32_16x16x32_bf16 v[110:113], v[146:149], v[194:197], v[110:113]
	v_mfma_f32_16x16x32_bf16 v[106:109], v[154:157], v[194:197], v[106:109]
	v_mfma_f32_16x16x32_bf16 v[94:97], v[146:149], v[202:205], v[94:97]
	v_mfma_f32_16x16x32_bf16 v[90:93], v[154:157], v[202:205], v[90:93]
	v_mfma_f32_16x16x32_bf16 v[78:81], v[146:149], v[210:213], v[78:81]
	v_mfma_f32_16x16x32_bf16 v[74:77], v[154:157], v[210:213], v[74:77]
	s_setprio 2
	s_setprio 0
	v_mfma_f32_16x16x32_bf16 v[118:121], v[166:169], v[182:185], v[118:121]
	v_mfma_f32_16x16x32_bf16 v[114:117], v[174:177], v[182:185], v[114:117]
	v_mfma_f32_16x16x32_bf16 v[102:105], v[166:169], v[190:193], v[102:105]
	v_mfma_f32_16x16x32_bf16 v[98:101], v[174:177], v[190:193], v[98:101]
	v_mfma_f32_16x16x32_bf16 v[86:89], v[166:169], v[198:201], v[86:89]
	v_mfma_f32_16x16x32_bf16 v[82:85], v[174:177], v[198:201], v[82:85]
	v_mfma_f32_16x16x32_bf16 v[70:73], v[166:169], v[206:209], v[70:73]
	v_mfma_f32_16x16x32_bf16 v[66:69], v[174:177], v[206:209], v[66:69]
	v_mfma_f32_16x16x32_bf16 v[118:121], v[170:173], v[186:189], v[118:121]
	v_mfma_f32_16x16x32_bf16 v[114:117], v[178:181], v[186:189], v[114:117]
	v_mfma_f32_16x16x32_bf16 v[102:105], v[170:173], v[194:197], v[102:105]
	v_mfma_f32_16x16x32_bf16 v[98:101], v[178:181], v[194:197], v[98:101]
	v_mfma_f32_16x16x32_bf16 v[86:89], v[170:173], v[202:205], v[86:89]
	v_mfma_f32_16x16x32_bf16 v[82:85], v[178:181], v[202:205], v[82:85]
	v_mfma_f32_16x16x32_bf16 v[70:73], v[170:173], v[210:213], v[70:73]
	v_mfma_f32_16x16x32_bf16 v[66:69], v[178:181], v[210:213], v[66:69]
	s_setprio 2
	s_barrier
	ds_read_b128 v[182:185], v162 offset:16384
	ds_read_b128 v[186:189], v162 offset:17408
	ds_read_b128 v[190:193], v162 offset:18432
	ds_read_b128 v[194:197], v162 offset:19456
	ds_read_b128 v[198:201], v162 offset:20480
	ds_read_b128 v[202:205], v162 offset:21504
	ds_read_b128 v[206:209], v162 offset:22528
	ds_read_b128 v[210:213], v162 offset:23552
	s_mov_b32 m0, s65
	v_lshl_add_u64 v[214:215], s[48:49], 0, v[132:133]
	global_load_lds_dwordx4 v[214:215], off
	v_lshl_add_u64 v[216:217], s[48:49], 0, v[136:137]
	s_mov_b32 m0, s62
	v_lshl_add_u64 v[218:219], s[52:53], 0, v[132:133]
	global_load_lds_dwordx4 v[216:217], off
	s_mov_b32 m0, s64
	v_lshl_add_u64 v[220:221], s[46:47], 0, v[134:135]
	global_load_lds_dwordx4 v[218:219], off
	v_lshl_add_u64 v[218:219], s[52:53], 0, v[136:137]
	s_mov_b32 m0, s63
	s_nop 0
	global_load_lds_dwordx4 v[218:219], off
	v_lshl_add_u64 v[218:219], s[46:47], 0, v[130:131]
	s_mov_b32 m0, s69
	s_nop 0
	global_load_lds_dwordx4 v[218:219], off
	s_mov_b32 m0, s70
	s_nop 0
	global_load_lds_dwordx4 v[220:221], off
	s_waitcnt vmcnt(8)
	s_waitcnt lgkmcnt(0)
	s_barrier
; #define PG8_STAGE(bufoff, gbase, voff) do { _Pragma("unroll") for (int _i = 0; _i < 2; ++_i) \
;         __builtin_amdgcn_global_load_lds((const unsigned*)((const char*)(gbase) + (voff)[_i]), (LAS unsigned*)(lds + (bufoff) + ldsw + _i * 8192), 16, 0, 0); } while (0)
; #define PG8_LDA(dst, b, h) do { _Pragma("unroll") for (int m = 0; m < 4; ++m) _Pragma("unroll") for (int k = 0; k < 2; ++k) dst[m][k] = *(const LAS bf16x8*)(lds + PG8_SA(b, h) + aoff + m * 2048 + k * 1024); } while (0)
; #define PG8_LDB(dst, b, h) do { _Pragma("unroll") for (int n = 0; n < 2; ++n) _Pragma("unroll") for (int k = 0; k < 2; ++k) dst[n][k] = *(const LAS bf16x8*)(lds + PG8_SB(b, h) + boff + n * 2048 + k * 1024); } while (0)
; #define PG8_MMA(ai, bj, At, Bt) do { __builtin_amdgcn_s_setprio(1); _Pragma("unroll") for (int m = 0; m < 4; ++m) _Pragma("unroll") for (int n = 0; n < 2; ++n) _Pragma("unroll") for (int k = 0; k < 2; ++k) \
;         acc[ai][bj][m][n] = __builtin_amdgcn_mfma_f32_16x16x32_bf16(Bt[n][k], At[m][k], acc[ai][bj][m][n], 0, 0, 0); __builtin_amdgcn_s_setprio(0); } while (0)
; #define PG8_WAIT_V(n) asm volatile("s_waitcnt vmcnt(" #n ")" ::: "memory")
; #define PG8_WAIT_L(n) asm volatile("s_waitcnt lgkmcnt(" #n ")" ::: "memory")
; #define PG8_BAR __builtin_amdgcn_s_barrier()
; #define PG8_SCHED __builtin_amdgcn_sched_barrier(0)
; template <class Epi>
; __device__ __forceinline__ void gemm_phase(LAS unsigned char* lds, const Gemm g, int G, int c, const Epi& E) {
;     ...
;             PG8_WAIT_V(8); PG8_WAIT_L(0); PG8_BAR; PG8_MMA(1, 0, At, B0); PG8_MMA(1, 1, At, B1); PG8_BAR; PG8_SCHED;
;             PG8_LDB(B0, 1, 0); PG8_LDB(B1, 1, 1); PG8_SCHED; PG8_LDA(At, 1, 0); PG8_STAGE(PG8_SA(0, 1), a2 + hstepA, voffA);
;             PG8_WAIT_V(8); PG8_WAIT_L(0); PG8_BAR; PG8_MMA(0, 0, At, B0); PG8_MMA(0, 1, At, B1); PG8_BAR; PG8_SCHED;
	s_setprio 0
	v_mfma_f32_16x16x32_bf16 v[62:65], v[142:145], v[182:185], v[62:65]
	v_mfma_f32_16x16x32_bf16 v[58:61], v[150:153], v[182:185], v[58:61]
	v_mfma_f32_16x16x32_bf16 v[46:49], v[142:145], v[190:193], v[46:49]
	v_mfma_f32_16x16x32_bf16 v[42:45], v[150:153], v[190:193], v[42:45]
	v_mfma_f32_16x16x32_bf16 v[30:33], v[142:145], v[198:201], v[30:33]
	v_mfma_f32_16x16x32_bf16 v[26:29], v[150:153], v[198:201], v[26:29]
	v_mfma_f32_16x16x32_bf16 v[14:17], v[142:145], v[206:209], v[14:17]
	v_mfma_f32_16x16x32_bf16 v[10:13], v[150:153], v[206:209], v[10:13]
	v_mfma_f32_16x16x32_bf16 v[62:65], v[146:149], v[186:189], v[62:65]
	v_mfma_f32_16x16x32_bf16 v[58:61], v[154:157], v[186:189], v[58:61]
	v_mfma_f32_16x16x32_bf16 v[46:49], v[146:149], v[194:197], v[46:49]
	v_mfma_f32_16x16x32_bf16 v[42:45], v[154:157], v[194:197], v[42:45]
	v_mfma_f32_16x16x32_bf16 v[30:33], v[146:149], v[202:205], v[30:33]
	v_mfma_f32_16x16x32_bf16 v[26:29], v[154:157], v[202:205], v[26:29]
	v_mfma_f32_16x16x32_bf16 v[14:17], v[146:149], v[210:213], v[14:17]
	v_mfma_f32_16x16x32_bf16 v[10:13], v[154:157], v[210:213], v[10:13]
	s_setprio 2
	s_setprio 0
	v_mfma_f32_16x16x32_bf16 v[54:57], v[166:169], v[182:185], v[54:57]
	v_mfma_f32_16x16x32_bf16 v[50:53], v[174:177], v[182:185], v[50:53]
	v_mfma_f32_16x16x32_bf16 v[38:41], v[166:169], v[190:193], v[38:41]
	v_mfma_f32_16x16x32_bf16 v[34:37], v[174:177], v[190:193], v[34:37]
	v_mfma_f32_16x16x32_bf16 v[22:25], v[166:169], v[198:201], v[22:25]
	v_mfma_f32_16x16x32_bf16 v[18:21], v[174:177], v[198:201], v[18:21]
	v_mfma_f32_16x16x32_bf16 v[6:9], v[166:169], v[206:209], v[6:9]
	v_mfma_f32_16x16x32_bf16 v[2:5], v[174:177], v[206:209], v[2:5]
	v_mfma_f32_16x16x32_bf16 v[54:57], v[170:173], v[186:189], v[54:57]
	v_mfma_f32_16x16x32_bf16 v[50:53], v[178:181], v[186:189], v[50:53]
	v_mfma_f32_16x16x32_bf16 v[38:41], v[170:173], v[194:197], v[38:41]
	v_mfma_f32_16x16x32_bf16 v[34:37], v[178:181], v[194:197], v[34:37]
	v_mfma_f32_16x16x32_bf16 v[22:25], v[170:173], v[202:205], v[22:25]
	v_mfma_f32_16x16x32_bf16 v[18:21], v[178:181], v[202:205], v[18:21]
	v_mfma_f32_16x16x32_bf16 v[6:9], v[170:173], v[210:213], v[6:9]
	v_mfma_f32_16x16x32_bf16 v[2:5], v[178:181], v[210:213], v[2:5]
	s_setprio 2
	s_barrier
	v_add_u32_e32 v154, s97, v159
	v_add_u32_e32 v178, s33, v159
	ds_read_b128 v[142:145], v154
	ds_read_b128 v[146:149], v154 offset:1024
	ds_read_b128 v[150:153], v154 offset:2048
	ds_read_b128 v[154:157], v154 offset:3072
	ds_read_b128 v[166:169], v178
	ds_read_b128 v[170:173], v178 offset:1024
	ds_read_b128 v[174:177], v178 offset:2048
	ds_read_b128 v[178:181], v178 offset:3072
	ds_read_b128 v[182:185], v162 offset:32768
	ds_read_b128 v[186:189], v162 offset:33792
	ds_read_b128 v[190:193], v162 offset:34816
	ds_read_b128 v[194:197], v162 offset:35840
	ds_read_b128 v[198:201], v162 offset:36864
	ds_read_b128 v[202:205], v162 offset:37888
	ds_read_b128 v[206:209], v162 offset:38912
	ds_read_b128 v[210:213], v162 offset:39936
	s_mov_b32 m0, s71
	v_lshl_add_u64 v[222:223], s[44:45], 0, v[130:131]
	global_load_lds_dwordx4 v[222:223], off
	v_lshl_add_u64 v[222:223], s[44:45], 0, v[134:135]
	s_mov_b32 m0, s72
	s_nop 0
	global_load_lds_dwordx4 v[222:223], off
	s_waitcnt vmcnt(8)
	s_waitcnt lgkmcnt(0)
	s_barrier
	s_setprio 0
	v_mfma_f32_16x16x32_bf16 v[126:129], v[142:145], v[182:185], v[126:129]
	v_mfma_f32_16x16x32_bf16 v[122:125], v[150:153], v[182:185], v[122:125]
	v_mfma_f32_16x16x32_bf16 v[110:113], v[142:145], v[190:193], v[110:113]
	v_mfma_f32_16x16x32_bf16 v[106:109], v[150:153], v[190:193], v[106:109]
	v_mfma_f32_16x16x32_bf16 v[94:97], v[142:145], v[198:201], v[94:97]
	v_mfma_f32_16x16x32_bf16 v[90:93], v[150:153], v[198:201], v[90:93]
	v_mfma_f32_16x16x32_bf16 v[78:81], v[142:145], v[206:209], v[78:81]
	v_mfma_f32_16x16x32_bf16 v[74:77], v[150:153], v[206:209], v[74:77]
	v_mfma_f32_16x16x32_bf16 v[126:129], v[146:149], v[186:189], v[126:129]
	v_mfma_f32_16x16x32_bf16 v[122:125], v[154:157], v[186:189], v[122:125]
	v_mfma_f32_16x16x32_bf16 v[110:113], v[146:149], v[194:197], v[110:113]
	v_mfma_f32_16x16x32_bf16 v[106:109], v[154:157], v[194:197], v[106:109]
	v_mfma_f32_16x16x32_bf16 v[94:97], v[146:149], v[202:205], v[94:97]
	v_mfma_f32_16x16x32_bf16 v[90:93], v[154:157], v[202:205], v[90:93]
	v_mfma_f32_16x16x32_bf16 v[78:81], v[146:149], v[210:213], v[78:81]
	v_mfma_f32_16x16x32_bf16 v[74:77], v[154:157], v[210:213], v[74:77]
	s_setprio 2
	s_setprio 0
	v_mfma_f32_16x16x32_bf16 v[118:121], v[166:169], v[182:185], v[118:121]
	v_mfma_f32_16x16x32_bf16 v[114:117], v[174:177], v[182:185], v[114:117]
	v_mfma_f32_16x16x32_bf16 v[102:105], v[166:169], v[190:193], v[102:105]
	v_mfma_f32_16x16x32_bf16 v[98:101], v[174:177], v[190:193], v[98:101]
	v_mfma_f32_16x16x32_bf16 v[86:89], v[166:169], v[198:201], v[86:89]
	v_mfma_f32_16x16x32_bf16 v[82:85], v[174:177], v[198:201], v[82:85]
	v_mfma_f32_16x16x32_bf16 v[70:73], v[166:169], v[206:209], v[70:73]
	v_mfma_f32_16x16x32_bf16 v[66:69], v[174:177], v[206:209], v[66:69]
	v_mfma_f32_16x16x32_bf16 v[118:121], v[170:173], v[186:189], v[118:121]
	v_mfma_f32_16x16x32_bf16 v[114:117], v[178:181], v[186:189], v[114:117]
	v_mfma_f32_16x16x32_bf16 v[102:105], v[170:173], v[194:197], v[102:105]
	v_mfma_f32_16x16x32_bf16 v[98:101], v[178:181], v[194:197], v[98:101]
	v_mfma_f32_16x16x32_bf16 v[86:89], v[170:173], v[202:205], v[86:89]
	v_mfma_f32_16x16x32_bf16 v[82:85], v[178:181], v[202:205], v[82:85]
	v_mfma_f32_16x16x32_bf16 v[70:73], v[170:173], v[210:213], v[70:73]
	v_mfma_f32_16x16x32_bf16 v[66:69], v[178:181], v[210:213], v[66:69]
	s_setprio 2
	s_barrier
; #define PG8_STAGE(bufoff, gbase, voff) do { _Pragma("unroll") for (int _i = 0; _i < 2; ++_i) \
;         __builtin_amdgcn_global_load_lds((const unsigned*)((const char*)(gbase) + (voff)[_i]), (LAS unsigned*)(lds + (bufoff) + ldsw + _i * 8192), 16, 0, 0); } while (0)
; #define PG8_LDA(dst, b, h) do { _Pragma("unroll") for (int m = 0; m < 4; ++m) _Pragma("unroll") for (int k = 0; k < 2; ++k) dst[m][k] = *(const LAS bf16x8*)(lds + PG8_SA(b, h) + aoff + m * 2048 + k * 1024); } while (0)
; #define PG8_MMA(ai, bj, At, Bt) do { __builtin_amdgcn_s_setprio(1); _Pragma("unroll") for (int m = 0; m < 4; ++m) _Pragma("unroll") for (int n = 0; n < 2; ++n) _Pragma("unroll") for (int k = 0; k < 2; ++k) \
;         acc[ai][bj][m][n] = __builtin_amdgcn_mfma_f32_16x16x32_bf16(Bt[n][k], At[m][k], acc[ai][bj][m][n], 0, 0, 0); __builtin_amdgcn_s_setprio(0); } while (0)
; #define PG8_WAIT_V(n) asm volatile("s_waitcnt vmcnt(" #n ")" ::: "memory")
; #define PG8_WAIT_L(n) asm volatile("s_waitcnt lgkmcnt(" #n ")" ::: "memory")
; #define PG8_BAR __builtin_amdgcn_s_barrier()
; #define PG8_SCHED __builtin_amdgcn_sched_barrier(0)
; template <class Epi>
; __device__ __forceinline__ void gemm_phase(LAS unsigned char* lds, const Gemm g, int G, int c, const Epi& E) {
;     ...
;             PG8_LDA(At, 1, 1); PG8_STAGE(PG8_SB(1, 0), b3, voffB); PG8_STAGE(PG8_SB(1, 1), b3 + hstepB, voffB); PG8_STAGE(PG8_SA(1, 0), a3, voffA);
;             PG8_WAIT_V(8); PG8_WAIT_L(0); PG8_BAR; PG8_MMA(1, 0, At, B0); PG8_MMA(1, 1, At, B1); PG8_BAR; PG8_SCHED;
;         }
	ds_read_b128 v[182:185], v162 offset:49152
	ds_read_b128 v[186:189], v162 offset:50176
	ds_read_b128 v[190:193], v162 offset:51200
	ds_read_b128 v[194:197], v162 offset:52224
	ds_read_b128 v[198:201], v162 offset:53248
	ds_read_b128 v[202:205], v162 offset:54272
	ds_read_b128 v[206:209], v162 offset:55296
	ds_read_b128 v[210:213], v162 offset:56320
	s_mov_b32 m0, s96
	v_lshl_add_u64 v[214:215], v[214:215], 0, s[22:23]
	global_load_lds_dwordx4 v[214:215], off
	v_lshl_add_u64 v[214:215], v[216:217], 0, s[22:23]
	s_mov_b32 m0, s94
	s_nop 0
	global_load_lds_dwordx4 v[214:215], off
	v_lshl_add_u64 v[214:215], s[10:11], 0, v[132:133]
	s_mov_b32 m0, s95
	s_nop 0
	global_load_lds_dwordx4 v[214:215], off
	v_lshl_add_u64 v[214:215], s[10:11], 0, v[136:137]
	s_mov_b32 m0, s93
	s_nop 0
	global_load_lds_dwordx4 v[214:215], off
	v_lshl_add_u64 v[214:215], v[218:219], 0, s[22:23]
	s_mov_b32 m0, s80
	s_nop 0
	global_load_lds_dwordx4 v[214:215], off
	v_lshl_add_u64 v[214:215], v[220:221], 0, s[22:23]
	s_mov_b32 m0, s81
	s_nop 0
	global_load_lds_dwordx4 v[214:215], off
	s_waitcnt vmcnt(8)
	s_waitcnt lgkmcnt(0)
	s_barrier
	s_setprio 0
	v_mfma_f32_16x16x32_bf16 v[62:65], v[142:145], v[182:185], v[62:65]
	v_mfma_f32_16x16x32_bf16 v[58:61], v[150:153], v[182:185], v[58:61]
	v_mfma_f32_16x16x32_bf16 v[46:49], v[142:145], v[190:193], v[46:49]
	v_mfma_f32_16x16x32_bf16 v[42:45], v[150:153], v[190:193], v[42:45]
	v_mfma_f32_16x16x32_bf16 v[30:33], v[142:145], v[198:201], v[30:33]
	v_mfma_f32_16x16x32_bf16 v[26:29], v[150:153], v[198:201], v[26:29]
	v_mfma_f32_16x16x32_bf16 v[14:17], v[142:145], v[206:209], v[14:17]
	v_mfma_f32_16x16x32_bf16 v[10:13], v[150:153], v[206:209], v[10:13]
	v_mfma_f32_16x16x32_bf16 v[62:65], v[146:149], v[186:189], v[62:65]
	v_mfma_f32_16x16x32_bf16 v[58:61], v[154:157], v[186:189], v[58:61]
	v_mfma_f32_16x16x32_bf16 v[46:49], v[146:149], v[194:197], v[46:49]
	v_mfma_f32_16x16x32_bf16 v[42:45], v[154:157], v[194:197], v[42:45]
	v_mfma_f32_16x16x32_bf16 v[30:33], v[146:149], v[202:205], v[30:33]
	v_mfma_f32_16x16x32_bf16 v[26:29], v[154:157], v[202:205], v[26:29]
	v_mfma_f32_16x16x32_bf16 v[14:17], v[146:149], v[210:213], v[14:17]
	v_mfma_f32_16x16x32_bf16 v[10:13], v[154:157], v[210:213], v[10:13]
	s_setprio 2
	s_setprio 0
	v_mfma_f32_16x16x32_bf16 v[54:57], v[166:169], v[182:185], v[54:57]
	v_mfma_f32_16x16x32_bf16 v[50:53], v[174:177], v[182:185], v[50:53]
	v_mfma_f32_16x16x32_bf16 v[38:41], v[166:169], v[190:193], v[38:41]
	v_mfma_f32_16x16x32_bf16 v[34:37], v[174:177], v[190:193], v[34:37]
	v_mfma_f32_16x16x32_bf16 v[22:25], v[166:169], v[198:201], v[22:25]
	v_mfma_f32_16x16x32_bf16 v[18:21], v[174:177], v[198:201], v[18:21]
	v_mfma_f32_16x16x32_bf16 v[6:9], v[166:169], v[206:209], v[6:9]
	v_mfma_f32_16x16x32_bf16 v[2:5], v[174:177], v[206:209], v[2:5]
	v_mfma_f32_16x16x32_bf16 v[54:57], v[170:173], v[186:189], v[54:57]
	v_mfma_f32_16x16x32_bf16 v[50:53], v[178:181], v[186:189], v[50:53]
	v_mfma_f32_16x16x32_bf16 v[38:41], v[170:173], v[194:197], v[38:41]
	v_mfma_f32_16x16x32_bf16 v[34:37], v[178:181], v[194:197], v[34:37]
	v_mfma_f32_16x16x32_bf16 v[22:25], v[170:173], v[202:205], v[22:25]
	v_mfma_f32_16x16x32_bf16 v[18:21], v[178:181], v[202:205], v[18:21]
	v_mfma_f32_16x16x32_bf16 v[6:9], v[170:173], v[210:213], v[6:9]
	v_mfma_f32_16x16x32_bf16 v[2:5], v[178:181], v[210:213], v[2:5]
	s_setprio 2
	s_barrier
	s_movk_i32 s44, 0x100
	s_andn2_b64 vcc, exec, s[4:5]
	s_mov_b64 s[10:11], -1
	s_mov_b64 s[4:5], 0
	s_cbranch_vccz .LBB0_1451
	s_and_b64 vcc, exec, s[24:25]
	s_cbranch_vccz .LBB0_1454
	s_barrier

; #define PG8_STAGE(bufoff, gbase, voff) do { _Pragma("unroll") for (int _i = 0; _i < 2; ++_i) \
;         __builtin_amdgcn_global_load_lds((const unsigned*)((const char*)(gbase) + (voff)[_i]), (LAS unsigned*)(lds + (bufoff) + ldsw + _i * 8192), 16, 0, 0); } while (0)
; #define PG8_LDA(dst, b, h) do { _Pragma("unroll") for (int m = 0; m < 4; ++m) _Pragma("unroll") for (int k = 0; k < 2; ++k) dst[m][k] = *(const LAS bf16x8*)(lds + PG8_SA(b, h) + aoff + m * 2048 + k * 1024); } while (0)
; #define PG8_LDB(dst, b, h) do { _Pragma("unroll") for (int n = 0; n < 2; ++n) _Pragma("unroll") for (int k = 0; k < 2; ++k) dst[n][k] = *(const LAS bf16x8*)(lds + PG8_SB(b, h) + boff + n * 2048 + k * 1024); } while (0)
; #define PG8_MMA(ai, bj, At, Bt) do { __builtin_amdgcn_s_setprio(1); _Pragma("unroll") for (int m = 0; m < 4; ++m) _Pragma("unroll") for (int n = 0; n < 2; ++n) _Pragma("unroll") for (int k = 0; k < 2; ++k) \
;         acc[ai][bj][m][n] = __builtin_amdgcn_mfma_f32_16x16x32_bf16(Bt[n][k], At[m][k], acc[ai][bj][m][n], 0, 0, 0); __builtin_amdgcn_s_setprio(0); } while (0)
; #define PG8_WAIT_V(n) asm volatile("s_waitcnt vmcnt(" #n ")" ::: "memory")
; #define PG8_WAIT_L(n) asm volatile("s_waitcnt lgkmcnt(" #n ")" ::: "memory")
; #define PG8_BAR __builtin_amdgcn_s_barrier()
; #define PG8_SCHED __builtin_amdgcn_sched_barrier(0)
; template <class Epi>
; __device__ __forceinline__ void gemm_phase(LAS unsigned char* lds, const Gemm g, int G, int c, const Epi& E) {
;     ...
;             const bool last = (t == nt - 2);
;             const char* a1 = cA + (size_t)(t + 1) * kstep;
;             const char* a2 = last ? nA : cA + (size_t)(t + 2) * kstep; const char* b2 = last ? nB : cB + (size_t)(t + 2) * kstep;
;             const char* a3 = a2 + kstep; const char* b3 = b2 + kstep;
;             PG8_LDB(B0, 0, 0); PG8_LDB(B1, 0, 1); PG8_SCHED; PG8_LDA(At, 0, 0); PG8_STAGE(PG8_SA(1, 1), a1 + hstepA, voffA);
;             PG8_WAIT_V(8); PG8_WAIT_L(0); PG8_BAR; PG8_MMA(0, 0, At, B0); PG8_MMA(0, 1, At, B1); PG8_BAR; PG8_SCHED;
;             PG8_LDA(At, 0, 1); PG8_STAGE(PG8_SB(0, 0), b2, voffB); PG8_STAGE(PG8_SB(0, 1), b2 + hstepB, voffB); PG8_STAGE(PG8_SA(0, 0), a2, voffA);
;             PG8_WAIT_V(8); PG8_WAIT_L(0); PG8_BAR; PG8_MMA(1, 0, At, B0); PG8_MMA(1, 1, At, B1); PG8_BAR; PG8_SCHED;
.LBB0_1537:
	ds_read_b128 v[130:133], v166
	ds_read_b128 v[134:137], v166 offset:1024
	ds_read_b128 v[150:153], v166 offset:2048
	ds_read_b128 v[154:157], v166 offset:3072
	ds_read_b128 v[158:161], v167
	ds_read_b128 v[172:175], v167 offset:1024
	ds_read_b128 v[176:179], v167 offset:2048
	ds_read_b128 v[180:183], v167 offset:3072
	ds_read_b128 v[184:187], v168
	ds_read_b128 v[188:191], v168 offset:1024
	ds_read_b128 v[192:195], v168 offset:2048
	ds_read_b128 v[196:199], v168 offset:3072
	ds_read_b128 v[200:203], v168 offset:4096
	ds_read_b128 v[204:207], v168 offset:5120
	ds_read_b128 v[208:211], v168 offset:6144
	ds_read_b128 v[212:215], v168 offset:7168
	s_add_u32 s33, s8, s44
	s_addc_u32 s45, s9, 0
	s_add_u32 s48, s33, 0x100
	s_addc_u32 s49, s45, 0
	s_and_b64 s[46:47], s[10:11], exec
	s_cselect_b32 s47, s41, s49
	s_cselect_b32 s46, s40, s48
	s_add_u32 s44, s6, s44
	s_addc_u32 s48, s7, 0
	s_add_u32 s44, s44, 0x100
	s_addc_u32 s48, s48, 0
	s_and_b64 s[10:11], s[10:11], exec
	s_cselect_b32 s49, s43, s48
	s_cselect_b32 s48, s42, s44
	s_add_u32 s54, s33, 0xb0080
	s_addc_u32 s55, s45, 0
	s_add_i32 s63, s87, s70
	s_add_i32 m0, s73, 0xc000
	s_add_i32 s64, s73, 0xe000
	s_add_i32 s74, s63, 0x2000
	s_add_u32 s52, s48, 0xb0000
	s_addc_u32 s53, s49, 0
	s_add_i32 s62, s88, s70
	s_add_i32 s75, s62, 0x2000
	s_add_i32 s97, 0, 0x18000
	s_add_i32 s33, 0, 0x1c000
	s_add_u32 s44, s46, 0xb0000
	s_addc_u32 s45, s47, 0
	s_add_i32 s96, s97, s70
	s_add_i32 s94, s96, 0x2000
	s_add_u32 s10, s48, 0xb0080
	s_addc_u32 s11, s49, 0
	s_add_i32 s95, s33, s70
	s_add_i32 s93, s95, 0x2000
	v_lshl_add_u64 v[162:163], s[54:55], 0, v[138:139]
	global_load_lds_dwordx4 v[162:163], off
	v_lshl_add_u64 v[162:163], s[54:55], 0, v[142:143]
	s_mov_b32 m0, s64
	s_nop 0
	global_load_lds_dwordx4 v[162:163], off
	s_waitcnt vmcnt(8)
	s_waitcnt lgkmcnt(0)
	s_barrier
	s_setprio 0
	v_mfma_f32_16x16x32_bf16 v[126:129], v[130:133], v[184:187], v[126:129]
	v_mfma_f32_16x16x32_bf16 v[122:125], v[150:153], v[184:187], v[122:125]
	v_mfma_f32_16x16x32_bf16 v[110:113], v[130:133], v[192:195], v[110:113]
	v_mfma_f32_16x16x32_bf16 v[106:109], v[150:153], v[192:195], v[106:109]
	v_mfma_f32_16x16x32_bf16 v[94:97], v[130:133], v[200:203], v[94:97]
	v_mfma_f32_16x16x32_bf16 v[90:93], v[150:153], v[200:203], v[90:93]
	v_mfma_f32_16x16x32_bf16 v[78:81], v[130:133], v[208:211], v[78:81]
	v_mfma_f32_16x16x32_bf16 v[74:77], v[150:153], v[208:211], v[74:77]
	v_mfma_f32_16x16x32_bf16 v[126:129], v[134:137], v[188:191], v[126:129]
	v_mfma_f32_16x16x32_bf16 v[122:125], v[154:157], v[188:191], v[122:125]
	v_mfma_f32_16x16x32_bf16 v[110:113], v[134:137], v[196:199], v[110:113]
	v_mfma_f32_16x16x32_bf16 v[106:109], v[154:157], v[196:199], v[106:109]
	v_mfma_f32_16x16x32_bf16 v[94:97], v[134:137], v[204:207], v[94:97]
	v_mfma_f32_16x16x32_bf16 v[90:93], v[154:157], v[204:207], v[90:93]
	v_mfma_f32_16x16x32_bf16 v[78:81], v[134:137], v[212:215], v[78:81]
	v_mfma_f32_16x16x32_bf16 v[74:77], v[154:157], v[212:215], v[74:77]
	s_setprio 2
	s_setprio 0
	v_mfma_f32_16x16x32_bf16 v[118:121], v[158:161], v[184:187], v[118:121]
	v_mfma_f32_16x16x32_bf16 v[114:117], v[176:179], v[184:187], v[114:117]
	v_mfma_f32_16x16x32_bf16 v[102:105], v[158:161], v[192:195], v[102:105]
	v_mfma_f32_16x16x32_bf16 v[98:101], v[176:179], v[192:195], v[98:101]
	v_mfma_f32_16x16x32_bf16 v[86:89], v[158:161], v[200:203], v[86:89]
	v_mfma_f32_16x16x32_bf16 v[82:85], v[176:179], v[200:203], v[82:85]
	v_mfma_f32_16x16x32_bf16 v[70:73], v[158:161], v[208:211], v[70:73]
	v_mfma_f32_16x16x32_bf16 v[66:69], v[176:179], v[208:211], v[66:69]
	v_mfma_f32_16x16x32_bf16 v[118:121], v[172:175], v[188:191], v[118:121]
	v_mfma_f32_16x16x32_bf16 v[114:117], v[180:183], v[188:191], v[114:117]
	v_mfma_f32_16x16x32_bf16 v[102:105], v[172:175], v[196:199], v[102:105]
	v_mfma_f32_16x16x32_bf16 v[98:101], v[180:183], v[196:199], v[98:101]
	v_mfma_f32_16x16x32_bf16 v[86:89], v[172:175], v[204:207], v[86:89]
	v_mfma_f32_16x16x32_bf16 v[82:85], v[180:183], v[204:207], v[82:85]
	v_mfma_f32_16x16x32_bf16 v[70:73], v[172:175], v[212:215], v[70:73]
	v_mfma_f32_16x16x32_bf16 v[66:69], v[180:183], v[212:215], v[66:69]
	s_setprio 2
	s_barrier
	ds_read_b128 v[184:187], v168 offset:16384
	ds_read_b128 v[188:191], v168 offset:17408
	ds_read_b128 v[192:195], v168 offset:18432
	ds_read_b128 v[196:199], v168 offset:19456
	ds_read_b128 v[200:203], v168 offset:20480
	ds_read_b128 v[204:207], v168 offset:21504
	ds_read_b128 v[208:211], v168 offset:22528
	ds_read_b128 v[212:215], v168 offset:23552
	s_mov_b32 m0, s63
	v_lshl_add_u64 v[162:163], s[48:49], 0, v[140:141]
	global_load_lds_dwordx4 v[162:163], off
	v_lshl_add_u64 v[216:217], s[48:49], 0, v[144:145]
	s_mov_b32 m0, s74
	v_lshl_add_u64 v[218:219], s[52:53], 0, v[140:141]
	global_load_lds_dwordx4 v[216:217], off
	s_mov_b32 m0, s62
	v_lshl_add_u64 v[220:221], s[46:47], 0, v[142:143]
	global_load_lds_dwordx4 v[218:219], off
	v_lshl_add_u64 v[218:219], s[52:53], 0, v[144:145]
	s_mov_b32 m0, s75
	s_nop 0
	global_load_lds_dwordx4 v[218:219], off
	v_lshl_add_u64 v[218:219], s[46:47], 0, v[138:139]
	s_mov_b32 m0, s73
	s_nop 0
	global_load_lds_dwordx4 v[218:219], off
	s_mov_b32 m0, s79
	s_nop 0
	global_load_lds_dwordx4 v[220:221], off
	s_waitcnt vmcnt(8)
	s_waitcnt lgkmcnt(0)
	s_barrier
; #define PG8_STAGE(bufoff, gbase, voff) do { _Pragma("unroll") for (int _i = 0; _i < 2; ++_i) \
;         __builtin_amdgcn_global_load_lds((const unsigned*)((const char*)(gbase) + (voff)[_i]), (LAS unsigned*)(lds + (bufoff) + ldsw + _i * 8192), 16, 0, 0); } while (0)
; #define PG8_LDA(dst, b, h) do { _Pragma("unroll") for (int m = 0; m < 4; ++m) _Pragma("unroll") for (int k = 0; k < 2; ++k) dst[m][k] = *(const LAS bf16x8*)(lds + PG8_SA(b, h) + aoff + m * 2048 + k * 1024); } while (0)
; #define PG8_LDB(dst, b, h) do { _Pragma("unroll") for (int n = 0; n < 2; ++n) _Pragma("unroll") for (int k = 0; k < 2; ++k) dst[n][k] = *(const LAS bf16x8*)(lds + PG8_SB(b, h) + boff + n * 2048 + k * 1024); } while (0)
; #define PG8_MMA(ai, bj, At, Bt) do { __builtin_amdgcn_s_setprio(1); _Pragma("unroll") for (int m = 0; m < 4; ++m) _Pragma("unroll") for (int n = 0; n < 2; ++n) _Pragma("unroll") for (int k = 0; k < 2; ++k) \
;         acc[ai][bj][m][n] = __builtin_amdgcn_mfma_f32_16x16x32_bf16(Bt[n][k], At[m][k], acc[ai][bj][m][n], 0, 0, 0); __builtin_amdgcn_s_setprio(0); } while (0)
; #define PG8_WAIT_V(n) asm volatile("s_waitcnt vmcnt(" #n ")" ::: "memory")
; #define PG8_WAIT_L(n) asm volatile("s_waitcnt lgkmcnt(" #n ")" ::: "memory")
; #define PG8_BAR __builtin_amdgcn_s_barrier()
; #define PG8_SCHED __builtin_amdgcn_sched_barrier(0)
; template <class Epi>
; __device__ __forceinline__ void gemm_phase(LAS unsigned char* lds, const Gemm g, int G, int c, const Epi& E) {
;     ...
;             PG8_WAIT_V(8); PG8_WAIT_L(0); PG8_BAR; PG8_MMA(1, 0, At, B0); PG8_MMA(1, 1, At, B1); PG8_BAR; PG8_SCHED;
;             PG8_LDB(B0, 1, 0); PG8_LDB(B1, 1, 1); PG8_SCHED; PG8_LDA(At, 1, 0); PG8_STAGE(PG8_SA(0, 1), a2 + hstepA, voffA);
;             PG8_WAIT_V(8); PG8_WAIT_L(0); PG8_BAR; PG8_MMA(0, 0, At, B0); PG8_MMA(0, 1, At, B1); PG8_BAR; PG8_SCHED;
	s_setprio 0
	v_mfma_f32_16x16x32_bf16 v[62:65], v[130:133], v[184:187], v[62:65]
	v_mfma_f32_16x16x32_bf16 v[58:61], v[150:153], v[184:187], v[58:61]
	v_mfma_f32_16x16x32_bf16 v[46:49], v[130:133], v[192:195], v[46:49]
	v_mfma_f32_16x16x32_bf16 v[42:45], v[150:153], v[192:195], v[42:45]
	v_mfma_f32_16x16x32_bf16 v[30:33], v[130:133], v[200:203], v[30:33]
	v_mfma_f32_16x16x32_bf16 v[26:29], v[150:153], v[200:203], v[26:29]
	v_mfma_f32_16x16x32_bf16 v[14:17], v[130:133], v[208:211], v[14:17]
	v_mfma_f32_16x16x32_bf16 v[10:13], v[150:153], v[208:211], v[10:13]
	v_mfma_f32_16x16x32_bf16 v[62:65], v[134:137], v[188:191], v[62:65]
	v_mfma_f32_16x16x32_bf16 v[58:61], v[154:157], v[188:191], v[58:61]
	v_mfma_f32_16x16x32_bf16 v[46:49], v[134:137], v[196:199], v[46:49]
	v_mfma_f32_16x16x32_bf16 v[42:45], v[154:157], v[196:199], v[42:45]
	v_mfma_f32_16x16x32_bf16 v[30:33], v[134:137], v[204:207], v[30:33]
	v_mfma_f32_16x16x32_bf16 v[26:29], v[154:157], v[204:207], v[26:29]
	v_mfma_f32_16x16x32_bf16 v[14:17], v[134:137], v[212:215], v[14:17]
	v_mfma_f32_16x16x32_bf16 v[10:13], v[154:157], v[212:215], v[10:13]
	s_setprio 2
	s_setprio 0
	v_mfma_f32_16x16x32_bf16 v[54:57], v[158:161], v[184:187], v[54:57]
	v_mfma_f32_16x16x32_bf16 v[50:53], v[176:179], v[184:187], v[50:53]
	v_mfma_f32_16x16x32_bf16 v[38:41], v[158:161], v[192:195], v[38:41]
	v_mfma_f32_16x16x32_bf16 v[34:37], v[176:179], v[192:195], v[34:37]
	v_mfma_f32_16x16x32_bf16 v[22:25], v[158:161], v[200:203], v[22:25]
	v_mfma_f32_16x16x32_bf16 v[18:21], v[176:179], v[200:203], v[18:21]
	v_mfma_f32_16x16x32_bf16 v[6:9], v[158:161], v[208:211], v[6:9]
	v_mfma_f32_16x16x32_bf16 v[2:5], v[176:179], v[208:211], v[2:5]
	v_mfma_f32_16x16x32_bf16 v[54:57], v[172:175], v[188:191], v[54:57]
	v_mfma_f32_16x16x32_bf16 v[50:53], v[180:183], v[188:191], v[50:53]
	v_mfma_f32_16x16x32_bf16 v[38:41], v[172:175], v[196:199], v[38:41]
	v_mfma_f32_16x16x32_bf16 v[34:37], v[180:183], v[196:199], v[34:37]
	v_mfma_f32_16x16x32_bf16 v[22:25], v[172:175], v[204:207], v[22:25]
	v_mfma_f32_16x16x32_bf16 v[18:21], v[180:183], v[204:207], v[18:21]
	v_mfma_f32_16x16x32_bf16 v[6:9], v[172:175], v[212:215], v[6:9]
	v_mfma_f32_16x16x32_bf16 v[2:5], v[180:183], v[212:215], v[2:5]
	s_setprio 2
	s_barrier
	v_add_u32_e32 v154, s97, v165
	v_add_u32_e32 v180, s33, v165
	ds_read_b128 v[130:133], v154
	ds_read_b128 v[134:137], v154 offset:1024
	ds_read_b128 v[150:153], v154 offset:2048
	ds_read_b128 v[154:157], v154 offset:3072
	ds_read_b128 v[158:161], v180
	ds_read_b128 v[172:175], v180 offset:1024
	ds_read_b128 v[176:179], v180 offset:2048
	ds_read_b128 v[180:183], v180 offset:3072
	ds_read_b128 v[184:187], v168 offset:32768
	ds_read_b128 v[188:191], v168 offset:33792
	ds_read_b128 v[192:195], v168 offset:34816
	ds_read_b128 v[196:199], v168 offset:35840
	ds_read_b128 v[200:203], v168 offset:36864
	ds_read_b128 v[204:207], v168 offset:37888
	ds_read_b128 v[208:211], v168 offset:38912
	ds_read_b128 v[212:215], v168 offset:39936
	s_mov_b32 m0, s80
	v_lshl_add_u64 v[222:223], s[44:45], 0, v[138:139]
	global_load_lds_dwordx4 v[222:223], off
	v_lshl_add_u64 v[222:223], s[44:45], 0, v[142:143]
	s_mov_b32 m0, s81
	s_nop 0
	global_load_lds_dwordx4 v[222:223], off
	s_waitcnt vmcnt(8)
	s_waitcnt lgkmcnt(0)
	s_barrier
	s_setprio 0
	v_mfma_f32_16x16x32_bf16 v[126:129], v[130:133], v[184:187], v[126:129]
	v_mfma_f32_16x16x32_bf16 v[122:125], v[150:153], v[184:187], v[122:125]
	v_mfma_f32_16x16x32_bf16 v[110:113], v[130:133], v[192:195], v[110:113]
	v_mfma_f32_16x16x32_bf16 v[106:109], v[150:153], v[192:195], v[106:109]
	v_mfma_f32_16x16x32_bf16 v[94:97], v[130:133], v[200:203], v[94:97]
	v_mfma_f32_16x16x32_bf16 v[90:93], v[150:153], v[200:203], v[90:93]
	v_mfma_f32_16x16x32_bf16 v[78:81], v[130:133], v[208:211], v[78:81]
	v_mfma_f32_16x16x32_bf16 v[74:77], v[150:153], v[208:211], v[74:77]
	v_mfma_f32_16x16x32_bf16 v[126:129], v[134:137], v[188:191], v[126:129]
	v_mfma_f32_16x16x32_bf16 v[122:125], v[154:157], v[188:191], v[122:125]
	v_mfma_f32_16x16x32_bf16 v[110:113], v[134:137], v[196:199], v[110:113]
	v_mfma_f32_16x16x32_bf16 v[106:109], v[154:157], v[196:199], v[106:109]
	v_mfma_f32_16x16x32_bf16 v[94:97], v[134:137], v[204:207], v[94:97]
	v_mfma_f32_16x16x32_bf16 v[90:93], v[154:157], v[204:207], v[90:93]
	v_mfma_f32_16x16x32_bf16 v[78:81], v[134:137], v[212:215], v[78:81]
	v_mfma_f32_16x16x32_bf16 v[74:77], v[154:157], v[212:215], v[74:77]
	s_setprio 2
	s_setprio 0
	v_mfma_f32_16x16x32_bf16 v[118:121], v[158:161], v[184:187], v[118:121]
	v_mfma_f32_16x16x32_bf16 v[114:117], v[176:179], v[184:187], v[114:117]
	v_mfma_f32_16x16x32_bf16 v[102:105], v[158:161], v[192:195], v[102:105]
	v_mfma_f32_16x16x32_bf16 v[98:101], v[176:179], v[192:195], v[98:101]
	v_mfma_f32_16x16x32_bf16 v[86:89], v[158:161], v[200:203], v[86:89]
	v_mfma_f32_16x16x32_bf16 v[82:85], v[176:179], v[200:203], v[82:85]
	v_mfma_f32_16x16x32_bf16 v[70:73], v[158:161], v[208:211], v[70:73]
	v_mfma_f32_16x16x32_bf16 v[66:69], v[176:179], v[208:211], v[66:69]
	v_mfma_f32_16x16x32_bf16 v[118:121], v[172:175], v[188:191], v[118:121]
	v_mfma_f32_16x16x32_bf16 v[114:117], v[180:183], v[188:191], v[114:117]
	v_mfma_f32_16x16x32_bf16 v[102:105], v[172:175], v[196:199], v[102:105]
	v_mfma_f32_16x16x32_bf16 v[98:101], v[180:183], v[196:199], v[98:101]
	v_mfma_f32_16x16x32_bf16 v[86:89], v[172:175], v[204:207], v[86:89]
	v_mfma_f32_16x16x32_bf16 v[82:85], v[180:183], v[204:207], v[82:85]
	v_mfma_f32_16x16x32_bf16 v[70:73], v[172:175], v[212:215], v[70:73]
	v_mfma_f32_16x16x32_bf16 v[66:69], v[180:183], v[212:215], v[66:69]
	s_setprio 2
	s_barrier
; #define PG8_STAGE(bufoff, gbase, voff) do { _Pragma("unroll") for (int _i = 0; _i < 2; ++_i) \
;         __builtin_amdgcn_global_load_lds((const unsigned*)((const char*)(gbase) + (voff)[_i]), (LAS unsigned*)(lds + (bufoff) + ldsw + _i * 8192), 16, 0, 0); } while (0)
; #define PG8_LDA(dst, b, h) do { _Pragma("unroll") for (int m = 0; m < 4; ++m) _Pragma("unroll") for (int k = 0; k < 2; ++k) dst[m][k] = *(const LAS bf16x8*)(lds + PG8_SA(b, h) + aoff + m * 2048 + k * 1024); } while (0)
; #define PG8_MMA(ai, bj, At, Bt) do { __builtin_amdgcn_s_setprio(1); _Pragma("unroll") for (int m = 0; m < 4; ++m) _Pragma("unroll") for (int n = 0; n < 2; ++n) _Pragma("unroll") for (int k = 0; k < 2; ++k) \
;         acc[ai][bj][m][n] = __builtin_amdgcn_mfma_f32_16x16x32_bf16(Bt[n][k], At[m][k], acc[ai][bj][m][n], 0, 0, 0); __builtin_amdgcn_s_setprio(0); } while (0)
; #define PG8_WAIT_V(n) asm volatile("s_waitcnt vmcnt(" #n ")" ::: "memory")
; #define PG8_WAIT_L(n) asm volatile("s_waitcnt lgkmcnt(" #n ")" ::: "memory")
; #define PG8_BAR __builtin_amdgcn_s_barrier()
; #define PG8_SCHED __builtin_amdgcn_sched_barrier(0)
; template <class Epi>
; __device__ __forceinline__ void gemm_phase(LAS unsigned char* lds, const Gemm g, int G, int c, const Epi& E) {
;     ...
;             PG8_LDA(At, 1, 1); PG8_STAGE(PG8_SB(1, 0), b3, voffB); PG8_STAGE(PG8_SB(1, 1), b3 + hstepB, voffB); PG8_STAGE(PG8_SA(1, 0), a3, voffA);
;             PG8_WAIT_V(8); PG8_WAIT_L(0); PG8_BAR; PG8_MMA(1, 0, At, B0); PG8_MMA(1, 1, At, B1); PG8_BAR; PG8_SCHED;
;         }
;         if (wr == 0) PG8_BAR;
	ds_read_b128 v[184:187], v168 offset:49152
	ds_read_b128 v[188:191], v168 offset:50176
	ds_read_b128 v[192:195], v168 offset:51200
	ds_read_b128 v[196:199], v168 offset:52224
	ds_read_b128 v[200:203], v168 offset:53248
	ds_read_b128 v[204:207], v168 offset:54272
	ds_read_b128 v[208:211], v168 offset:55296
	ds_read_b128 v[212:215], v168 offset:56320
	s_mov_b32 m0, s96
	v_lshl_add_u64 v[162:163], v[162:163], 0, s[22:23]
	global_load_lds_dwordx4 v[162:163], off
	v_lshl_add_u64 v[162:163], v[216:217], 0, s[22:23]
	s_mov_b32 m0, s94
	s_nop 0
	global_load_lds_dwordx4 v[162:163], off
	v_lshl_add_u64 v[162:163], s[10:11], 0, v[140:141]
	s_mov_b32 m0, s95
	s_nop 0
	global_load_lds_dwordx4 v[162:163], off
	v_lshl_add_u64 v[162:163], s[10:11], 0, v[144:145]
	s_mov_b32 m0, s93
	s_nop 0
	global_load_lds_dwordx4 v[162:163], off
	v_lshl_add_u64 v[162:163], v[218:219], 0, s[22:23]
	s_mov_b32 m0, s85
	s_nop 0
	global_load_lds_dwordx4 v[162:163], off
	v_lshl_add_u64 v[162:163], v[220:221], 0, s[22:23]
	s_mov_b32 m0, s86
	s_nop 0
	global_load_lds_dwordx4 v[162:163], off
	s_waitcnt vmcnt(8)
	s_waitcnt lgkmcnt(0)
	s_barrier
	s_setprio 0
	v_mfma_f32_16x16x32_bf16 v[62:65], v[130:133], v[184:187], v[62:65]
	v_mfma_f32_16x16x32_bf16 v[58:61], v[150:153], v[184:187], v[58:61]
	v_mfma_f32_16x16x32_bf16 v[46:49], v[130:133], v[192:195], v[46:49]
	v_mfma_f32_16x16x32_bf16 v[42:45], v[150:153], v[192:195], v[42:45]
	v_mfma_f32_16x16x32_bf16 v[30:33], v[130:133], v[200:203], v[30:33]
	v_mfma_f32_16x16x32_bf16 v[26:29], v[150:153], v[200:203], v[26:29]
	v_mfma_f32_16x16x32_bf16 v[14:17], v[130:133], v[208:211], v[14:17]
	v_mfma_f32_16x16x32_bf16 v[10:13], v[150:153], v[208:211], v[10:13]
	v_mfma_f32_16x16x32_bf16 v[62:65], v[134:137], v[188:191], v[62:65]
	v_mfma_f32_16x16x32_bf16 v[58:61], v[154:157], v[188:191], v[58:61]
	v_mfma_f32_16x16x32_bf16 v[46:49], v[134:137], v[196:199], v[46:49]
	v_mfma_f32_16x16x32_bf16 v[42:45], v[154:157], v[196:199], v[42:45]
	v_mfma_f32_16x16x32_bf16 v[30:33], v[134:137], v[204:207], v[30:33]
	v_mfma_f32_16x16x32_bf16 v[26:29], v[154:157], v[204:207], v[26:29]
	v_mfma_f32_16x16x32_bf16 v[14:17], v[134:137], v[212:215], v[14:17]
	v_mfma_f32_16x16x32_bf16 v[10:13], v[154:157], v[212:215], v[10:13]
	s_setprio 2
	s_setprio 0
	v_mfma_f32_16x16x32_bf16 v[54:57], v[158:161], v[184:187], v[54:57]
	v_mfma_f32_16x16x32_bf16 v[50:53], v[176:179], v[184:187], v[50:53]
	v_mfma_f32_16x16x32_bf16 v[38:41], v[158:161], v[192:195], v[38:41]
	v_mfma_f32_16x16x32_bf16 v[34:37], v[176:179], v[192:195], v[34:37]
	v_mfma_f32_16x16x32_bf16 v[22:25], v[158:161], v[200:203], v[22:25]
	v_mfma_f32_16x16x32_bf16 v[18:21], v[176:179], v[200:203], v[18:21]
	v_mfma_f32_16x16x32_bf16 v[6:9], v[158:161], v[208:211], v[6:9]
	v_mfma_f32_16x16x32_bf16 v[2:5], v[176:179], v[208:211], v[2:5]
	v_mfma_f32_16x16x32_bf16 v[54:57], v[172:175], v[188:191], v[54:57]
	v_mfma_f32_16x16x32_bf16 v[50:53], v[180:183], v[188:191], v[50:53]
	v_mfma_f32_16x16x32_bf16 v[38:41], v[172:175], v[196:199], v[38:41]
	v_mfma_f32_16x16x32_bf16 v[34:37], v[180:183], v[196:199], v[34:37]
	v_mfma_f32_16x16x32_bf16 v[22:25], v[172:175], v[204:207], v[22:25]
	v_mfma_f32_16x16x32_bf16 v[18:21], v[180:183], v[204:207], v[18:21]
	v_mfma_f32_16x16x32_bf16 v[6:9], v[172:175], v[212:215], v[6:9]
	v_mfma_f32_16x16x32_bf16 v[2:5], v[180:183], v[212:215], v[2:5]
	s_setprio 2
	s_barrier
	s_movk_i32 s44, 0x100
	s_andn2_b64 vcc, exec, s[4:5]
	s_mov_b64 s[10:11], -1
	s_mov_b64 s[4:5], 0
	s_cbranch_vccz .LBB0_1537
	s_and_b64 vcc, exec, s[24:25]
	s_cbranch_vccz .LBB0_1540
	s_barrier

; #define PG8_STAGE(bufoff, gbase, voff) do { _Pragma("unroll") for (int _i = 0; _i < 2; ++_i) \
;         __builtin_amdgcn_global_load_lds((const unsigned*)((const char*)(gbase) + (voff)[_i]), (LAS unsigned*)(lds + (bufoff) + ldsw + _i * 8192), 16, 0, 0); } while (0)
; #define PG8_LDA(dst, b, h) do { _Pragma("unroll") for (int m = 0; m < 4; ++m) _Pragma("unroll") for (int k = 0; k < 2; ++k) dst[m][k] = *(const LAS bf16x8*)(lds + PG8_SA(b, h) + aoff + m * 2048 + k * 1024); } while (0)
; #define PG8_LDB(dst, b, h) do { _Pragma("unroll") for (int n = 0; n < 2; ++n) _Pragma("unroll") for (int k = 0; k < 2; ++k) dst[n][k] = *(const LAS bf16x8*)(lds + PG8_SB(b, h) + boff + n * 2048 + k * 1024); } while (0)
; #define PG8_MMA(ai, bj, At, Bt) do { __builtin_amdgcn_s_setprio(1); _Pragma("unroll") for (int m = 0; m < 4; ++m) _Pragma("unroll") for (int n = 0; n < 2; ++n) _Pragma("unroll") for (int k = 0; k < 2; ++k) \
;         acc[ai][bj][m][n] = __builtin_amdgcn_mfma_f32_16x16x32_bf16(Bt[n][k], At[m][k], acc[ai][bj][m][n], 0, 0, 0); __builtin_amdgcn_s_setprio(0); } while (0)
; #define PG8_WAIT_V(n) asm volatile("s_waitcnt vmcnt(" #n ")" ::: "memory")
; #define PG8_WAIT_L(n) asm volatile("s_waitcnt lgkmcnt(" #n ")" ::: "memory")
; #define PG8_BAR __builtin_amdgcn_s_barrier()
; #define PG8_SCHED __builtin_amdgcn_sched_barrier(0)
; template <class Epi>
; __device__ __forceinline__ void gemm_phase(LAS unsigned char* lds, const Gemm g, int G, int c, const Epi& E) {
;     ...
;             const bool last = (t == nt - 2);
;             const char* a1 = cA + (size_t)(t + 1) * kstep;
;             const char* a2 = last ? nA : cA + (size_t)(t + 2) * kstep; const char* b2 = last ? nB : cB + (size_t)(t + 2) * kstep;
;             const char* a3 = a2 + kstep; const char* b3 = b2 + kstep;
;             PG8_LDB(B0, 0, 0); PG8_LDB(B1, 0, 1); PG8_SCHED; PG8_LDA(At, 0, 0); PG8_STAGE(PG8_SA(1, 1), a1 + hstepA, voffA);
;             PG8_WAIT_V(8); PG8_WAIT_L(0); PG8_BAR; PG8_MMA(0, 0, At, B0); PG8_MMA(0, 1, At, B1); PG8_BAR; PG8_SCHED;
;             PG8_LDA(At, 0, 1); PG8_STAGE(PG8_SB(0, 0), b2, voffB); PG8_STAGE(PG8_SB(0, 1), b2 + hstepB, voffB); PG8_STAGE(PG8_SA(0, 0), a2, voffA);
;             PG8_WAIT_V(8); PG8_WAIT_L(0); PG8_BAR; PG8_MMA(1, 0, At, B0); PG8_MMA(1, 1, At, B1); PG8_BAR; PG8_SCHED;
.LBB0_1653:
	ds_read_b128 v[142:145], v166
	ds_read_b128 v[146:149], v166 offset:1024
	ds_read_b128 v[150:153], v166 offset:2048
	ds_read_b128 v[154:157], v166 offset:3072
	ds_read_b128 v[158:161], v167
	ds_read_b128 v[170:173], v167 offset:1024
	ds_read_b128 v[174:177], v167 offset:2048
	ds_read_b128 v[178:181], v167 offset:3072
	ds_read_b128 v[182:185], v168
	ds_read_b128 v[186:189], v168 offset:1024
	ds_read_b128 v[190:193], v168 offset:2048
	ds_read_b128 v[194:197], v168 offset:3072
	ds_read_b128 v[198:201], v168 offset:4096
	ds_read_b128 v[202:205], v168 offset:5120
	ds_read_b128 v[206:209], v168 offset:6144
	ds_read_b128 v[210:213], v168 offset:7168
	s_add_u32 s33, s8, s48
	s_addc_u32 s49, s9, 0
	s_add_u32 s54, s33, 0x100
	s_addc_u32 s55, s49, 0
	s_and_b64 s[52:53], s[46:47], exec
	s_cselect_b32 s53, s41, s55
	s_cselect_b32 s52, s40, s54
	s_add_u32 s48, s6, s48
	s_addc_u32 s54, s7, 0
	s_add_u32 s48, s48, 0x100
	s_addc_u32 s54, s54, 0
	s_and_b64 s[46:47], s[46:47], exec
	s_cselect_b32 s55, s43, s54
	s_cselect_b32 s54, s42, s48
	s_add_u32 s58, s33, 0xb0080
	s_addc_u32 s59, s49, 0
	s_add_i32 s63, s80, s23
	s_add_i32 m0, s68, 0xc000
	s_add_i32 s64, s68, 0xe000
	s_add_i32 s74, s63, 0x2000
	s_add_u32 s56, s54, 0xb0000
	s_addc_u32 s57, s55, 0
	s_add_i32 s62, s81, s23
	s_add_i32 s75, s62, 0x2000
	s_add_i32 s93, 0, 0x18000
	s_add_i32 s33, 0, 0x1c000
	s_add_u32 s48, s52, 0xb0000
	s_addc_u32 s49, s53, 0
	s_add_i32 s92, s93, s23
	s_add_i32 s90, s92, 0x2000
	s_add_u32 s46, s54, 0xb0080
	s_addc_u32 s47, s55, 0
	s_add_i32 s91, s33, s23
	s_add_i32 s89, s91, 0x2000
	v_lshl_add_u64 v[162:163], s[58:59], 0, v[136:137]
	global_load_lds_dwordx4 v[162:163], off
	v_lshl_add_u64 v[162:163], s[58:59], 0, v[132:133]
	s_mov_b32 m0, s64
	s_nop 0
	global_load_lds_dwordx4 v[162:163], off
	s_waitcnt vmcnt(8)
	s_waitcnt lgkmcnt(0)
	s_barrier
	s_setprio 0
	v_mfma_f32_16x16x32_bf16 v[126:129], v[142:145], v[182:185], v[126:129]
	v_mfma_f32_16x16x32_bf16 v[122:125], v[150:153], v[182:185], v[122:125]
	v_mfma_f32_16x16x32_bf16 v[110:113], v[142:145], v[190:193], v[110:113]
	v_mfma_f32_16x16x32_bf16 v[106:109], v[150:153], v[190:193], v[106:109]
	v_mfma_f32_16x16x32_bf16 v[94:97], v[142:145], v[198:201], v[94:97]
	v_mfma_f32_16x16x32_bf16 v[90:93], v[150:153], v[198:201], v[90:93]
	v_mfma_f32_16x16x32_bf16 v[78:81], v[142:145], v[206:209], v[78:81]
	v_mfma_f32_16x16x32_bf16 v[74:77], v[150:153], v[206:209], v[74:77]
	v_mfma_f32_16x16x32_bf16 v[126:129], v[146:149], v[186:189], v[126:129]
	v_mfma_f32_16x16x32_bf16 v[122:125], v[154:157], v[186:189], v[122:125]
	v_mfma_f32_16x16x32_bf16 v[110:113], v[146:149], v[194:197], v[110:113]
	v_mfma_f32_16x16x32_bf16 v[106:109], v[154:157], v[194:197], v[106:109]
	v_mfma_f32_16x16x32_bf16 v[94:97], v[146:149], v[202:205], v[94:97]
	v_mfma_f32_16x16x32_bf16 v[90:93], v[154:157], v[202:205], v[90:93]
	v_mfma_f32_16x16x32_bf16 v[78:81], v[146:149], v[210:213], v[78:81]
	v_mfma_f32_16x16x32_bf16 v[74:77], v[154:157], v[210:213], v[74:77]
	s_setprio 2
	s_setprio 0
	v_mfma_f32_16x16x32_bf16 v[118:121], v[158:161], v[182:185], v[118:121]
	v_mfma_f32_16x16x32_bf16 v[114:117], v[174:177], v[182:185], v[114:117]
	v_mfma_f32_16x16x32_bf16 v[102:105], v[158:161], v[190:193], v[102:105]
	v_mfma_f32_16x16x32_bf16 v[98:101], v[174:177], v[190:193], v[98:101]
	v_mfma_f32_16x16x32_bf16 v[86:89], v[158:161], v[198:201], v[86:89]
	v_mfma_f32_16x16x32_bf16 v[82:85], v[174:177], v[198:201], v[82:85]
	v_mfma_f32_16x16x32_bf16 v[70:73], v[158:161], v[206:209], v[70:73]
	v_mfma_f32_16x16x32_bf16 v[66:69], v[174:177], v[206:209], v[66:69]
	v_mfma_f32_16x16x32_bf16 v[118:121], v[170:173], v[186:189], v[118:121]
	v_mfma_f32_16x16x32_bf16 v[114:117], v[178:181], v[186:189], v[114:117]
	v_mfma_f32_16x16x32_bf16 v[102:105], v[170:173], v[194:197], v[102:105]
	v_mfma_f32_16x16x32_bf16 v[98:101], v[178:181], v[194:197], v[98:101]
	v_mfma_f32_16x16x32_bf16 v[86:89], v[170:173], v[202:205], v[86:89]
	v_mfma_f32_16x16x32_bf16 v[82:85], v[178:181], v[202:205], v[82:85]
	v_mfma_f32_16x16x32_bf16 v[70:73], v[170:173], v[210:213], v[70:73]
	v_mfma_f32_16x16x32_bf16 v[66:69], v[178:181], v[210:213], v[66:69]
	s_setprio 2
	s_barrier
	ds_read_b128 v[182:185], v168 offset:16384
	ds_read_b128 v[186:189], v168 offset:17408
	ds_read_b128 v[190:193], v168 offset:18432
	ds_read_b128 v[194:197], v168 offset:19456
	ds_read_b128 v[198:201], v168 offset:20480
	ds_read_b128 v[202:205], v168 offset:21504
	ds_read_b128 v[206:209], v168 offset:22528
	ds_read_b128 v[210:213], v168 offset:23552
	s_mov_b32 m0, s63
	v_lshl_add_u64 v[162:163], s[54:55], 0, v[134:135]
	global_load_lds_dwordx4 v[162:163], off
	v_lshl_add_u64 v[214:215], s[54:55], 0, v[130:131]
	s_mov_b32 m0, s74
	v_lshl_add_u64 v[216:217], s[56:57], 0, v[134:135]
	global_load_lds_dwordx4 v[214:215], off
	s_mov_b32 m0, s62
	v_lshl_add_u64 v[218:219], s[52:53], 0, v[132:133]
	global_load_lds_dwordx4 v[216:217], off
	v_lshl_add_u64 v[216:217], s[56:57], 0, v[130:131]
	s_mov_b32 m0, s75
	s_nop 0
	global_load_lds_dwordx4 v[216:217], off
	v_lshl_add_u64 v[216:217], s[52:53], 0, v[136:137]
	s_mov_b32 m0, s68
	s_nop 0
	global_load_lds_dwordx4 v[216:217], off
	s_mov_b32 m0, s69
	s_nop 0
	global_load_lds_dwordx4 v[218:219], off
	s_waitcnt vmcnt(8)
	s_waitcnt lgkmcnt(0)
	s_barrier
; #define PG8_STAGE(bufoff, gbase, voff) do { _Pragma("unroll") for (int _i = 0; _i < 2; ++_i) \
;         __builtin_amdgcn_global_load_lds((const unsigned*)((const char*)(gbase) + (voff)[_i]), (LAS unsigned*)(lds + (bufoff) + ldsw + _i * 8192), 16, 0, 0); } while (0)
; #define PG8_LDA(dst, b, h) do { _Pragma("unroll") for (int m = 0; m < 4; ++m) _Pragma("unroll") for (int k = 0; k < 2; ++k) dst[m][k] = *(const LAS bf16x8*)(lds + PG8_SA(b, h) + aoff + m * 2048 + k * 1024); } while (0)
; #define PG8_LDB(dst, b, h) do { _Pragma("unroll") for (int n = 0; n < 2; ++n) _Pragma("unroll") for (int k = 0; k < 2; ++k) dst[n][k] = *(const LAS bf16x8*)(lds + PG8_SB(b, h) + boff + n * 2048 + k * 1024); } while (0)
; #define PG8_MMA(ai, bj, At, Bt) do { __builtin_amdgcn_s_setprio(1); _Pragma("unroll") for (int m = 0; m < 4; ++m) _Pragma("unroll") for (int n = 0; n < 2; ++n) _Pragma("unroll") for (int k = 0; k < 2; ++k) \
;         acc[ai][bj][m][n] = __builtin_amdgcn_mfma_f32_16x16x32_bf16(Bt[n][k], At[m][k], acc[ai][bj][m][n], 0, 0, 0); __builtin_amdgcn_s_setprio(0); } while (0)
; #define PG8_WAIT_V(n) asm volatile("s_waitcnt vmcnt(" #n ")" ::: "memory")
; #define PG8_WAIT_L(n) asm volatile("s_waitcnt lgkmcnt(" #n ")" ::: "memory")
; #define PG8_BAR __builtin_amdgcn_s_barrier()
; #define PG8_SCHED __builtin_amdgcn_sched_barrier(0)
; template <class Epi>
; __device__ __forceinline__ void gemm_phase(LAS unsigned char* lds, const Gemm g, int G, int c, const Epi& E) {
;     ...
;             PG8_WAIT_V(8); PG8_WAIT_L(0); PG8_BAR; PG8_MMA(1, 0, At, B0); PG8_MMA(1, 1, At, B1); PG8_BAR; PG8_SCHED;
;             PG8_LDB(B0, 1, 0); PG8_LDB(B1, 1, 1); PG8_SCHED; PG8_LDA(At, 1, 0); PG8_STAGE(PG8_SA(0, 1), a2 + hstepA, voffA);
;             PG8_WAIT_V(8); PG8_WAIT_L(0); PG8_BAR; PG8_MMA(0, 0, At, B0); PG8_MMA(0, 1, At, B1); PG8_BAR; PG8_SCHED;
	s_setprio 0
	v_mfma_f32_16x16x32_bf16 v[62:65], v[142:145], v[182:185], v[62:65]
	v_mfma_f32_16x16x32_bf16 v[58:61], v[150:153], v[182:185], v[58:61]
	v_mfma_f32_16x16x32_bf16 v[46:49], v[142:145], v[190:193], v[46:49]
	v_mfma_f32_16x16x32_bf16 v[42:45], v[150:153], v[190:193], v[42:45]
	v_mfma_f32_16x16x32_bf16 v[30:33], v[142:145], v[198:201], v[30:33]
	v_mfma_f32_16x16x32_bf16 v[26:29], v[150:153], v[198:201], v[26:29]
	v_mfma_f32_16x16x32_bf16 v[14:17], v[142:145], v[206:209], v[14:17]
	v_mfma_f32_16x16x32_bf16 v[10:13], v[150:153], v[206:209], v[10:13]
	v_mfma_f32_16x16x32_bf16 v[62:65], v[146:149], v[186:189], v[62:65]
	v_mfma_f32_16x16x32_bf16 v[58:61], v[154:157], v[186:189], v[58:61]
	v_mfma_f32_16x16x32_bf16 v[46:49], v[146:149], v[194:197], v[46:49]
	v_mfma_f32_16x16x32_bf16 v[42:45], v[154:157], v[194:197], v[42:45]
	v_mfma_f32_16x16x32_bf16 v[30:33], v[146:149], v[202:205], v[30:33]
	v_mfma_f32_16x16x32_bf16 v[26:29], v[154:157], v[202:205], v[26:29]
	v_mfma_f32_16x16x32_bf16 v[14:17], v[146:149], v[210:213], v[14:17]
	v_mfma_f32_16x16x32_bf16 v[10:13], v[154:157], v[210:213], v[10:13]
	s_setprio 2
	s_setprio 0
	v_mfma_f32_16x16x32_bf16 v[54:57], v[158:161], v[182:185], v[54:57]
	v_mfma_f32_16x16x32_bf16 v[50:53], v[174:177], v[182:185], v[50:53]
	v_mfma_f32_16x16x32_bf16 v[38:41], v[158:161], v[190:193], v[38:41]
	v_mfma_f32_16x16x32_bf16 v[34:37], v[174:177], v[190:193], v[34:37]
	v_mfma_f32_16x16x32_bf16 v[22:25], v[158:161], v[198:201], v[22:25]
	v_mfma_f32_16x16x32_bf16 v[18:21], v[174:177], v[198:201], v[18:21]
	v_mfma_f32_16x16x32_bf16 v[6:9], v[158:161], v[206:209], v[6:9]
	v_mfma_f32_16x16x32_bf16 v[2:5], v[174:177], v[206:209], v[2:5]
	v_mfma_f32_16x16x32_bf16 v[54:57], v[170:173], v[186:189], v[54:57]
	v_mfma_f32_16x16x32_bf16 v[50:53], v[178:181], v[186:189], v[50:53]
	v_mfma_f32_16x16x32_bf16 v[38:41], v[170:173], v[194:197], v[38:41]
	v_mfma_f32_16x16x32_bf16 v[34:37], v[178:181], v[194:197], v[34:37]
	v_mfma_f32_16x16x32_bf16 v[22:25], v[170:173], v[202:205], v[22:25]
	v_mfma_f32_16x16x32_bf16 v[18:21], v[178:181], v[202:205], v[18:21]
	v_mfma_f32_16x16x32_bf16 v[6:9], v[170:173], v[210:213], v[6:9]
	v_mfma_f32_16x16x32_bf16 v[2:5], v[178:181], v[210:213], v[2:5]
	s_setprio 2
	s_barrier
	v_add_u32_e32 v154, s93, v165
	v_add_u32_e32 v178, s33, v165
	ds_read_b128 v[142:145], v154
	ds_read_b128 v[146:149], v154 offset:1024
	ds_read_b128 v[150:153], v154 offset:2048
	ds_read_b128 v[154:157], v154 offset:3072
	ds_read_b128 v[158:161], v178
	ds_read_b128 v[170:173], v178 offset:1024
	ds_read_b128 v[174:177], v178 offset:2048
	ds_read_b128 v[178:181], v178 offset:3072
	ds_read_b128 v[182:185], v168 offset:32768
	ds_read_b128 v[186:189], v168 offset:33792
	ds_read_b128 v[190:193], v168 offset:34816
	ds_read_b128 v[194:197], v168 offset:35840
	ds_read_b128 v[198:201], v168 offset:36864
	ds_read_b128 v[202:205], v168 offset:37888
	ds_read_b128 v[206:209], v168 offset:38912
	ds_read_b128 v[210:213], v168 offset:39936
	s_mov_b32 m0, s70
	v_lshl_add_u64 v[220:221], s[48:49], 0, v[136:137]
	global_load_lds_dwordx4 v[220:221], off
	v_lshl_add_u64 v[220:221], s[48:49], 0, v[132:133]
	s_mov_b32 m0, s71
	s_nop 0
	global_load_lds_dwordx4 v[220:221], off
	s_waitcnt vmcnt(8)
	s_waitcnt lgkmcnt(0)
	s_barrier
	s_setprio 0
	v_mfma_f32_16x16x32_bf16 v[126:129], v[142:145], v[182:185], v[126:129]
	v_mfma_f32_16x16x32_bf16 v[122:125], v[150:153], v[182:185], v[122:125]
	v_mfma_f32_16x16x32_bf16 v[110:113], v[142:145], v[190:193], v[110:113]
	v_mfma_f32_16x16x32_bf16 v[106:109], v[150:153], v[190:193], v[106:109]
	v_mfma_f32_16x16x32_bf16 v[94:97], v[142:145], v[198:201], v[94:97]
	v_mfma_f32_16x16x32_bf16 v[90:93], v[150:153], v[198:201], v[90:93]
	v_mfma_f32_16x16x32_bf16 v[78:81], v[142:145], v[206:209], v[78:81]
	v_mfma_f32_16x16x32_bf16 v[74:77], v[150:153], v[206:209], v[74:77]
	v_mfma_f32_16x16x32_bf16 v[126:129], v[146:149], v[186:189], v[126:129]
	v_mfma_f32_16x16x32_bf16 v[122:125], v[154:157], v[186:189], v[122:125]
	v_mfma_f32_16x16x32_bf16 v[110:113], v[146:149], v[194:197], v[110:113]
	v_mfma_f32_16x16x32_bf16 v[106:109], v[154:157], v[194:197], v[106:109]
	v_mfma_f32_16x16x32_bf16 v[94:97], v[146:149], v[202:205], v[94:97]
	v_mfma_f32_16x16x32_bf16 v[90:93], v[154:157], v[202:205], v[90:93]
	v_mfma_f32_16x16x32_bf16 v[78:81], v[146:149], v[210:213], v[78:81]
	v_mfma_f32_16x16x32_bf16 v[74:77], v[154:157], v[210:213], v[74:77]
	s_setprio 2
	s_setprio 0
	v_mfma_f32_16x16x32_bf16 v[118:121], v[158:161], v[182:185], v[118:121]
	v_mfma_f32_16x16x32_bf16 v[114:117], v[174:177], v[182:185], v[114:117]
	v_mfma_f32_16x16x32_bf16 v[102:105], v[158:161], v[190:193], v[102:105]
	v_mfma_f32_16x16x32_bf16 v[98:101], v[174:177], v[190:193], v[98:101]
	v_mfma_f32_16x16x32_bf16 v[86:89], v[158:161], v[198:201], v[86:89]
	v_mfma_f32_16x16x32_bf16 v[82:85], v[174:177], v[198:201], v[82:85]
	v_mfma_f32_16x16x32_bf16 v[70:73], v[158:161], v[206:209], v[70:73]
	v_mfma_f32_16x16x32_bf16 v[66:69], v[174:177], v[206:209], v[66:69]
	v_mfma_f32_16x16x32_bf16 v[118:121], v[170:173], v[186:189], v[118:121]
	v_mfma_f32_16x16x32_bf16 v[114:117], v[178:181], v[186:189], v[114:117]
	v_mfma_f32_16x16x32_bf16 v[102:105], v[170:173], v[194:197], v[102:105]
	v_mfma_f32_16x16x32_bf16 v[98:101], v[178:181], v[194:197], v[98:101]
	v_mfma_f32_16x16x32_bf16 v[86:89], v[170:173], v[202:205], v[86:89]
	v_mfma_f32_16x16x32_bf16 v[82:85], v[178:181], v[202:205], v[82:85]
	v_mfma_f32_16x16x32_bf16 v[70:73], v[170:173], v[210:213], v[70:73]
	v_mfma_f32_16x16x32_bf16 v[66:69], v[178:181], v[210:213], v[66:69]
	s_setprio 2
	s_barrier
; #define PG8_STAGE(bufoff, gbase, voff) do { _Pragma("unroll") for (int _i = 0; _i < 2; ++_i) \
;         __builtin_amdgcn_global_load_lds((const unsigned*)((const char*)(gbase) + (voff)[_i]), (LAS unsigned*)(lds + (bufoff) + ldsw + _i * 8192), 16, 0, 0); } while (0)
; #define PG8_LDA(dst, b, h) do { _Pragma("unroll") for (int m = 0; m < 4; ++m) _Pragma("unroll") for (int k = 0; k < 2; ++k) dst[m][k] = *(const LAS bf16x8*)(lds + PG8_SA(b, h) + aoff + m * 2048 + k * 1024); } while (0)
; #define PG8_MMA(ai, bj, At, Bt) do { __builtin_amdgcn_s_setprio(1); _Pragma("unroll") for (int m = 0; m < 4; ++m) _Pragma("unroll") for (int n = 0; n < 2; ++n) _Pragma("unroll") for (int k = 0; k < 2; ++k) \
;         acc[ai][bj][m][n] = __builtin_amdgcn_mfma_f32_16x16x32_bf16(Bt[n][k], At[m][k], acc[ai][bj][m][n], 0, 0, 0); __builtin_amdgcn_s_setprio(0); } while (0)
; #define PG8_WAIT_V(n) asm volatile("s_waitcnt vmcnt(" #n ")" ::: "memory")
; #define PG8_WAIT_L(n) asm volatile("s_waitcnt lgkmcnt(" #n ")" ::: "memory")
; #define PG8_BAR __builtin_amdgcn_s_barrier()
; #define PG8_SCHED __builtin_amdgcn_sched_barrier(0)
; template <class Epi>
; __device__ __forceinline__ void gemm_phase(LAS unsigned char* lds, const Gemm g, int G, int c, const Epi& E) {
;     ...
;             PG8_LDA(At, 1, 1); PG8_STAGE(PG8_SB(1, 0), b3, voffB); PG8_STAGE(PG8_SB(1, 1), b3 + hstepB, voffB); PG8_STAGE(PG8_SA(1, 0), a3, voffA);
;             PG8_WAIT_V(8); PG8_WAIT_L(0); PG8_BAR; PG8_MMA(1, 0, At, B0); PG8_MMA(1, 1, At, B1); PG8_BAR; PG8_SCHED;
;         }
;         if (wr == 0) PG8_BAR;
	ds_read_b128 v[182:185], v168 offset:49152
	ds_read_b128 v[186:189], v168 offset:50176
	ds_read_b128 v[190:193], v168 offset:51200
	ds_read_b128 v[194:197], v168 offset:52224
	ds_read_b128 v[198:201], v168 offset:53248
	ds_read_b128 v[202:205], v168 offset:54272
	ds_read_b128 v[206:209], v168 offset:55296
	ds_read_b128 v[210:213], v168 offset:56320
	s_mov_b32 m0, s92
	v_lshl_add_u64 v[162:163], v[162:163], 0, s[18:19]
	global_load_lds_dwordx4 v[162:163], off
	v_lshl_add_u64 v[162:163], v[214:215], 0, s[18:19]
	s_mov_b32 m0, s90
	s_nop 0
	global_load_lds_dwordx4 v[162:163], off
	v_lshl_add_u64 v[162:163], s[46:47], 0, v[134:135]
	s_mov_b32 m0, s91
	s_nop 0
	global_load_lds_dwordx4 v[162:163], off
	v_lshl_add_u64 v[162:163], s[46:47], 0, v[130:131]
	s_mov_b32 m0, s89
	s_nop 0
	global_load_lds_dwordx4 v[162:163], off
	v_lshl_add_u64 v[162:163], v[216:217], 0, s[18:19]
	s_mov_b32 m0, s78
	s_nop 0
	global_load_lds_dwordx4 v[162:163], off
	v_lshl_add_u64 v[162:163], v[218:219], 0, s[18:19]
	s_mov_b32 m0, s79
	s_nop 0
	global_load_lds_dwordx4 v[162:163], off
	s_waitcnt vmcnt(8)
	s_waitcnt lgkmcnt(0)
	s_barrier
	s_setprio 0
	v_mfma_f32_16x16x32_bf16 v[62:65], v[142:145], v[182:185], v[62:65]
	v_mfma_f32_16x16x32_bf16 v[58:61], v[150:153], v[182:185], v[58:61]
	v_mfma_f32_16x16x32_bf16 v[46:49], v[142:145], v[190:193], v[46:49]
	v_mfma_f32_16x16x32_bf16 v[42:45], v[150:153], v[190:193], v[42:45]
	v_mfma_f32_16x16x32_bf16 v[30:33], v[142:145], v[198:201], v[30:33]
	v_mfma_f32_16x16x32_bf16 v[26:29], v[150:153], v[198:201], v[26:29]
	v_mfma_f32_16x16x32_bf16 v[14:17], v[142:145], v[206:209], v[14:17]
	v_mfma_f32_16x16x32_bf16 v[10:13], v[150:153], v[206:209], v[10:13]
	v_mfma_f32_16x16x32_bf16 v[62:65], v[146:149], v[186:189], v[62:65]
	v_mfma_f32_16x16x32_bf16 v[58:61], v[154:157], v[186:189], v[58:61]
	v_mfma_f32_16x16x32_bf16 v[46:49], v[146:149], v[194:197], v[46:49]
	v_mfma_f32_16x16x32_bf16 v[42:45], v[154:157], v[194:197], v[42:45]
	v_mfma_f32_16x16x32_bf16 v[30:33], v[146:149], v[202:205], v[30:33]
	v_mfma_f32_16x16x32_bf16 v[26:29], v[154:157], v[202:205], v[26:29]
	v_mfma_f32_16x16x32_bf16 v[14:17], v[146:149], v[210:213], v[14:17]
	v_mfma_f32_16x16x32_bf16 v[10:13], v[154:157], v[210:213], v[10:13]
	s_setprio 2
	s_setprio 0
	v_mfma_f32_16x16x32_bf16 v[54:57], v[158:161], v[182:185], v[54:57]
	v_mfma_f32_16x16x32_bf16 v[50:53], v[174:177], v[182:185], v[50:53]
	v_mfma_f32_16x16x32_bf16 v[38:41], v[158:161], v[190:193], v[38:41]
	v_mfma_f32_16x16x32_bf16 v[34:37], v[174:177], v[190:193], v[34:37]
	v_mfma_f32_16x16x32_bf16 v[22:25], v[158:161], v[198:201], v[22:25]
	v_mfma_f32_16x16x32_bf16 v[18:21], v[174:177], v[198:201], v[18:21]
	v_mfma_f32_16x16x32_bf16 v[6:9], v[158:161], v[206:209], v[6:9]
	v_mfma_f32_16x16x32_bf16 v[2:5], v[174:177], v[206:209], v[2:5]
	v_mfma_f32_16x16x32_bf16 v[54:57], v[170:173], v[186:189], v[54:57]
	v_mfma_f32_16x16x32_bf16 v[50:53], v[178:181], v[186:189], v[50:53]
	v_mfma_f32_16x16x32_bf16 v[38:41], v[170:173], v[194:197], v[38:41]
	v_mfma_f32_16x16x32_bf16 v[34:37], v[178:181], v[194:197], v[34:37]
	v_mfma_f32_16x16x32_bf16 v[22:25], v[170:173], v[202:205], v[22:25]
	v_mfma_f32_16x16x32_bf16 v[18:21], v[178:181], v[202:205], v[18:21]
	v_mfma_f32_16x16x32_bf16 v[6:9], v[170:173], v[210:213], v[6:9]
	v_mfma_f32_16x16x32_bf16 v[2:5], v[178:181], v[210:213], v[2:5]
	s_setprio 2
	s_barrier
	s_movk_i32 s48, 0x100
	s_andn2_b64 vcc, exec, s[4:5]
	s_mov_b64 s[46:47], -1
	s_mov_b64 s[4:5], 0
	s_cbranch_vccz .LBB0_1653
	s_and_b64 vcc, exec, s[20:21]
	s_cbranch_vccz .LBB0_1656
	s_barrier

; #define PG8_STAGE(bufoff, gbase, voff) do { _Pragma("unroll") for (int _i = 0; _i < 2; ++_i) \
;         __builtin_amdgcn_global_load_lds((const unsigned*)((const char*)(gbase) + (voff)[_i]), (LAS unsigned*)(lds + (bufoff) + ldsw + _i * 8192), 16, 0, 0); } while (0)
; #define PG8_LDA(dst, b, h) do { _Pragma("unroll") for (int m = 0; m < 4; ++m) _Pragma("unroll") for (int k = 0; k < 2; ++k) dst[m][k] = *(const LAS bf16x8*)(lds + PG8_SA(b, h) + aoff + m * 2048 + k * 1024); } while (0)
; #define PG8_LDB(dst, b, h) do { _Pragma("unroll") for (int n = 0; n < 2; ++n) _Pragma("unroll") for (int k = 0; k < 2; ++k) dst[n][k] = *(const LAS bf16x8*)(lds + PG8_SB(b, h) + boff + n * 2048 + k * 1024); } while (0)
; #define PG8_MMA(ai, bj, At, Bt) do { __builtin_amdgcn_s_setprio(1); _Pragma("unroll") for (int m = 0; m < 4; ++m) _Pragma("unroll") for (int n = 0; n < 2; ++n) _Pragma("unroll") for (int k = 0; k < 2; ++k) \
;         acc[ai][bj][m][n] = __builtin_amdgcn_mfma_f32_16x16x32_bf16(Bt[n][k], At[m][k], acc[ai][bj][m][n], 0, 0, 0); __builtin_amdgcn_s_setprio(0); } while (0)
; #define PG8_WAIT_V(n) asm volatile("s_waitcnt vmcnt(" #n ")" ::: "memory")
; #define PG8_WAIT_L(n) asm volatile("s_waitcnt lgkmcnt(" #n ")" ::: "memory")
; #define PG8_BAR __builtin_amdgcn_s_barrier()
; #define PG8_SCHED __builtin_amdgcn_sched_barrier(0)
; template <class Epi>
; __device__ __forceinline__ void gemm_phase(LAS unsigned char* lds, const Gemm g, int G, int c, const Epi& E) {
;     ...
;             const bool last = (t == nt - 2);
;             const char* a1 = cA + (size_t)(t + 1) * kstep;
;             const char* a2 = last ? nA : cA + (size_t)(t + 2) * kstep; const char* b2 = last ? nB : cB + (size_t)(t + 2) * kstep;
;             const char* a3 = a2 + kstep; const char* b3 = b2 + kstep;
;             PG8_LDB(B0, 0, 0); PG8_LDB(B1, 0, 1); PG8_SCHED; PG8_LDA(At, 0, 0); PG8_STAGE(PG8_SA(1, 1), a1 + hstepA, voffA);
;             PG8_WAIT_V(8); PG8_WAIT_L(0); PG8_BAR; PG8_MMA(0, 0, At, B0); PG8_MMA(0, 1, At, B1); PG8_BAR; PG8_SCHED;
;             PG8_LDA(At, 0, 1); PG8_STAGE(PG8_SB(0, 0), b2, voffB); PG8_STAGE(PG8_SB(0, 1), b2 + hstepB, voffB); PG8_STAGE(PG8_SA(0, 0), a2, voffA);
;             PG8_WAIT_V(8); PG8_WAIT_L(0); PG8_BAR; PG8_MMA(1, 0, At, B0); PG8_MMA(1, 1, At, B1); PG8_BAR; PG8_SCHED;
.LBB0_1825:
	ds_read_b128 v[146:149], v152
	ds_read_b128 v[156:159], v152 offset:1024
	ds_read_b128 v[160:163], v152 offset:2048
	ds_read_b128 v[164:167], v152 offset:3072
	ds_read_b128 v[168:171], v153
	ds_read_b128 v[172:175], v153 offset:1024
	ds_read_b128 v[176:179], v153 offset:2048
	ds_read_b128 v[180:183], v153 offset:3072
	ds_read_b128 v[184:187], v154
	ds_read_b128 v[188:191], v154 offset:1024
	ds_read_b128 v[192:195], v154 offset:2048
	ds_read_b128 v[196:199], v154 offset:3072
	ds_read_b128 v[200:203], v154 offset:4096
	ds_read_b128 v[204:207], v154 offset:5120
	ds_read_b128 v[208:211], v154 offset:6144
	ds_read_b128 v[212:215], v154 offset:7168
	s_add_u32 s33, s40, 0xfff00080
	s_addc_u32 s42, s41, -1
	s_cmp_eq_u32 s68, 60
	s_cselect_b32 s45, s15, s42
	s_cselect_b32 s44, s63, s33
	s_cselect_b32 s43, s11, s67
	s_cselect_b32 s42, s13, s66
	v_lshl_add_u64 v[216:217], s[40:41], 0, v[138:139]
	s_add_i32 m0, s17, 0xc000
	s_nop 0
	global_load_lds_dwordx4 v[216:217], off
	v_lshl_add_u64 v[216:217], s[40:41], 0, v[140:141]
	s_add_i32 m0, s17, 0xe000
	s_nop 0
	global_load_lds_dwordx4 v[216:217], off
	s_waitcnt vmcnt(8)
	s_waitcnt lgkmcnt(0)
	s_barrier
	s_setprio 0
	v_mfma_f32_16x16x32_bf16 v[126:129], v[146:149], v[184:187], v[126:129]
	v_mfma_f32_16x16x32_bf16 v[122:125], v[160:163], v[184:187], v[122:125]
	v_mfma_f32_16x16x32_bf16 v[118:121], v[146:149], v[192:195], v[118:121]
	v_mfma_f32_16x16x32_bf16 v[110:113], v[160:163], v[192:195], v[110:113]
	v_mfma_f32_16x16x32_bf16 v[102:105], v[146:149], v[200:203], v[102:105]
	v_mfma_f32_16x16x32_bf16 v[94:97], v[160:163], v[200:203], v[94:97]
	v_mfma_f32_16x16x32_bf16 v[86:89], v[146:149], v[208:211], v[86:89]
	v_mfma_f32_16x16x32_bf16 v[78:81], v[160:163], v[208:211], v[78:81]
	v_mfma_f32_16x16x32_bf16 v[126:129], v[156:159], v[188:191], v[126:129]
	v_mfma_f32_16x16x32_bf16 v[122:125], v[164:167], v[188:191], v[122:125]
	v_mfma_f32_16x16x32_bf16 v[118:121], v[156:159], v[196:199], v[118:121]
	v_mfma_f32_16x16x32_bf16 v[110:113], v[164:167], v[196:199], v[110:113]
	v_mfma_f32_16x16x32_bf16 v[102:105], v[156:159], v[204:207], v[102:105]
	v_mfma_f32_16x16x32_bf16 v[94:97], v[164:167], v[204:207], v[94:97]
	v_mfma_f32_16x16x32_bf16 v[86:89], v[156:159], v[212:215], v[86:89]
	v_mfma_f32_16x16x32_bf16 v[78:81], v[164:167], v[212:215], v[78:81]
	s_setprio 2
	s_setprio 0
	v_mfma_f32_16x16x32_bf16 v[114:117], v[168:171], v[184:187], v[114:117]
	v_mfma_f32_16x16x32_bf16 v[106:109], v[176:179], v[184:187], v[106:109]
	v_mfma_f32_16x16x32_bf16 v[98:101], v[168:171], v[192:195], v[98:101]
	v_mfma_f32_16x16x32_bf16 v[90:93], v[176:179], v[192:195], v[90:93]
	v_mfma_f32_16x16x32_bf16 v[82:85], v[168:171], v[200:203], v[82:85]
	v_mfma_f32_16x16x32_bf16 v[74:77], v[176:179], v[200:203], v[74:77]
	v_mfma_f32_16x16x32_bf16 v[70:73], v[168:171], v[208:211], v[70:73]
	v_mfma_f32_16x16x32_bf16 v[66:69], v[176:179], v[208:211], v[66:69]
	v_mfma_f32_16x16x32_bf16 v[114:117], v[172:175], v[188:191], v[114:117]
	v_mfma_f32_16x16x32_bf16 v[106:109], v[180:183], v[188:191], v[106:109]
	v_mfma_f32_16x16x32_bf16 v[98:101], v[172:175], v[196:199], v[98:101]
	v_mfma_f32_16x16x32_bf16 v[90:93], v[180:183], v[196:199], v[90:93]
	v_mfma_f32_16x16x32_bf16 v[82:85], v[172:175], v[204:207], v[82:85]
	v_mfma_f32_16x16x32_bf16 v[74:77], v[180:183], v[204:207], v[74:77]
	v_mfma_f32_16x16x32_bf16 v[70:73], v[172:175], v[212:215], v[70:73]
	v_mfma_f32_16x16x32_bf16 v[66:69], v[180:183], v[212:215], v[66:69]
	s_setprio 2
	s_barrier
	ds_read_b128 v[184:187], v154 offset:16384
	ds_read_b128 v[188:191], v154 offset:17408
	ds_read_b128 v[192:195], v154 offset:18432
	ds_read_b128 v[196:199], v154 offset:19456
	ds_read_b128 v[200:203], v154 offset:20480
	ds_read_b128 v[204:207], v154 offset:21504
	ds_read_b128 v[208:211], v154 offset:22528
	ds_read_b128 v[212:215], v154 offset:23552
	s_add_i32 s33, s61, s52
	v_lshl_add_u64 v[216:217], s[42:43], 0, v[134:135]
	s_mov_b32 m0, s33
	s_nop 0
	global_load_lds_dwordx4 v[216:217], off
	s_add_i32 m0, s33, 0x2000
	s_add_u32 s64, s42, 0x100000
	v_lshl_add_u64 v[218:219], s[42:43], 0, v[130:131]
	s_addc_u32 s65, s43, 0
	s_add_i32 s33, s62, s52
	global_load_lds_dwordx4 v[218:219], off
	v_lshl_add_u64 v[220:221], s[64:65], 0, v[134:135]
	s_mov_b32 m0, s33
	v_lshl_add_u64 v[222:223], s[44:45], 0, v[132:133]
	global_load_lds_dwordx4 v[220:221], off
	v_lshl_add_u64 v[220:221], s[64:65], 0, v[130:131]
	s_add_i32 m0, s33, 0x2000
	s_nop 0
	global_load_lds_dwordx4 v[220:221], off
	v_lshl_add_u64 v[220:221], s[44:45], 0, v[136:137]
	s_mov_b32 m0, s17
	s_nop 0
	global_load_lds_dwordx4 v[220:221], off
	s_mov_b32 m0, s37
	s_nop 0
	global_load_lds_dwordx4 v[222:223], off
	s_waitcnt vmcnt(8)
	s_waitcnt lgkmcnt(0)
	s_barrier
; #define PG8_STAGE(bufoff, gbase, voff) do { _Pragma("unroll") for (int _i = 0; _i < 2; ++_i) \
;         __builtin_amdgcn_global_load_lds((const unsigned*)((const char*)(gbase) + (voff)[_i]), (LAS unsigned*)(lds + (bufoff) + ldsw + _i * 8192), 16, 0, 0); } while (0)
; #define PG8_LDA(dst, b, h) do { _Pragma("unroll") for (int m = 0; m < 4; ++m) _Pragma("unroll") for (int k = 0; k < 2; ++k) dst[m][k] = *(const LAS bf16x8*)(lds + PG8_SA(b, h) + aoff + m * 2048 + k * 1024); } while (0)
; #define PG8_LDB(dst, b, h) do { _Pragma("unroll") for (int n = 0; n < 2; ++n) _Pragma("unroll") for (int k = 0; k < 2; ++k) dst[n][k] = *(const LAS bf16x8*)(lds + PG8_SB(b, h) + boff + n * 2048 + k * 1024); } while (0)
; #define PG8_MMA(ai, bj, At, Bt) do { __builtin_amdgcn_s_setprio(1); _Pragma("unroll") for (int m = 0; m < 4; ++m) _Pragma("unroll") for (int n = 0; n < 2; ++n) _Pragma("unroll") for (int k = 0; k < 2; ++k) \
;         acc[ai][bj][m][n] = __builtin_amdgcn_mfma_f32_16x16x32_bf16(Bt[n][k], At[m][k], acc[ai][bj][m][n], 0, 0, 0); __builtin_amdgcn_s_setprio(0); } while (0)
; #define PG8_WAIT_V(n) asm volatile("s_waitcnt vmcnt(" #n ")" ::: "memory")
; #define PG8_WAIT_L(n) asm volatile("s_waitcnt lgkmcnt(" #n ")" ::: "memory")
; #define PG8_BAR __builtin_amdgcn_s_barrier()
; #define PG8_SCHED __builtin_amdgcn_sched_barrier(0)
; template <class Epi>
; __device__ __forceinline__ void gemm_phase(LAS unsigned char* lds, const Gemm g, int G, int c, const Epi& E) {
;     ...
;             PG8_WAIT_V(8); PG8_WAIT_L(0); PG8_BAR; PG8_MMA(1, 0, At, B0); PG8_MMA(1, 1, At, B1); PG8_BAR; PG8_SCHED;
;             PG8_LDB(B0, 1, 0); PG8_LDB(B1, 1, 1); PG8_SCHED; PG8_LDA(At, 1, 0); PG8_STAGE(PG8_SA(0, 1), a2 + hstepA, voffA);
;             PG8_WAIT_V(8); PG8_WAIT_L(0); PG8_BAR; PG8_MMA(0, 0, At, B0); PG8_MMA(0, 1, At, B1); PG8_BAR; PG8_SCHED;
	s_setprio 0
	v_mfma_f32_16x16x32_bf16 v[62:65], v[146:149], v[184:187], v[62:65]
	v_mfma_f32_16x16x32_bf16 v[58:61], v[160:163], v[184:187], v[58:61]
	v_mfma_f32_16x16x32_bf16 v[54:57], v[146:149], v[192:195], v[54:57]
	v_mfma_f32_16x16x32_bf16 v[46:49], v[160:163], v[192:195], v[46:49]
	v_mfma_f32_16x16x32_bf16 v[38:41], v[146:149], v[200:203], v[38:41]
	v_mfma_f32_16x16x32_bf16 v[30:33], v[160:163], v[200:203], v[30:33]
	v_mfma_f32_16x16x32_bf16 v[22:25], v[146:149], v[208:211], v[22:25]
	v_mfma_f32_16x16x32_bf16 v[14:17], v[160:163], v[208:211], v[14:17]
	v_mfma_f32_16x16x32_bf16 v[62:65], v[156:159], v[188:191], v[62:65]
	v_mfma_f32_16x16x32_bf16 v[58:61], v[164:167], v[188:191], v[58:61]
	v_mfma_f32_16x16x32_bf16 v[54:57], v[156:159], v[196:199], v[54:57]
	v_mfma_f32_16x16x32_bf16 v[46:49], v[164:167], v[196:199], v[46:49]
	v_mfma_f32_16x16x32_bf16 v[38:41], v[156:159], v[204:207], v[38:41]
	v_mfma_f32_16x16x32_bf16 v[30:33], v[164:167], v[204:207], v[30:33]
	v_mfma_f32_16x16x32_bf16 v[22:25], v[156:159], v[212:215], v[22:25]
	v_mfma_f32_16x16x32_bf16 v[14:17], v[164:167], v[212:215], v[14:17]
	s_setprio 2
	s_setprio 0
	v_mfma_f32_16x16x32_bf16 v[50:53], v[168:171], v[184:187], v[50:53]
	v_mfma_f32_16x16x32_bf16 v[42:45], v[176:179], v[184:187], v[42:45]
	v_mfma_f32_16x16x32_bf16 v[34:37], v[168:171], v[192:195], v[34:37]
	v_mfma_f32_16x16x32_bf16 v[26:29], v[176:179], v[192:195], v[26:29]
	v_mfma_f32_16x16x32_bf16 v[18:21], v[168:171], v[200:203], v[18:21]
	v_mfma_f32_16x16x32_bf16 v[10:13], v[176:179], v[200:203], v[10:13]
	v_mfma_f32_16x16x32_bf16 v[6:9], v[168:171], v[208:211], v[6:9]
	v_mfma_f32_16x16x32_bf16 v[2:5], v[176:179], v[208:211], v[2:5]
	v_mfma_f32_16x16x32_bf16 v[50:53], v[172:175], v[188:191], v[50:53]
	v_mfma_f32_16x16x32_bf16 v[42:45], v[180:183], v[188:191], v[42:45]
	v_mfma_f32_16x16x32_bf16 v[34:37], v[172:175], v[196:199], v[34:37]
	v_mfma_f32_16x16x32_bf16 v[26:29], v[180:183], v[196:199], v[26:29]
	v_mfma_f32_16x16x32_bf16 v[18:21], v[172:175], v[204:207], v[18:21]
	v_mfma_f32_16x16x32_bf16 v[10:13], v[180:183], v[204:207], v[10:13]
	v_mfma_f32_16x16x32_bf16 v[6:9], v[172:175], v[212:215], v[6:9]
	v_mfma_f32_16x16x32_bf16 v[2:5], v[180:183], v[212:215], v[2:5]
	s_setprio 2
	s_barrier
	s_add_i32 s33, 0, 0x18000
	v_add_u32_e32 v155, s33, v151
	s_add_i32 s64, 0, 0x1c000
	ds_read_b128 v[146:149], v155
	ds_read_b128 v[156:159], v155 offset:1024
	ds_read_b128 v[160:163], v155 offset:2048
	ds_read_b128 v[164:167], v155 offset:3072
	v_add_u32_e32 v155, s64, v151
	ds_read_b128 v[168:171], v155
	ds_read_b128 v[172:175], v155 offset:1024
	ds_read_b128 v[176:179], v155 offset:2048
	ds_read_b128 v[180:183], v155 offset:3072
	ds_read_b128 v[184:187], v154 offset:32768
	ds_read_b128 v[188:191], v154 offset:33792
	ds_read_b128 v[192:195], v154 offset:34816
	ds_read_b128 v[196:199], v154 offset:35840
	ds_read_b128 v[200:203], v154 offset:36864
	ds_read_b128 v[204:207], v154 offset:37888
	ds_read_b128 v[208:211], v154 offset:38912
	ds_read_b128 v[212:215], v154 offset:39936
	s_add_u32 s44, s44, 0x100000
	s_addc_u32 s45, s45, 0
	s_mov_b32 m0, s39
	v_lshl_add_u64 v[226:227], s[44:45], 0, v[136:137]
	global_load_lds_dwordx4 v[226:227], off
	v_lshl_add_u64 v[226:227], s[44:45], 0, v[132:133]
	s_mov_b32 m0, s53
	s_nop 0
	global_load_lds_dwordx4 v[226:227], off
	s_waitcnt vmcnt(8)
	s_waitcnt lgkmcnt(0)
	s_barrier
	s_setprio 0
	v_mfma_f32_16x16x32_bf16 v[126:129], v[146:149], v[184:187], v[126:129]
	v_mfma_f32_16x16x32_bf16 v[122:125], v[160:163], v[184:187], v[122:125]
	v_mfma_f32_16x16x32_bf16 v[118:121], v[146:149], v[192:195], v[118:121]
	v_mfma_f32_16x16x32_bf16 v[110:113], v[160:163], v[192:195], v[110:113]
	v_mfma_f32_16x16x32_bf16 v[102:105], v[146:149], v[200:203], v[102:105]
	v_mfma_f32_16x16x32_bf16 v[94:97], v[160:163], v[200:203], v[94:97]
	v_mfma_f32_16x16x32_bf16 v[86:89], v[146:149], v[208:211], v[86:89]
	v_mfma_f32_16x16x32_bf16 v[78:81], v[160:163], v[208:211], v[78:81]
	v_mfma_f32_16x16x32_bf16 v[126:129], v[156:159], v[188:191], v[126:129]
	v_mfma_f32_16x16x32_bf16 v[122:125], v[164:167], v[188:191], v[122:125]
	v_mfma_f32_16x16x32_bf16 v[118:121], v[156:159], v[196:199], v[118:121]
	v_mfma_f32_16x16x32_bf16 v[110:113], v[164:167], v[196:199], v[110:113]
	v_mfma_f32_16x16x32_bf16 v[102:105], v[156:159], v[204:207], v[102:105]
	v_mfma_f32_16x16x32_bf16 v[94:97], v[164:167], v[204:207], v[94:97]
	v_mfma_f32_16x16x32_bf16 v[86:89], v[156:159], v[212:215], v[86:89]
	v_mfma_f32_16x16x32_bf16 v[78:81], v[164:167], v[212:215], v[78:81]
	s_setprio 2
	s_setprio 0
	v_mfma_f32_16x16x32_bf16 v[114:117], v[168:171], v[184:187], v[114:117]
	v_mfma_f32_16x16x32_bf16 v[106:109], v[176:179], v[184:187], v[106:109]
	v_mfma_f32_16x16x32_bf16 v[98:101], v[168:171], v[192:195], v[98:101]
	v_mfma_f32_16x16x32_bf16 v[90:93], v[176:179], v[192:195], v[90:93]
	v_mfma_f32_16x16x32_bf16 v[82:85], v[168:171], v[200:203], v[82:85]
	v_mfma_f32_16x16x32_bf16 v[74:77], v[176:179], v[200:203], v[74:77]
	v_mfma_f32_16x16x32_bf16 v[70:73], v[168:171], v[208:211], v[70:73]
	v_mfma_f32_16x16x32_bf16 v[66:69], v[176:179], v[208:211], v[66:69]
	v_mfma_f32_16x16x32_bf16 v[114:117], v[172:175], v[188:191], v[114:117]
	v_mfma_f32_16x16x32_bf16 v[106:109], v[180:183], v[188:191], v[106:109]
	v_mfma_f32_16x16x32_bf16 v[98:101], v[172:175], v[196:199], v[98:101]
	v_mfma_f32_16x16x32_bf16 v[90:93], v[180:183], v[196:199], v[90:93]
	v_mfma_f32_16x16x32_bf16 v[82:85], v[172:175], v[204:207], v[82:85]
	v_mfma_f32_16x16x32_bf16 v[74:77], v[180:183], v[204:207], v[74:77]
	v_mfma_f32_16x16x32_bf16 v[70:73], v[172:175], v[212:215], v[70:73]
	v_mfma_f32_16x16x32_bf16 v[66:69], v[180:183], v[212:215], v[66:69]
	s_setprio 2
	s_barrier
; #define PG8_STAGE(bufoff, gbase, voff) do { _Pragma("unroll") for (int _i = 0; _i < 2; ++_i) \
;         __builtin_amdgcn_global_load_lds((const unsigned*)((const char*)(gbase) + (voff)[_i]), (LAS unsigned*)(lds + (bufoff) + ldsw + _i * 8192), 16, 0, 0); } while (0)
; #define PG8_LDA(dst, b, h) do { _Pragma("unroll") for (int m = 0; m < 4; ++m) _Pragma("unroll") for (int k = 0; k < 2; ++k) dst[m][k] = *(const LAS bf16x8*)(lds + PG8_SA(b, h) + aoff + m * 2048 + k * 1024); } while (0)
; #define PG8_MMA(ai, bj, At, Bt) do { __builtin_amdgcn_s_setprio(1); _Pragma("unroll") for (int m = 0; m < 4; ++m) _Pragma("unroll") for (int n = 0; n < 2; ++n) _Pragma("unroll") for (int k = 0; k < 2; ++k) \
;         acc[ai][bj][m][n] = __builtin_amdgcn_mfma_f32_16x16x32_bf16(Bt[n][k], At[m][k], acc[ai][bj][m][n], 0, 0, 0); __builtin_amdgcn_s_setprio(0); } while (0)
; #define PG8_WAIT_V(n) asm volatile("s_waitcnt vmcnt(" #n ")" ::: "memory")
; #define PG8_WAIT_L(n) asm volatile("s_waitcnt lgkmcnt(" #n ")" ::: "memory")
; #define PG8_BAR __builtin_amdgcn_s_barrier()
; #define PG8_SCHED __builtin_amdgcn_sched_barrier(0)
; template <class Epi>
; __device__ __forceinline__ void gemm_phase(LAS unsigned char* lds, const Gemm g, int G, int c, const Epi& E) {
;     ...
;             PG8_LDA(At, 1, 1); PG8_STAGE(PG8_SB(1, 0), b3, voffB); PG8_STAGE(PG8_SB(1, 1), b3 + hstepB, voffB); PG8_STAGE(PG8_SA(1, 0), a3, voffA);
;             PG8_WAIT_V(8); PG8_WAIT_L(0); PG8_BAR; PG8_MMA(1, 0, At, B0); PG8_MMA(1, 1, At, B1); PG8_BAR; PG8_SCHED;
;         }
;         if (wr == 0) PG8_BAR;
	ds_read_b128 v[184:187], v154 offset:49152
	ds_read_b128 v[188:191], v154 offset:50176
	ds_read_b128 v[192:195], v154 offset:51200
	ds_read_b128 v[196:199], v154 offset:52224
	ds_read_b128 v[200:203], v154 offset:53248
	ds_read_b128 v[204:207], v154 offset:54272
	ds_read_b128 v[208:211], v154 offset:55296
	ds_read_b128 v[212:215], v154 offset:56320
	s_add_i32 s33, s33, s52
	v_lshl_add_u64 v[216:217], v[216:217], 0, s[6:7]
	s_mov_b32 m0, s33
	s_nop 0
	global_load_lds_dwordx4 v[216:217], off
	s_add_i32 m0, s33, 0x2000
	s_add_u32 s42, s42, 0x100080
	v_lshl_add_u64 v[216:217], v[218:219], 0, s[6:7]
	s_addc_u32 s43, s43, 0
	s_add_i32 s33, s64, s52
	global_load_lds_dwordx4 v[216:217], off
	v_lshl_add_u64 v[216:217], s[42:43], 0, v[134:135]
	s_mov_b32 m0, s33
	s_nop 0
	global_load_lds_dwordx4 v[216:217], off
	v_lshl_add_u64 v[216:217], s[42:43], 0, v[130:131]
	s_add_i32 m0, s33, 0x2000
	s_nop 0
	global_load_lds_dwordx4 v[216:217], off
	v_lshl_add_u64 v[216:217], v[220:221], 0, s[6:7]
	s_mov_b32 m0, s59
	s_nop 0
	global_load_lds_dwordx4 v[216:217], off
	v_lshl_add_u64 v[216:217], v[222:223], 0, s[6:7]
	s_mov_b32 m0, s60
	s_nop 0
	global_load_lds_dwordx4 v[216:217], off
	s_waitcnt vmcnt(8)
	s_waitcnt lgkmcnt(0)
	s_barrier
	s_setprio 0
	v_mfma_f32_16x16x32_bf16 v[62:65], v[146:149], v[184:187], v[62:65]
	v_mfma_f32_16x16x32_bf16 v[58:61], v[160:163], v[184:187], v[58:61]
	v_mfma_f32_16x16x32_bf16 v[54:57], v[146:149], v[192:195], v[54:57]
	v_mfma_f32_16x16x32_bf16 v[46:49], v[160:163], v[192:195], v[46:49]
	v_mfma_f32_16x16x32_bf16 v[38:41], v[146:149], v[200:203], v[38:41]
	v_mfma_f32_16x16x32_bf16 v[30:33], v[160:163], v[200:203], v[30:33]
	v_mfma_f32_16x16x32_bf16 v[22:25], v[146:149], v[208:211], v[22:25]
	v_mfma_f32_16x16x32_bf16 v[14:17], v[160:163], v[208:211], v[14:17]
	v_mfma_f32_16x16x32_bf16 v[62:65], v[156:159], v[188:191], v[62:65]
	v_mfma_f32_16x16x32_bf16 v[58:61], v[164:167], v[188:191], v[58:61]
	v_mfma_f32_16x16x32_bf16 v[54:57], v[156:159], v[196:199], v[54:57]
	v_mfma_f32_16x16x32_bf16 v[46:49], v[164:167], v[196:199], v[46:49]
	v_mfma_f32_16x16x32_bf16 v[38:41], v[156:159], v[204:207], v[38:41]
	v_mfma_f32_16x16x32_bf16 v[30:33], v[164:167], v[204:207], v[30:33]
	v_mfma_f32_16x16x32_bf16 v[22:25], v[156:159], v[212:215], v[22:25]
	v_mfma_f32_16x16x32_bf16 v[14:17], v[164:167], v[212:215], v[14:17]
	s_setprio 2
	s_setprio 0
	v_mfma_f32_16x16x32_bf16 v[50:53], v[168:171], v[184:187], v[50:53]
	v_mfma_f32_16x16x32_bf16 v[42:45], v[176:179], v[184:187], v[42:45]
	v_mfma_f32_16x16x32_bf16 v[34:37], v[168:171], v[192:195], v[34:37]
	v_mfma_f32_16x16x32_bf16 v[26:29], v[176:179], v[192:195], v[26:29]
	v_mfma_f32_16x16x32_bf16 v[18:21], v[168:171], v[200:203], v[18:21]
	v_mfma_f32_16x16x32_bf16 v[10:13], v[176:179], v[200:203], v[10:13]
	v_mfma_f32_16x16x32_bf16 v[6:9], v[168:171], v[208:211], v[6:9]
	v_mfma_f32_16x16x32_bf16 v[2:5], v[176:179], v[208:211], v[2:5]
	v_mfma_f32_16x16x32_bf16 v[50:53], v[172:175], v[188:191], v[50:53]
	v_mfma_f32_16x16x32_bf16 v[42:45], v[180:183], v[188:191], v[42:45]
	v_mfma_f32_16x16x32_bf16 v[34:37], v[172:175], v[196:199], v[34:37]
	v_mfma_f32_16x16x32_bf16 v[26:29], v[180:183], v[196:199], v[26:29]
	v_mfma_f32_16x16x32_bf16 v[18:21], v[172:175], v[204:207], v[18:21]
	v_mfma_f32_16x16x32_bf16 v[10:13], v[180:183], v[204:207], v[10:13]
	v_mfma_f32_16x16x32_bf16 v[6:9], v[172:175], v[212:215], v[6:9]
	v_mfma_f32_16x16x32_bf16 v[2:5], v[180:183], v[212:215], v[2:5]
	s_setprio 2
	s_barrier
	s_add_i32 s68, s68, 2
	s_add_u32 s40, s40, 0x100
	s_addc_u32 s41, s41, 0
	s_add_u32 s66, s66, 0x100
	s_addc_u32 s67, s67, 0
	s_cmp_gt_u32 s68, 61
	s_cbranch_scc0 .LBB0_1825
	s_and_b64 vcc, exec, s[8:9]
	s_cbranch_vccz .LBB0_1828
	s_barrier

; #define PG8_STAGE(bufoff, gbase, voff) do { _Pragma("unroll") for (int _i = 0; _i < 2; ++_i) \
;         __builtin_amdgcn_global_load_lds((const unsigned*)((const char*)(gbase) + (voff)[_i]), (LAS unsigned*)(lds + (bufoff) + ldsw + _i * 8192), 16, 0, 0); } while (0)
; #define PG8_LDA(dst, b, h) do { _Pragma("unroll") for (int m = 0; m < 4; ++m) _Pragma("unroll") for (int k = 0; k < 2; ++k) dst[m][k] = *(const LAS bf16x8*)(lds + PG8_SA(b, h) + aoff + m * 2048 + k * 1024); } while (0)
; #define PG8_LDB(dst, b, h) do { _Pragma("unroll") for (int n = 0; n < 2; ++n) _Pragma("unroll") for (int k = 0; k < 2; ++k) dst[n][k] = *(const LAS bf16x8*)(lds + PG8_SB(b, h) + boff + n * 2048 + k * 1024); } while (0)
; #define PG8_MMA(ai, bj, At, Bt) do { __builtin_amdgcn_s_setprio(1); _Pragma("unroll") for (int m = 0; m < 4; ++m) _Pragma("unroll") for (int n = 0; n < 2; ++n) _Pragma("unroll") for (int k = 0; k < 2; ++k) \
;         acc[ai][bj][m][n] = __builtin_amdgcn_mfma_f32_16x16x32_bf16(Bt[n][k], At[m][k], acc[ai][bj][m][n], 0, 0, 0); __builtin_amdgcn_s_setprio(0); } while (0)
; #define PG8_WAIT_V(n) asm volatile("s_waitcnt vmcnt(" #n ")" ::: "memory")
; #define PG8_WAIT_L(n) asm volatile("s_waitcnt lgkmcnt(" #n ")" ::: "memory")
; #define PG8_BAR __builtin_amdgcn_s_barrier()
; #define PG8_SCHED __builtin_amdgcn_sched_barrier(0)
; template <class Epi>
; __device__ __forceinline__ void gemm_phase(LAS unsigned char* lds, const Gemm g, int G, int c, const Epi& E) {
;     ...
;             const bool last = (t == nt - 2);
;             const char* a1 = cA + (size_t)(t + 1) * kstep;
;             const char* a2 = last ? nA : cA + (size_t)(t + 2) * kstep; const char* b2 = last ? nB : cB + (size_t)(t + 2) * kstep;
;             const char* a3 = a2 + kstep; const char* b3 = b2 + kstep;
;             PG8_LDB(B0, 0, 0); PG8_LDB(B1, 0, 1); PG8_SCHED; PG8_LDA(At, 0, 0); PG8_STAGE(PG8_SA(1, 1), a1 + hstepA, voffA);
;             PG8_WAIT_V(8); PG8_WAIT_L(0); PG8_BAR; PG8_MMA(0, 0, At, B0); PG8_MMA(0, 1, At, B1); PG8_BAR; PG8_SCHED;
;             PG8_LDA(At, 0, 1); PG8_STAGE(PG8_SB(0, 0), b2, voffB); PG8_STAGE(PG8_SB(0, 1), b2 + hstepB, voffB); PG8_STAGE(PG8_SA(0, 0), a2, voffA);
;             PG8_WAIT_V(8); PG8_WAIT_L(0); PG8_BAR; PG8_MMA(1, 0, At, B0); PG8_MMA(1, 1, At, B1); PG8_BAR; PG8_SCHED;
.LBB0_1931:
	ds_read_b128 v[122:125], v168
	ds_read_b128 v[126:129], v168 offset:1024
	ds_read_b128 v[130:133], v168 offset:2048
	ds_read_b128 v[134:137], v168 offset:3072
	ds_read_b128 v[162:165], v169
	ds_read_b128 v[172:175], v169 offset:1024
	ds_read_b128 v[176:179], v169 offset:2048
	ds_read_b128 v[180:183], v169 offset:3072
	ds_read_b128 v[184:187], v170
	ds_read_b128 v[188:191], v170 offset:1024
	ds_read_b128 v[192:195], v170 offset:2048
	ds_read_b128 v[196:199], v170 offset:3072
	ds_read_b128 v[200:203], v170 offset:4096
	ds_read_b128 v[204:207], v170 offset:5120
	ds_read_b128 v[208:211], v170 offset:6144
	ds_read_b128 v[212:215], v170 offset:7168
	s_add_u32 s33, s4, 0xfffc0080
	s_addc_u32 s36, s5, -1
	s_cmp_eq_u32 s62, 12
	s_cselect_b32 s39, s19, s36
	s_cselect_b32 s38, s18, s33
	s_cselect_b32 s37, s15, s61
	s_cselect_b32 s36, s17, s60
	v_lshl_add_u64 v[216:217], s[4:5], 0, v[154:155]
	s_add_i32 m0, s23, 0xc000
	s_nop 0
	global_load_lds_dwordx4 v[216:217], off
	v_lshl_add_u64 v[216:217], s[4:5], 0, v[156:157]
	s_add_i32 m0, s23, 0xe000
	s_nop 0
	global_load_lds_dwordx4 v[216:217], off
	s_waitcnt vmcnt(8)
	s_waitcnt lgkmcnt(0)
	s_barrier
	s_setprio 0
	v_mfma_f32_16x16x32_bf16 v[142:145], v[122:125], v[184:187], v[142:145]
	v_mfma_f32_16x16x32_bf16 v[138:141], v[130:133], v[184:187], v[138:141]
	v_mfma_f32_16x16x32_bf16 v[118:121], v[122:125], v[192:195], v[118:121]
	v_mfma_f32_16x16x32_bf16 v[106:109], v[130:133], v[192:195], v[106:109]
	v_mfma_f32_16x16x32_bf16 v[102:105], v[122:125], v[200:203], v[102:105]
	v_mfma_f32_16x16x32_bf16 v[90:93], v[130:133], v[200:203], v[90:93]
	v_mfma_f32_16x16x32_bf16 v[86:89], v[122:125], v[208:211], v[86:89]
	v_mfma_f32_16x16x32_bf16 v[74:77], v[130:133], v[208:211], v[74:77]
	v_mfma_f32_16x16x32_bf16 v[142:145], v[126:129], v[188:191], v[142:145]
	v_mfma_f32_16x16x32_bf16 v[138:141], v[134:137], v[188:191], v[138:141]
	v_mfma_f32_16x16x32_bf16 v[118:121], v[126:129], v[196:199], v[118:121]
	v_mfma_f32_16x16x32_bf16 v[106:109], v[134:137], v[196:199], v[106:109]
	v_mfma_f32_16x16x32_bf16 v[102:105], v[126:129], v[204:207], v[102:105]
	v_mfma_f32_16x16x32_bf16 v[90:93], v[134:137], v[204:207], v[90:93]
	v_mfma_f32_16x16x32_bf16 v[86:89], v[126:129], v[212:215], v[86:89]
	v_mfma_f32_16x16x32_bf16 v[74:77], v[134:137], v[212:215], v[74:77]
	s_setprio 2
	s_setprio 0
	v_mfma_f32_16x16x32_bf16 v[114:117], v[162:165], v[184:187], v[114:117]
	v_mfma_f32_16x16x32_bf16 v[110:113], v[176:179], v[184:187], v[110:113]
	v_mfma_f32_16x16x32_bf16 v[98:101], v[162:165], v[192:195], v[98:101]
	v_mfma_f32_16x16x32_bf16 v[94:97], v[176:179], v[192:195], v[94:97]
	v_mfma_f32_16x16x32_bf16 v[82:85], v[162:165], v[200:203], v[82:85]
	v_mfma_f32_16x16x32_bf16 v[78:81], v[176:179], v[200:203], v[78:81]
	v_mfma_f32_16x16x32_bf16 v[70:73], v[162:165], v[208:211], v[70:73]
	v_mfma_f32_16x16x32_bf16 v[66:69], v[176:179], v[208:211], v[66:69]
	v_mfma_f32_16x16x32_bf16 v[114:117], v[172:175], v[188:191], v[114:117]
	v_mfma_f32_16x16x32_bf16 v[110:113], v[180:183], v[188:191], v[110:113]
	v_mfma_f32_16x16x32_bf16 v[98:101], v[172:175], v[196:199], v[98:101]
	v_mfma_f32_16x16x32_bf16 v[94:97], v[180:183], v[196:199], v[94:97]
	v_mfma_f32_16x16x32_bf16 v[82:85], v[172:175], v[204:207], v[82:85]
	v_mfma_f32_16x16x32_bf16 v[78:81], v[180:183], v[204:207], v[78:81]
	v_mfma_f32_16x16x32_bf16 v[70:73], v[172:175], v[212:215], v[70:73]
	v_mfma_f32_16x16x32_bf16 v[66:69], v[180:183], v[212:215], v[66:69]
	s_setprio 2
	s_barrier
	ds_read_b128 v[184:187], v170 offset:16384
	ds_read_b128 v[188:191], v170 offset:17408
	ds_read_b128 v[192:195], v170 offset:18432
	ds_read_b128 v[196:199], v170 offset:19456
	ds_read_b128 v[200:203], v170 offset:20480
	ds_read_b128 v[204:207], v170 offset:21504
	ds_read_b128 v[208:211], v170 offset:22528
	ds_read_b128 v[212:215], v170 offset:23552
	s_add_i32 s33, s56, s42
	v_lshl_add_u64 v[216:217], s[36:37], 0, v[150:151]
	s_mov_b32 m0, s33
	s_nop 0
	global_load_lds_dwordx4 v[216:217], off
	s_add_i32 m0, s33, 0x2000
	s_add_u32 s64, s36, 0x40000
	v_lshl_add_u64 v[218:219], s[36:37], 0, v[146:147]
	s_addc_u32 s65, s37, 0
	s_add_i32 s33, s57, s42
	global_load_lds_dwordx4 v[218:219], off
	v_lshl_add_u64 v[220:221], s[64:65], 0, v[150:151]
	s_mov_b32 m0, s33
	v_lshl_add_u64 v[222:223], s[38:39], 0, v[148:149]
	global_load_lds_dwordx4 v[220:221], off
	v_lshl_add_u64 v[220:221], s[64:65], 0, v[146:147]
	s_add_i32 m0, s33, 0x2000
	s_nop 0
	global_load_lds_dwordx4 v[220:221], off
	v_lshl_add_u64 v[220:221], s[38:39], 0, v[152:153]
	s_mov_b32 m0, s23
	s_nop 0
	global_load_lds_dwordx4 v[220:221], off
	s_mov_b32 m0, s25
	s_nop 0
	global_load_lds_dwordx4 v[222:223], off
	s_waitcnt vmcnt(8)
	s_waitcnt lgkmcnt(0)
	s_barrier
; #define PG8_STAGE(bufoff, gbase, voff) do { _Pragma("unroll") for (int _i = 0; _i < 2; ++_i) \
;         __builtin_amdgcn_global_load_lds((const unsigned*)((const char*)(gbase) + (voff)[_i]), (LAS unsigned*)(lds + (bufoff) + ldsw + _i * 8192), 16, 0, 0); } while (0)
; #define PG8_LDA(dst, b, h) do { _Pragma("unroll") for (int m = 0; m < 4; ++m) _Pragma("unroll") for (int k = 0; k < 2; ++k) dst[m][k] = *(const LAS bf16x8*)(lds + PG8_SA(b, h) + aoff + m * 2048 + k * 1024); } while (0)
; #define PG8_LDB(dst, b, h) do { _Pragma("unroll") for (int n = 0; n < 2; ++n) _Pragma("unroll") for (int k = 0; k < 2; ++k) dst[n][k] = *(const LAS bf16x8*)(lds + PG8_SB(b, h) + boff + n * 2048 + k * 1024); } while (0)
; #define PG8_MMA(ai, bj, At, Bt) do { __builtin_amdgcn_s_setprio(1); _Pragma("unroll") for (int m = 0; m < 4; ++m) _Pragma("unroll") for (int n = 0; n < 2; ++n) _Pragma("unroll") for (int k = 0; k < 2; ++k) \
;         acc[ai][bj][m][n] = __builtin_amdgcn_mfma_f32_16x16x32_bf16(Bt[n][k], At[m][k], acc[ai][bj][m][n], 0, 0, 0); __builtin_amdgcn_s_setprio(0); } while (0)
; #define PG8_WAIT_V(n) asm volatile("s_waitcnt vmcnt(" #n ")" ::: "memory")
; #define PG8_WAIT_L(n) asm volatile("s_waitcnt lgkmcnt(" #n ")" ::: "memory")
; #define PG8_BAR __builtin_amdgcn_s_barrier()
; #define PG8_SCHED __builtin_amdgcn_sched_barrier(0)
; template <class Epi>
; __device__ __forceinline__ void gemm_phase(LAS unsigned char* lds, const Gemm g, int G, int c, const Epi& E) {
;     ...
;             PG8_WAIT_V(8); PG8_WAIT_L(0); PG8_BAR; PG8_MMA(1, 0, At, B0); PG8_MMA(1, 1, At, B1); PG8_BAR; PG8_SCHED;
;             PG8_LDB(B0, 1, 0); PG8_LDB(B1, 1, 1); PG8_SCHED; PG8_LDA(At, 1, 0); PG8_STAGE(PG8_SA(0, 1), a2 + hstepA, voffA);
;             PG8_WAIT_V(8); PG8_WAIT_L(0); PG8_BAR; PG8_MMA(0, 0, At, B0); PG8_MMA(0, 1, At, B1); PG8_BAR; PG8_SCHED;
	s_setprio 0
	v_mfma_f32_16x16x32_bf16 v[62:65], v[122:125], v[184:187], v[62:65]
	v_mfma_f32_16x16x32_bf16 v[58:61], v[130:133], v[184:187], v[58:61]
	v_mfma_f32_16x16x32_bf16 v[54:57], v[122:125], v[192:195], v[54:57]
	v_mfma_f32_16x16x32_bf16 v[42:45], v[130:133], v[192:195], v[42:45]
	v_mfma_f32_16x16x32_bf16 v[38:41], v[122:125], v[200:203], v[38:41]
	v_mfma_f32_16x16x32_bf16 v[26:29], v[130:133], v[200:203], v[26:29]
	v_mfma_f32_16x16x32_bf16 v[22:25], v[122:125], v[208:211], v[22:25]
	v_mfma_f32_16x16x32_bf16 v[10:13], v[130:133], v[208:211], v[10:13]
	v_mfma_f32_16x16x32_bf16 v[62:65], v[126:129], v[188:191], v[62:65]
	v_mfma_f32_16x16x32_bf16 v[58:61], v[134:137], v[188:191], v[58:61]
	v_mfma_f32_16x16x32_bf16 v[54:57], v[126:129], v[196:199], v[54:57]
	v_mfma_f32_16x16x32_bf16 v[42:45], v[134:137], v[196:199], v[42:45]
	v_mfma_f32_16x16x32_bf16 v[38:41], v[126:129], v[204:207], v[38:41]
	v_mfma_f32_16x16x32_bf16 v[26:29], v[134:137], v[204:207], v[26:29]
	v_mfma_f32_16x16x32_bf16 v[22:25], v[126:129], v[212:215], v[22:25]
	v_mfma_f32_16x16x32_bf16 v[10:13], v[134:137], v[212:215], v[10:13]
	s_setprio 2
	s_setprio 0
	v_mfma_f32_16x16x32_bf16 v[50:53], v[162:165], v[184:187], v[50:53]
	v_mfma_f32_16x16x32_bf16 v[46:49], v[176:179], v[184:187], v[46:49]
	v_mfma_f32_16x16x32_bf16 v[34:37], v[162:165], v[192:195], v[34:37]
	v_mfma_f32_16x16x32_bf16 v[30:33], v[176:179], v[192:195], v[30:33]
	v_mfma_f32_16x16x32_bf16 v[18:21], v[162:165], v[200:203], v[18:21]
	v_mfma_f32_16x16x32_bf16 v[14:17], v[176:179], v[200:203], v[14:17]
	v_mfma_f32_16x16x32_bf16 v[6:9], v[162:165], v[208:211], v[6:9]
	v_mfma_f32_16x16x32_bf16 v[2:5], v[176:179], v[208:211], v[2:5]
	v_mfma_f32_16x16x32_bf16 v[50:53], v[172:175], v[188:191], v[50:53]
	v_mfma_f32_16x16x32_bf16 v[46:49], v[180:183], v[188:191], v[46:49]
	v_mfma_f32_16x16x32_bf16 v[34:37], v[172:175], v[196:199], v[34:37]
	v_mfma_f32_16x16x32_bf16 v[30:33], v[180:183], v[196:199], v[30:33]
	v_mfma_f32_16x16x32_bf16 v[18:21], v[172:175], v[204:207], v[18:21]
	v_mfma_f32_16x16x32_bf16 v[14:17], v[180:183], v[204:207], v[14:17]
	v_mfma_f32_16x16x32_bf16 v[6:9], v[172:175], v[212:215], v[6:9]
	v_mfma_f32_16x16x32_bf16 v[2:5], v[180:183], v[212:215], v[2:5]
	s_setprio 2
	s_barrier
	s_add_i32 s33, 0, 0x18000
	s_add_i32 s63, 0, 0x1c000
	v_add_u32_e32 v134, s33, v167
	v_add_u32_e32 v171, s63, v167
	ds_read_b128 v[122:125], v134
	ds_read_b128 v[126:129], v134 offset:1024
	ds_read_b128 v[130:133], v134 offset:2048
	ds_read_b128 v[134:137], v134 offset:3072
	ds_read_b128 v[162:165], v171
	ds_read_b128 v[172:175], v171 offset:1024
	ds_read_b128 v[176:179], v171 offset:2048
	ds_read_b128 v[180:183], v171 offset:3072
	ds_read_b128 v[184:187], v170 offset:32768
	ds_read_b128 v[188:191], v170 offset:33792
	ds_read_b128 v[192:195], v170 offset:34816
	ds_read_b128 v[196:199], v170 offset:35840
	ds_read_b128 v[200:203], v170 offset:36864
	ds_read_b128 v[204:207], v170 offset:37888
	ds_read_b128 v[208:211], v170 offset:38912
	ds_read_b128 v[212:215], v170 offset:39936
	s_add_u32 s38, s38, 0x40000
	s_addc_u32 s39, s39, 0
	s_mov_b32 m0, s44
	v_lshl_add_u64 v[224:225], s[38:39], 0, v[152:153]
	global_load_lds_dwordx4 v[224:225], off
	v_lshl_add_u64 v[224:225], s[38:39], 0, v[148:149]
	s_mov_b32 m0, s45
	s_nop 0
	global_load_lds_dwordx4 v[224:225], off
	s_waitcnt vmcnt(8)
	s_waitcnt lgkmcnt(0)
	s_barrier
	s_setprio 0
	v_mfma_f32_16x16x32_bf16 v[142:145], v[122:125], v[184:187], v[142:145]
	v_mfma_f32_16x16x32_bf16 v[138:141], v[130:133], v[184:187], v[138:141]
	v_mfma_f32_16x16x32_bf16 v[118:121], v[122:125], v[192:195], v[118:121]
	v_mfma_f32_16x16x32_bf16 v[106:109], v[130:133], v[192:195], v[106:109]
	v_mfma_f32_16x16x32_bf16 v[102:105], v[122:125], v[200:203], v[102:105]
	v_mfma_f32_16x16x32_bf16 v[90:93], v[130:133], v[200:203], v[90:93]
	v_mfma_f32_16x16x32_bf16 v[86:89], v[122:125], v[208:211], v[86:89]
	v_mfma_f32_16x16x32_bf16 v[74:77], v[130:133], v[208:211], v[74:77]
	v_mfma_f32_16x16x32_bf16 v[142:145], v[126:129], v[188:191], v[142:145]
	v_mfma_f32_16x16x32_bf16 v[138:141], v[134:137], v[188:191], v[138:141]
	v_mfma_f32_16x16x32_bf16 v[118:121], v[126:129], v[196:199], v[118:121]
	v_mfma_f32_16x16x32_bf16 v[106:109], v[134:137], v[196:199], v[106:109]
	v_mfma_f32_16x16x32_bf16 v[102:105], v[126:129], v[204:207], v[102:105]
	v_mfma_f32_16x16x32_bf16 v[90:93], v[134:137], v[204:207], v[90:93]
	v_mfma_f32_16x16x32_bf16 v[86:89], v[126:129], v[212:215], v[86:89]
	v_mfma_f32_16x16x32_bf16 v[74:77], v[134:137], v[212:215], v[74:77]
	s_setprio 2
	s_setprio 0
	v_mfma_f32_16x16x32_bf16 v[114:117], v[162:165], v[184:187], v[114:117]
	v_mfma_f32_16x16x32_bf16 v[110:113], v[176:179], v[184:187], v[110:113]
	v_mfma_f32_16x16x32_bf16 v[98:101], v[162:165], v[192:195], v[98:101]
	v_mfma_f32_16x16x32_bf16 v[94:97], v[176:179], v[192:195], v[94:97]
	v_mfma_f32_16x16x32_bf16 v[82:85], v[162:165], v[200:203], v[82:85]
	v_mfma_f32_16x16x32_bf16 v[78:81], v[176:179], v[200:203], v[78:81]
	v_mfma_f32_16x16x32_bf16 v[70:73], v[162:165], v[208:211], v[70:73]
	v_mfma_f32_16x16x32_bf16 v[66:69], v[176:179], v[208:211], v[66:69]
	v_mfma_f32_16x16x32_bf16 v[114:117], v[172:175], v[188:191], v[114:117]
	v_mfma_f32_16x16x32_bf16 v[110:113], v[180:183], v[188:191], v[110:113]
	v_mfma_f32_16x16x32_bf16 v[98:101], v[172:175], v[196:199], v[98:101]
	v_mfma_f32_16x16x32_bf16 v[94:97], v[180:183], v[196:199], v[94:97]
	v_mfma_f32_16x16x32_bf16 v[82:85], v[172:175], v[204:207], v[82:85]
	v_mfma_f32_16x16x32_bf16 v[78:81], v[180:183], v[204:207], v[78:81]
	v_mfma_f32_16x16x32_bf16 v[70:73], v[172:175], v[212:215], v[70:73]
	v_mfma_f32_16x16x32_bf16 v[66:69], v[180:183], v[212:215], v[66:69]
	s_setprio 2
	s_barrier
; #define PG8_STAGE(bufoff, gbase, voff) do { _Pragma("unroll") for (int _i = 0; _i < 2; ++_i) \
;         __builtin_amdgcn_global_load_lds((const unsigned*)((const char*)(gbase) + (voff)[_i]), (LAS unsigned*)(lds + (bufoff) + ldsw + _i * 8192), 16, 0, 0); } while (0)
; #define PG8_LDA(dst, b, h) do { _Pragma("unroll") for (int m = 0; m < 4; ++m) _Pragma("unroll") for (int k = 0; k < 2; ++k) dst[m][k] = *(const LAS bf16x8*)(lds + PG8_SA(b, h) + aoff + m * 2048 + k * 1024); } while (0)
; #define PG8_MMA(ai, bj, At, Bt) do { __builtin_amdgcn_s_setprio(1); _Pragma("unroll") for (int m = 0; m < 4; ++m) _Pragma("unroll") for (int n = 0; n < 2; ++n) _Pragma("unroll") for (int k = 0; k < 2; ++k) \
;         acc[ai][bj][m][n] = __builtin_amdgcn_mfma_f32_16x16x32_bf16(Bt[n][k], At[m][k], acc[ai][bj][m][n], 0, 0, 0); __builtin_amdgcn_s_setprio(0); } while (0)
; #define PG8_WAIT_V(n) asm volatile("s_waitcnt vmcnt(" #n ")" ::: "memory")
; #define PG8_WAIT_L(n) asm volatile("s_waitcnt lgkmcnt(" #n ")" ::: "memory")
; #define PG8_BAR __builtin_amdgcn_s_barrier()
; #define PG8_SCHED __builtin_amdgcn_sched_barrier(0)
; template <class Epi>
; __device__ __forceinline__ void gemm_phase(LAS unsigned char* lds, const Gemm g, int G, int c, const Epi& E) {
;     ...
;             PG8_LDA(At, 1, 1); PG8_STAGE(PG8_SB(1, 0), b3, voffB); PG8_STAGE(PG8_SB(1, 1), b3 + hstepB, voffB); PG8_STAGE(PG8_SA(1, 0), a3, voffA);
;             PG8_WAIT_V(8); PG8_WAIT_L(0); PG8_BAR; PG8_MMA(1, 0, At, B0); PG8_MMA(1, 1, At, B1); PG8_BAR; PG8_SCHED;
;         }
;         if (wr == 0) PG8_BAR;
	ds_read_b128 v[184:187], v170 offset:49152
	ds_read_b128 v[188:191], v170 offset:50176
	ds_read_b128 v[192:195], v170 offset:51200
	ds_read_b128 v[196:199], v170 offset:52224
	ds_read_b128 v[200:203], v170 offset:53248
	ds_read_b128 v[204:207], v170 offset:54272
	ds_read_b128 v[208:211], v170 offset:55296
	ds_read_b128 v[212:215], v170 offset:56320
	s_add_i32 s33, s33, s42
	v_lshl_add_u64 v[216:217], v[216:217], 0, s[10:11]
	s_mov_b32 m0, s33
	s_nop 0
	global_load_lds_dwordx4 v[216:217], off
	s_add_i32 m0, s33, 0x2000
	s_add_u32 s36, s36, 0x40080
	v_lshl_add_u64 v[216:217], v[218:219], 0, s[10:11]
	s_addc_u32 s37, s37, 0
	s_add_i32 s33, s63, s42
	global_load_lds_dwordx4 v[216:217], off
	v_lshl_add_u64 v[216:217], s[36:37], 0, v[150:151]
	s_mov_b32 m0, s33
	s_nop 0
	global_load_lds_dwordx4 v[216:217], off
	v_lshl_add_u64 v[216:217], s[36:37], 0, v[146:147]
	s_add_i32 m0, s33, 0x2000
	s_nop 0
	global_load_lds_dwordx4 v[216:217], off
	v_lshl_add_u64 v[216:217], v[220:221], 0, s[10:11]
	s_mov_b32 m0, s53
	s_nop 0
	global_load_lds_dwordx4 v[216:217], off
	v_lshl_add_u64 v[216:217], v[222:223], 0, s[10:11]
	s_mov_b32 m0, s54
	s_nop 0
	global_load_lds_dwordx4 v[216:217], off
	s_waitcnt vmcnt(8)
	s_waitcnt lgkmcnt(0)
	s_barrier
	s_setprio 0
	v_mfma_f32_16x16x32_bf16 v[62:65], v[122:125], v[184:187], v[62:65]
	v_mfma_f32_16x16x32_bf16 v[58:61], v[130:133], v[184:187], v[58:61]
	v_mfma_f32_16x16x32_bf16 v[54:57], v[122:125], v[192:195], v[54:57]
	v_mfma_f32_16x16x32_bf16 v[42:45], v[130:133], v[192:195], v[42:45]
	v_mfma_f32_16x16x32_bf16 v[38:41], v[122:125], v[200:203], v[38:41]
	v_mfma_f32_16x16x32_bf16 v[26:29], v[130:133], v[200:203], v[26:29]
	v_mfma_f32_16x16x32_bf16 v[22:25], v[122:125], v[208:211], v[22:25]
	v_mfma_f32_16x16x32_bf16 v[10:13], v[130:133], v[208:211], v[10:13]
	v_mfma_f32_16x16x32_bf16 v[62:65], v[126:129], v[188:191], v[62:65]
	v_mfma_f32_16x16x32_bf16 v[58:61], v[134:137], v[188:191], v[58:61]
	v_mfma_f32_16x16x32_bf16 v[54:57], v[126:129], v[196:199], v[54:57]
	v_mfma_f32_16x16x32_bf16 v[42:45], v[134:137], v[196:199], v[42:45]
	v_mfma_f32_16x16x32_bf16 v[38:41], v[126:129], v[204:207], v[38:41]
	v_mfma_f32_16x16x32_bf16 v[26:29], v[134:137], v[204:207], v[26:29]
	v_mfma_f32_16x16x32_bf16 v[22:25], v[126:129], v[212:215], v[22:25]
	v_mfma_f32_16x16x32_bf16 v[10:13], v[134:137], v[212:215], v[10:13]
	s_setprio 2
	s_setprio 0
	v_mfma_f32_16x16x32_bf16 v[50:53], v[162:165], v[184:187], v[50:53]
	v_mfma_f32_16x16x32_bf16 v[46:49], v[176:179], v[184:187], v[46:49]
	v_mfma_f32_16x16x32_bf16 v[34:37], v[162:165], v[192:195], v[34:37]
	v_mfma_f32_16x16x32_bf16 v[30:33], v[176:179], v[192:195], v[30:33]
	v_mfma_f32_16x16x32_bf16 v[18:21], v[162:165], v[200:203], v[18:21]
	v_mfma_f32_16x16x32_bf16 v[14:17], v[176:179], v[200:203], v[14:17]
	v_mfma_f32_16x16x32_bf16 v[6:9], v[162:165], v[208:211], v[6:9]
	v_mfma_f32_16x16x32_bf16 v[2:5], v[176:179], v[208:211], v[2:5]
	v_mfma_f32_16x16x32_bf16 v[50:53], v[172:175], v[188:191], v[50:53]
	v_mfma_f32_16x16x32_bf16 v[46:49], v[180:183], v[188:191], v[46:49]
	v_mfma_f32_16x16x32_bf16 v[34:37], v[172:175], v[196:199], v[34:37]
	v_mfma_f32_16x16x32_bf16 v[30:33], v[180:183], v[196:199], v[30:33]
	v_mfma_f32_16x16x32_bf16 v[18:21], v[172:175], v[204:207], v[18:21]
	v_mfma_f32_16x16x32_bf16 v[14:17], v[180:183], v[204:207], v[14:17]
	v_mfma_f32_16x16x32_bf16 v[6:9], v[172:175], v[212:215], v[6:9]
	v_mfma_f32_16x16x32_bf16 v[2:5], v[180:183], v[212:215], v[2:5]
	s_setprio 2
	s_barrier
	s_add_i32 s62, s62, 2
	s_add_u32 s4, s4, 0x100
	s_addc_u32 s5, s5, 0
	s_add_u32 s60, s60, 0x100
	s_addc_u32 s61, s61, 0
	s_cmp_gt_u32 s62, 13
	s_cbranch_scc0 .LBB0_1931
	s_and_b64 vcc, exec, s[12:13]
	s_cbranch_vccz .LBB0_1934
	s_barrier

; #define PG8_STAGE(bufoff, gbase, voff) do { _Pragma("unroll") for (int _i = 0; _i < 2; ++_i) \
;         __builtin_amdgcn_global_load_lds((const unsigned*)((const char*)(gbase) + (voff)[_i]), (LAS unsigned*)(lds + (bufoff) + ldsw + _i * 8192), 16, 0, 0); } while (0)
; #define PG8_LDA(dst, b, h) do { _Pragma("unroll") for (int m = 0; m < 4; ++m) _Pragma("unroll") for (int k = 0; k < 2; ++k) dst[m][k] = *(const LAS bf16x8*)(lds + PG8_SA(b, h) + aoff + m * 2048 + k * 1024); } while (0)
; #define PG8_LDB(dst, b, h) do { _Pragma("unroll") for (int n = 0; n < 2; ++n) _Pragma("unroll") for (int k = 0; k < 2; ++k) dst[n][k] = *(const LAS bf16x8*)(lds + PG8_SB(b, h) + boff + n * 2048 + k * 1024); } while (0)
; #define PG8_MMA(ai, bj, At, Bt) do { __builtin_amdgcn_s_setprio(1); _Pragma("unroll") for (int m = 0; m < 4; ++m) _Pragma("unroll") for (int n = 0; n < 2; ++n) _Pragma("unroll") for (int k = 0; k < 2; ++k) \
;         acc[ai][bj][m][n] = __builtin_amdgcn_mfma_f32_16x16x32_bf16(Bt[n][k], At[m][k], acc[ai][bj][m][n], 0, 0, 0); __builtin_amdgcn_s_setprio(0); } while (0)
; #define PG8_WAIT_V(n) asm volatile("s_waitcnt vmcnt(" #n ")" ::: "memory")
; #define PG8_WAIT_L(n) asm volatile("s_waitcnt lgkmcnt(" #n ")" ::: "memory")
; #define PG8_BAR __builtin_amdgcn_s_barrier()
; #define PG8_SCHED __builtin_amdgcn_sched_barrier(0)
; template <class Epi>
; __device__ __forceinline__ void gemm_phase(LAS unsigned char* lds, const Gemm g, int G, int c, const Epi& E) {
;     ...
;             const bool last = (t == nt - 2);
;             const char* a1 = cA + (size_t)(t + 1) * kstep;
;             const char* a2 = last ? nA : cA + (size_t)(t + 2) * kstep; const char* b2 = last ? nB : cB + (size_t)(t + 2) * kstep;
;             const char* a3 = a2 + kstep; const char* b3 = b2 + kstep;
;             PG8_LDB(B0, 0, 0); PG8_LDB(B1, 0, 1); PG8_SCHED; PG8_LDA(At, 0, 0); PG8_STAGE(PG8_SA(1, 1), a1 + hstepA, voffA);
;             PG8_WAIT_V(8); PG8_WAIT_L(0); PG8_BAR; PG8_MMA(0, 0, At, B0); PG8_MMA(0, 1, At, B1); PG8_BAR; PG8_SCHED;
;             PG8_LDA(At, 0, 1); PG8_STAGE(PG8_SB(0, 0), b2, voffB); PG8_STAGE(PG8_SB(0, 1), b2 + hstepB, voffB); PG8_STAGE(PG8_SA(0, 0), a2, voffA);
;             PG8_WAIT_V(8); PG8_WAIT_L(0); PG8_BAR; PG8_MMA(1, 0, At, B0); PG8_MMA(1, 1, At, B1); PG8_BAR; PG8_SCHED;
.LBB0_2084:
	ds_read_b128 v[152:155], v148
	ds_read_b128 v[156:159], v148 offset:1024
	ds_read_b128 v[160:163], v148 offset:2048
	ds_read_b128 v[164:167], v148 offset:3072
	ds_read_b128 v[168:171], v149
	ds_read_b128 v[172:175], v149 offset:1024
	ds_read_b128 v[176:179], v149 offset:2048
	ds_read_b128 v[180:183], v149 offset:3072
	ds_read_b128 v[184:187], v150
	ds_read_b128 v[188:191], v150 offset:1024
	ds_read_b128 v[192:195], v150 offset:2048
	ds_read_b128 v[196:199], v150 offset:3072
	ds_read_b128 v[200:203], v150 offset:4096
	ds_read_b128 v[204:207], v150 offset:5120
	ds_read_b128 v[208:211], v150 offset:6144
	ds_read_b128 v[212:215], v150 offset:7168
	s_add_u32 s33, s4, 0xfffc0080
	s_addc_u32 s38, s5, -1
	s_cmp_eq_u32 s68, 12
	s_cselect_b32 s41, s21, s38
	s_cselect_b32 s40, s20, s33
	s_cselect_b32 s39, s17, s67
	s_cselect_b32 s38, s19, s66
	v_lshl_add_u64 v[216:217], s[4:5], 0, v[138:139]
	s_add_i32 m0, s25, 0xc000
	s_nop 0
	global_load_lds_dwordx4 v[216:217], off
	v_lshl_add_u64 v[216:217], s[4:5], 0, v[140:141]
	s_add_i32 m0, s25, 0xe000
	s_nop 0
	global_load_lds_dwordx4 v[216:217], off
	s_waitcnt vmcnt(8)
	s_waitcnt lgkmcnt(0)
	s_barrier
	s_setprio 0
	v_mfma_f32_16x16x32_bf16 v[126:129], v[152:155], v[184:187], v[126:129]
	v_mfma_f32_16x16x32_bf16 v[122:125], v[160:163], v[184:187], v[122:125]
	v_mfma_f32_16x16x32_bf16 v[110:113], v[152:155], v[192:195], v[110:113]
	v_mfma_f32_16x16x32_bf16 v[106:109], v[160:163], v[192:195], v[106:109]
	v_mfma_f32_16x16x32_bf16 v[94:97], v[152:155], v[200:203], v[94:97]
	v_mfma_f32_16x16x32_bf16 v[90:93], v[160:163], v[200:203], v[90:93]
	v_mfma_f32_16x16x32_bf16 v[78:81], v[152:155], v[208:211], v[78:81]
	v_mfma_f32_16x16x32_bf16 v[74:77], v[160:163], v[208:211], v[74:77]
	v_mfma_f32_16x16x32_bf16 v[126:129], v[156:159], v[188:191], v[126:129]
	v_mfma_f32_16x16x32_bf16 v[122:125], v[164:167], v[188:191], v[122:125]
	v_mfma_f32_16x16x32_bf16 v[110:113], v[156:159], v[196:199], v[110:113]
	v_mfma_f32_16x16x32_bf16 v[106:109], v[164:167], v[196:199], v[106:109]
	v_mfma_f32_16x16x32_bf16 v[94:97], v[156:159], v[204:207], v[94:97]
	v_mfma_f32_16x16x32_bf16 v[90:93], v[164:167], v[204:207], v[90:93]
	v_mfma_f32_16x16x32_bf16 v[78:81], v[156:159], v[212:215], v[78:81]
	v_mfma_f32_16x16x32_bf16 v[74:77], v[164:167], v[212:215], v[74:77]
	s_setprio 2
	s_setprio 0
	v_mfma_f32_16x16x32_bf16 v[118:121], v[168:171], v[184:187], v[118:121]
	v_mfma_f32_16x16x32_bf16 v[114:117], v[176:179], v[184:187], v[114:117]
	v_mfma_f32_16x16x32_bf16 v[102:105], v[168:171], v[192:195], v[102:105]
	v_mfma_f32_16x16x32_bf16 v[98:101], v[176:179], v[192:195], v[98:101]
	v_mfma_f32_16x16x32_bf16 v[86:89], v[168:171], v[200:203], v[86:89]
	v_mfma_f32_16x16x32_bf16 v[82:85], v[176:179], v[200:203], v[82:85]
	v_mfma_f32_16x16x32_bf16 v[70:73], v[168:171], v[208:211], v[70:73]
	v_mfma_f32_16x16x32_bf16 v[66:69], v[176:179], v[208:211], v[66:69]
	v_mfma_f32_16x16x32_bf16 v[118:121], v[172:175], v[188:191], v[118:121]
	v_mfma_f32_16x16x32_bf16 v[114:117], v[180:183], v[188:191], v[114:117]
	v_mfma_f32_16x16x32_bf16 v[102:105], v[172:175], v[196:199], v[102:105]
	v_mfma_f32_16x16x32_bf16 v[98:101], v[180:183], v[196:199], v[98:101]
	v_mfma_f32_16x16x32_bf16 v[86:89], v[172:175], v[204:207], v[86:89]
	v_mfma_f32_16x16x32_bf16 v[82:85], v[180:183], v[204:207], v[82:85]
	v_mfma_f32_16x16x32_bf16 v[70:73], v[172:175], v[212:215], v[70:73]
	v_mfma_f32_16x16x32_bf16 v[66:69], v[180:183], v[212:215], v[66:69]
	s_setprio 2
	s_barrier
	ds_read_b128 v[184:187], v150 offset:16384
	ds_read_b128 v[188:191], v150 offset:17408
	ds_read_b128 v[192:195], v150 offset:18432
	ds_read_b128 v[196:199], v150 offset:19456
	ds_read_b128 v[200:203], v150 offset:20480
	ds_read_b128 v[204:207], v150 offset:21504
	ds_read_b128 v[208:211], v150 offset:22528
	ds_read_b128 v[212:215], v150 offset:23552
	s_add_i32 s33, s56, s46
	v_lshl_add_u64 v[216:217], s[38:39], 0, v[134:135]
	s_mov_b32 m0, s33
	s_nop 0
	global_load_lds_dwordx4 v[216:217], off
	s_add_i32 m0, s33, 0x2000
	s_add_u32 s70, s38, 0x40000
	v_lshl_add_u64 v[218:219], s[38:39], 0, v[130:131]
	s_addc_u32 s71, s39, 0
	s_add_i32 s33, s57, s46
	global_load_lds_dwordx4 v[218:219], off
	v_lshl_add_u64 v[220:221], s[70:71], 0, v[134:135]
	s_mov_b32 m0, s33
	v_lshl_add_u64 v[222:223], s[40:41], 0, v[132:133]
	global_load_lds_dwordx4 v[220:221], off
	v_lshl_add_u64 v[220:221], s[70:71], 0, v[130:131]
	s_add_i32 m0, s33, 0x2000
	s_nop 0
	global_load_lds_dwordx4 v[220:221], off
	v_lshl_add_u64 v[220:221], s[40:41], 0, v[136:137]
	s_mov_b32 m0, s25
	s_nop 0
	global_load_lds_dwordx4 v[220:221], off
	s_mov_b32 m0, s37
	s_nop 0
	global_load_lds_dwordx4 v[222:223], off
	s_waitcnt vmcnt(8)
	s_waitcnt lgkmcnt(0)
	s_barrier
; #define PG8_STAGE(bufoff, gbase, voff) do { _Pragma("unroll") for (int _i = 0; _i < 2; ++_i) \
;         __builtin_amdgcn_global_load_lds((const unsigned*)((const char*)(gbase) + (voff)[_i]), (LAS unsigned*)(lds + (bufoff) + ldsw + _i * 8192), 16, 0, 0); } while (0)
; #define PG8_LDA(dst, b, h) do { _Pragma("unroll") for (int m = 0; m < 4; ++m) _Pragma("unroll") for (int k = 0; k < 2; ++k) dst[m][k] = *(const LAS bf16x8*)(lds + PG8_SA(b, h) + aoff + m * 2048 + k * 1024); } while (0)
; #define PG8_LDB(dst, b, h) do { _Pragma("unroll") for (int n = 0; n < 2; ++n) _Pragma("unroll") for (int k = 0; k < 2; ++k) dst[n][k] = *(const LAS bf16x8*)(lds + PG8_SB(b, h) + boff + n * 2048 + k * 1024); } while (0)
; #define PG8_MMA(ai, bj, At, Bt) do { __builtin_amdgcn_s_setprio(1); _Pragma("unroll") for (int m = 0; m < 4; ++m) _Pragma("unroll") for (int n = 0; n < 2; ++n) _Pragma("unroll") for (int k = 0; k < 2; ++k) \
;         acc[ai][bj][m][n] = __builtin_amdgcn_mfma_f32_16x16x32_bf16(Bt[n][k], At[m][k], acc[ai][bj][m][n], 0, 0, 0); __builtin_amdgcn_s_setprio(0); } while (0)
; #define PG8_WAIT_V(n) asm volatile("s_waitcnt vmcnt(" #n ")" ::: "memory")
; #define PG8_WAIT_L(n) asm volatile("s_waitcnt lgkmcnt(" #n ")" ::: "memory")
; #define PG8_BAR __builtin_amdgcn_s_barrier()
; #define PG8_SCHED __builtin_amdgcn_sched_barrier(0)
; template <class Epi>
; __device__ __forceinline__ void gemm_phase(LAS unsigned char* lds, const Gemm g, int G, int c, const Epi& E) {
;     ...
;             PG8_WAIT_V(8); PG8_WAIT_L(0); PG8_BAR; PG8_MMA(1, 0, At, B0); PG8_MMA(1, 1, At, B1); PG8_BAR; PG8_SCHED;
;             PG8_LDB(B0, 1, 0); PG8_LDB(B1, 1, 1); PG8_SCHED; PG8_LDA(At, 1, 0); PG8_STAGE(PG8_SA(0, 1), a2 + hstepA, voffA);
;             PG8_WAIT_V(8); PG8_WAIT_L(0); PG8_BAR; PG8_MMA(0, 0, At, B0); PG8_MMA(0, 1, At, B1); PG8_BAR; PG8_SCHED;
	s_setprio 0
	v_mfma_f32_16x16x32_bf16 v[62:65], v[152:155], v[184:187], v[62:65]
	v_mfma_f32_16x16x32_bf16 v[58:61], v[160:163], v[184:187], v[58:61]
	v_mfma_f32_16x16x32_bf16 v[46:49], v[152:155], v[192:195], v[46:49]
	v_mfma_f32_16x16x32_bf16 v[42:45], v[160:163], v[192:195], v[42:45]
	v_mfma_f32_16x16x32_bf16 v[30:33], v[152:155], v[200:203], v[30:33]
	v_mfma_f32_16x16x32_bf16 v[26:29], v[160:163], v[200:203], v[26:29]
	v_mfma_f32_16x16x32_bf16 v[14:17], v[152:155], v[208:211], v[14:17]
	v_mfma_f32_16x16x32_bf16 v[10:13], v[160:163], v[208:211], v[10:13]
	v_mfma_f32_16x16x32_bf16 v[62:65], v[156:159], v[188:191], v[62:65]
	v_mfma_f32_16x16x32_bf16 v[58:61], v[164:167], v[188:191], v[58:61]
	v_mfma_f32_16x16x32_bf16 v[46:49], v[156:159], v[196:199], v[46:49]
	v_mfma_f32_16x16x32_bf16 v[42:45], v[164:167], v[196:199], v[42:45]
	v_mfma_f32_16x16x32_bf16 v[30:33], v[156:159], v[204:207], v[30:33]
	v_mfma_f32_16x16x32_bf16 v[26:29], v[164:167], v[204:207], v[26:29]
	v_mfma_f32_16x16x32_bf16 v[14:17], v[156:159], v[212:215], v[14:17]
	v_mfma_f32_16x16x32_bf16 v[10:13], v[164:167], v[212:215], v[10:13]
	s_setprio 2
	s_setprio 0
	v_mfma_f32_16x16x32_bf16 v[54:57], v[168:171], v[184:187], v[54:57]
	v_mfma_f32_16x16x32_bf16 v[50:53], v[176:179], v[184:187], v[50:53]
	v_mfma_f32_16x16x32_bf16 v[38:41], v[168:171], v[192:195], v[38:41]
	v_mfma_f32_16x16x32_bf16 v[34:37], v[176:179], v[192:195], v[34:37]
	v_mfma_f32_16x16x32_bf16 v[22:25], v[168:171], v[200:203], v[22:25]
	v_mfma_f32_16x16x32_bf16 v[18:21], v[176:179], v[200:203], v[18:21]
	v_mfma_f32_16x16x32_bf16 v[6:9], v[168:171], v[208:211], v[6:9]
	v_mfma_f32_16x16x32_bf16 v[2:5], v[176:179], v[208:211], v[2:5]
	v_mfma_f32_16x16x32_bf16 v[54:57], v[172:175], v[188:191], v[54:57]
	v_mfma_f32_16x16x32_bf16 v[50:53], v[180:183], v[188:191], v[50:53]
	v_mfma_f32_16x16x32_bf16 v[38:41], v[172:175], v[196:199], v[38:41]
	v_mfma_f32_16x16x32_bf16 v[34:37], v[180:183], v[196:199], v[34:37]
	v_mfma_f32_16x16x32_bf16 v[22:25], v[172:175], v[204:207], v[22:25]
	v_mfma_f32_16x16x32_bf16 v[18:21], v[180:183], v[204:207], v[18:21]
	v_mfma_f32_16x16x32_bf16 v[6:9], v[172:175], v[212:215], v[6:9]
	v_mfma_f32_16x16x32_bf16 v[2:5], v[180:183], v[212:215], v[2:5]
	s_setprio 2
	s_barrier
	s_add_i32 s33, 0, 0x18000
	s_add_i32 s69, 0, 0x1c000
	v_add_u32_e32 v164, s33, v147
	v_add_u32_e32 v180, s69, v147
	ds_read_b128 v[152:155], v164
	ds_read_b128 v[156:159], v164 offset:1024
	ds_read_b128 v[160:163], v164 offset:2048
	ds_read_b128 v[164:167], v164 offset:3072
	ds_read_b128 v[168:171], v180
	ds_read_b128 v[172:175], v180 offset:1024
	ds_read_b128 v[176:179], v180 offset:2048
	ds_read_b128 v[180:183], v180 offset:3072
	ds_read_b128 v[184:187], v150 offset:32768
	ds_read_b128 v[188:191], v150 offset:33792
	ds_read_b128 v[192:195], v150 offset:34816
	ds_read_b128 v[196:199], v150 offset:35840
	ds_read_b128 v[200:203], v150 offset:36864
	ds_read_b128 v[204:207], v150 offset:37888
	ds_read_b128 v[208:211], v150 offset:38912
	ds_read_b128 v[212:215], v150 offset:39936
	s_add_u32 s40, s40, 0x40000
	s_addc_u32 s41, s41, 0
	s_mov_b32 m0, s47
	v_lshl_add_u64 v[224:225], s[40:41], 0, v[136:137]
	global_load_lds_dwordx4 v[224:225], off
	v_lshl_add_u64 v[224:225], s[40:41], 0, v[132:133]
	s_mov_b32 m0, s48
	s_nop 0
	global_load_lds_dwordx4 v[224:225], off
	s_waitcnt vmcnt(8)
	s_waitcnt lgkmcnt(0)
	s_barrier
	s_setprio 0
	v_mfma_f32_16x16x32_bf16 v[126:129], v[152:155], v[184:187], v[126:129]
	v_mfma_f32_16x16x32_bf16 v[122:125], v[160:163], v[184:187], v[122:125]
	v_mfma_f32_16x16x32_bf16 v[110:113], v[152:155], v[192:195], v[110:113]
	v_mfma_f32_16x16x32_bf16 v[106:109], v[160:163], v[192:195], v[106:109]
	v_mfma_f32_16x16x32_bf16 v[94:97], v[152:155], v[200:203], v[94:97]
	v_mfma_f32_16x16x32_bf16 v[90:93], v[160:163], v[200:203], v[90:93]
	v_mfma_f32_16x16x32_bf16 v[78:81], v[152:155], v[208:211], v[78:81]
	v_mfma_f32_16x16x32_bf16 v[74:77], v[160:163], v[208:211], v[74:77]
	v_mfma_f32_16x16x32_bf16 v[126:129], v[156:159], v[188:191], v[126:129]
	v_mfma_f32_16x16x32_bf16 v[122:125], v[164:167], v[188:191], v[122:125]
	v_mfma_f32_16x16x32_bf16 v[110:113], v[156:159], v[196:199], v[110:113]
	v_mfma_f32_16x16x32_bf16 v[106:109], v[164:167], v[196:199], v[106:109]
	v_mfma_f32_16x16x32_bf16 v[94:97], v[156:159], v[204:207], v[94:97]
	v_mfma_f32_16x16x32_bf16 v[90:93], v[164:167], v[204:207], v[90:93]
	v_mfma_f32_16x16x32_bf16 v[78:81], v[156:159], v[212:215], v[78:81]
	v_mfma_f32_16x16x32_bf16 v[74:77], v[164:167], v[212:215], v[74:77]
	s_setprio 2
	s_setprio 0
	v_mfma_f32_16x16x32_bf16 v[118:121], v[168:171], v[184:187], v[118:121]
	v_mfma_f32_16x16x32_bf16 v[114:117], v[176:179], v[184:187], v[114:117]
	v_mfma_f32_16x16x32_bf16 v[102:105], v[168:171], v[192:195], v[102:105]
	v_mfma_f32_16x16x32_bf16 v[98:101], v[176:179], v[192:195], v[98:101]
	v_mfma_f32_16x16x32_bf16 v[86:89], v[168:171], v[200:203], v[86:89]
	v_mfma_f32_16x16x32_bf16 v[82:85], v[176:179], v[200:203], v[82:85]
	v_mfma_f32_16x16x32_bf16 v[70:73], v[168:171], v[208:211], v[70:73]
	v_mfma_f32_16x16x32_bf16 v[66:69], v[176:179], v[208:211], v[66:69]
	v_mfma_f32_16x16x32_bf16 v[118:121], v[172:175], v[188:191], v[118:121]
	v_mfma_f32_16x16x32_bf16 v[114:117], v[180:183], v[188:191], v[114:117]
	v_mfma_f32_16x16x32_bf16 v[102:105], v[172:175], v[196:199], v[102:105]
	v_mfma_f32_16x16x32_bf16 v[98:101], v[180:183], v[196:199], v[98:101]
	v_mfma_f32_16x16x32_bf16 v[86:89], v[172:175], v[204:207], v[86:89]
	v_mfma_f32_16x16x32_bf16 v[82:85], v[180:183], v[204:207], v[82:85]
	v_mfma_f32_16x16x32_bf16 v[70:73], v[172:175], v[212:215], v[70:73]
	v_mfma_f32_16x16x32_bf16 v[66:69], v[180:183], v[212:215], v[66:69]
	s_setprio 2
	s_barrier
; #define PG8_STAGE(bufoff, gbase, voff) do { _Pragma("unroll") for (int _i = 0; _i < 2; ++_i) \
;         __builtin_amdgcn_global_load_lds((const unsigned*)((const char*)(gbase) + (voff)[_i]), (LAS unsigned*)(lds + (bufoff) + ldsw + _i * 8192), 16, 0, 0); } while (0)
; #define PG8_LDA(dst, b, h) do { _Pragma("unroll") for (int m = 0; m < 4; ++m) _Pragma("unroll") for (int k = 0; k < 2; ++k) dst[m][k] = *(const LAS bf16x8*)(lds + PG8_SA(b, h) + aoff + m * 2048 + k * 1024); } while (0)
; #define PG8_MMA(ai, bj, At, Bt) do { __builtin_amdgcn_s_setprio(1); _Pragma("unroll") for (int m = 0; m < 4; ++m) _Pragma("unroll") for (int n = 0; n < 2; ++n) _Pragma("unroll") for (int k = 0; k < 2; ++k) \
;         acc[ai][bj][m][n] = __builtin_amdgcn_mfma_f32_16x16x32_bf16(Bt[n][k], At[m][k], acc[ai][bj][m][n], 0, 0, 0); __builtin_amdgcn_s_setprio(0); } while (0)
; #define PG8_WAIT_V(n) asm volatile("s_waitcnt vmcnt(" #n ")" ::: "memory")
; #define PG8_WAIT_L(n) asm volatile("s_waitcnt lgkmcnt(" #n ")" ::: "memory")
; #define PG8_BAR __builtin_amdgcn_s_barrier()
; #define PG8_SCHED __builtin_amdgcn_sched_barrier(0)
; template <class Epi>
; __device__ __forceinline__ void gemm_phase(LAS unsigned char* lds, const Gemm g, int G, int c, const Epi& E) {
;     ...
;             PG8_LDA(At, 1, 1); PG8_STAGE(PG8_SB(1, 0), b3, voffB); PG8_STAGE(PG8_SB(1, 1), b3 + hstepB, voffB); PG8_STAGE(PG8_SA(1, 0), a3, voffA);
;             PG8_WAIT_V(8); PG8_WAIT_L(0); PG8_BAR; PG8_MMA(1, 0, At, B0); PG8_MMA(1, 1, At, B1); PG8_BAR; PG8_SCHED;
;         }
;         if (wr == 0) PG8_BAR;
	ds_read_b128 v[184:187], v150 offset:49152
	ds_read_b128 v[188:191], v150 offset:50176
	ds_read_b128 v[192:195], v150 offset:51200
	ds_read_b128 v[196:199], v150 offset:52224
	ds_read_b128 v[200:203], v150 offset:53248
	ds_read_b128 v[204:207], v150 offset:54272
	ds_read_b128 v[208:211], v150 offset:55296
	ds_read_b128 v[212:215], v150 offset:56320
	s_add_i32 s33, s33, s46
	v_lshl_add_u64 v[216:217], v[216:217], 0, s[12:13]
	s_mov_b32 m0, s33
	s_nop 0
	global_load_lds_dwordx4 v[216:217], off
	s_add_i32 m0, s33, 0x2000
	s_add_u32 s38, s38, 0x40080
	v_lshl_add_u64 v[216:217], v[218:219], 0, s[12:13]
	s_addc_u32 s39, s39, 0
	s_add_i32 s33, s69, s46
	global_load_lds_dwordx4 v[216:217], off
	v_lshl_add_u64 v[216:217], s[38:39], 0, v[134:135]
	s_mov_b32 m0, s33
	s_nop 0
	global_load_lds_dwordx4 v[216:217], off
	v_lshl_add_u64 v[216:217], s[38:39], 0, v[130:131]
	s_add_i32 m0, s33, 0x2000
	s_nop 0
	global_load_lds_dwordx4 v[216:217], off
	v_lshl_add_u64 v[216:217], v[220:221], 0, s[12:13]
	s_mov_b32 m0, s53
	s_nop 0
	global_load_lds_dwordx4 v[216:217], off
	v_lshl_add_u64 v[216:217], v[222:223], 0, s[12:13]
	s_mov_b32 m0, s54
	s_nop 0
	global_load_lds_dwordx4 v[216:217], off
	s_waitcnt vmcnt(8)
	s_waitcnt lgkmcnt(0)
	s_barrier
	s_setprio 0
	v_mfma_f32_16x16x32_bf16 v[62:65], v[152:155], v[184:187], v[62:65]
	v_mfma_f32_16x16x32_bf16 v[58:61], v[160:163], v[184:187], v[58:61]
	v_mfma_f32_16x16x32_bf16 v[46:49], v[152:155], v[192:195], v[46:49]
	v_mfma_f32_16x16x32_bf16 v[42:45], v[160:163], v[192:195], v[42:45]
	v_mfma_f32_16x16x32_bf16 v[30:33], v[152:155], v[200:203], v[30:33]
	v_mfma_f32_16x16x32_bf16 v[26:29], v[160:163], v[200:203], v[26:29]
	v_mfma_f32_16x16x32_bf16 v[14:17], v[152:155], v[208:211], v[14:17]
	v_mfma_f32_16x16x32_bf16 v[10:13], v[160:163], v[208:211], v[10:13]
	v_mfma_f32_16x16x32_bf16 v[62:65], v[156:159], v[188:191], v[62:65]
	v_mfma_f32_16x16x32_bf16 v[58:61], v[164:167], v[188:191], v[58:61]
	v_mfma_f32_16x16x32_bf16 v[46:49], v[156:159], v[196:199], v[46:49]
	v_mfma_f32_16x16x32_bf16 v[42:45], v[164:167], v[196:199], v[42:45]
	v_mfma_f32_16x16x32_bf16 v[30:33], v[156:159], v[204:207], v[30:33]
	v_mfma_f32_16x16x32_bf16 v[26:29], v[164:167], v[204:207], v[26:29]
	v_mfma_f32_16x16x32_bf16 v[14:17], v[156:159], v[212:215], v[14:17]
	v_mfma_f32_16x16x32_bf16 v[10:13], v[164:167], v[212:215], v[10:13]
	s_setprio 2
	s_setprio 0
	v_mfma_f32_16x16x32_bf16 v[54:57], v[168:171], v[184:187], v[54:57]
	v_mfma_f32_16x16x32_bf16 v[50:53], v[176:179], v[184:187], v[50:53]
	v_mfma_f32_16x16x32_bf16 v[38:41], v[168:171], v[192:195], v[38:41]
	v_mfma_f32_16x16x32_bf16 v[34:37], v[176:179], v[192:195], v[34:37]
	v_mfma_f32_16x16x32_bf16 v[22:25], v[168:171], v[200:203], v[22:25]
	v_mfma_f32_16x16x32_bf16 v[18:21], v[176:179], v[200:203], v[18:21]
	v_mfma_f32_16x16x32_bf16 v[6:9], v[168:171], v[208:211], v[6:9]
	v_mfma_f32_16x16x32_bf16 v[2:5], v[176:179], v[208:211], v[2:5]
	v_mfma_f32_16x16x32_bf16 v[54:57], v[172:175], v[188:191], v[54:57]
	v_mfma_f32_16x16x32_bf16 v[50:53], v[180:183], v[188:191], v[50:53]
	v_mfma_f32_16x16x32_bf16 v[38:41], v[172:175], v[196:199], v[38:41]
	v_mfma_f32_16x16x32_bf16 v[34:37], v[180:183], v[196:199], v[34:37]
	v_mfma_f32_16x16x32_bf16 v[22:25], v[172:175], v[204:207], v[22:25]
	v_mfma_f32_16x16x32_bf16 v[18:21], v[180:183], v[204:207], v[18:21]
	v_mfma_f32_16x16x32_bf16 v[6:9], v[172:175], v[212:215], v[6:9]
	v_mfma_f32_16x16x32_bf16 v[2:5], v[180:183], v[212:215], v[2:5]
	s_setprio 2
	s_barrier
	s_add_i32 s68, s68, 2
	s_add_u32 s4, s4, 0x100
	s_addc_u32 s5, s5, 0
	s_add_u32 s66, s66, 0x100
	s_addc_u32 s67, s67, 0
	s_cmp_gt_u32 s68, 13
	s_cbranch_scc0 .LBB0_2084
	s_and_b64 vcc, exec, s[14:15]
	s_cbranch_vccz .LBB0_2087
	s_barrier

; #define PG8_STAGE(bufoff, gbase, voff) do { _Pragma("unroll") for (int _i = 0; _i < 2; ++_i) \
;         __builtin_amdgcn_global_load_lds((const unsigned*)((const char*)(gbase) + (voff)[_i]), (LAS unsigned*)(lds + (bufoff) + ldsw + _i * 8192), 16, 0, 0); } while (0)
; #define PG8_LDA(dst, b, h) do { _Pragma("unroll") for (int m = 0; m < 4; ++m) _Pragma("unroll") for (int k = 0; k < 2; ++k) dst[m][k] = *(const LAS bf16x8*)(lds + PG8_SA(b, h) + aoff + m * 2048 + k * 1024); } while (0)
; #define PG8_LDB(dst, b, h) do { _Pragma("unroll") for (int n = 0; n < 2; ++n) _Pragma("unroll") for (int k = 0; k < 2; ++k) dst[n][k] = *(const LAS bf16x8*)(lds + PG8_SB(b, h) + boff + n * 2048 + k * 1024); } while (0)
; #define PG8_MMA(ai, bj, At, Bt) do { __builtin_amdgcn_s_setprio(1); _Pragma("unroll") for (int m = 0; m < 4; ++m) _Pragma("unroll") for (int n = 0; n < 2; ++n) _Pragma("unroll") for (int k = 0; k < 2; ++k) \
;         acc[ai][bj][m][n] = __builtin_amdgcn_mfma_f32_16x16x32_bf16(Bt[n][k], At[m][k], acc[ai][bj][m][n], 0, 0, 0); __builtin_amdgcn_s_setprio(0); } while (0)
; #define PG8_WAIT_V(n) asm volatile("s_waitcnt vmcnt(" #n ")" ::: "memory")
; #define PG8_WAIT_L(n) asm volatile("s_waitcnt lgkmcnt(" #n ")" ::: "memory")
; #define PG8_BAR __builtin_amdgcn_s_barrier()
; #define PG8_SCHED __builtin_amdgcn_sched_barrier(0)
; template <class Epi>
; __device__ __forceinline__ void gemm_phase(LAS unsigned char* lds, const Gemm g, int G, int c, const Epi& E) {
;     ...
;             const bool last = (t == nt - 2);
;             const char* a1 = cA + (size_t)(t + 1) * kstep;
;             const char* a2 = last ? nA : cA + (size_t)(t + 2) * kstep; const char* b2 = last ? nB : cB + (size_t)(t + 2) * kstep;
;             const char* a3 = a2 + kstep; const char* b3 = b2 + kstep;
;             PG8_LDB(B0, 0, 0); PG8_LDB(B1, 0, 1); PG8_SCHED; PG8_LDA(At, 0, 0); PG8_STAGE(PG8_SA(1, 1), a1 + hstepA, voffA);
;             PG8_WAIT_V(8); PG8_WAIT_L(0); PG8_BAR; PG8_MMA(0, 0, At, B0); PG8_MMA(0, 1, At, B1); PG8_BAR; PG8_SCHED;
;             PG8_LDA(At, 0, 1); PG8_STAGE(PG8_SB(0, 0), b2, voffB); PG8_STAGE(PG8_SB(0, 1), b2 + hstepB, voffB); PG8_STAGE(PG8_SA(0, 0), a2, voffA);
;             PG8_WAIT_V(8); PG8_WAIT_L(0); PG8_BAR; PG8_MMA(1, 0, At, B0); PG8_MMA(1, 1, At, B1); PG8_BAR; PG8_SCHED;
.LBB0_2169:
	ds_read_b128 v[106:109], v168
	ds_read_b128 v[110:113], v168 offset:1024
	ds_read_b128 v[114:117], v168 offset:2048
	ds_read_b128 v[118:121], v168 offset:3072
	ds_read_b128 v[162:165], v169
	ds_read_b128 v[172:175], v169 offset:1024
	ds_read_b128 v[176:179], v169 offset:2048
	ds_read_b128 v[180:183], v169 offset:3072
	ds_read_b128 v[184:187], v170
	ds_read_b128 v[188:191], v170 offset:1024
	ds_read_b128 v[192:195], v170 offset:2048
	ds_read_b128 v[196:199], v170 offset:3072
	ds_read_b128 v[200:203], v170 offset:4096
	ds_read_b128 v[204:207], v170 offset:5120
	ds_read_b128 v[208:211], v170 offset:6144
	ds_read_b128 v[212:215], v170 offset:7168
	s_add_u32 s20, s18, 0x100
	s_addc_u32 s21, s19, 0
	s_cmp_eq_u32 s62, 40
	s_cselect_b32 s25, s5, s21
	s_cselect_b32 s24, s4, s20
	s_cselect_b32 s23, s17, s61
	s_cselect_b32 s22, s16, s60
	v_lshl_add_u64 v[216:217], s[18:19], 0, v[154:155]
	s_add_i32 m0, s40, 0xc000
	s_nop 0
	global_load_lds_dwordx4 v[216:217], off
	v_lshl_add_u64 v[216:217], s[18:19], 0, v[156:157]
	s_add_i32 m0, s40, 0xe000
	s_nop 0
	global_load_lds_dwordx4 v[216:217], off
	s_waitcnt vmcnt(8)
	s_waitcnt lgkmcnt(0)
	s_barrier
	s_setprio 0
	v_mfma_f32_16x16x32_bf16 v[142:145], v[106:109], v[184:187], v[142:145]
	v_mfma_f32_16x16x32_bf16 v[138:141], v[114:117], v[184:187], v[138:141]
	v_mfma_f32_16x16x32_bf16 v[126:129], v[106:109], v[192:195], v[126:129]
	v_mfma_f32_16x16x32_bf16 v[122:125], v[114:117], v[192:195], v[122:125]
	v_mfma_f32_16x16x32_bf16 v[94:97], v[106:109], v[200:203], v[94:97]
	v_mfma_f32_16x16x32_bf16 v[90:93], v[114:117], v[200:203], v[90:93]
	v_mfma_f32_16x16x32_bf16 v[78:81], v[106:109], v[208:211], v[78:81]
	v_mfma_f32_16x16x32_bf16 v[74:77], v[114:117], v[208:211], v[74:77]
	v_mfma_f32_16x16x32_bf16 v[142:145], v[110:113], v[188:191], v[142:145]
	v_mfma_f32_16x16x32_bf16 v[138:141], v[118:121], v[188:191], v[138:141]
	v_mfma_f32_16x16x32_bf16 v[126:129], v[110:113], v[196:199], v[126:129]
	v_mfma_f32_16x16x32_bf16 v[122:125], v[118:121], v[196:199], v[122:125]
	v_mfma_f32_16x16x32_bf16 v[94:97], v[110:113], v[204:207], v[94:97]
	v_mfma_f32_16x16x32_bf16 v[90:93], v[118:121], v[204:207], v[90:93]
	v_mfma_f32_16x16x32_bf16 v[78:81], v[110:113], v[212:215], v[78:81]
	v_mfma_f32_16x16x32_bf16 v[74:77], v[118:121], v[212:215], v[74:77]
	s_setprio 2
	s_setprio 0
	v_mfma_f32_16x16x32_bf16 v[134:137], v[162:165], v[184:187], v[134:137]
	v_mfma_f32_16x16x32_bf16 v[130:133], v[176:179], v[184:187], v[130:133]
	v_mfma_f32_16x16x32_bf16 v[102:105], v[162:165], v[192:195], v[102:105]
	v_mfma_f32_16x16x32_bf16 v[98:101], v[176:179], v[192:195], v[98:101]
	v_mfma_f32_16x16x32_bf16 v[86:89], v[162:165], v[200:203], v[86:89]
	v_mfma_f32_16x16x32_bf16 v[82:85], v[176:179], v[200:203], v[82:85]
	v_mfma_f32_16x16x32_bf16 v[70:73], v[162:165], v[208:211], v[70:73]
	v_mfma_f32_16x16x32_bf16 v[66:69], v[176:179], v[208:211], v[66:69]
	v_mfma_f32_16x16x32_bf16 v[134:137], v[172:175], v[188:191], v[134:137]
	v_mfma_f32_16x16x32_bf16 v[130:133], v[180:183], v[188:191], v[130:133]
	v_mfma_f32_16x16x32_bf16 v[102:105], v[172:175], v[196:199], v[102:105]
	v_mfma_f32_16x16x32_bf16 v[98:101], v[180:183], v[196:199], v[98:101]
	v_mfma_f32_16x16x32_bf16 v[86:89], v[172:175], v[204:207], v[86:89]
	v_mfma_f32_16x16x32_bf16 v[82:85], v[180:183], v[204:207], v[82:85]
	v_mfma_f32_16x16x32_bf16 v[70:73], v[172:175], v[212:215], v[70:73]
	v_mfma_f32_16x16x32_bf16 v[66:69], v[180:183], v[212:215], v[66:69]
	s_setprio 2
	s_barrier
	ds_read_b128 v[184:187], v170 offset:16384
	ds_read_b128 v[188:191], v170 offset:17408
	ds_read_b128 v[192:195], v170 offset:18432
	ds_read_b128 v[196:199], v170 offset:19456
	ds_read_b128 v[200:203], v170 offset:20480
	ds_read_b128 v[204:207], v170 offset:21504
	ds_read_b128 v[208:211], v170 offset:22528
	ds_read_b128 v[212:215], v170 offset:23552
	s_add_i32 s18, s52, s38
	v_lshl_add_u64 v[216:217], s[22:23], 0, v[150:151]
	s_mov_b32 m0, s18
	s_nop 0
	global_load_lds_dwordx4 v[216:217], off
	s_add_i32 m0, s18, 0x2000
	s_add_u32 s18, s22, 0xb0000
	v_lshl_add_u64 v[218:219], s[22:23], 0, v[146:147]
	s_addc_u32 s19, s23, 0
	s_add_i32 s33, s53, s38
	global_load_lds_dwordx4 v[218:219], off
	v_lshl_add_u64 v[220:221], s[18:19], 0, v[150:151]
	s_mov_b32 m0, s33
	v_lshl_add_u64 v[222:223], s[24:25], 0, v[148:149]
	global_load_lds_dwordx4 v[220:221], off
	v_lshl_add_u64 v[220:221], s[18:19], 0, v[146:147]
	s_add_i32 m0, s33, 0x2000
	s_nop 0
	global_load_lds_dwordx4 v[220:221], off
	v_lshl_add_u64 v[220:221], s[24:25], 0, v[152:153]
	s_mov_b32 m0, s40
	s_nop 0
	global_load_lds_dwordx4 v[220:221], off
	s_mov_b32 m0, s41
	s_nop 0
	global_load_lds_dwordx4 v[222:223], off
	s_waitcnt vmcnt(8)
	s_waitcnt lgkmcnt(0)
	s_barrier
; #define PG8_STAGE(bufoff, gbase, voff) do { _Pragma("unroll") for (int _i = 0; _i < 2; ++_i) \
;         __builtin_amdgcn_global_load_lds((const unsigned*)((const char*)(gbase) + (voff)[_i]), (LAS unsigned*)(lds + (bufoff) + ldsw + _i * 8192), 16, 0, 0); } while (0)
; #define PG8_LDA(dst, b, h) do { _Pragma("unroll") for (int m = 0; m < 4; ++m) _Pragma("unroll") for (int k = 0; k < 2; ++k) dst[m][k] = *(const LAS bf16x8*)(lds + PG8_SA(b, h) + aoff + m * 2048 + k * 1024); } while (0)
; #define PG8_LDB(dst, b, h) do { _Pragma("unroll") for (int n = 0; n < 2; ++n) _Pragma("unroll") for (int k = 0; k < 2; ++k) dst[n][k] = *(const LAS bf16x8*)(lds + PG8_SB(b, h) + boff + n * 2048 + k * 1024); } while (0)
; #define PG8_MMA(ai, bj, At, Bt) do { __builtin_amdgcn_s_setprio(1); _Pragma("unroll") for (int m = 0; m < 4; ++m) _Pragma("unroll") for (int n = 0; n < 2; ++n) _Pragma("unroll") for (int k = 0; k < 2; ++k) \
;         acc[ai][bj][m][n] = __builtin_amdgcn_mfma_f32_16x16x32_bf16(Bt[n][k], At[m][k], acc[ai][bj][m][n], 0, 0, 0); __builtin_amdgcn_s_setprio(0); } while (0)
; #define PG8_WAIT_V(n) asm volatile("s_waitcnt vmcnt(" #n ")" ::: "memory")
; #define PG8_WAIT_L(n) asm volatile("s_waitcnt lgkmcnt(" #n ")" ::: "memory")
; #define PG8_BAR __builtin_amdgcn_s_barrier()
; #define PG8_SCHED __builtin_amdgcn_sched_barrier(0)
; template <class Epi>
; __device__ __forceinline__ void gemm_phase(LAS unsigned char* lds, const Gemm g, int G, int c, const Epi& E) {
;     ...
;             PG8_WAIT_V(8); PG8_WAIT_L(0); PG8_BAR; PG8_MMA(1, 0, At, B0); PG8_MMA(1, 1, At, B1); PG8_BAR; PG8_SCHED;
;             PG8_LDB(B0, 1, 0); PG8_LDB(B1, 1, 1); PG8_SCHED; PG8_LDA(At, 1, 0); PG8_STAGE(PG8_SA(0, 1), a2 + hstepA, voffA);
;             PG8_WAIT_V(8); PG8_WAIT_L(0); PG8_BAR; PG8_MMA(0, 0, At, B0); PG8_MMA(0, 1, At, B1); PG8_BAR; PG8_SCHED;
	s_setprio 0
	v_mfma_f32_16x16x32_bf16 v[62:65], v[106:109], v[184:187], v[62:65]
	v_mfma_f32_16x16x32_bf16 v[58:61], v[114:117], v[184:187], v[58:61]
	v_mfma_f32_16x16x32_bf16 v[46:49], v[106:109], v[192:195], v[46:49]
	v_mfma_f32_16x16x32_bf16 v[42:45], v[114:117], v[192:195], v[42:45]
	v_mfma_f32_16x16x32_bf16 v[30:33], v[106:109], v[200:203], v[30:33]
	v_mfma_f32_16x16x32_bf16 v[26:29], v[114:117], v[200:203], v[26:29]
	v_mfma_f32_16x16x32_bf16 v[14:17], v[106:109], v[208:211], v[14:17]
	v_mfma_f32_16x16x32_bf16 v[10:13], v[114:117], v[208:211], v[10:13]
	v_mfma_f32_16x16x32_bf16 v[62:65], v[110:113], v[188:191], v[62:65]
	v_mfma_f32_16x16x32_bf16 v[58:61], v[118:121], v[188:191], v[58:61]
	v_mfma_f32_16x16x32_bf16 v[46:49], v[110:113], v[196:199], v[46:49]
	v_mfma_f32_16x16x32_bf16 v[42:45], v[118:121], v[196:199], v[42:45]
	v_mfma_f32_16x16x32_bf16 v[30:33], v[110:113], v[204:207], v[30:33]
	v_mfma_f32_16x16x32_bf16 v[26:29], v[118:121], v[204:207], v[26:29]
	v_mfma_f32_16x16x32_bf16 v[14:17], v[110:113], v[212:215], v[14:17]
	v_mfma_f32_16x16x32_bf16 v[10:13], v[118:121], v[212:215], v[10:13]
	s_setprio 2
	s_setprio 0
	v_mfma_f32_16x16x32_bf16 v[54:57], v[162:165], v[184:187], v[54:57]
	v_mfma_f32_16x16x32_bf16 v[50:53], v[176:179], v[184:187], v[50:53]
	v_mfma_f32_16x16x32_bf16 v[38:41], v[162:165], v[192:195], v[38:41]
	v_mfma_f32_16x16x32_bf16 v[34:37], v[176:179], v[192:195], v[34:37]
	v_mfma_f32_16x16x32_bf16 v[22:25], v[162:165], v[200:203], v[22:25]
	v_mfma_f32_16x16x32_bf16 v[18:21], v[176:179], v[200:203], v[18:21]
	v_mfma_f32_16x16x32_bf16 v[6:9], v[162:165], v[208:211], v[6:9]
	v_mfma_f32_16x16x32_bf16 v[2:5], v[176:179], v[208:211], v[2:5]
	v_mfma_f32_16x16x32_bf16 v[54:57], v[172:175], v[188:191], v[54:57]
	v_mfma_f32_16x16x32_bf16 v[50:53], v[180:183], v[188:191], v[50:53]
	v_mfma_f32_16x16x32_bf16 v[38:41], v[172:175], v[196:199], v[38:41]
	v_mfma_f32_16x16x32_bf16 v[34:37], v[180:183], v[196:199], v[34:37]
	v_mfma_f32_16x16x32_bf16 v[22:25], v[172:175], v[204:207], v[22:25]
	v_mfma_f32_16x16x32_bf16 v[18:21], v[180:183], v[204:207], v[18:21]
	v_mfma_f32_16x16x32_bf16 v[6:9], v[172:175], v[212:215], v[6:9]
	v_mfma_f32_16x16x32_bf16 v[2:5], v[180:183], v[212:215], v[2:5]
	s_setprio 2
	s_barrier
	s_add_i32 s33, 0, 0x18000
	s_add_i32 s63, 0, 0x1c000
	v_add_u32_e32 v118, s33, v167
	v_add_u32_e32 v171, s63, v167
	ds_read_b128 v[106:109], v118
	ds_read_b128 v[110:113], v118 offset:1024
	ds_read_b128 v[114:117], v118 offset:2048
	ds_read_b128 v[118:121], v118 offset:3072
	ds_read_b128 v[162:165], v171
	ds_read_b128 v[172:175], v171 offset:1024
	ds_read_b128 v[176:179], v171 offset:2048
	ds_read_b128 v[180:183], v171 offset:3072
	ds_read_b128 v[184:187], v170 offset:32768
	ds_read_b128 v[188:191], v170 offset:33792
	ds_read_b128 v[192:195], v170 offset:34816
	ds_read_b128 v[196:199], v170 offset:35840
	ds_read_b128 v[200:203], v170 offset:36864
	ds_read_b128 v[204:207], v170 offset:37888
	ds_read_b128 v[208:211], v170 offset:38912
	ds_read_b128 v[212:215], v170 offset:39936
	s_add_u32 s18, s24, 0xb0000
	s_addc_u32 s19, s25, 0
	s_mov_b32 m0, s42
	v_lshl_add_u64 v[224:225], s[18:19], 0, v[152:153]
	global_load_lds_dwordx4 v[224:225], off
	v_lshl_add_u64 v[224:225], s[18:19], 0, v[148:149]
	s_mov_b32 m0, s43
	s_nop 0
	global_load_lds_dwordx4 v[224:225], off
	s_waitcnt vmcnt(8)
	s_waitcnt lgkmcnt(0)
	s_barrier
	s_setprio 0
	v_mfma_f32_16x16x32_bf16 v[142:145], v[106:109], v[184:187], v[142:145]
	v_mfma_f32_16x16x32_bf16 v[138:141], v[114:117], v[184:187], v[138:141]
	v_mfma_f32_16x16x32_bf16 v[126:129], v[106:109], v[192:195], v[126:129]
	v_mfma_f32_16x16x32_bf16 v[122:125], v[114:117], v[192:195], v[122:125]
	v_mfma_f32_16x16x32_bf16 v[94:97], v[106:109], v[200:203], v[94:97]
	v_mfma_f32_16x16x32_bf16 v[90:93], v[114:117], v[200:203], v[90:93]
	v_mfma_f32_16x16x32_bf16 v[78:81], v[106:109], v[208:211], v[78:81]
	v_mfma_f32_16x16x32_bf16 v[74:77], v[114:117], v[208:211], v[74:77]
	v_mfma_f32_16x16x32_bf16 v[142:145], v[110:113], v[188:191], v[142:145]
	v_mfma_f32_16x16x32_bf16 v[138:141], v[118:121], v[188:191], v[138:141]
	v_mfma_f32_16x16x32_bf16 v[126:129], v[110:113], v[196:199], v[126:129]
	v_mfma_f32_16x16x32_bf16 v[122:125], v[118:121], v[196:199], v[122:125]
	v_mfma_f32_16x16x32_bf16 v[94:97], v[110:113], v[204:207], v[94:97]
	v_mfma_f32_16x16x32_bf16 v[90:93], v[118:121], v[204:207], v[90:93]
	v_mfma_f32_16x16x32_bf16 v[78:81], v[110:113], v[212:215], v[78:81]
	v_mfma_f32_16x16x32_bf16 v[74:77], v[118:121], v[212:215], v[74:77]
	s_setprio 2
	s_setprio 0
	v_mfma_f32_16x16x32_bf16 v[134:137], v[162:165], v[184:187], v[134:137]
	v_mfma_f32_16x16x32_bf16 v[130:133], v[176:179], v[184:187], v[130:133]
	v_mfma_f32_16x16x32_bf16 v[102:105], v[162:165], v[192:195], v[102:105]
	v_mfma_f32_16x16x32_bf16 v[98:101], v[176:179], v[192:195], v[98:101]
	v_mfma_f32_16x16x32_bf16 v[86:89], v[162:165], v[200:203], v[86:89]
	v_mfma_f32_16x16x32_bf16 v[82:85], v[176:179], v[200:203], v[82:85]
	v_mfma_f32_16x16x32_bf16 v[70:73], v[162:165], v[208:211], v[70:73]
	v_mfma_f32_16x16x32_bf16 v[66:69], v[176:179], v[208:211], v[66:69]
	v_mfma_f32_16x16x32_bf16 v[134:137], v[172:175], v[188:191], v[134:137]
	v_mfma_f32_16x16x32_bf16 v[130:133], v[180:183], v[188:191], v[130:133]
	v_mfma_f32_16x16x32_bf16 v[102:105], v[172:175], v[196:199], v[102:105]
	v_mfma_f32_16x16x32_bf16 v[98:101], v[180:183], v[196:199], v[98:101]
	v_mfma_f32_16x16x32_bf16 v[86:89], v[172:175], v[204:207], v[86:89]
	v_mfma_f32_16x16x32_bf16 v[82:85], v[180:183], v[204:207], v[82:85]
	v_mfma_f32_16x16x32_bf16 v[70:73], v[172:175], v[212:215], v[70:73]
	v_mfma_f32_16x16x32_bf16 v[66:69], v[180:183], v[212:215], v[66:69]
	s_setprio 2
	s_barrier
; #define PG8_STAGE(bufoff, gbase, voff) do { _Pragma("unroll") for (int _i = 0; _i < 2; ++_i) \
;         __builtin_amdgcn_global_load_lds((const unsigned*)((const char*)(gbase) + (voff)[_i]), (LAS unsigned*)(lds + (bufoff) + ldsw + _i * 8192), 16, 0, 0); } while (0)
; #define PG8_LDA(dst, b, h) do { _Pragma("unroll") for (int m = 0; m < 4; ++m) _Pragma("unroll") for (int k = 0; k < 2; ++k) dst[m][k] = *(const LAS bf16x8*)(lds + PG8_SA(b, h) + aoff + m * 2048 + k * 1024); } while (0)
; #define PG8_MMA(ai, bj, At, Bt) do { __builtin_amdgcn_s_setprio(1); _Pragma("unroll") for (int m = 0; m < 4; ++m) _Pragma("unroll") for (int n = 0; n < 2; ++n) _Pragma("unroll") for (int k = 0; k < 2; ++k) \
;         acc[ai][bj][m][n] = __builtin_amdgcn_mfma_f32_16x16x32_bf16(Bt[n][k], At[m][k], acc[ai][bj][m][n], 0, 0, 0); __builtin_amdgcn_s_setprio(0); } while (0)
; #define PG8_WAIT_V(n) asm volatile("s_waitcnt vmcnt(" #n ")" ::: "memory")
; #define PG8_WAIT_L(n) asm volatile("s_waitcnt lgkmcnt(" #n ")" ::: "memory")
; #define PG8_BAR __builtin_amdgcn_s_barrier()
; #define PG8_SCHED __builtin_amdgcn_sched_barrier(0)
; template <class Epi>
; __device__ __forceinline__ void gemm_phase(LAS unsigned char* lds, const Gemm g, int G, int c, const Epi& E) {
;     ...
;             PG8_LDA(At, 1, 1); PG8_STAGE(PG8_SB(1, 0), b3, voffB); PG8_STAGE(PG8_SB(1, 1), b3 + hstepB, voffB); PG8_STAGE(PG8_SA(1, 0), a3, voffA);
;             PG8_WAIT_V(8); PG8_WAIT_L(0); PG8_BAR; PG8_MMA(1, 0, At, B0); PG8_MMA(1, 1, At, B1); PG8_BAR; PG8_SCHED;
;         }
;         if (wr == 0) PG8_BAR;
	ds_read_b128 v[184:187], v170 offset:49152
	ds_read_b128 v[188:191], v170 offset:50176
	ds_read_b128 v[192:195], v170 offset:51200
	ds_read_b128 v[196:199], v170 offset:52224
	ds_read_b128 v[200:203], v170 offset:53248
	ds_read_b128 v[204:207], v170 offset:54272
	ds_read_b128 v[208:211], v170 offset:55296
	ds_read_b128 v[212:215], v170 offset:56320
	s_add_i32 s18, s33, s38
	v_lshl_add_u64 v[216:217], v[216:217], 0, s[12:13]
	s_mov_b32 m0, s18
	s_nop 0
	global_load_lds_dwordx4 v[216:217], off
	s_add_i32 m0, s18, 0x2000
	s_add_u32 s18, s22, 0xb0080
	v_lshl_add_u64 v[216:217], v[218:219], 0, s[12:13]
	s_addc_u32 s19, s23, 0
	s_add_i32 s22, s63, s38
	global_load_lds_dwordx4 v[216:217], off
	v_lshl_add_u64 v[216:217], s[18:19], 0, v[150:151]
	s_mov_b32 m0, s22
	s_nop 0
	global_load_lds_dwordx4 v[216:217], off
	v_lshl_add_u64 v[216:217], s[18:19], 0, v[146:147]
	s_add_i32 m0, s22, 0x2000
	s_nop 0
	global_load_lds_dwordx4 v[216:217], off
	v_lshl_add_u64 v[216:217], v[220:221], 0, s[12:13]
	s_mov_b32 m0, s49
	s_nop 0
	global_load_lds_dwordx4 v[216:217], off
	v_lshl_add_u64 v[216:217], v[222:223], 0, s[12:13]
	s_mov_b32 m0, s50
	s_nop 0
	global_load_lds_dwordx4 v[216:217], off
	s_waitcnt vmcnt(8)
	s_waitcnt lgkmcnt(0)
	s_barrier
	s_setprio 0
	v_mfma_f32_16x16x32_bf16 v[62:65], v[106:109], v[184:187], v[62:65]
	v_mfma_f32_16x16x32_bf16 v[58:61], v[114:117], v[184:187], v[58:61]
	v_mfma_f32_16x16x32_bf16 v[46:49], v[106:109], v[192:195], v[46:49]
	v_mfma_f32_16x16x32_bf16 v[42:45], v[114:117], v[192:195], v[42:45]
	v_mfma_f32_16x16x32_bf16 v[30:33], v[106:109], v[200:203], v[30:33]
	v_mfma_f32_16x16x32_bf16 v[26:29], v[114:117], v[200:203], v[26:29]
	v_mfma_f32_16x16x32_bf16 v[14:17], v[106:109], v[208:211], v[14:17]
	v_mfma_f32_16x16x32_bf16 v[10:13], v[114:117], v[208:211], v[10:13]
	v_mfma_f32_16x16x32_bf16 v[62:65], v[110:113], v[188:191], v[62:65]
	v_mfma_f32_16x16x32_bf16 v[58:61], v[118:121], v[188:191], v[58:61]
	v_mfma_f32_16x16x32_bf16 v[46:49], v[110:113], v[196:199], v[46:49]
	v_mfma_f32_16x16x32_bf16 v[42:45], v[118:121], v[196:199], v[42:45]
	v_mfma_f32_16x16x32_bf16 v[30:33], v[110:113], v[204:207], v[30:33]
	v_mfma_f32_16x16x32_bf16 v[26:29], v[118:121], v[204:207], v[26:29]
	v_mfma_f32_16x16x32_bf16 v[14:17], v[110:113], v[212:215], v[14:17]
	v_mfma_f32_16x16x32_bf16 v[10:13], v[118:121], v[212:215], v[10:13]
	s_setprio 2
	s_setprio 0
	v_mfma_f32_16x16x32_bf16 v[54:57], v[162:165], v[184:187], v[54:57]
	v_mfma_f32_16x16x32_bf16 v[50:53], v[176:179], v[184:187], v[50:53]
	v_mfma_f32_16x16x32_bf16 v[38:41], v[162:165], v[192:195], v[38:41]
	v_mfma_f32_16x16x32_bf16 v[34:37], v[176:179], v[192:195], v[34:37]
	v_mfma_f32_16x16x32_bf16 v[22:25], v[162:165], v[200:203], v[22:25]
	v_mfma_f32_16x16x32_bf16 v[18:21], v[176:179], v[200:203], v[18:21]
	v_mfma_f32_16x16x32_bf16 v[6:9], v[162:165], v[208:211], v[6:9]
	v_mfma_f32_16x16x32_bf16 v[2:5], v[176:179], v[208:211], v[2:5]
	v_mfma_f32_16x16x32_bf16 v[54:57], v[172:175], v[188:191], v[54:57]
	v_mfma_f32_16x16x32_bf16 v[50:53], v[180:183], v[188:191], v[50:53]
	v_mfma_f32_16x16x32_bf16 v[38:41], v[172:175], v[196:199], v[38:41]
	v_mfma_f32_16x16x32_bf16 v[34:37], v[180:183], v[196:199], v[34:37]
	v_mfma_f32_16x16x32_bf16 v[22:25], v[172:175], v[204:207], v[22:25]
	v_mfma_f32_16x16x32_bf16 v[18:21], v[180:183], v[204:207], v[18:21]
	v_mfma_f32_16x16x32_bf16 v[6:9], v[172:175], v[212:215], v[6:9]
	v_mfma_f32_16x16x32_bf16 v[2:5], v[180:183], v[212:215], v[2:5]
	s_setprio 2
	s_barrier
	s_add_i32 s62, s62, 2
	s_add_u32 s60, s60, 0x100
	s_addc_u32 s61, s61, 0
	s_cmp_gt_u32 s62, 41
	s_mov_b64 s[18:19], s[20:21]
	s_cbranch_scc0 .LBB0_2169
	s_and_b64 vcc, exec, s[14:15]
	s_cbranch_vccz .LBB0_2172
	s_barrier
